# v58 + strategy 'one static priority raise for the younger half': s_setprio 1 once per unit K-loop for waves 4-7, all per-segment setprio flips deleted
# speedup vs baseline: 1.0035x; 1.0006x over previous
; #define PG8_STAGE(bufoff, gbase, voff) do { _Pragma("unroll") for (int _i = 0; _i < 2; ++_i) \
;         __builtin_amdgcn_global_load_lds((const unsigned*)((const char*)(gbase) + (voff)[_i]), (PG8_LAS unsigned*)(lds + (bufoff) + ldsw + _i * 8192), 16, 0, 0); } while (0)
; #define PG8_WAIT_V(n) asm volatile("s_waitcnt vmcnt(" #n ")" ::: "memory")
; template <class Epi, class Sched, bool ALIGN_EPI = false, bool SP2 = false>
; __device__ __forceinline__ void gemm_phase(PG8_LAS unsigned char* lds, const Gemm g, const Sched& S, const Epi& E, const int tid_in) {
;     ...
;         const bool has_next = S.next(ui + 1, nxt);
;         const char* nA = has_next ? (const char*)g.A + (size_t)nxt.pm * tstep : cA; const char* nB = has_next ? (const char*)g.Bt + (size_t)nxt.pn * tstep : cB;
;         for (int t = 0; t < nt; t += 2) {
;             if constexpr (Epi::KSPLIT > 0) { if (t == Epi::KSPLIT / BK) E.midk(acc, cur, wr, wc, fr, fq); }
;             const bool last = (t == nt - 2);
;             const char* a1 = cA + (size_t)(t + 1) * kstep;
;             const char* a2 = last ? nA : cA + (size_t)(t + 2) * kstep; const char* b2 = last ? nB : cB + (size_t)(t + 2) * kstep;
;             const char* a3 = a2 + kstep; const char* b3 = b2 + kstep;
;             if (last && has_next) S.a_ready(nxt);
;             if constexpr (SP2) {
;             PG8_LDB(B0, 0, 0); PG8_LDB(B1, 0, 1); PG8_SCHED; PG8_LDA(At, 0, 0); PG8_STAGE(PG8_SA(1, 1), a1 + hstep, voffA);
;             PG8_WAIT_V(8); PG8_WAIT_L(0); PG8_BAR; PG8_MMA(0, 0, At, B0); PG8_MMA(0, 1, At, B1); PG8_BAR; PG8_SCHED;
;             PG8_LDA(At, 0, 1); PG8_STAGE(PG8_SB(0, 0), b2, voffB); PG8_STAGE(PG8_SB(0, 1), b2 + hstep, voffB); PG8_STAGE(PG8_SA(0, 0), a2, voffA);
;             PG8_WAIT_V(8); PG8_WAIT_L(0); PG8_BAR; PG8_MMA(1, 0, At, B0); PG8_MMA(1, 1, At, B1); PG8_BAR; PG8_SCHED;
;             PG8_LDB(B0, 1, 0); PG8_LDB(B1, 1, 1); PG8_SCHED; PG8_LDA(At, 1, 0); PG8_STAGE(PG8_SA(0, 1), a2 + hstep, voffA);
;             PG8_WAIT_V(8); PG8_WAIT_L(0); PG8_BAR; PG8_MMA(0, 0, At, B0); PG8_MMA(0, 1, At, B1); PG8_BAR; PG8_SCHED;
;             PG8_LDA(At, 1, 1); PG8_STAGE(PG8_SB(1, 0), b3, voffB); PG8_STAGE(PG8_SB(1, 1), b3 + hstep, voffB); PG8_STAGE(PG8_SA(1, 0), a3, voffA);
;             PG8_WAIT_V(8); PG8_WAIT_L(0); PG8_BAR; PG8_MMA(1, 0, At, B0); PG8_MMA(1, 1, At, B1); PG8_BAR; PG8_SCHED;
.LBB0_351:
	s_ashr_i32 s27, s26, 31
	s_lshl_b64 s[28:29], s[26:27], 20
	s_add_u32 s28, s1, s28
	s_addc_u32 s29, s5, s29
	s_and_b64 s[30:31], s[36:37], exec
	s_cselect_b32 s27, s29, s35
	s_cselect_b32 s53, s28, s34
	s_ashr_i32 s25, s24, 31
	s_lshl_b64 s[30:31], s[24:25], 20
	s_add_u32 s30, s8, s30
	s_addc_u32 s31, s10, s31
	s_and_b64 s[42:43], s[36:37], exec
	s_cselect_b32 s25, s31, s39
	s_cselect_b32 s54, s30, s38
	s_add_u32 s34, s34, 0x80080
	s_addc_u32 s35, s35, 0
	s_add_u32 s55, s38, 0x100
	v_mov_b32_e32 v0, 0
	s_addc_u32 s56, s39, 0
	s_mov_b32 s57, -2
	s_cmp_lt_u32 s19, 0x1000
	s_cbranch_scc1 .LPRIO_352
	s_setprio 1
.LPRIO_352:
	s_mov_b32 m0, s49
	s_nop 0
	global_load_lds_dwordx4 v132, s[100:101]
	s_add_u32 s38, s34, 0xfff80080
	s_addc_u32 s39, s35, -1
	s_add_i32 s58, 0, 0x10000
	s_cmp_eq_u32 s57, 28
	s_cselect_b32 s43, s27, s39
	s_cselect_b32 s42, s53, s38
	v_add_u32_e32 v145, s58, v142
	s_cselect_b32 s39, s25, s56
	s_cselect_b32 s38, s54, s55
	s_add_i32 s60, 0, 0x14000
	ds_read_b128 v[146:149], v145
	ds_read_b128 v[150:153], v145 offset:1024
	ds_read_b128 v[154:157], v145 offset:2048
	ds_read_b128 v[158:161], v145 offset:3072
	v_add_u32_e32 v145, s60, v142
	ds_read_b128 v[162:165], v145
	ds_read_b128 v[166:169], v145 offset:1024
	ds_read_b128 v[170:173], v145 offset:2048
	ds_read_b128 v[174:177], v145 offset:3072
	s_add_i32 m0, s44, 0xc000
	ds_read_b128 v[178:181], v144
	ds_read_b128 v[182:185], v144 offset:1024
	ds_read_b128 v[186:189], v144 offset:2048
	ds_read_b128 v[190:193], v144 offset:3072
	ds_read_b128 v[194:197], v144 offset:4096
	ds_read_b128 v[198:201], v144 offset:5120
	ds_read_b128 v[202:205], v144 offset:6144
	ds_read_b128 v[208:211], v144 offset:7168
	global_load_lds_dwordx4 v138, s[34:35]
	s_add_i32 m0, s44, 0xe000
	s_nop 0
	global_load_lds_dwordx4 v140, s[34:35]
	s_waitcnt vmcnt(8)
	s_waitcnt lgkmcnt(0)
	s_barrier
	v_mfma_f32_16x16x32_bf16 v[126:129], v[146:149], v[178:181], 0
	v_mfma_f32_16x16x32_bf16 v[122:125], v[154:157], v[178:181], 0
	v_mfma_f32_16x16x32_bf16 v[114:117], v[146:149], v[186:189], 0
	v_mfma_f32_16x16x32_bf16 v[106:109], v[154:157], v[186:189], 0
	v_mfma_f32_16x16x32_bf16 v[98:101], v[146:149], v[194:197], 0
	v_mfma_f32_16x16x32_bf16 v[90:93], v[154:157], v[194:197], 0
	v_mfma_f32_16x16x32_bf16 v[82:85], v[146:149], v[202:205], 0
	v_mfma_f32_16x16x32_bf16 v[74:77], v[154:157], v[202:205], 0
	v_mfma_f32_16x16x32_bf16 v[126:129], v[150:153], v[182:185], v[126:129]
	v_mfma_f32_16x16x32_bf16 v[122:125], v[158:161], v[182:185], v[122:125]
	v_mfma_f32_16x16x32_bf16 v[114:117], v[150:153], v[190:193], v[114:117]
	v_mfma_f32_16x16x32_bf16 v[106:109], v[158:161], v[190:193], v[106:109]
	v_mfma_f32_16x16x32_bf16 v[98:101], v[150:153], v[198:201], v[98:101]
	v_mfma_f32_16x16x32_bf16 v[90:93], v[158:161], v[198:201], v[90:93]
	v_mfma_f32_16x16x32_bf16 v[82:85], v[150:153], v[208:211], v[82:85]
	v_mfma_f32_16x16x32_bf16 v[74:77], v[158:161], v[208:211], v[74:77]
	v_mfma_f32_16x16x32_bf16 v[118:121], v[162:165], v[178:181], 0
	v_mfma_f32_16x16x32_bf16 v[110:113], v[170:173], v[178:181], 0
	v_mfma_f32_16x16x32_bf16 v[102:105], v[162:165], v[186:189], 0
	v_mfma_f32_16x16x32_bf16 v[94:97], v[170:173], v[186:189], 0
	v_mfma_f32_16x16x32_bf16 v[86:89], v[162:165], v[194:197], 0
	v_mfma_f32_16x16x32_bf16 v[78:81], v[170:173], v[194:197], 0
	v_mfma_f32_16x16x32_bf16 v[70:73], v[162:165], v[202:205], 0
	v_mfma_f32_16x16x32_bf16 v[66:69], v[170:173], v[202:205], 0
	v_mfma_f32_16x16x32_bf16 v[118:121], v[166:169], v[182:185], v[118:121]
	v_mfma_f32_16x16x32_bf16 v[110:113], v[174:177], v[182:185], v[110:113]
	v_mfma_f32_16x16x32_bf16 v[102:105], v[166:169], v[190:193], v[102:105]
	v_mfma_f32_16x16x32_bf16 v[94:97], v[174:177], v[190:193], v[94:97]
	v_mfma_f32_16x16x32_bf16 v[86:89], v[166:169], v[198:201], v[86:89]
	v_mfma_f32_16x16x32_bf16 v[78:81], v[174:177], v[198:201], v[78:81]
	v_mfma_f32_16x16x32_bf16 v[70:73], v[166:169], v[208:211], v[70:73]
	v_mfma_f32_16x16x32_bf16 v[66:69], v[174:177], v[208:211], v[66:69]
	s_barrier
	s_add_i32 s58, s58, s19
	s_add_u32 s98, s38, 0x80
	s_addc_u32 s99, s39, 0
	s_mov_b32 m0, s58
	ds_read_b128 v[178:181], v144 offset:16384
	ds_read_b128 v[182:185], v144 offset:17408
	ds_read_b128 v[186:189], v144 offset:18432
	ds_read_b128 v[190:193], v144 offset:19456
	ds_read_b128 v[194:197], v144 offset:20480
	ds_read_b128 v[198:201], v144 offset:21504
	ds_read_b128 v[202:205], v144 offset:22528
	ds_read_b128 v[208:211], v144 offset:23552
	global_load_lds_dwordx4 v134, s[38:39]
	s_add_i32 m0, s58, 0x2000
	s_add_u32 s58, s38, 0x80000
	s_addc_u32 s59, s39, 0
	s_add_i32 s60, s60, s19
	global_load_lds_dwordx4 v130, s[38:39]
	s_mov_b32 m0, s60
	s_add_u32 s100, s42, 0x80
	s_addc_u32 s101, s43, 0
	global_load_lds_dwordx4 v134, s[58:59]
	s_add_i32 m0, s60, 0x2000
	s_nop 0
	global_load_lds_dwordx4 v130, s[58:59]
	s_mov_b32 m0, s44
	s_nop 0
	global_load_lds_dwordx4 v136, s[42:43]
	s_waitcnt vmcnt(7)
	s_waitcnt lgkmcnt(0)
	s_barrier
; #define PG8_STAGE(bufoff, gbase, voff) do { _Pragma("unroll") for (int _i = 0; _i < 2; ++_i) \
;         __builtin_amdgcn_global_load_lds((const unsigned*)((const char*)(gbase) + (voff)[_i]), (PG8_LAS unsigned*)(lds + (bufoff) + ldsw + _i * 8192), 16, 0, 0); } while (0)
; #define PG8_LDA(dst, b, h) do { _Pragma("unroll") for (int m = 0; m < 4; ++m) _Pragma("unroll") for (int k = 0; k < 2; ++k) dst[m][k] = *(const PG8_LAS bf16x8*)(lds + PG8_SA(b, h) + aoff + m * 2048 + k * 1024); } while (0)
; #define PG8_LDB(dst, b, h) do { _Pragma("unroll") for (int n = 0; n < 2; ++n) _Pragma("unroll") for (int k = 0; k < 2; ++k) dst[n][k] = *(const PG8_LAS bf16x8*)(lds + PG8_SB(b, h) + boff + n * 2048 + k * 1024); } while (0)
; #define PG8_MMA(ai, bj, At, Bt) do { __builtin_amdgcn_s_setprio(1); _Pragma("unroll") for (int m = 0; m < 4; ++m) _Pragma("unroll") for (int n = 0; n < 2; ++n) _Pragma("unroll") for (int k = 0; k < 2; ++k) \
;         acc[ai][bj][m][n] = __builtin_amdgcn_mfma_f32_16x16x32_bf16(Bt[n][k], At[m][k], acc[ai][bj][m][n], 0, 0, 0); __builtin_amdgcn_s_setprio(0); } while (0)
; template <class Epi, class Sched, bool ALIGN_EPI = false, bool SP2 = false>
; __device__ __forceinline__ void gemm_phase(PG8_LAS unsigned char* lds, const Gemm g, const Sched& S, const Epi& E, const int tid_in) {
;     ...
;             if constexpr (SP2) {
;             PG8_LDB(B0, 0, 0); PG8_LDB(B1, 0, 1); PG8_SCHED; PG8_LDA(At, 0, 0); PG8_STAGE(PG8_SA(1, 1), a1 + hstep, voffA);
;             PG8_WAIT_V(8); PG8_WAIT_L(0); PG8_BAR; PG8_MMA(0, 0, At, B0); PG8_MMA(0, 1, At, B1); PG8_BAR; PG8_SCHED;
;             PG8_LDA(At, 0, 1); PG8_STAGE(PG8_SB(0, 0), b2, voffB); PG8_STAGE(PG8_SB(0, 1), b2 + hstep, voffB); PG8_STAGE(PG8_SA(0, 0), a2, voffA);
;             PG8_WAIT_V(8); PG8_WAIT_L(0); PG8_BAR; PG8_MMA(1, 0, At, B0); PG8_MMA(1, 1, At, B1); PG8_BAR; PG8_SCHED;
;             PG8_LDB(B0, 1, 0); PG8_LDB(B1, 1, 1); PG8_SCHED; PG8_LDA(At, 1, 0); PG8_STAGE(PG8_SA(0, 1), a2 + hstep, voffA);
;             PG8_WAIT_V(8); PG8_WAIT_L(0); PG8_BAR; PG8_MMA(0, 0, At, B0); PG8_MMA(0, 1, At, B1); PG8_BAR; PG8_SCHED;
;             PG8_LDA(At, 1, 1); PG8_STAGE(PG8_SB(1, 0), b3, voffB); PG8_STAGE(PG8_SB(1, 1), b3 + hstep, voffB); PG8_STAGE(PG8_SA(1, 0), a3, voffA);
;             PG8_WAIT_V(8); PG8_WAIT_L(0); PG8_BAR; PG8_MMA(1, 0, At, B0); PG8_MMA(1, 1, At, B1); PG8_BAR; PG8_SCHED;
	v_mfma_f32_16x16x32_bf16 v[62:65], v[146:149], v[178:181], 0
	v_mfma_f32_16x16x32_bf16 v[58:61], v[154:157], v[178:181], 0
	v_mfma_f32_16x16x32_bf16 v[50:53], v[146:149], v[186:189], 0
	v_mfma_f32_16x16x32_bf16 v[42:45], v[154:157], v[186:189], 0
	v_mfma_f32_16x16x32_bf16 v[34:37], v[146:149], v[194:197], 0
	v_mfma_f32_16x16x32_bf16 v[26:29], v[154:157], v[194:197], 0
	v_mfma_f32_16x16x32_bf16 v[16:19], v[146:149], v[202:205], 0
	v_mfma_f32_16x16x32_bf16 v[8:11], v[154:157], v[202:205], 0
	v_mfma_f32_16x16x32_bf16 v[62:65], v[150:153], v[182:185], v[62:65]
	v_mfma_f32_16x16x32_bf16 v[58:61], v[158:161], v[182:185], v[58:61]
	v_mfma_f32_16x16x32_bf16 v[50:53], v[150:153], v[190:193], v[50:53]
	v_mfma_f32_16x16x32_bf16 v[42:45], v[158:161], v[190:193], v[42:45]
	v_mfma_f32_16x16x32_bf16 v[34:37], v[150:153], v[198:201], v[34:37]
	v_mfma_f32_16x16x32_bf16 v[26:29], v[158:161], v[198:201], v[26:29]
	v_mfma_f32_16x16x32_bf16 v[16:19], v[150:153], v[208:211], v[16:19]
	v_mfma_f32_16x16x32_bf16 v[8:11], v[158:161], v[208:211], v[8:11]
	v_mfma_f32_16x16x32_bf16 v[54:57], v[162:165], v[178:181], 0
	v_mfma_f32_16x16x32_bf16 v[46:49], v[170:173], v[178:181], 0
	v_mfma_f32_16x16x32_bf16 v[38:41], v[162:165], v[186:189], 0
	v_mfma_f32_16x16x32_bf16 v[30:33], v[170:173], v[186:189], 0
	v_mfma_f32_16x16x32_bf16 v[22:25], v[162:165], v[194:197], 0
	v_mfma_f32_16x16x32_bf16 v[12:15], v[170:173], v[194:197], 0
	v_mfma_f32_16x16x32_bf16 v[4:7], v[162:165], v[202:205], 0
	v_mfma_f32_16x16x32_bf16 v[0:3], v[170:173], v[202:205], 0
	v_mfma_f32_16x16x32_bf16 v[54:57], v[166:169], v[182:185], v[54:57]
	v_mfma_f32_16x16x32_bf16 v[46:49], v[174:177], v[182:185], v[46:49]
	v_mfma_f32_16x16x32_bf16 v[38:41], v[166:169], v[190:193], v[38:41]
	v_mfma_f32_16x16x32_bf16 v[30:33], v[174:177], v[190:193], v[30:33]
	v_mfma_f32_16x16x32_bf16 v[22:25], v[166:169], v[198:201], v[22:25]
	v_mfma_f32_16x16x32_bf16 v[12:15], v[174:177], v[198:201], v[12:15]
	v_mfma_f32_16x16x32_bf16 v[4:7], v[166:169], v[208:211], v[4:7]
	v_mfma_f32_16x16x32_bf16 v[0:3], v[174:177], v[208:211], v[0:3]
	s_barrier
	s_add_i32 s58, 0, 0x18000
	v_add_u32_e32 v145, s58, v142
	s_add_i32 s59, 0, 0x1c000
	ds_read_b128 v[146:149], v145
	ds_read_b128 v[150:153], v145 offset:1024
	ds_read_b128 v[154:157], v145 offset:2048
	ds_read_b128 v[158:161], v145 offset:3072
	v_add_u32_e32 v145, s59, v142
	ds_read_b128 v[162:165], v145
	ds_read_b128 v[166:169], v145 offset:1024
	ds_read_b128 v[170:173], v145 offset:2048
	ds_read_b128 v[174:177], v145 offset:3072
	s_mov_b32 m0, s45
	s_nop 0
	global_load_lds_dwordx4 v132, s[42:43]
	s_add_u32 s42, s42, 0x80000
	s_addc_u32 s43, s43, 0
	s_mov_b32 m0, s46
	ds_read_b128 v[178:181], v144 offset:32768
	ds_read_b128 v[182:185], v144 offset:33792
	ds_read_b128 v[186:189], v144 offset:34816
	ds_read_b128 v[190:193], v144 offset:35840
	ds_read_b128 v[194:197], v144 offset:36864
	ds_read_b128 v[198:201], v144 offset:37888
	ds_read_b128 v[202:205], v144 offset:38912
	ds_read_b128 v[208:211], v144 offset:39936
	global_load_lds_dwordx4 v136, s[42:43]
	s_mov_b32 m0, s47
	s_nop 0
	global_load_lds_dwordx4 v132, s[42:43]
	s_waitcnt vmcnt(8)
	s_waitcnt lgkmcnt(0)
	s_barrier
	v_mfma_f32_16x16x32_bf16 v[126:129], v[146:149], v[178:181], v[126:129]
	v_mfma_f32_16x16x32_bf16 v[122:125], v[154:157], v[178:181], v[122:125]
	v_mfma_f32_16x16x32_bf16 v[114:117], v[146:149], v[186:189], v[114:117]
	v_mfma_f32_16x16x32_bf16 v[106:109], v[154:157], v[186:189], v[106:109]
	v_mfma_f32_16x16x32_bf16 v[98:101], v[146:149], v[194:197], v[98:101]
	v_mfma_f32_16x16x32_bf16 v[90:93], v[154:157], v[194:197], v[90:93]
	v_mfma_f32_16x16x32_bf16 v[82:85], v[146:149], v[202:205], v[82:85]
	v_mfma_f32_16x16x32_bf16 v[74:77], v[154:157], v[202:205], v[74:77]
	v_mfma_f32_16x16x32_bf16 v[126:129], v[150:153], v[182:185], v[126:129]
	v_mfma_f32_16x16x32_bf16 v[122:125], v[158:161], v[182:185], v[122:125]
	v_mfma_f32_16x16x32_bf16 v[114:117], v[150:153], v[190:193], v[114:117]
	v_mfma_f32_16x16x32_bf16 v[106:109], v[158:161], v[190:193], v[106:109]
	v_mfma_f32_16x16x32_bf16 v[98:101], v[150:153], v[198:201], v[98:101]
	v_mfma_f32_16x16x32_bf16 v[90:93], v[158:161], v[198:201], v[90:93]
	v_mfma_f32_16x16x32_bf16 v[82:85], v[150:153], v[208:211], v[82:85]
	v_mfma_f32_16x16x32_bf16 v[74:77], v[158:161], v[208:211], v[74:77]
	v_mfma_f32_16x16x32_bf16 v[118:121], v[162:165], v[178:181], v[118:121]
	v_mfma_f32_16x16x32_bf16 v[110:113], v[170:173], v[178:181], v[110:113]
	v_mfma_f32_16x16x32_bf16 v[102:105], v[162:165], v[186:189], v[102:105]
	v_mfma_f32_16x16x32_bf16 v[94:97], v[170:173], v[186:189], v[94:97]
	v_mfma_f32_16x16x32_bf16 v[86:89], v[162:165], v[194:197], v[86:89]
	v_mfma_f32_16x16x32_bf16 v[78:81], v[170:173], v[194:197], v[78:81]
	v_mfma_f32_16x16x32_bf16 v[70:73], v[162:165], v[202:205], v[70:73]
	v_mfma_f32_16x16x32_bf16 v[66:69], v[170:173], v[202:205], v[66:69]
	v_mfma_f32_16x16x32_bf16 v[118:121], v[166:169], v[182:185], v[118:121]
	v_mfma_f32_16x16x32_bf16 v[110:113], v[174:177], v[182:185], v[110:113]
	v_mfma_f32_16x16x32_bf16 v[102:105], v[166:169], v[190:193], v[102:105]
	v_mfma_f32_16x16x32_bf16 v[94:97], v[174:177], v[190:193], v[94:97]
	v_mfma_f32_16x16x32_bf16 v[86:89], v[166:169], v[198:201], v[86:89]
	v_mfma_f32_16x16x32_bf16 v[78:81], v[174:177], v[198:201], v[78:81]
	v_mfma_f32_16x16x32_bf16 v[70:73], v[166:169], v[208:211], v[70:73]
	v_mfma_f32_16x16x32_bf16 v[66:69], v[174:177], v[208:211], v[66:69]
	s_barrier
; #define PG8_STAGE(bufoff, gbase, voff) do { _Pragma("unroll") for (int _i = 0; _i < 2; ++_i) \
;         __builtin_amdgcn_global_load_lds((const unsigned*)((const char*)(gbase) + (voff)[_i]), (PG8_LAS unsigned*)(lds + (bufoff) + ldsw + _i * 8192), 16, 0, 0); } while (0)
; #define PG8_LDA(dst, b, h) do { _Pragma("unroll") for (int m = 0; m < 4; ++m) _Pragma("unroll") for (int k = 0; k < 2; ++k) dst[m][k] = *(const PG8_LAS bf16x8*)(lds + PG8_SA(b, h) + aoff + m * 2048 + k * 1024); } while (0)
; #define PG8_LDB(dst, b, h) do { _Pragma("unroll") for (int n = 0; n < 2; ++n) _Pragma("unroll") for (int k = 0; k < 2; ++k) dst[n][k] = *(const PG8_LAS bf16x8*)(lds + PG8_SB(b, h) + boff + n * 2048 + k * 1024); } while (0)
; #define PG8_MMA(ai, bj, At, Bt) do { __builtin_amdgcn_s_setprio(1); _Pragma("unroll") for (int m = 0; m < 4; ++m) _Pragma("unroll") for (int n = 0; n < 2; ++n) _Pragma("unroll") for (int k = 0; k < 2; ++k) \
;         acc[ai][bj][m][n] = __builtin_amdgcn_mfma_f32_16x16x32_bf16(Bt[n][k], At[m][k], acc[ai][bj][m][n], 0, 0, 0); __builtin_amdgcn_s_setprio(0); } while (0)
; template <class Epi, class Sched, bool ALIGN_EPI = false, bool SP2 = false>
; __device__ __forceinline__ void gemm_phase(PG8_LAS unsigned char* lds, const Gemm g, const Sched& S, const Epi& E, const int tid_in) {
;     ...
;             if constexpr (SP2) {
;             PG8_LDB(B0, 0, 0); PG8_LDB(B1, 0, 1); PG8_SCHED; PG8_LDA(At, 0, 0); PG8_STAGE(PG8_SA(1, 1), a1 + hstep, voffA);
;             PG8_WAIT_V(8); PG8_WAIT_L(0); PG8_BAR; PG8_MMA(0, 0, At, B0); PG8_MMA(0, 1, At, B1); PG8_BAR; PG8_SCHED;
;             PG8_LDA(At, 0, 1); PG8_STAGE(PG8_SB(0, 0), b2, voffB); PG8_STAGE(PG8_SB(0, 1), b2 + hstep, voffB); PG8_STAGE(PG8_SA(0, 0), a2, voffA);
;             PG8_WAIT_V(8); PG8_WAIT_L(0); PG8_BAR; PG8_MMA(1, 0, At, B0); PG8_MMA(1, 1, At, B1); PG8_BAR; PG8_SCHED;
;             PG8_LDB(B0, 1, 0); PG8_LDB(B1, 1, 1); PG8_SCHED; PG8_LDA(At, 1, 0); PG8_STAGE(PG8_SA(0, 1), a2 + hstep, voffA);
;             PG8_WAIT_V(8); PG8_WAIT_L(0); PG8_BAR; PG8_MMA(0, 0, At, B0); PG8_MMA(0, 1, At, B1); PG8_BAR; PG8_SCHED;
;             PG8_LDA(At, 1, 1); PG8_STAGE(PG8_SB(1, 0), b3, voffB); PG8_STAGE(PG8_SB(1, 1), b3 + hstep, voffB); PG8_STAGE(PG8_SA(1, 0), a3, voffA);
;             PG8_WAIT_V(8); PG8_WAIT_L(0); PG8_BAR; PG8_MMA(1, 0, At, B0); PG8_MMA(1, 1, At, B1); PG8_BAR; PG8_SCHED;
	s_add_i32 s42, s58, s19
	s_mov_b32 m0, s42
	ds_read_b128 v[178:181], v144 offset:49152
	ds_read_b128 v[182:185], v144 offset:50176
	ds_read_b128 v[186:189], v144 offset:51200
	ds_read_b128 v[190:193], v144 offset:52224
	ds_read_b128 v[194:197], v144 offset:53248
	ds_read_b128 v[198:201], v144 offset:54272
	ds_read_b128 v[202:205], v144 offset:55296
	ds_read_b128 v[208:211], v144 offset:56320
	global_load_lds_dwordx4 v134, s[98:99]
	s_add_i32 m0, s42, 0x2000
	s_add_u32 s38, s38, 0x80080
	s_addc_u32 s39, s39, 0
	s_add_i32 s42, s59, s19
	global_load_lds_dwordx4 v130, s[98:99]
	s_mov_b32 m0, s42
	s_nop 0
	global_load_lds_dwordx4 v134, s[38:39]
	s_add_i32 m0, s42, 0x2000
	s_nop 0
	global_load_lds_dwordx4 v130, s[38:39]
	s_mov_b32 m0, s48
	s_nop 0
	global_load_lds_dwordx4 v136, s[100:101]
	s_waitcnt vmcnt(7)
	s_waitcnt lgkmcnt(0)
	s_barrier
	v_mfma_f32_16x16x32_bf16 v[62:65], v[146:149], v[178:181], v[62:65]
	v_mfma_f32_16x16x32_bf16 v[58:61], v[154:157], v[178:181], v[58:61]
	v_mfma_f32_16x16x32_bf16 v[50:53], v[146:149], v[186:189], v[50:53]
	v_mfma_f32_16x16x32_bf16 v[42:45], v[154:157], v[186:189], v[42:45]
	v_mfma_f32_16x16x32_bf16 v[34:37], v[146:149], v[194:197], v[34:37]
	v_mfma_f32_16x16x32_bf16 v[26:29], v[154:157], v[194:197], v[26:29]
	v_mfma_f32_16x16x32_bf16 v[16:19], v[146:149], v[202:205], v[16:19]
	v_mfma_f32_16x16x32_bf16 v[8:11], v[154:157], v[202:205], v[8:11]
	v_mfma_f32_16x16x32_bf16 v[62:65], v[150:153], v[182:185], v[62:65]
	v_mfma_f32_16x16x32_bf16 v[58:61], v[158:161], v[182:185], v[58:61]
	v_mfma_f32_16x16x32_bf16 v[50:53], v[150:153], v[190:193], v[50:53]
	v_mfma_f32_16x16x32_bf16 v[42:45], v[158:161], v[190:193], v[42:45]
	v_mfma_f32_16x16x32_bf16 v[34:37], v[150:153], v[198:201], v[34:37]
	v_mfma_f32_16x16x32_bf16 v[26:29], v[158:161], v[198:201], v[26:29]
	v_mfma_f32_16x16x32_bf16 v[16:19], v[150:153], v[208:211], v[16:19]
	v_mfma_f32_16x16x32_bf16 v[8:11], v[158:161], v[208:211], v[8:11]
	v_mfma_f32_16x16x32_bf16 v[54:57], v[162:165], v[178:181], v[54:57]
	v_mfma_f32_16x16x32_bf16 v[46:49], v[170:173], v[178:181], v[46:49]
	v_mfma_f32_16x16x32_bf16 v[38:41], v[162:165], v[186:189], v[38:41]
	v_mfma_f32_16x16x32_bf16 v[30:33], v[170:173], v[186:189], v[30:33]
	v_mfma_f32_16x16x32_bf16 v[22:25], v[162:165], v[194:197], v[22:25]
	v_mfma_f32_16x16x32_bf16 v[12:15], v[170:173], v[194:197], v[12:15]
	v_mfma_f32_16x16x32_bf16 v[4:7], v[162:165], v[202:205], v[4:7]
	v_mfma_f32_16x16x32_bf16 v[0:3], v[170:173], v[202:205], v[0:3]
	v_mfma_f32_16x16x32_bf16 v[54:57], v[166:169], v[182:185], v[54:57]
	v_mfma_f32_16x16x32_bf16 v[46:49], v[174:177], v[182:185], v[46:49]
	v_mfma_f32_16x16x32_bf16 v[38:41], v[166:169], v[190:193], v[38:41]
	v_mfma_f32_16x16x32_bf16 v[30:33], v[174:177], v[190:193], v[30:33]
	v_mfma_f32_16x16x32_bf16 v[22:25], v[166:169], v[198:201], v[22:25]
	v_mfma_f32_16x16x32_bf16 v[12:15], v[174:177], v[198:201], v[12:15]
	v_mfma_f32_16x16x32_bf16 v[4:7], v[166:169], v[208:211], v[4:7]
	v_mfma_f32_16x16x32_bf16 v[0:3], v[174:177], v[208:211], v[0:3]
	s_barrier
	s_add_i32 s57, s57, 2
	s_add_u32 s34, s34, 0x100
	s_addc_u32 s35, s35, 0
	s_add_u32 s55, s55, 0x100
	s_addc_u32 s56, s56, 0
	s_cmp_gt_u32 s57, 29
.LBB0_352:
	s_mov_b32 m0, s49
	s_nop 0
	global_load_lds_dwordx4 v132, s[100:101]
	s_add_u32 s38, s34, 0xfff80080
	s_addc_u32 s39, s35, -1
	s_add_i32 s58, 0, 0x10000
	s_cmp_eq_u32 s57, 28
	s_cselect_b32 s43, s27, s39
	s_cselect_b32 s42, s53, s38
	v_add_u32_e32 v145, s58, v142
	s_cselect_b32 s39, s25, s56
	s_cselect_b32 s38, s54, s55
	s_add_i32 s60, 0, 0x14000
	ds_read_b128 v[146:149], v145
	ds_read_b128 v[150:153], v145 offset:1024
	ds_read_b128 v[154:157], v145 offset:2048
	ds_read_b128 v[158:161], v145 offset:3072
	v_add_u32_e32 v145, s60, v142
	ds_read_b128 v[162:165], v145
	ds_read_b128 v[166:169], v145 offset:1024
	ds_read_b128 v[170:173], v145 offset:2048
	ds_read_b128 v[174:177], v145 offset:3072
	s_add_i32 m0, s44, 0xc000
	ds_read_b128 v[178:181], v144
	ds_read_b128 v[182:185], v144 offset:1024
	ds_read_b128 v[186:189], v144 offset:2048
	ds_read_b128 v[190:193], v144 offset:3072
	ds_read_b128 v[194:197], v144 offset:4096
	ds_read_b128 v[198:201], v144 offset:5120
	ds_read_b128 v[202:205], v144 offset:6144
	ds_read_b128 v[208:211], v144 offset:7168
	global_load_lds_dwordx4 v138, s[34:35]
	s_add_i32 m0, s44, 0xe000
	s_nop 0
	global_load_lds_dwordx4 v140, s[34:35]
	s_waitcnt vmcnt(8)
	s_waitcnt lgkmcnt(0)
	s_barrier
	v_mfma_f32_16x16x32_bf16 v[126:129], v[146:149], v[178:181], v[126:129]
	v_mfma_f32_16x16x32_bf16 v[122:125], v[154:157], v[178:181], v[122:125]
	v_mfma_f32_16x16x32_bf16 v[114:117], v[146:149], v[186:189], v[114:117]
	v_mfma_f32_16x16x32_bf16 v[106:109], v[154:157], v[186:189], v[106:109]
	v_mfma_f32_16x16x32_bf16 v[98:101], v[146:149], v[194:197], v[98:101]
	v_mfma_f32_16x16x32_bf16 v[90:93], v[154:157], v[194:197], v[90:93]
	v_mfma_f32_16x16x32_bf16 v[82:85], v[146:149], v[202:205], v[82:85]
	v_mfma_f32_16x16x32_bf16 v[74:77], v[154:157], v[202:205], v[74:77]
	v_mfma_f32_16x16x32_bf16 v[126:129], v[150:153], v[182:185], v[126:129]
	v_mfma_f32_16x16x32_bf16 v[122:125], v[158:161], v[182:185], v[122:125]
	v_mfma_f32_16x16x32_bf16 v[114:117], v[150:153], v[190:193], v[114:117]
	v_mfma_f32_16x16x32_bf16 v[106:109], v[158:161], v[190:193], v[106:109]
	v_mfma_f32_16x16x32_bf16 v[98:101], v[150:153], v[198:201], v[98:101]
	v_mfma_f32_16x16x32_bf16 v[90:93], v[158:161], v[198:201], v[90:93]
	v_mfma_f32_16x16x32_bf16 v[82:85], v[150:153], v[208:211], v[82:85]
	v_mfma_f32_16x16x32_bf16 v[74:77], v[158:161], v[208:211], v[74:77]
	v_mfma_f32_16x16x32_bf16 v[118:121], v[162:165], v[178:181], v[118:121]
	v_mfma_f32_16x16x32_bf16 v[110:113], v[170:173], v[178:181], v[110:113]
	v_mfma_f32_16x16x32_bf16 v[102:105], v[162:165], v[186:189], v[102:105]
	v_mfma_f32_16x16x32_bf16 v[94:97], v[170:173], v[186:189], v[94:97]
	v_mfma_f32_16x16x32_bf16 v[86:89], v[162:165], v[194:197], v[86:89]
	v_mfma_f32_16x16x32_bf16 v[78:81], v[170:173], v[194:197], v[78:81]
	v_mfma_f32_16x16x32_bf16 v[70:73], v[162:165], v[202:205], v[70:73]
	v_mfma_f32_16x16x32_bf16 v[66:69], v[170:173], v[202:205], v[66:69]
	v_mfma_f32_16x16x32_bf16 v[118:121], v[166:169], v[182:185], v[118:121]
	v_mfma_f32_16x16x32_bf16 v[110:113], v[174:177], v[182:185], v[110:113]
	v_mfma_f32_16x16x32_bf16 v[102:105], v[166:169], v[190:193], v[102:105]
	v_mfma_f32_16x16x32_bf16 v[94:97], v[174:177], v[190:193], v[94:97]
	v_mfma_f32_16x16x32_bf16 v[86:89], v[166:169], v[198:201], v[86:89]
	v_mfma_f32_16x16x32_bf16 v[78:81], v[174:177], v[198:201], v[78:81]
	v_mfma_f32_16x16x32_bf16 v[70:73], v[166:169], v[208:211], v[70:73]
	v_mfma_f32_16x16x32_bf16 v[66:69], v[174:177], v[208:211], v[66:69]
	s_barrier
; #define PG8_STAGE(bufoff, gbase, voff) do { _Pragma("unroll") for (int _i = 0; _i < 2; ++_i) \
;         __builtin_amdgcn_global_load_lds((const unsigned*)((const char*)(gbase) + (voff)[_i]), (PG8_LAS unsigned*)(lds + (bufoff) + ldsw + _i * 8192), 16, 0, 0); } while (0)
; #define PG8_LDA(dst, b, h) do { _Pragma("unroll") for (int m = 0; m < 4; ++m) _Pragma("unroll") for (int k = 0; k < 2; ++k) dst[m][k] = *(const PG8_LAS bf16x8*)(lds + PG8_SA(b, h) + aoff + m * 2048 + k * 1024); } while (0)
; #define PG8_LDB(dst, b, h) do { _Pragma("unroll") for (int n = 0; n < 2; ++n) _Pragma("unroll") for (int k = 0; k < 2; ++k) dst[n][k] = *(const PG8_LAS bf16x8*)(lds + PG8_SB(b, h) + boff + n * 2048 + k * 1024); } while (0)
; #define PG8_MMA(ai, bj, At, Bt) do { __builtin_amdgcn_s_setprio(1); _Pragma("unroll") for (int m = 0; m < 4; ++m) _Pragma("unroll") for (int n = 0; n < 2; ++n) _Pragma("unroll") for (int k = 0; k < 2; ++k) \
;         acc[ai][bj][m][n] = __builtin_amdgcn_mfma_f32_16x16x32_bf16(Bt[n][k], At[m][k], acc[ai][bj][m][n], 0, 0, 0); __builtin_amdgcn_s_setprio(0); } while (0)
; template <class Epi, class Sched, bool ALIGN_EPI = false, bool SP2 = false>
; __device__ __forceinline__ void gemm_phase(PG8_LAS unsigned char* lds, const Gemm g, const Sched& S, const Epi& E, const int tid_in) {
;     ...
;             if constexpr (SP2) {
;             PG8_LDB(B0, 0, 0); PG8_LDB(B1, 0, 1); PG8_SCHED; PG8_LDA(At, 0, 0); PG8_STAGE(PG8_SA(1, 1), a1 + hstep, voffA);
;             PG8_WAIT_V(8); PG8_WAIT_L(0); PG8_BAR; PG8_MMA(0, 0, At, B0); PG8_MMA(0, 1, At, B1); PG8_BAR; PG8_SCHED;
;             PG8_LDA(At, 0, 1); PG8_STAGE(PG8_SB(0, 0), b2, voffB); PG8_STAGE(PG8_SB(0, 1), b2 + hstep, voffB); PG8_STAGE(PG8_SA(0, 0), a2, voffA);
;             PG8_WAIT_V(8); PG8_WAIT_L(0); PG8_BAR; PG8_MMA(1, 0, At, B0); PG8_MMA(1, 1, At, B1); PG8_BAR; PG8_SCHED;
;             PG8_LDB(B0, 1, 0); PG8_LDB(B1, 1, 1); PG8_SCHED; PG8_LDA(At, 1, 0); PG8_STAGE(PG8_SA(0, 1), a2 + hstep, voffA);
;             PG8_WAIT_V(8); PG8_WAIT_L(0); PG8_BAR; PG8_MMA(0, 0, At, B0); PG8_MMA(0, 1, At, B1); PG8_BAR; PG8_SCHED;
;             PG8_LDA(At, 1, 1); PG8_STAGE(PG8_SB(1, 0), b3, voffB); PG8_STAGE(PG8_SB(1, 1), b3 + hstep, voffB); PG8_STAGE(PG8_SA(1, 0), a3, voffA);
;             PG8_WAIT_V(8); PG8_WAIT_L(0); PG8_BAR; PG8_MMA(1, 0, At, B0); PG8_MMA(1, 1, At, B1); PG8_BAR; PG8_SCHED;
	s_add_i32 s58, s58, s19
	s_add_u32 s98, s38, 0x80
	s_addc_u32 s99, s39, 0
	s_mov_b32 m0, s58
	ds_read_b128 v[178:181], v144 offset:16384
	ds_read_b128 v[182:185], v144 offset:17408
	ds_read_b128 v[186:189], v144 offset:18432
	ds_read_b128 v[190:193], v144 offset:19456
	ds_read_b128 v[194:197], v144 offset:20480
	ds_read_b128 v[198:201], v144 offset:21504
	ds_read_b128 v[202:205], v144 offset:22528
	ds_read_b128 v[208:211], v144 offset:23552
	global_load_lds_dwordx4 v134, s[38:39]
	s_add_i32 m0, s58, 0x2000
	s_add_u32 s58, s38, 0x80000
	s_addc_u32 s59, s39, 0
	s_add_i32 s60, s60, s19
	global_load_lds_dwordx4 v130, s[38:39]
	s_mov_b32 m0, s60
	s_add_u32 s100, s42, 0x80
	s_addc_u32 s101, s43, 0
	global_load_lds_dwordx4 v134, s[58:59]
	s_add_i32 m0, s60, 0x2000
	s_nop 0
	global_load_lds_dwordx4 v130, s[58:59]
	s_mov_b32 m0, s44
	s_nop 0
	global_load_lds_dwordx4 v136, s[42:43]
	s_waitcnt vmcnt(7)
	s_waitcnt lgkmcnt(0)
	s_barrier
	v_mfma_f32_16x16x32_bf16 v[62:65], v[146:149], v[178:181], v[62:65]
	v_mfma_f32_16x16x32_bf16 v[58:61], v[154:157], v[178:181], v[58:61]
	v_mfma_f32_16x16x32_bf16 v[50:53], v[146:149], v[186:189], v[50:53]
	v_mfma_f32_16x16x32_bf16 v[42:45], v[154:157], v[186:189], v[42:45]
	v_mfma_f32_16x16x32_bf16 v[34:37], v[146:149], v[194:197], v[34:37]
	v_mfma_f32_16x16x32_bf16 v[26:29], v[154:157], v[194:197], v[26:29]
	v_mfma_f32_16x16x32_bf16 v[16:19], v[146:149], v[202:205], v[16:19]
	v_mfma_f32_16x16x32_bf16 v[8:11], v[154:157], v[202:205], v[8:11]
	v_mfma_f32_16x16x32_bf16 v[62:65], v[150:153], v[182:185], v[62:65]
	v_mfma_f32_16x16x32_bf16 v[58:61], v[158:161], v[182:185], v[58:61]
	v_mfma_f32_16x16x32_bf16 v[50:53], v[150:153], v[190:193], v[50:53]
	v_mfma_f32_16x16x32_bf16 v[42:45], v[158:161], v[190:193], v[42:45]
	v_mfma_f32_16x16x32_bf16 v[34:37], v[150:153], v[198:201], v[34:37]
	v_mfma_f32_16x16x32_bf16 v[26:29], v[158:161], v[198:201], v[26:29]
	v_mfma_f32_16x16x32_bf16 v[16:19], v[150:153], v[208:211], v[16:19]
	v_mfma_f32_16x16x32_bf16 v[8:11], v[158:161], v[208:211], v[8:11]
	v_mfma_f32_16x16x32_bf16 v[54:57], v[162:165], v[178:181], v[54:57]
	v_mfma_f32_16x16x32_bf16 v[46:49], v[170:173], v[178:181], v[46:49]
	v_mfma_f32_16x16x32_bf16 v[38:41], v[162:165], v[186:189], v[38:41]
	v_mfma_f32_16x16x32_bf16 v[30:33], v[170:173], v[186:189], v[30:33]
	v_mfma_f32_16x16x32_bf16 v[22:25], v[162:165], v[194:197], v[22:25]
	v_mfma_f32_16x16x32_bf16 v[12:15], v[170:173], v[194:197], v[12:15]
	v_mfma_f32_16x16x32_bf16 v[4:7], v[162:165], v[202:205], v[4:7]
	v_mfma_f32_16x16x32_bf16 v[0:3], v[170:173], v[202:205], v[0:3]
	v_mfma_f32_16x16x32_bf16 v[54:57], v[166:169], v[182:185], v[54:57]
	v_mfma_f32_16x16x32_bf16 v[46:49], v[174:177], v[182:185], v[46:49]
	v_mfma_f32_16x16x32_bf16 v[38:41], v[166:169], v[190:193], v[38:41]
	v_mfma_f32_16x16x32_bf16 v[30:33], v[174:177], v[190:193], v[30:33]
	v_mfma_f32_16x16x32_bf16 v[22:25], v[166:169], v[198:201], v[22:25]
	v_mfma_f32_16x16x32_bf16 v[12:15], v[174:177], v[198:201], v[12:15]
	v_mfma_f32_16x16x32_bf16 v[4:7], v[166:169], v[208:211], v[4:7]
	v_mfma_f32_16x16x32_bf16 v[0:3], v[174:177], v[208:211], v[0:3]
	s_barrier
	s_add_i32 s58, 0, 0x18000
	v_add_u32_e32 v145, s58, v142
	s_add_i32 s59, 0, 0x1c000
	ds_read_b128 v[146:149], v145
	ds_read_b128 v[150:153], v145 offset:1024
	ds_read_b128 v[154:157], v145 offset:2048
	ds_read_b128 v[158:161], v145 offset:3072
	v_add_u32_e32 v145, s59, v142
	ds_read_b128 v[162:165], v145
	ds_read_b128 v[166:169], v145 offset:1024
	ds_read_b128 v[170:173], v145 offset:2048
	ds_read_b128 v[174:177], v145 offset:3072
	s_mov_b32 m0, s45
	s_nop 0
	global_load_lds_dwordx4 v132, s[42:43]
	s_add_u32 s42, s42, 0x80000
	s_addc_u32 s43, s43, 0
	s_mov_b32 m0, s46
	ds_read_b128 v[178:181], v144 offset:32768
	ds_read_b128 v[182:185], v144 offset:33792
	ds_read_b128 v[186:189], v144 offset:34816
	ds_read_b128 v[190:193], v144 offset:35840
	ds_read_b128 v[194:197], v144 offset:36864
	ds_read_b128 v[198:201], v144 offset:37888
	ds_read_b128 v[202:205], v144 offset:38912
	ds_read_b128 v[208:211], v144 offset:39936
	global_load_lds_dwordx4 v136, s[42:43]
	s_mov_b32 m0, s47
	s_nop 0
	global_load_lds_dwordx4 v132, s[42:43]
	s_waitcnt vmcnt(8)
	s_waitcnt lgkmcnt(0)
	s_barrier
; #define PG8_STAGE(bufoff, gbase, voff) do { _Pragma("unroll") for (int _i = 0; _i < 2; ++_i) \
;         __builtin_amdgcn_global_load_lds((const unsigned*)((const char*)(gbase) + (voff)[_i]), (PG8_LAS unsigned*)(lds + (bufoff) + ldsw + _i * 8192), 16, 0, 0); } while (0)
; #define PG8_LDA(dst, b, h) do { _Pragma("unroll") for (int m = 0; m < 4; ++m) _Pragma("unroll") for (int k = 0; k < 2; ++k) dst[m][k] = *(const PG8_LAS bf16x8*)(lds + PG8_SA(b, h) + aoff + m * 2048 + k * 1024); } while (0)
; #define PG8_WAIT_V(n) asm volatile("s_waitcnt vmcnt(" #n ")" ::: "memory")
; template <class Epi, class Sched, bool ALIGN_EPI = false, bool SP2 = false>
; __device__ __forceinline__ void gemm_phase(PG8_LAS unsigned char* lds, const Gemm g, const Sched& S, const Epi& E, const int tid_in) {
;     ...
;         for (int t = 0; t < nt; t += 2) {
;             if constexpr (Epi::KSPLIT > 0) { if (t == Epi::KSPLIT / BK) E.midk(acc, cur, wr, wc, fr, fq); }
;             const bool last = (t == nt - 2);
;             const char* a1 = cA + (size_t)(t + 1) * kstep;
;             const char* a2 = last ? nA : cA + (size_t)(t + 2) * kstep; const char* b2 = last ? nB : cB + (size_t)(t + 2) * kstep;
;             const char* a3 = a2 + kstep; const char* b3 = b2 + kstep;
;             if (last && has_next) S.a_ready(nxt);
;             if constexpr (SP2) {
;             PG8_LDB(B0, 0, 0); PG8_LDB(B1, 0, 1); PG8_SCHED; PG8_LDA(At, 0, 0); PG8_STAGE(PG8_SA(1, 1), a1 + hstep, voffA);
;             PG8_WAIT_V(8); PG8_WAIT_L(0); PG8_BAR; PG8_MMA(0, 0, At, B0); PG8_MMA(0, 1, At, B1); PG8_BAR; PG8_SCHED;
;             PG8_LDA(At, 0, 1); PG8_STAGE(PG8_SB(0, 0), b2, voffB); PG8_STAGE(PG8_SB(0, 1), b2 + hstep, voffB); PG8_STAGE(PG8_SA(0, 0), a2, voffA);
;             PG8_WAIT_V(8); PG8_WAIT_L(0); PG8_BAR; PG8_MMA(1, 0, At, B0); PG8_MMA(1, 1, At, B1); PG8_BAR; PG8_SCHED;
;             PG8_LDB(B0, 1, 0); PG8_LDB(B1, 1, 1); PG8_SCHED; PG8_LDA(At, 1, 0); PG8_STAGE(PG8_SA(0, 1), a2 + hstep, voffA);
;             PG8_WAIT_V(8); PG8_WAIT_L(0); PG8_BAR; PG8_MMA(0, 0, At, B0); PG8_MMA(0, 1, At, B1); PG8_BAR; PG8_SCHED;
;             PG8_LDA(At, 1, 1); PG8_STAGE(PG8_SB(1, 0), b3, voffB); PG8_STAGE(PG8_SB(1, 1), b3 + hstep, voffB); PG8_STAGE(PG8_SA(1, 0), a3, voffA);
;             PG8_WAIT_V(8); PG8_WAIT_L(0); PG8_BAR; PG8_MMA(1, 0, At, B0); PG8_MMA(1, 1, At, B1); PG8_BAR; PG8_SCHED;
	v_mfma_f32_16x16x32_bf16 v[126:129], v[146:149], v[178:181], v[126:129]
	v_mfma_f32_16x16x32_bf16 v[122:125], v[154:157], v[178:181], v[122:125]
	v_mfma_f32_16x16x32_bf16 v[114:117], v[146:149], v[186:189], v[114:117]
	v_mfma_f32_16x16x32_bf16 v[106:109], v[154:157], v[186:189], v[106:109]
	v_mfma_f32_16x16x32_bf16 v[98:101], v[146:149], v[194:197], v[98:101]
	v_mfma_f32_16x16x32_bf16 v[90:93], v[154:157], v[194:197], v[90:93]
	v_mfma_f32_16x16x32_bf16 v[82:85], v[146:149], v[202:205], v[82:85]
	v_mfma_f32_16x16x32_bf16 v[74:77], v[154:157], v[202:205], v[74:77]
	v_mfma_f32_16x16x32_bf16 v[126:129], v[150:153], v[182:185], v[126:129]
	v_mfma_f32_16x16x32_bf16 v[122:125], v[158:161], v[182:185], v[122:125]
	v_mfma_f32_16x16x32_bf16 v[114:117], v[150:153], v[190:193], v[114:117]
	v_mfma_f32_16x16x32_bf16 v[106:109], v[158:161], v[190:193], v[106:109]
	v_mfma_f32_16x16x32_bf16 v[98:101], v[150:153], v[198:201], v[98:101]
	v_mfma_f32_16x16x32_bf16 v[90:93], v[158:161], v[198:201], v[90:93]
	v_mfma_f32_16x16x32_bf16 v[82:85], v[150:153], v[208:211], v[82:85]
	v_mfma_f32_16x16x32_bf16 v[74:77], v[158:161], v[208:211], v[74:77]
	v_mfma_f32_16x16x32_bf16 v[118:121], v[162:165], v[178:181], v[118:121]
	v_mfma_f32_16x16x32_bf16 v[110:113], v[170:173], v[178:181], v[110:113]
	v_mfma_f32_16x16x32_bf16 v[102:105], v[162:165], v[186:189], v[102:105]
	v_mfma_f32_16x16x32_bf16 v[94:97], v[170:173], v[186:189], v[94:97]
	v_mfma_f32_16x16x32_bf16 v[86:89], v[162:165], v[194:197], v[86:89]
	v_mfma_f32_16x16x32_bf16 v[78:81], v[170:173], v[194:197], v[78:81]
	v_mfma_f32_16x16x32_bf16 v[70:73], v[162:165], v[202:205], v[70:73]
	v_mfma_f32_16x16x32_bf16 v[66:69], v[170:173], v[202:205], v[66:69]
	v_mfma_f32_16x16x32_bf16 v[118:121], v[166:169], v[182:185], v[118:121]
	v_mfma_f32_16x16x32_bf16 v[110:113], v[174:177], v[182:185], v[110:113]
	v_mfma_f32_16x16x32_bf16 v[102:105], v[166:169], v[190:193], v[102:105]
	v_mfma_f32_16x16x32_bf16 v[94:97], v[174:177], v[190:193], v[94:97]
	v_mfma_f32_16x16x32_bf16 v[86:89], v[166:169], v[198:201], v[86:89]
	v_mfma_f32_16x16x32_bf16 v[78:81], v[174:177], v[198:201], v[78:81]
	v_mfma_f32_16x16x32_bf16 v[70:73], v[166:169], v[208:211], v[70:73]
	v_mfma_f32_16x16x32_bf16 v[66:69], v[174:177], v[208:211], v[66:69]
	s_barrier
	s_add_i32 s42, s58, s19
	s_mov_b32 m0, s42
	ds_read_b128 v[178:181], v144 offset:49152
	ds_read_b128 v[182:185], v144 offset:50176
	ds_read_b128 v[186:189], v144 offset:51200
	ds_read_b128 v[190:193], v144 offset:52224
	ds_read_b128 v[194:197], v144 offset:53248
	ds_read_b128 v[198:201], v144 offset:54272
	ds_read_b128 v[202:205], v144 offset:55296
	ds_read_b128 v[208:211], v144 offset:56320
	global_load_lds_dwordx4 v134, s[98:99]
	s_add_i32 m0, s42, 0x2000
	s_add_u32 s38, s38, 0x80080
	s_addc_u32 s39, s39, 0
	s_add_i32 s42, s59, s19
	global_load_lds_dwordx4 v130, s[98:99]
	s_mov_b32 m0, s42
	s_nop 0
	global_load_lds_dwordx4 v134, s[38:39]
	s_add_i32 m0, s42, 0x2000
	s_nop 0
	global_load_lds_dwordx4 v130, s[38:39]
	s_mov_b32 m0, s48
	s_nop 0
	global_load_lds_dwordx4 v136, s[100:101]
	s_waitcnt vmcnt(7)
	s_waitcnt lgkmcnt(0)
	s_barrier
	v_mfma_f32_16x16x32_bf16 v[62:65], v[146:149], v[178:181], v[62:65]
	v_mfma_f32_16x16x32_bf16 v[58:61], v[154:157], v[178:181], v[58:61]
	v_mfma_f32_16x16x32_bf16 v[50:53], v[146:149], v[186:189], v[50:53]
	v_mfma_f32_16x16x32_bf16 v[42:45], v[154:157], v[186:189], v[42:45]
	v_mfma_f32_16x16x32_bf16 v[34:37], v[146:149], v[194:197], v[34:37]
	v_mfma_f32_16x16x32_bf16 v[26:29], v[154:157], v[194:197], v[26:29]
	v_mfma_f32_16x16x32_bf16 v[16:19], v[146:149], v[202:205], v[16:19]
	v_mfma_f32_16x16x32_bf16 v[8:11], v[154:157], v[202:205], v[8:11]
	v_mfma_f32_16x16x32_bf16 v[62:65], v[150:153], v[182:185], v[62:65]
	v_mfma_f32_16x16x32_bf16 v[58:61], v[158:161], v[182:185], v[58:61]
	v_mfma_f32_16x16x32_bf16 v[50:53], v[150:153], v[190:193], v[50:53]
	v_mfma_f32_16x16x32_bf16 v[42:45], v[158:161], v[190:193], v[42:45]
	v_mfma_f32_16x16x32_bf16 v[34:37], v[150:153], v[198:201], v[34:37]
	v_mfma_f32_16x16x32_bf16 v[26:29], v[158:161], v[198:201], v[26:29]
	v_mfma_f32_16x16x32_bf16 v[16:19], v[150:153], v[208:211], v[16:19]
	v_mfma_f32_16x16x32_bf16 v[8:11], v[158:161], v[208:211], v[8:11]
	v_mfma_f32_16x16x32_bf16 v[54:57], v[162:165], v[178:181], v[54:57]
	v_mfma_f32_16x16x32_bf16 v[46:49], v[170:173], v[178:181], v[46:49]
	v_mfma_f32_16x16x32_bf16 v[38:41], v[162:165], v[186:189], v[38:41]
	v_mfma_f32_16x16x32_bf16 v[30:33], v[170:173], v[186:189], v[30:33]
	v_mfma_f32_16x16x32_bf16 v[22:25], v[162:165], v[194:197], v[22:25]
	v_mfma_f32_16x16x32_bf16 v[12:15], v[170:173], v[194:197], v[12:15]
	v_mfma_f32_16x16x32_bf16 v[4:7], v[162:165], v[202:205], v[4:7]
	v_mfma_f32_16x16x32_bf16 v[0:3], v[170:173], v[202:205], v[0:3]
	v_mfma_f32_16x16x32_bf16 v[54:57], v[166:169], v[182:185], v[54:57]
	v_mfma_f32_16x16x32_bf16 v[46:49], v[174:177], v[182:185], v[46:49]
	v_mfma_f32_16x16x32_bf16 v[38:41], v[166:169], v[190:193], v[38:41]
	v_mfma_f32_16x16x32_bf16 v[30:33], v[174:177], v[190:193], v[30:33]
	v_mfma_f32_16x16x32_bf16 v[22:25], v[166:169], v[198:201], v[22:25]
	v_mfma_f32_16x16x32_bf16 v[12:15], v[174:177], v[198:201], v[12:15]
	v_mfma_f32_16x16x32_bf16 v[4:7], v[166:169], v[208:211], v[4:7]
	v_mfma_f32_16x16x32_bf16 v[0:3], v[174:177], v[208:211], v[0:3]
	s_barrier
	s_add_i32 s57, s57, 2
	s_add_u32 s34, s34, 0x100
	s_addc_u32 s35, s35, 0
	s_add_u32 s55, s55, 0x100
	s_addc_u32 s56, s56, 0
	s_cmp_gt_u32 s57, 29
	s_cbranch_scc0 .LBB0_352
	s_setprio 0
	s_and_b64 vcc, exec, s[22:23]
	s_cbranch_vccz .LBB0_355
	s_barrier

; #define PG8_STAGE(bufoff, gbase, voff) do { _Pragma("unroll") for (int _i = 0; _i < 2; ++_i) \
;         __builtin_amdgcn_global_load_lds((const unsigned*)((const char*)(gbase) + (voff)[_i]), (PG8_LAS unsigned*)(lds + (bufoff) + ldsw + _i * 8192), 16, 0, 0); } while (0)
; #define PG8_WAIT_V(n) asm volatile("s_waitcnt vmcnt(" #n ")" ::: "memory")
; template <class Epi, class Sched, bool ALIGN_EPI = false, bool SP2 = false>
; __device__ __forceinline__ void gemm_phase(PG8_LAS unsigned char* lds, const Gemm g, const Sched& S, const Epi& E, const int tid_in) {
;     ...
;         const bool has_next = S.next(ui + 1, nxt);
;         const char* nA = has_next ? (const char*)g.A + (size_t)nxt.pm * tstep : cA; const char* nB = has_next ? (const char*)g.Bt + (size_t)nxt.pn * tstep : cB;
;         for (int t = 0; t < nt; t += 2) {
;             if constexpr (Epi::KSPLIT > 0) { if (t == Epi::KSPLIT / BK) E.midk(acc, cur, wr, wc, fr, fq); }
;             const bool last = (t == nt - 2);
;             const char* a1 = cA + (size_t)(t + 1) * kstep;
;             const char* a2 = last ? nA : cA + (size_t)(t + 2) * kstep; const char* b2 = last ? nB : cB + (size_t)(t + 2) * kstep;
;             const char* a3 = a2 + kstep; const char* b3 = b2 + kstep;
;             if (last && has_next) S.a_ready(nxt);
;             if constexpr (SP2) {
;             PG8_LDB(B0, 0, 0); PG8_LDB(B1, 0, 1); PG8_SCHED; PG8_LDA(At, 0, 0); PG8_STAGE(PG8_SA(1, 1), a1 + hstep, voffA);
;             PG8_WAIT_V(8); PG8_WAIT_L(0); PG8_BAR; PG8_MMA(0, 0, At, B0); PG8_MMA(0, 1, At, B1); PG8_BAR; PG8_SCHED;
;             PG8_LDA(At, 0, 1); PG8_STAGE(PG8_SB(0, 0), b2, voffB); PG8_STAGE(PG8_SB(0, 1), b2 + hstep, voffB); PG8_STAGE(PG8_SA(0, 0), a2, voffA);
;             PG8_WAIT_V(8); PG8_WAIT_L(0); PG8_BAR; PG8_MMA(1, 0, At, B0); PG8_MMA(1, 1, At, B1); PG8_BAR; PG8_SCHED;
;             PG8_LDB(B0, 1, 0); PG8_LDB(B1, 1, 1); PG8_SCHED; PG8_LDA(At, 1, 0); PG8_STAGE(PG8_SA(0, 1), a2 + hstep, voffA);
;             PG8_WAIT_V(8); PG8_WAIT_L(0); PG8_BAR; PG8_MMA(0, 0, At, B0); PG8_MMA(0, 1, At, B1); PG8_BAR; PG8_SCHED;
;             PG8_LDA(At, 1, 1); PG8_STAGE(PG8_SB(1, 0), b3, voffB); PG8_STAGE(PG8_SB(1, 1), b3 + hstep, voffB); PG8_STAGE(PG8_SA(1, 0), a3, voffA);
;             PG8_WAIT_V(8); PG8_WAIT_L(0); PG8_BAR; PG8_MMA(1, 0, At, B0); PG8_MMA(1, 1, At, B1); PG8_BAR; PG8_SCHED;
.LBB0_373:
	s_ashr_i32 s25, s24, 31
	s_lshl_b64 s[26:27], s[24:25], 20
	s_add_u32 s26, s1, s26
	s_addc_u32 s27, s5, s27
	s_and_b64 s[28:29], s[36:37], exec
	s_cselect_b32 s21, s27, s35
	s_cselect_b32 s25, s26, s34
	s_ashr_i32 s23, s22, 31
	s_lshl_b64 s[28:29], s[22:23], 20
	s_add_u32 s28, s8, s28
	s_addc_u32 s29, s10, s29
	s_and_b64 s[42:43], s[36:37], exec
	s_cselect_b32 s23, s29, s39
	s_cselect_b32 s51, s28, s38
	s_add_u32 s34, s34, 0x80080
	s_addc_u32 s35, s35, 0
	s_add_u32 s52, s38, 0x100
	v_mov_b32_e32 v0, 0
	s_addc_u32 s53, s39, 0
	s_mov_b32 s54, -2
	s_cmp_lt_u32 s19, 0x1000
	s_cbranch_scc1 .LPRIO_374
	s_setprio 1
.LPRIO_374:
	s_mov_b32 m0, s49
	s_nop 0
	global_load_lds_dwordx4 v134, s[100:101]
	s_add_u32 s38, s34, 0xfff80080
	s_addc_u32 s39, s35, -1
	s_add_i32 s55, 0, 0x10000
	s_cmp_eq_u32 s54, 28
	s_cselect_b32 s43, s21, s39
	s_cselect_b32 s42, s25, s38
	v_add_u32_e32 v144, s55, v21
	s_cselect_b32 s39, s23, s53
	s_cselect_b32 s38, s51, s52
	s_add_i32 s58, 0, 0x14000
	ds_read_b128 v[148:151], v144
	ds_read_b128 v[152:155], v144 offset:1024
	ds_read_b128 v[156:159], v144 offset:2048
	ds_read_b128 v[160:163], v144 offset:3072
	v_add_u32_e32 v144, s58, v21
	ds_read_b128 v[164:167], v144
	ds_read_b128 v[168:171], v144 offset:1024
	ds_read_b128 v[172:175], v144 offset:2048
	ds_read_b128 v[176:179], v144 offset:3072
	s_add_i32 m0, s44, 0xc000
	ds_read_b128 v[180:183], v147
	ds_read_b128 v[184:187], v147 offset:1024
	ds_read_b128 v[188:191], v147 offset:2048
	ds_read_b128 v[192:195], v147 offset:3072
	ds_read_b128 v[196:199], v147 offset:4096
	ds_read_b128 v[200:203], v147 offset:5120
	ds_read_b128 v[208:211], v147 offset:6144
	ds_read_b128 v[212:215], v147 offset:7168
	global_load_lds_dwordx4 v140, s[34:35]
	s_add_i32 m0, s44, 0xe000
	s_nop 0
	global_load_lds_dwordx4 v142, s[34:35]
	s_waitcnt vmcnt(8)
	s_waitcnt lgkmcnt(0)
	s_barrier
	v_mfma_f32_16x16x32_bf16 v[126:129], v[148:151], v[180:183], 0
	v_mfma_f32_16x16x32_bf16 v[122:125], v[156:159], v[180:183], 0
	v_mfma_f32_16x16x32_bf16 v[118:121], v[148:151], v[188:191], 0
	v_mfma_f32_16x16x32_bf16 v[110:113], v[156:159], v[188:191], 0
	v_mfma_f32_16x16x32_bf16 v[102:105], v[148:151], v[196:199], 0
	v_mfma_f32_16x16x32_bf16 v[94:97], v[156:159], v[196:199], 0
	v_mfma_f32_16x16x32_bf16 v[86:89], v[148:151], v[208:211], 0
	v_mfma_f32_16x16x32_bf16 v[78:81], v[156:159], v[208:211], 0
	v_mfma_f32_16x16x32_bf16 v[126:129], v[152:155], v[184:187], v[126:129]
	v_mfma_f32_16x16x32_bf16 v[122:125], v[160:163], v[184:187], v[122:125]
	v_mfma_f32_16x16x32_bf16 v[118:121], v[152:155], v[192:195], v[118:121]
	v_mfma_f32_16x16x32_bf16 v[110:113], v[160:163], v[192:195], v[110:113]
	v_mfma_f32_16x16x32_bf16 v[102:105], v[152:155], v[200:203], v[102:105]
	v_mfma_f32_16x16x32_bf16 v[94:97], v[160:163], v[200:203], v[94:97]
	v_mfma_f32_16x16x32_bf16 v[86:89], v[152:155], v[212:215], v[86:89]
	v_mfma_f32_16x16x32_bf16 v[78:81], v[160:163], v[212:215], v[78:81]
	v_mfma_f32_16x16x32_bf16 v[114:117], v[164:167], v[180:183], 0
	v_mfma_f32_16x16x32_bf16 v[106:109], v[172:175], v[180:183], 0
	v_mfma_f32_16x16x32_bf16 v[98:101], v[164:167], v[188:191], 0
	v_mfma_f32_16x16x32_bf16 v[90:93], v[172:175], v[188:191], 0
	v_mfma_f32_16x16x32_bf16 v[82:85], v[164:167], v[196:199], 0
	v_mfma_f32_16x16x32_bf16 v[74:77], v[172:175], v[196:199], 0
	v_mfma_f32_16x16x32_bf16 v[70:73], v[164:167], v[208:211], 0
	v_mfma_f32_16x16x32_bf16 v[66:69], v[172:175], v[208:211], 0
	v_mfma_f32_16x16x32_bf16 v[114:117], v[168:171], v[184:187], v[114:117]
	v_mfma_f32_16x16x32_bf16 v[106:109], v[176:179], v[184:187], v[106:109]
	v_mfma_f32_16x16x32_bf16 v[98:101], v[168:171], v[192:195], v[98:101]
	v_mfma_f32_16x16x32_bf16 v[90:93], v[176:179], v[192:195], v[90:93]
	v_mfma_f32_16x16x32_bf16 v[82:85], v[168:171], v[200:203], v[82:85]
	v_mfma_f32_16x16x32_bf16 v[74:77], v[176:179], v[200:203], v[74:77]
	v_mfma_f32_16x16x32_bf16 v[70:73], v[168:171], v[212:215], v[70:73]
	v_mfma_f32_16x16x32_bf16 v[66:69], v[176:179], v[212:215], v[66:69]
	s_barrier
	s_add_i32 s55, s55, s19
	s_add_u32 s98, s38, 0x80
	s_addc_u32 s99, s39, 0
	s_mov_b32 m0, s55
	ds_read_b128 v[180:183], v147 offset:16384
	ds_read_b128 v[184:187], v147 offset:17408
	ds_read_b128 v[188:191], v147 offset:18432
	ds_read_b128 v[192:195], v147 offset:19456
	ds_read_b128 v[196:199], v147 offset:20480
	ds_read_b128 v[200:203], v147 offset:21504
	ds_read_b128 v[208:211], v147 offset:22528
	ds_read_b128 v[212:215], v147 offset:23552
	global_load_lds_dwordx4 v132, s[38:39]
	s_add_i32 m0, s55, 0x2000
	s_add_u32 s56, s38, 0x80000
	s_addc_u32 s57, s39, 0
	s_add_i32 s55, s58, s19
	global_load_lds_dwordx4 v136, s[38:39]
	s_mov_b32 m0, s55
	s_add_u32 s100, s42, 0x80
	s_addc_u32 s101, s43, 0
	global_load_lds_dwordx4 v132, s[56:57]
	s_add_i32 m0, s55, 0x2000
	s_nop 0
	global_load_lds_dwordx4 v136, s[56:57]
	s_mov_b32 m0, s44
	s_nop 0
	global_load_lds_dwordx4 v130, s[42:43]
	s_waitcnt vmcnt(7)
	s_waitcnt lgkmcnt(0)
	s_barrier
; #define PG8_STAGE(bufoff, gbase, voff) do { _Pragma("unroll") for (int _i = 0; _i < 2; ++_i) \
;         __builtin_amdgcn_global_load_lds((const unsigned*)((const char*)(gbase) + (voff)[_i]), (PG8_LAS unsigned*)(lds + (bufoff) + ldsw + _i * 8192), 16, 0, 0); } while (0)
; #define PG8_LDA(dst, b, h) do { _Pragma("unroll") for (int m = 0; m < 4; ++m) _Pragma("unroll") for (int k = 0; k < 2; ++k) dst[m][k] = *(const PG8_LAS bf16x8*)(lds + PG8_SA(b, h) + aoff + m * 2048 + k * 1024); } while (0)
; #define PG8_LDB(dst, b, h) do { _Pragma("unroll") for (int n = 0; n < 2; ++n) _Pragma("unroll") for (int k = 0; k < 2; ++k) dst[n][k] = *(const PG8_LAS bf16x8*)(lds + PG8_SB(b, h) + boff + n * 2048 + k * 1024); } while (0)
; #define PG8_MMA(ai, bj, At, Bt) do { __builtin_amdgcn_s_setprio(1); _Pragma("unroll") for (int m = 0; m < 4; ++m) _Pragma("unroll") for (int n = 0; n < 2; ++n) _Pragma("unroll") for (int k = 0; k < 2; ++k) \
;         acc[ai][bj][m][n] = __builtin_amdgcn_mfma_f32_16x16x32_bf16(Bt[n][k], At[m][k], acc[ai][bj][m][n], 0, 0, 0); __builtin_amdgcn_s_setprio(0); } while (0)
; template <class Epi, class Sched, bool ALIGN_EPI = false, bool SP2 = false>
; __device__ __forceinline__ void gemm_phase(PG8_LAS unsigned char* lds, const Gemm g, const Sched& S, const Epi& E, const int tid_in) {
;     ...
;             if constexpr (SP2) {
;             PG8_LDB(B0, 0, 0); PG8_LDB(B1, 0, 1); PG8_SCHED; PG8_LDA(At, 0, 0); PG8_STAGE(PG8_SA(1, 1), a1 + hstep, voffA);
;             PG8_WAIT_V(8); PG8_WAIT_L(0); PG8_BAR; PG8_MMA(0, 0, At, B0); PG8_MMA(0, 1, At, B1); PG8_BAR; PG8_SCHED;
;             PG8_LDA(At, 0, 1); PG8_STAGE(PG8_SB(0, 0), b2, voffB); PG8_STAGE(PG8_SB(0, 1), b2 + hstep, voffB); PG8_STAGE(PG8_SA(0, 0), a2, voffA);
;             PG8_WAIT_V(8); PG8_WAIT_L(0); PG8_BAR; PG8_MMA(1, 0, At, B0); PG8_MMA(1, 1, At, B1); PG8_BAR; PG8_SCHED;
;             PG8_LDB(B0, 1, 0); PG8_LDB(B1, 1, 1); PG8_SCHED; PG8_LDA(At, 1, 0); PG8_STAGE(PG8_SA(0, 1), a2 + hstep, voffA);
;             PG8_WAIT_V(8); PG8_WAIT_L(0); PG8_BAR; PG8_MMA(0, 0, At, B0); PG8_MMA(0, 1, At, B1); PG8_BAR; PG8_SCHED;
;             PG8_LDA(At, 1, 1); PG8_STAGE(PG8_SB(1, 0), b3, voffB); PG8_STAGE(PG8_SB(1, 1), b3 + hstep, voffB); PG8_STAGE(PG8_SA(1, 0), a3, voffA);
;             PG8_WAIT_V(8); PG8_WAIT_L(0); PG8_BAR; PG8_MMA(1, 0, At, B0); PG8_MMA(1, 1, At, B1); PG8_BAR; PG8_SCHED;
	v_mfma_f32_16x16x32_bf16 v[62:65], v[148:151], v[180:183], 0
	v_mfma_f32_16x16x32_bf16 v[58:61], v[156:159], v[180:183], 0
	v_mfma_f32_16x16x32_bf16 v[54:57], v[148:151], v[188:191], 0
	v_mfma_f32_16x16x32_bf16 v[46:49], v[156:159], v[188:191], 0
	v_mfma_f32_16x16x32_bf16 v[38:41], v[148:151], v[196:199], 0
	v_mfma_f32_16x16x32_bf16 v[30:33], v[156:159], v[196:199], 0
	v_mfma_f32_16x16x32_bf16 v[22:25], v[148:151], v[208:211], 0
	v_mfma_f32_16x16x32_bf16 v[12:15], v[156:159], v[208:211], 0
	v_mfma_f32_16x16x32_bf16 v[62:65], v[152:155], v[184:187], v[62:65]
	v_mfma_f32_16x16x32_bf16 v[58:61], v[160:163], v[184:187], v[58:61]
	v_mfma_f32_16x16x32_bf16 v[54:57], v[152:155], v[192:195], v[54:57]
	v_mfma_f32_16x16x32_bf16 v[46:49], v[160:163], v[192:195], v[46:49]
	v_mfma_f32_16x16x32_bf16 v[38:41], v[152:155], v[200:203], v[38:41]
	v_mfma_f32_16x16x32_bf16 v[30:33], v[160:163], v[200:203], v[30:33]
	v_mfma_f32_16x16x32_bf16 v[22:25], v[152:155], v[212:215], v[22:25]
	v_mfma_f32_16x16x32_bf16 v[12:15], v[160:163], v[212:215], v[12:15]
	v_mfma_f32_16x16x32_bf16 v[50:53], v[164:167], v[180:183], 0
	v_mfma_f32_16x16x32_bf16 v[42:45], v[172:175], v[180:183], 0
	v_mfma_f32_16x16x32_bf16 v[34:37], v[164:167], v[188:191], 0
	v_mfma_f32_16x16x32_bf16 v[26:29], v[172:175], v[188:191], 0
	v_mfma_f32_16x16x32_bf16 v[16:19], v[164:167], v[196:199], 0
	v_mfma_f32_16x16x32_bf16 v[8:11], v[172:175], v[196:199], 0
	v_mfma_f32_16x16x32_bf16 v[4:7], v[164:167], v[208:211], 0
	v_mfma_f32_16x16x32_bf16 v[0:3], v[172:175], v[208:211], 0
	v_mfma_f32_16x16x32_bf16 v[50:53], v[168:171], v[184:187], v[50:53]
	v_mfma_f32_16x16x32_bf16 v[42:45], v[176:179], v[184:187], v[42:45]
	v_mfma_f32_16x16x32_bf16 v[34:37], v[168:171], v[192:195], v[34:37]
	v_mfma_f32_16x16x32_bf16 v[26:29], v[176:179], v[192:195], v[26:29]
	v_mfma_f32_16x16x32_bf16 v[16:19], v[168:171], v[200:203], v[16:19]
	v_mfma_f32_16x16x32_bf16 v[8:11], v[176:179], v[200:203], v[8:11]
	v_mfma_f32_16x16x32_bf16 v[4:7], v[168:171], v[212:215], v[4:7]
	v_mfma_f32_16x16x32_bf16 v[0:3], v[176:179], v[212:215], v[0:3]
	s_barrier
	s_add_i32 s55, 0, 0x18000
	s_add_i32 s56, 0, 0x1c000
	v_add_u32_e32 v160, s55, v21
	v_add_u32_e32 v176, s56, v21
	ds_read_b128 v[148:151], v160
	ds_read_b128 v[152:155], v160 offset:1024
	ds_read_b128 v[156:159], v160 offset:2048
	ds_read_b128 v[160:163], v160 offset:3072
	ds_read_b128 v[164:167], v176
	ds_read_b128 v[168:171], v176 offset:1024
	ds_read_b128 v[172:175], v176 offset:2048
	ds_read_b128 v[176:179], v176 offset:3072
	s_mov_b32 m0, s45
	s_nop 0
	global_load_lds_dwordx4 v134, s[42:43]
	s_add_u32 s42, s42, 0x80000
	s_addc_u32 s43, s43, 0
	s_mov_b32 m0, s46
	ds_read_b128 v[180:183], v147 offset:32768
	ds_read_b128 v[184:187], v147 offset:33792
	ds_read_b128 v[188:191], v147 offset:34816
	ds_read_b128 v[192:195], v147 offset:35840
	ds_read_b128 v[196:199], v147 offset:36864
	ds_read_b128 v[200:203], v147 offset:37888
	ds_read_b128 v[208:211], v147 offset:38912
	ds_read_b128 v[212:215], v147 offset:39936
	global_load_lds_dwordx4 v130, s[42:43]
	s_mov_b32 m0, s47
	s_nop 0
	global_load_lds_dwordx4 v134, s[42:43]
	s_waitcnt vmcnt(8)
	s_waitcnt lgkmcnt(0)
	s_barrier
	v_mfma_f32_16x16x32_bf16 v[126:129], v[148:151], v[180:183], v[126:129]
	v_mfma_f32_16x16x32_bf16 v[122:125], v[156:159], v[180:183], v[122:125]
	v_mfma_f32_16x16x32_bf16 v[118:121], v[148:151], v[188:191], v[118:121]
	v_mfma_f32_16x16x32_bf16 v[110:113], v[156:159], v[188:191], v[110:113]
	v_mfma_f32_16x16x32_bf16 v[102:105], v[148:151], v[196:199], v[102:105]
	v_mfma_f32_16x16x32_bf16 v[94:97], v[156:159], v[196:199], v[94:97]
	v_mfma_f32_16x16x32_bf16 v[86:89], v[148:151], v[208:211], v[86:89]
	v_mfma_f32_16x16x32_bf16 v[78:81], v[156:159], v[208:211], v[78:81]
	v_mfma_f32_16x16x32_bf16 v[126:129], v[152:155], v[184:187], v[126:129]
	v_mfma_f32_16x16x32_bf16 v[122:125], v[160:163], v[184:187], v[122:125]
	v_mfma_f32_16x16x32_bf16 v[118:121], v[152:155], v[192:195], v[118:121]
	v_mfma_f32_16x16x32_bf16 v[110:113], v[160:163], v[192:195], v[110:113]
	v_mfma_f32_16x16x32_bf16 v[102:105], v[152:155], v[200:203], v[102:105]
	v_mfma_f32_16x16x32_bf16 v[94:97], v[160:163], v[200:203], v[94:97]
	v_mfma_f32_16x16x32_bf16 v[86:89], v[152:155], v[212:215], v[86:89]
	v_mfma_f32_16x16x32_bf16 v[78:81], v[160:163], v[212:215], v[78:81]
	v_mfma_f32_16x16x32_bf16 v[114:117], v[164:167], v[180:183], v[114:117]
	v_mfma_f32_16x16x32_bf16 v[106:109], v[172:175], v[180:183], v[106:109]
	v_mfma_f32_16x16x32_bf16 v[98:101], v[164:167], v[188:191], v[98:101]
	v_mfma_f32_16x16x32_bf16 v[90:93], v[172:175], v[188:191], v[90:93]
	v_mfma_f32_16x16x32_bf16 v[82:85], v[164:167], v[196:199], v[82:85]
	v_mfma_f32_16x16x32_bf16 v[74:77], v[172:175], v[196:199], v[74:77]
	v_mfma_f32_16x16x32_bf16 v[70:73], v[164:167], v[208:211], v[70:73]
	v_mfma_f32_16x16x32_bf16 v[66:69], v[172:175], v[208:211], v[66:69]
	v_mfma_f32_16x16x32_bf16 v[114:117], v[168:171], v[184:187], v[114:117]
	v_mfma_f32_16x16x32_bf16 v[106:109], v[176:179], v[184:187], v[106:109]
	v_mfma_f32_16x16x32_bf16 v[98:101], v[168:171], v[192:195], v[98:101]
	v_mfma_f32_16x16x32_bf16 v[90:93], v[176:179], v[192:195], v[90:93]
	v_mfma_f32_16x16x32_bf16 v[82:85], v[168:171], v[200:203], v[82:85]
	v_mfma_f32_16x16x32_bf16 v[74:77], v[176:179], v[200:203], v[74:77]
	v_mfma_f32_16x16x32_bf16 v[70:73], v[168:171], v[212:215], v[70:73]
	v_mfma_f32_16x16x32_bf16 v[66:69], v[176:179], v[212:215], v[66:69]
	s_barrier
; #define PG8_STAGE(bufoff, gbase, voff) do { _Pragma("unroll") for (int _i = 0; _i < 2; ++_i) \
;         __builtin_amdgcn_global_load_lds((const unsigned*)((const char*)(gbase) + (voff)[_i]), (PG8_LAS unsigned*)(lds + (bufoff) + ldsw + _i * 8192), 16, 0, 0); } while (0)
; #define PG8_LDA(dst, b, h) do { _Pragma("unroll") for (int m = 0; m < 4; ++m) _Pragma("unroll") for (int k = 0; k < 2; ++k) dst[m][k] = *(const PG8_LAS bf16x8*)(lds + PG8_SA(b, h) + aoff + m * 2048 + k * 1024); } while (0)
; #define PG8_LDB(dst, b, h) do { _Pragma("unroll") for (int n = 0; n < 2; ++n) _Pragma("unroll") for (int k = 0; k < 2; ++k) dst[n][k] = *(const PG8_LAS bf16x8*)(lds + PG8_SB(b, h) + boff + n * 2048 + k * 1024); } while (0)
; #define PG8_MMA(ai, bj, At, Bt) do { __builtin_amdgcn_s_setprio(1); _Pragma("unroll") for (int m = 0; m < 4; ++m) _Pragma("unroll") for (int n = 0; n < 2; ++n) _Pragma("unroll") for (int k = 0; k < 2; ++k) \
;         acc[ai][bj][m][n] = __builtin_amdgcn_mfma_f32_16x16x32_bf16(Bt[n][k], At[m][k], acc[ai][bj][m][n], 0, 0, 0); __builtin_amdgcn_s_setprio(0); } while (0)
; template <class Epi, class Sched, bool ALIGN_EPI = false, bool SP2 = false>
; __device__ __forceinline__ void gemm_phase(PG8_LAS unsigned char* lds, const Gemm g, const Sched& S, const Epi& E, const int tid_in) {
;     ...
;             if constexpr (SP2) {
;             PG8_LDB(B0, 0, 0); PG8_LDB(B1, 0, 1); PG8_SCHED; PG8_LDA(At, 0, 0); PG8_STAGE(PG8_SA(1, 1), a1 + hstep, voffA);
;             PG8_WAIT_V(8); PG8_WAIT_L(0); PG8_BAR; PG8_MMA(0, 0, At, B0); PG8_MMA(0, 1, At, B1); PG8_BAR; PG8_SCHED;
;             PG8_LDA(At, 0, 1); PG8_STAGE(PG8_SB(0, 0), b2, voffB); PG8_STAGE(PG8_SB(0, 1), b2 + hstep, voffB); PG8_STAGE(PG8_SA(0, 0), a2, voffA);
;             PG8_WAIT_V(8); PG8_WAIT_L(0); PG8_BAR; PG8_MMA(1, 0, At, B0); PG8_MMA(1, 1, At, B1); PG8_BAR; PG8_SCHED;
;             PG8_LDB(B0, 1, 0); PG8_LDB(B1, 1, 1); PG8_SCHED; PG8_LDA(At, 1, 0); PG8_STAGE(PG8_SA(0, 1), a2 + hstep, voffA);
;             PG8_WAIT_V(8); PG8_WAIT_L(0); PG8_BAR; PG8_MMA(0, 0, At, B0); PG8_MMA(0, 1, At, B1); PG8_BAR; PG8_SCHED;
;             PG8_LDA(At, 1, 1); PG8_STAGE(PG8_SB(1, 0), b3, voffB); PG8_STAGE(PG8_SB(1, 1), b3 + hstep, voffB); PG8_STAGE(PG8_SA(1, 0), a3, voffA);
;             PG8_WAIT_V(8); PG8_WAIT_L(0); PG8_BAR; PG8_MMA(1, 0, At, B0); PG8_MMA(1, 1, At, B1); PG8_BAR; PG8_SCHED;
	s_add_i32 s42, s55, s19
	s_mov_b32 m0, s42
	ds_read_b128 v[180:183], v147 offset:49152
	ds_read_b128 v[184:187], v147 offset:50176
	ds_read_b128 v[188:191], v147 offset:51200
	ds_read_b128 v[192:195], v147 offset:52224
	ds_read_b128 v[196:199], v147 offset:53248
	ds_read_b128 v[200:203], v147 offset:54272
	ds_read_b128 v[208:211], v147 offset:55296
	ds_read_b128 v[212:215], v147 offset:56320
	global_load_lds_dwordx4 v132, s[98:99]
	s_add_i32 m0, s42, 0x2000
	s_add_u32 s38, s38, 0x80080
	s_addc_u32 s39, s39, 0
	s_add_i32 s42, s56, s19
	global_load_lds_dwordx4 v136, s[98:99]
	s_mov_b32 m0, s42
	s_nop 0
	global_load_lds_dwordx4 v132, s[38:39]
	s_add_i32 m0, s42, 0x2000
	s_nop 0
	global_load_lds_dwordx4 v136, s[38:39]
	s_mov_b32 m0, s48
	s_nop 0
	global_load_lds_dwordx4 v130, s[100:101]
	s_waitcnt vmcnt(7)
	s_waitcnt lgkmcnt(0)
	s_barrier
	v_mfma_f32_16x16x32_bf16 v[62:65], v[148:151], v[180:183], v[62:65]
	v_mfma_f32_16x16x32_bf16 v[58:61], v[156:159], v[180:183], v[58:61]
	v_mfma_f32_16x16x32_bf16 v[54:57], v[148:151], v[188:191], v[54:57]
	v_mfma_f32_16x16x32_bf16 v[46:49], v[156:159], v[188:191], v[46:49]
	v_mfma_f32_16x16x32_bf16 v[38:41], v[148:151], v[196:199], v[38:41]
	v_mfma_f32_16x16x32_bf16 v[30:33], v[156:159], v[196:199], v[30:33]
	v_mfma_f32_16x16x32_bf16 v[22:25], v[148:151], v[208:211], v[22:25]
	v_mfma_f32_16x16x32_bf16 v[12:15], v[156:159], v[208:211], v[12:15]
	v_mfma_f32_16x16x32_bf16 v[62:65], v[152:155], v[184:187], v[62:65]
	v_mfma_f32_16x16x32_bf16 v[58:61], v[160:163], v[184:187], v[58:61]
	v_mfma_f32_16x16x32_bf16 v[54:57], v[152:155], v[192:195], v[54:57]
	v_mfma_f32_16x16x32_bf16 v[46:49], v[160:163], v[192:195], v[46:49]
	v_mfma_f32_16x16x32_bf16 v[38:41], v[152:155], v[200:203], v[38:41]
	v_mfma_f32_16x16x32_bf16 v[30:33], v[160:163], v[200:203], v[30:33]
	v_mfma_f32_16x16x32_bf16 v[22:25], v[152:155], v[212:215], v[22:25]
	v_mfma_f32_16x16x32_bf16 v[12:15], v[160:163], v[212:215], v[12:15]
	v_mfma_f32_16x16x32_bf16 v[50:53], v[164:167], v[180:183], v[50:53]
	v_mfma_f32_16x16x32_bf16 v[42:45], v[172:175], v[180:183], v[42:45]
	v_mfma_f32_16x16x32_bf16 v[34:37], v[164:167], v[188:191], v[34:37]
	v_mfma_f32_16x16x32_bf16 v[26:29], v[172:175], v[188:191], v[26:29]
	v_mfma_f32_16x16x32_bf16 v[16:19], v[164:167], v[196:199], v[16:19]
	v_mfma_f32_16x16x32_bf16 v[8:11], v[172:175], v[196:199], v[8:11]
	v_mfma_f32_16x16x32_bf16 v[4:7], v[164:167], v[208:211], v[4:7]
	v_mfma_f32_16x16x32_bf16 v[0:3], v[172:175], v[208:211], v[0:3]
	v_mfma_f32_16x16x32_bf16 v[50:53], v[168:171], v[184:187], v[50:53]
	v_mfma_f32_16x16x32_bf16 v[42:45], v[176:179], v[184:187], v[42:45]
	v_mfma_f32_16x16x32_bf16 v[34:37], v[168:171], v[192:195], v[34:37]
	v_mfma_f32_16x16x32_bf16 v[26:29], v[176:179], v[192:195], v[26:29]
	v_mfma_f32_16x16x32_bf16 v[16:19], v[168:171], v[200:203], v[16:19]
	v_mfma_f32_16x16x32_bf16 v[8:11], v[176:179], v[200:203], v[8:11]
	v_mfma_f32_16x16x32_bf16 v[4:7], v[168:171], v[212:215], v[4:7]
	v_mfma_f32_16x16x32_bf16 v[0:3], v[176:179], v[212:215], v[0:3]
	s_barrier
	s_add_i32 s54, s54, 2
	s_add_u32 s34, s34, 0x100
	s_addc_u32 s35, s35, 0
	s_add_u32 s52, s52, 0x100
	s_addc_u32 s53, s53, 0
	s_cmp_gt_u32 s54, 29
.LBB0_374:
	s_mov_b32 m0, s49
	s_nop 0
	global_load_lds_dwordx4 v134, s[100:101]
	s_add_u32 s38, s34, 0xfff80080
	s_addc_u32 s39, s35, -1
	s_add_i32 s55, 0, 0x10000
	s_cmp_eq_u32 s54, 28
	s_cselect_b32 s43, s21, s39
	s_cselect_b32 s42, s25, s38
	v_add_u32_e32 v144, s55, v21
	s_cselect_b32 s39, s23, s53
	s_cselect_b32 s38, s51, s52
	s_add_i32 s58, 0, 0x14000
	ds_read_b128 v[148:151], v144
	ds_read_b128 v[152:155], v144 offset:1024
	ds_read_b128 v[156:159], v144 offset:2048
	ds_read_b128 v[160:163], v144 offset:3072
	v_add_u32_e32 v144, s58, v21
	ds_read_b128 v[164:167], v144
	ds_read_b128 v[168:171], v144 offset:1024
	ds_read_b128 v[172:175], v144 offset:2048
	ds_read_b128 v[176:179], v144 offset:3072
	s_add_i32 m0, s44, 0xc000
	ds_read_b128 v[180:183], v147
	ds_read_b128 v[184:187], v147 offset:1024
	ds_read_b128 v[188:191], v147 offset:2048
	ds_read_b128 v[192:195], v147 offset:3072
	ds_read_b128 v[196:199], v147 offset:4096
	ds_read_b128 v[200:203], v147 offset:5120
	ds_read_b128 v[208:211], v147 offset:6144
	ds_read_b128 v[212:215], v147 offset:7168
	global_load_lds_dwordx4 v140, s[34:35]
	s_add_i32 m0, s44, 0xe000
	s_nop 0
	global_load_lds_dwordx4 v142, s[34:35]
	s_waitcnt vmcnt(8)
	s_waitcnt lgkmcnt(0)
	s_barrier
	v_mfma_f32_16x16x32_bf16 v[126:129], v[148:151], v[180:183], v[126:129]
	v_mfma_f32_16x16x32_bf16 v[122:125], v[156:159], v[180:183], v[122:125]
	v_mfma_f32_16x16x32_bf16 v[118:121], v[148:151], v[188:191], v[118:121]
	v_mfma_f32_16x16x32_bf16 v[110:113], v[156:159], v[188:191], v[110:113]
	v_mfma_f32_16x16x32_bf16 v[102:105], v[148:151], v[196:199], v[102:105]
	v_mfma_f32_16x16x32_bf16 v[94:97], v[156:159], v[196:199], v[94:97]
	v_mfma_f32_16x16x32_bf16 v[86:89], v[148:151], v[208:211], v[86:89]
	v_mfma_f32_16x16x32_bf16 v[78:81], v[156:159], v[208:211], v[78:81]
	v_mfma_f32_16x16x32_bf16 v[126:129], v[152:155], v[184:187], v[126:129]
	v_mfma_f32_16x16x32_bf16 v[122:125], v[160:163], v[184:187], v[122:125]
	v_mfma_f32_16x16x32_bf16 v[118:121], v[152:155], v[192:195], v[118:121]
	v_mfma_f32_16x16x32_bf16 v[110:113], v[160:163], v[192:195], v[110:113]
	v_mfma_f32_16x16x32_bf16 v[102:105], v[152:155], v[200:203], v[102:105]
	v_mfma_f32_16x16x32_bf16 v[94:97], v[160:163], v[200:203], v[94:97]
	v_mfma_f32_16x16x32_bf16 v[86:89], v[152:155], v[212:215], v[86:89]
	v_mfma_f32_16x16x32_bf16 v[78:81], v[160:163], v[212:215], v[78:81]
	v_mfma_f32_16x16x32_bf16 v[114:117], v[164:167], v[180:183], v[114:117]
	v_mfma_f32_16x16x32_bf16 v[106:109], v[172:175], v[180:183], v[106:109]
	v_mfma_f32_16x16x32_bf16 v[98:101], v[164:167], v[188:191], v[98:101]
	v_mfma_f32_16x16x32_bf16 v[90:93], v[172:175], v[188:191], v[90:93]
	v_mfma_f32_16x16x32_bf16 v[82:85], v[164:167], v[196:199], v[82:85]
	v_mfma_f32_16x16x32_bf16 v[74:77], v[172:175], v[196:199], v[74:77]
	v_mfma_f32_16x16x32_bf16 v[70:73], v[164:167], v[208:211], v[70:73]
	v_mfma_f32_16x16x32_bf16 v[66:69], v[172:175], v[208:211], v[66:69]
	v_mfma_f32_16x16x32_bf16 v[114:117], v[168:171], v[184:187], v[114:117]
	v_mfma_f32_16x16x32_bf16 v[106:109], v[176:179], v[184:187], v[106:109]
	v_mfma_f32_16x16x32_bf16 v[98:101], v[168:171], v[192:195], v[98:101]
	v_mfma_f32_16x16x32_bf16 v[90:93], v[176:179], v[192:195], v[90:93]
	v_mfma_f32_16x16x32_bf16 v[82:85], v[168:171], v[200:203], v[82:85]
	v_mfma_f32_16x16x32_bf16 v[74:77], v[176:179], v[200:203], v[74:77]
	v_mfma_f32_16x16x32_bf16 v[70:73], v[168:171], v[212:215], v[70:73]
	v_mfma_f32_16x16x32_bf16 v[66:69], v[176:179], v[212:215], v[66:69]
	s_barrier
; #define PG8_STAGE(bufoff, gbase, voff) do { _Pragma("unroll") for (int _i = 0; _i < 2; ++_i) \
;         __builtin_amdgcn_global_load_lds((const unsigned*)((const char*)(gbase) + (voff)[_i]), (PG8_LAS unsigned*)(lds + (bufoff) + ldsw + _i * 8192), 16, 0, 0); } while (0)
; #define PG8_LDA(dst, b, h) do { _Pragma("unroll") for (int m = 0; m < 4; ++m) _Pragma("unroll") for (int k = 0; k < 2; ++k) dst[m][k] = *(const PG8_LAS bf16x8*)(lds + PG8_SA(b, h) + aoff + m * 2048 + k * 1024); } while (0)
; #define PG8_LDB(dst, b, h) do { _Pragma("unroll") for (int n = 0; n < 2; ++n) _Pragma("unroll") for (int k = 0; k < 2; ++k) dst[n][k] = *(const PG8_LAS bf16x8*)(lds + PG8_SB(b, h) + boff + n * 2048 + k * 1024); } while (0)
; #define PG8_MMA(ai, bj, At, Bt) do { __builtin_amdgcn_s_setprio(1); _Pragma("unroll") for (int m = 0; m < 4; ++m) _Pragma("unroll") for (int n = 0; n < 2; ++n) _Pragma("unroll") for (int k = 0; k < 2; ++k) \
;         acc[ai][bj][m][n] = __builtin_amdgcn_mfma_f32_16x16x32_bf16(Bt[n][k], At[m][k], acc[ai][bj][m][n], 0, 0, 0); __builtin_amdgcn_s_setprio(0); } while (0)
; template <class Epi, class Sched, bool ALIGN_EPI = false, bool SP2 = false>
; __device__ __forceinline__ void gemm_phase(PG8_LAS unsigned char* lds, const Gemm g, const Sched& S, const Epi& E, const int tid_in) {
;     ...
;             if constexpr (SP2) {
;             PG8_LDB(B0, 0, 0); PG8_LDB(B1, 0, 1); PG8_SCHED; PG8_LDA(At, 0, 0); PG8_STAGE(PG8_SA(1, 1), a1 + hstep, voffA);
;             PG8_WAIT_V(8); PG8_WAIT_L(0); PG8_BAR; PG8_MMA(0, 0, At, B0); PG8_MMA(0, 1, At, B1); PG8_BAR; PG8_SCHED;
;             PG8_LDA(At, 0, 1); PG8_STAGE(PG8_SB(0, 0), b2, voffB); PG8_STAGE(PG8_SB(0, 1), b2 + hstep, voffB); PG8_STAGE(PG8_SA(0, 0), a2, voffA);
;             PG8_WAIT_V(8); PG8_WAIT_L(0); PG8_BAR; PG8_MMA(1, 0, At, B0); PG8_MMA(1, 1, At, B1); PG8_BAR; PG8_SCHED;
;             PG8_LDB(B0, 1, 0); PG8_LDB(B1, 1, 1); PG8_SCHED; PG8_LDA(At, 1, 0); PG8_STAGE(PG8_SA(0, 1), a2 + hstep, voffA);
;             PG8_WAIT_V(8); PG8_WAIT_L(0); PG8_BAR; PG8_MMA(0, 0, At, B0); PG8_MMA(0, 1, At, B1); PG8_BAR; PG8_SCHED;
;             PG8_LDA(At, 1, 1); PG8_STAGE(PG8_SB(1, 0), b3, voffB); PG8_STAGE(PG8_SB(1, 1), b3 + hstep, voffB); PG8_STAGE(PG8_SA(1, 0), a3, voffA);
;             PG8_WAIT_V(8); PG8_WAIT_L(0); PG8_BAR; PG8_MMA(1, 0, At, B0); PG8_MMA(1, 1, At, B1); PG8_BAR; PG8_SCHED;
	s_add_i32 s55, s55, s19
	s_add_u32 s98, s38, 0x80
	s_addc_u32 s99, s39, 0
	s_mov_b32 m0, s55
	ds_read_b128 v[180:183], v147 offset:16384
	ds_read_b128 v[184:187], v147 offset:17408
	ds_read_b128 v[188:191], v147 offset:18432
	ds_read_b128 v[192:195], v147 offset:19456
	ds_read_b128 v[196:199], v147 offset:20480
	ds_read_b128 v[200:203], v147 offset:21504
	ds_read_b128 v[208:211], v147 offset:22528
	ds_read_b128 v[212:215], v147 offset:23552
	global_load_lds_dwordx4 v132, s[38:39]
	s_add_i32 m0, s55, 0x2000
	s_add_u32 s56, s38, 0x80000
	s_addc_u32 s57, s39, 0
	s_add_i32 s55, s58, s19
	global_load_lds_dwordx4 v136, s[38:39]
	s_mov_b32 m0, s55
	s_add_u32 s100, s42, 0x80
	s_addc_u32 s101, s43, 0
	global_load_lds_dwordx4 v132, s[56:57]
	s_add_i32 m0, s55, 0x2000
	s_nop 0
	global_load_lds_dwordx4 v136, s[56:57]
	s_mov_b32 m0, s44
	s_nop 0
	global_load_lds_dwordx4 v130, s[42:43]
	s_waitcnt vmcnt(7)
	s_waitcnt lgkmcnt(0)
	s_barrier
	v_mfma_f32_16x16x32_bf16 v[62:65], v[148:151], v[180:183], v[62:65]
	v_mfma_f32_16x16x32_bf16 v[58:61], v[156:159], v[180:183], v[58:61]
	v_mfma_f32_16x16x32_bf16 v[54:57], v[148:151], v[188:191], v[54:57]
	v_mfma_f32_16x16x32_bf16 v[46:49], v[156:159], v[188:191], v[46:49]
	v_mfma_f32_16x16x32_bf16 v[38:41], v[148:151], v[196:199], v[38:41]
	v_mfma_f32_16x16x32_bf16 v[30:33], v[156:159], v[196:199], v[30:33]
	v_mfma_f32_16x16x32_bf16 v[22:25], v[148:151], v[208:211], v[22:25]
	v_mfma_f32_16x16x32_bf16 v[12:15], v[156:159], v[208:211], v[12:15]
	v_mfma_f32_16x16x32_bf16 v[62:65], v[152:155], v[184:187], v[62:65]
	v_mfma_f32_16x16x32_bf16 v[58:61], v[160:163], v[184:187], v[58:61]
	v_mfma_f32_16x16x32_bf16 v[54:57], v[152:155], v[192:195], v[54:57]
	v_mfma_f32_16x16x32_bf16 v[46:49], v[160:163], v[192:195], v[46:49]
	v_mfma_f32_16x16x32_bf16 v[38:41], v[152:155], v[200:203], v[38:41]
	v_mfma_f32_16x16x32_bf16 v[30:33], v[160:163], v[200:203], v[30:33]
	v_mfma_f32_16x16x32_bf16 v[22:25], v[152:155], v[212:215], v[22:25]
	v_mfma_f32_16x16x32_bf16 v[12:15], v[160:163], v[212:215], v[12:15]
	v_mfma_f32_16x16x32_bf16 v[50:53], v[164:167], v[180:183], v[50:53]
	v_mfma_f32_16x16x32_bf16 v[42:45], v[172:175], v[180:183], v[42:45]
	v_mfma_f32_16x16x32_bf16 v[34:37], v[164:167], v[188:191], v[34:37]
	v_mfma_f32_16x16x32_bf16 v[26:29], v[172:175], v[188:191], v[26:29]
	v_mfma_f32_16x16x32_bf16 v[16:19], v[164:167], v[196:199], v[16:19]
	v_mfma_f32_16x16x32_bf16 v[8:11], v[172:175], v[196:199], v[8:11]
	v_mfma_f32_16x16x32_bf16 v[4:7], v[164:167], v[208:211], v[4:7]
	v_mfma_f32_16x16x32_bf16 v[0:3], v[172:175], v[208:211], v[0:3]
	v_mfma_f32_16x16x32_bf16 v[50:53], v[168:171], v[184:187], v[50:53]
	v_mfma_f32_16x16x32_bf16 v[42:45], v[176:179], v[184:187], v[42:45]
	v_mfma_f32_16x16x32_bf16 v[34:37], v[168:171], v[192:195], v[34:37]
	v_mfma_f32_16x16x32_bf16 v[26:29], v[176:179], v[192:195], v[26:29]
	v_mfma_f32_16x16x32_bf16 v[16:19], v[168:171], v[200:203], v[16:19]
	v_mfma_f32_16x16x32_bf16 v[8:11], v[176:179], v[200:203], v[8:11]
	v_mfma_f32_16x16x32_bf16 v[4:7], v[168:171], v[212:215], v[4:7]
	v_mfma_f32_16x16x32_bf16 v[0:3], v[176:179], v[212:215], v[0:3]
	s_barrier
	s_add_i32 s55, 0, 0x18000
	s_add_i32 s56, 0, 0x1c000
	v_add_u32_e32 v160, s55, v21
	v_add_u32_e32 v176, s56, v21
	ds_read_b128 v[148:151], v160
	ds_read_b128 v[152:155], v160 offset:1024
	ds_read_b128 v[156:159], v160 offset:2048
	ds_read_b128 v[160:163], v160 offset:3072
	ds_read_b128 v[164:167], v176
	ds_read_b128 v[168:171], v176 offset:1024
	ds_read_b128 v[172:175], v176 offset:2048
	ds_read_b128 v[176:179], v176 offset:3072
	s_mov_b32 m0, s45
	s_nop 0
	global_load_lds_dwordx4 v134, s[42:43]
	s_add_u32 s42, s42, 0x80000
	s_addc_u32 s43, s43, 0
	s_mov_b32 m0, s46
	ds_read_b128 v[180:183], v147 offset:32768
	ds_read_b128 v[184:187], v147 offset:33792
	ds_read_b128 v[188:191], v147 offset:34816
	ds_read_b128 v[192:195], v147 offset:35840
	ds_read_b128 v[196:199], v147 offset:36864
	ds_read_b128 v[200:203], v147 offset:37888
	ds_read_b128 v[208:211], v147 offset:38912
	ds_read_b128 v[212:215], v147 offset:39936
	global_load_lds_dwordx4 v130, s[42:43]
	s_mov_b32 m0, s47
	s_nop 0
	global_load_lds_dwordx4 v134, s[42:43]
	s_waitcnt vmcnt(8)
	s_waitcnt lgkmcnt(0)
	s_barrier
; #define PG8_STAGE(bufoff, gbase, voff) do { _Pragma("unroll") for (int _i = 0; _i < 2; ++_i) \
;         __builtin_amdgcn_global_load_lds((const unsigned*)((const char*)(gbase) + (voff)[_i]), (PG8_LAS unsigned*)(lds + (bufoff) + ldsw + _i * 8192), 16, 0, 0); } while (0)
; #define PG8_LDA(dst, b, h) do { _Pragma("unroll") for (int m = 0; m < 4; ++m) _Pragma("unroll") for (int k = 0; k < 2; ++k) dst[m][k] = *(const PG8_LAS bf16x8*)(lds + PG8_SA(b, h) + aoff + m * 2048 + k * 1024); } while (0)
; #define PG8_WAIT_V(n) asm volatile("s_waitcnt vmcnt(" #n ")" ::: "memory")
; template <class Epi, class Sched, bool ALIGN_EPI = false, bool SP2 = false>
; __device__ __forceinline__ void gemm_phase(PG8_LAS unsigned char* lds, const Gemm g, const Sched& S, const Epi& E, const int tid_in) {
;     ...
;         for (int t = 0; t < nt; t += 2) {
;             if constexpr (Epi::KSPLIT > 0) { if (t == Epi::KSPLIT / BK) E.midk(acc, cur, wr, wc, fr, fq); }
;             const bool last = (t == nt - 2);
;             const char* a1 = cA + (size_t)(t + 1) * kstep;
;             const char* a2 = last ? nA : cA + (size_t)(t + 2) * kstep; const char* b2 = last ? nB : cB + (size_t)(t + 2) * kstep;
;             const char* a3 = a2 + kstep; const char* b3 = b2 + kstep;
;             if (last && has_next) S.a_ready(nxt);
;             if constexpr (SP2) {
;             PG8_LDB(B0, 0, 0); PG8_LDB(B1, 0, 1); PG8_SCHED; PG8_LDA(At, 0, 0); PG8_STAGE(PG8_SA(1, 1), a1 + hstep, voffA);
;             PG8_WAIT_V(8); PG8_WAIT_L(0); PG8_BAR; PG8_MMA(0, 0, At, B0); PG8_MMA(0, 1, At, B1); PG8_BAR; PG8_SCHED;
;             PG8_LDA(At, 0, 1); PG8_STAGE(PG8_SB(0, 0), b2, voffB); PG8_STAGE(PG8_SB(0, 1), b2 + hstep, voffB); PG8_STAGE(PG8_SA(0, 0), a2, voffA);
;             PG8_WAIT_V(8); PG8_WAIT_L(0); PG8_BAR; PG8_MMA(1, 0, At, B0); PG8_MMA(1, 1, At, B1); PG8_BAR; PG8_SCHED;
;             PG8_LDB(B0, 1, 0); PG8_LDB(B1, 1, 1); PG8_SCHED; PG8_LDA(At, 1, 0); PG8_STAGE(PG8_SA(0, 1), a2 + hstep, voffA);
;             PG8_WAIT_V(8); PG8_WAIT_L(0); PG8_BAR; PG8_MMA(0, 0, At, B0); PG8_MMA(0, 1, At, B1); PG8_BAR; PG8_SCHED;
;             PG8_LDA(At, 1, 1); PG8_STAGE(PG8_SB(1, 0), b3, voffB); PG8_STAGE(PG8_SB(1, 1), b3 + hstep, voffB); PG8_STAGE(PG8_SA(1, 0), a3, voffA);
;             PG8_WAIT_V(8); PG8_WAIT_L(0); PG8_BAR; PG8_MMA(1, 0, At, B0); PG8_MMA(1, 1, At, B1); PG8_BAR; PG8_SCHED;
	v_mfma_f32_16x16x32_bf16 v[126:129], v[148:151], v[180:183], v[126:129]
	v_mfma_f32_16x16x32_bf16 v[122:125], v[156:159], v[180:183], v[122:125]
	v_mfma_f32_16x16x32_bf16 v[118:121], v[148:151], v[188:191], v[118:121]
	v_mfma_f32_16x16x32_bf16 v[110:113], v[156:159], v[188:191], v[110:113]
	v_mfma_f32_16x16x32_bf16 v[102:105], v[148:151], v[196:199], v[102:105]
	v_mfma_f32_16x16x32_bf16 v[94:97], v[156:159], v[196:199], v[94:97]
	v_mfma_f32_16x16x32_bf16 v[86:89], v[148:151], v[208:211], v[86:89]
	v_mfma_f32_16x16x32_bf16 v[78:81], v[156:159], v[208:211], v[78:81]
	v_mfma_f32_16x16x32_bf16 v[126:129], v[152:155], v[184:187], v[126:129]
	v_mfma_f32_16x16x32_bf16 v[122:125], v[160:163], v[184:187], v[122:125]
	v_mfma_f32_16x16x32_bf16 v[118:121], v[152:155], v[192:195], v[118:121]
	v_mfma_f32_16x16x32_bf16 v[110:113], v[160:163], v[192:195], v[110:113]
	v_mfma_f32_16x16x32_bf16 v[102:105], v[152:155], v[200:203], v[102:105]
	v_mfma_f32_16x16x32_bf16 v[94:97], v[160:163], v[200:203], v[94:97]
	v_mfma_f32_16x16x32_bf16 v[86:89], v[152:155], v[212:215], v[86:89]
	v_mfma_f32_16x16x32_bf16 v[78:81], v[160:163], v[212:215], v[78:81]
	v_mfma_f32_16x16x32_bf16 v[114:117], v[164:167], v[180:183], v[114:117]
	v_mfma_f32_16x16x32_bf16 v[106:109], v[172:175], v[180:183], v[106:109]
	v_mfma_f32_16x16x32_bf16 v[98:101], v[164:167], v[188:191], v[98:101]
	v_mfma_f32_16x16x32_bf16 v[90:93], v[172:175], v[188:191], v[90:93]
	v_mfma_f32_16x16x32_bf16 v[82:85], v[164:167], v[196:199], v[82:85]
	v_mfma_f32_16x16x32_bf16 v[74:77], v[172:175], v[196:199], v[74:77]
	v_mfma_f32_16x16x32_bf16 v[70:73], v[164:167], v[208:211], v[70:73]
	v_mfma_f32_16x16x32_bf16 v[66:69], v[172:175], v[208:211], v[66:69]
	v_mfma_f32_16x16x32_bf16 v[114:117], v[168:171], v[184:187], v[114:117]
	v_mfma_f32_16x16x32_bf16 v[106:109], v[176:179], v[184:187], v[106:109]
	v_mfma_f32_16x16x32_bf16 v[98:101], v[168:171], v[192:195], v[98:101]
	v_mfma_f32_16x16x32_bf16 v[90:93], v[176:179], v[192:195], v[90:93]
	v_mfma_f32_16x16x32_bf16 v[82:85], v[168:171], v[200:203], v[82:85]
	v_mfma_f32_16x16x32_bf16 v[74:77], v[176:179], v[200:203], v[74:77]
	v_mfma_f32_16x16x32_bf16 v[70:73], v[168:171], v[212:215], v[70:73]
	v_mfma_f32_16x16x32_bf16 v[66:69], v[176:179], v[212:215], v[66:69]
	s_barrier
	s_add_i32 s42, s55, s19
	s_mov_b32 m0, s42
	ds_read_b128 v[180:183], v147 offset:49152
	ds_read_b128 v[184:187], v147 offset:50176
	ds_read_b128 v[188:191], v147 offset:51200
	ds_read_b128 v[192:195], v147 offset:52224
	ds_read_b128 v[196:199], v147 offset:53248
	ds_read_b128 v[200:203], v147 offset:54272
	ds_read_b128 v[208:211], v147 offset:55296
	ds_read_b128 v[212:215], v147 offset:56320
	global_load_lds_dwordx4 v132, s[98:99]
	s_add_i32 m0, s42, 0x2000
	s_add_u32 s38, s38, 0x80080
	s_addc_u32 s39, s39, 0
	s_add_i32 s42, s56, s19
	global_load_lds_dwordx4 v136, s[98:99]
	s_mov_b32 m0, s42
	s_nop 0
	global_load_lds_dwordx4 v132, s[38:39]
	s_add_i32 m0, s42, 0x2000
	s_nop 0
	global_load_lds_dwordx4 v136, s[38:39]
	s_mov_b32 m0, s48
	s_nop 0
	global_load_lds_dwordx4 v130, s[100:101]
	s_waitcnt vmcnt(7)
	s_waitcnt lgkmcnt(0)
	s_barrier
	v_mfma_f32_16x16x32_bf16 v[62:65], v[148:151], v[180:183], v[62:65]
	v_mfma_f32_16x16x32_bf16 v[58:61], v[156:159], v[180:183], v[58:61]
	v_mfma_f32_16x16x32_bf16 v[54:57], v[148:151], v[188:191], v[54:57]
	v_mfma_f32_16x16x32_bf16 v[46:49], v[156:159], v[188:191], v[46:49]
	v_mfma_f32_16x16x32_bf16 v[38:41], v[148:151], v[196:199], v[38:41]
	v_mfma_f32_16x16x32_bf16 v[30:33], v[156:159], v[196:199], v[30:33]
	v_mfma_f32_16x16x32_bf16 v[22:25], v[148:151], v[208:211], v[22:25]
	v_mfma_f32_16x16x32_bf16 v[12:15], v[156:159], v[208:211], v[12:15]
	v_mfma_f32_16x16x32_bf16 v[62:65], v[152:155], v[184:187], v[62:65]
	v_mfma_f32_16x16x32_bf16 v[58:61], v[160:163], v[184:187], v[58:61]
	v_mfma_f32_16x16x32_bf16 v[54:57], v[152:155], v[192:195], v[54:57]
	v_mfma_f32_16x16x32_bf16 v[46:49], v[160:163], v[192:195], v[46:49]
	v_mfma_f32_16x16x32_bf16 v[38:41], v[152:155], v[200:203], v[38:41]
	v_mfma_f32_16x16x32_bf16 v[30:33], v[160:163], v[200:203], v[30:33]
	v_mfma_f32_16x16x32_bf16 v[22:25], v[152:155], v[212:215], v[22:25]
	v_mfma_f32_16x16x32_bf16 v[12:15], v[160:163], v[212:215], v[12:15]
	v_mfma_f32_16x16x32_bf16 v[50:53], v[164:167], v[180:183], v[50:53]
	v_mfma_f32_16x16x32_bf16 v[42:45], v[172:175], v[180:183], v[42:45]
	v_mfma_f32_16x16x32_bf16 v[34:37], v[164:167], v[188:191], v[34:37]
	v_mfma_f32_16x16x32_bf16 v[26:29], v[172:175], v[188:191], v[26:29]
	v_mfma_f32_16x16x32_bf16 v[16:19], v[164:167], v[196:199], v[16:19]
	v_mfma_f32_16x16x32_bf16 v[8:11], v[172:175], v[196:199], v[8:11]
	v_mfma_f32_16x16x32_bf16 v[4:7], v[164:167], v[208:211], v[4:7]
	v_mfma_f32_16x16x32_bf16 v[0:3], v[172:175], v[208:211], v[0:3]
	v_mfma_f32_16x16x32_bf16 v[50:53], v[168:171], v[184:187], v[50:53]
	v_mfma_f32_16x16x32_bf16 v[42:45], v[176:179], v[184:187], v[42:45]
	v_mfma_f32_16x16x32_bf16 v[34:37], v[168:171], v[192:195], v[34:37]
	v_mfma_f32_16x16x32_bf16 v[26:29], v[176:179], v[192:195], v[26:29]
	v_mfma_f32_16x16x32_bf16 v[16:19], v[168:171], v[200:203], v[16:19]
	v_mfma_f32_16x16x32_bf16 v[8:11], v[176:179], v[200:203], v[8:11]
	v_mfma_f32_16x16x32_bf16 v[4:7], v[168:171], v[212:215], v[4:7]
	v_mfma_f32_16x16x32_bf16 v[0:3], v[176:179], v[212:215], v[0:3]
	s_barrier
	s_add_i32 s54, s54, 2
	s_add_u32 s34, s34, 0x100
	s_addc_u32 s35, s35, 0
	s_add_u32 s52, s52, 0x100
	s_addc_u32 s53, s53, 0
	s_cmp_gt_u32 s54, 29
	s_cbranch_scc0 .LBB0_374
	s_setprio 0
	s_and_b64 vcc, exec, s[6:7]
	v_readlane_b32 s52, v255, 9
	v_readlane_b32 s53, v255, 10
	s_cbranch_vccz .LBB0_377
	s_barrier

; #define PG8_STAGE(bufoff, gbase, voff) do { _Pragma("unroll") for (int _i = 0; _i < 2; ++_i) \
;         __builtin_amdgcn_global_load_lds((const unsigned*)((const char*)(gbase) + (voff)[_i]), (PG8_LAS unsigned*)(lds + (bufoff) + ldsw + _i * 8192), 16, 0, 0); } while (0)
; #define PG8_WAIT_V(n) asm volatile("s_waitcnt vmcnt(" #n ")" ::: "memory")
; template <class Epi, class Sched, bool ALIGN_EPI = false, bool SP2 = false>
; __device__ __forceinline__ void gemm_phase(PG8_LAS unsigned char* lds, const Gemm g, const Sched& S, const Epi& E, const int tid_in) {
;     ...
;         const bool has_next = S.next(ui + 1, nxt);
;         const char* nA = has_next ? (const char*)g.A + (size_t)nxt.pm * tstep : cA; const char* nB = has_next ? (const char*)g.Bt + (size_t)nxt.pn * tstep : cB;
;         for (int t = 0; t < nt; t += 2) {
;             if constexpr (Epi::KSPLIT > 0) { if (t == Epi::KSPLIT / BK) E.midk(acc, cur, wr, wc, fr, fq); }
;             const bool last = (t == nt - 2);
;             const char* a1 = cA + (size_t)(t + 1) * kstep;
;             const char* a2 = last ? nA : cA + (size_t)(t + 2) * kstep; const char* b2 = last ? nB : cB + (size_t)(t + 2) * kstep;
;             const char* a3 = a2 + kstep; const char* b3 = b2 + kstep;
;             if (last && has_next) S.a_ready(nxt);
;             if constexpr (SP2) {
;             PG8_LDB(B0, 0, 0); PG8_LDB(B1, 0, 1); PG8_SCHED; PG8_LDA(At, 0, 0); PG8_STAGE(PG8_SA(1, 1), a1 + hstep, voffA);
;             PG8_WAIT_V(8); PG8_WAIT_L(0); PG8_BAR; PG8_MMA(0, 0, At, B0); PG8_MMA(0, 1, At, B1); PG8_BAR; PG8_SCHED;
;             PG8_LDA(At, 0, 1); PG8_STAGE(PG8_SB(0, 0), b2, voffB); PG8_STAGE(PG8_SB(0, 1), b2 + hstep, voffB); PG8_STAGE(PG8_SA(0, 0), a2, voffA);
;             PG8_WAIT_V(8); PG8_WAIT_L(0); PG8_BAR; PG8_MMA(1, 0, At, B0); PG8_MMA(1, 1, At, B1); PG8_BAR; PG8_SCHED;
;             PG8_LDB(B0, 1, 0); PG8_LDB(B1, 1, 1); PG8_SCHED; PG8_LDA(At, 1, 0); PG8_STAGE(PG8_SA(0, 1), a2 + hstep, voffA);
;             PG8_WAIT_V(8); PG8_WAIT_L(0); PG8_BAR; PG8_MMA(0, 0, At, B0); PG8_MMA(0, 1, At, B1); PG8_BAR; PG8_SCHED;
;             PG8_LDA(At, 1, 1); PG8_STAGE(PG8_SB(1, 0), b3, voffB); PG8_STAGE(PG8_SB(1, 1), b3 + hstep, voffB); PG8_STAGE(PG8_SA(1, 0), a3, voffA);
;             PG8_WAIT_V(8); PG8_WAIT_L(0); PG8_BAR; PG8_MMA(1, 0, At, B0); PG8_MMA(1, 1, At, B1); PG8_BAR; PG8_SCHED;
.LBB0_393:
	s_ashr_i32 s23, s22, 31
	s_lshl_b64 s[24:25], s[22:23], 20
	s_add_u32 s24, s1, s24
	s_addc_u32 s25, s5, s25
	s_and_b64 s[26:27], s[36:37], exec
	s_cselect_b32 s23, s25, s29
	s_cselect_b32 s49, s24, s28
	s_ashr_i32 s21, s20, 31
	s_lshl_b64 s[26:27], s[20:21], 20
	s_add_u32 s26, s8, s26
	s_addc_u32 s27, s10, s27
	s_and_b64 s[34:35], s[36:37], exec
	s_cselect_b32 s21, s27, s31
	s_cselect_b32 s50, s26, s30
	s_add_u32 s28, s28, 0x80080
	s_addc_u32 s29, s29, 0
	s_add_u32 s51, s30, 0x100
	v_mov_b32_e32 v0, 0
	s_addc_u32 s52, s31, 0
	s_mov_b32 s53, -2
	s_cmp_lt_u32 s19, 0x1000
	s_cbranch_scc1 .LPRIO_394
	s_setprio 1
.LPRIO_394:
	s_mov_b32 m0, s45
	s_nop 0
	global_load_lds_dwordx4 v132, s[100:101]
	s_add_u32 s30, s28, 0xfff80080
	s_addc_u32 s31, s29, -1
	s_add_i32 s54, 0, 0x10000
	s_cmp_eq_u32 s53, 28
	s_cselect_b32 s35, s23, s31
	s_cselect_b32 s34, s49, s30
	v_add_u32_e32 v144, s54, v21
	s_cselect_b32 s31, s21, s52
	s_cselect_b32 s30, s50, s51
	s_add_i32 s56, 0, 0x14000
	ds_read_b128 v[148:151], v144
	ds_read_b128 v[152:155], v144 offset:1024
	ds_read_b128 v[156:159], v144 offset:2048
	ds_read_b128 v[160:163], v144 offset:3072
	v_add_u32_e32 v144, s56, v21
	ds_read_b128 v[164:167], v144
	ds_read_b128 v[168:171], v144 offset:1024
	ds_read_b128 v[172:175], v144 offset:2048
	ds_read_b128 v[176:179], v144 offset:3072
	s_add_i32 m0, s38, 0xc000
	ds_read_b128 v[180:183], v147
	ds_read_b128 v[184:187], v147 offset:1024
	ds_read_b128 v[188:191], v147 offset:2048
	ds_read_b128 v[192:195], v147 offset:3072
	ds_read_b128 v[196:199], v147 offset:4096
	ds_read_b128 v[200:203], v147 offset:5120
	ds_read_b128 v[208:211], v147 offset:6144
	ds_read_b128 v[212:215], v147 offset:7168
	global_load_lds_dwordx4 v140, s[28:29]
	s_add_i32 m0, s38, 0xe000
	s_nop 0
	global_load_lds_dwordx4 v142, s[28:29]
	s_waitcnt vmcnt(8)
	s_waitcnt lgkmcnt(0)
	s_barrier
	v_mfma_f32_16x16x32_bf16 v[126:129], v[148:151], v[180:183], 0
	v_mfma_f32_16x16x32_bf16 v[122:125], v[156:159], v[180:183], 0
	v_mfma_f32_16x16x32_bf16 v[118:121], v[148:151], v[188:191], 0
	v_mfma_f32_16x16x32_bf16 v[110:113], v[156:159], v[188:191], 0
	v_mfma_f32_16x16x32_bf16 v[102:105], v[148:151], v[196:199], 0
	v_mfma_f32_16x16x32_bf16 v[94:97], v[156:159], v[196:199], 0
	v_mfma_f32_16x16x32_bf16 v[86:89], v[148:151], v[208:211], 0
	v_mfma_f32_16x16x32_bf16 v[78:81], v[156:159], v[208:211], 0
	v_mfma_f32_16x16x32_bf16 v[126:129], v[152:155], v[184:187], v[126:129]
	v_mfma_f32_16x16x32_bf16 v[122:125], v[160:163], v[184:187], v[122:125]
	v_mfma_f32_16x16x32_bf16 v[118:121], v[152:155], v[192:195], v[118:121]
	v_mfma_f32_16x16x32_bf16 v[110:113], v[160:163], v[192:195], v[110:113]
	v_mfma_f32_16x16x32_bf16 v[102:105], v[152:155], v[200:203], v[102:105]
	v_mfma_f32_16x16x32_bf16 v[94:97], v[160:163], v[200:203], v[94:97]
	v_mfma_f32_16x16x32_bf16 v[86:89], v[152:155], v[212:215], v[86:89]
	v_mfma_f32_16x16x32_bf16 v[78:81], v[160:163], v[212:215], v[78:81]
	v_mfma_f32_16x16x32_bf16 v[114:117], v[164:167], v[180:183], 0
	v_mfma_f32_16x16x32_bf16 v[106:109], v[172:175], v[180:183], 0
	v_mfma_f32_16x16x32_bf16 v[98:101], v[164:167], v[188:191], 0
	v_mfma_f32_16x16x32_bf16 v[90:93], v[172:175], v[188:191], 0
	v_mfma_f32_16x16x32_bf16 v[82:85], v[164:167], v[196:199], 0
	v_mfma_f32_16x16x32_bf16 v[74:77], v[172:175], v[196:199], 0
	v_mfma_f32_16x16x32_bf16 v[70:73], v[164:167], v[208:211], 0
	v_mfma_f32_16x16x32_bf16 v[66:69], v[172:175], v[208:211], 0
	v_mfma_f32_16x16x32_bf16 v[114:117], v[168:171], v[184:187], v[114:117]
	v_mfma_f32_16x16x32_bf16 v[106:109], v[176:179], v[184:187], v[106:109]
	v_mfma_f32_16x16x32_bf16 v[98:101], v[168:171], v[192:195], v[98:101]
	v_mfma_f32_16x16x32_bf16 v[90:93], v[176:179], v[192:195], v[90:93]
	v_mfma_f32_16x16x32_bf16 v[82:85], v[168:171], v[200:203], v[82:85]
	v_mfma_f32_16x16x32_bf16 v[74:77], v[176:179], v[200:203], v[74:77]
	v_mfma_f32_16x16x32_bf16 v[70:73], v[168:171], v[212:215], v[70:73]
	v_mfma_f32_16x16x32_bf16 v[66:69], v[176:179], v[212:215], v[66:69]
	s_barrier
	s_add_i32 s54, s54, s19
	s_add_u32 s98, s30, 0x80
	s_addc_u32 s99, s31, 0
	s_mov_b32 m0, s54
	ds_read_b128 v[180:183], v147 offset:16384
	ds_read_b128 v[184:187], v147 offset:17408
	ds_read_b128 v[188:191], v147 offset:18432
	ds_read_b128 v[192:195], v147 offset:19456
	ds_read_b128 v[196:199], v147 offset:20480
	ds_read_b128 v[200:203], v147 offset:21504
	ds_read_b128 v[208:211], v147 offset:22528
	ds_read_b128 v[212:215], v147 offset:23552
	global_load_lds_dwordx4 v134, s[30:31]
	s_add_i32 m0, s54, 0x2000
	s_add_u32 s54, s30, 0x80000
	s_addc_u32 s55, s31, 0
	s_add_i32 s56, s56, s19
	global_load_lds_dwordx4 v130, s[30:31]
	s_mov_b32 m0, s56
	s_add_u32 s100, s34, 0x80
	s_addc_u32 s101, s35, 0
	global_load_lds_dwordx4 v134, s[54:55]
	s_add_i32 m0, s56, 0x2000
	s_nop 0
	global_load_lds_dwordx4 v130, s[54:55]
	s_mov_b32 m0, s38
	s_nop 0
	global_load_lds_dwordx4 v136, s[34:35]
	s_waitcnt vmcnt(7)
	s_waitcnt lgkmcnt(0)
	s_barrier
; #define PG8_STAGE(bufoff, gbase, voff) do { _Pragma("unroll") for (int _i = 0; _i < 2; ++_i) \
;         __builtin_amdgcn_global_load_lds((const unsigned*)((const char*)(gbase) + (voff)[_i]), (PG8_LAS unsigned*)(lds + (bufoff) + ldsw + _i * 8192), 16, 0, 0); } while (0)
; #define PG8_LDA(dst, b, h) do { _Pragma("unroll") for (int m = 0; m < 4; ++m) _Pragma("unroll") for (int k = 0; k < 2; ++k) dst[m][k] = *(const PG8_LAS bf16x8*)(lds + PG8_SA(b, h) + aoff + m * 2048 + k * 1024); } while (0)
; #define PG8_LDB(dst, b, h) do { _Pragma("unroll") for (int n = 0; n < 2; ++n) _Pragma("unroll") for (int k = 0; k < 2; ++k) dst[n][k] = *(const PG8_LAS bf16x8*)(lds + PG8_SB(b, h) + boff + n * 2048 + k * 1024); } while (0)
; #define PG8_MMA(ai, bj, At, Bt) do { __builtin_amdgcn_s_setprio(1); _Pragma("unroll") for (int m = 0; m < 4; ++m) _Pragma("unroll") for (int n = 0; n < 2; ++n) _Pragma("unroll") for (int k = 0; k < 2; ++k) \
;         acc[ai][bj][m][n] = __builtin_amdgcn_mfma_f32_16x16x32_bf16(Bt[n][k], At[m][k], acc[ai][bj][m][n], 0, 0, 0); __builtin_amdgcn_s_setprio(0); } while (0)
; template <class Epi, class Sched, bool ALIGN_EPI = false, bool SP2 = false>
; __device__ __forceinline__ void gemm_phase(PG8_LAS unsigned char* lds, const Gemm g, const Sched& S, const Epi& E, const int tid_in) {
;     ...
;             if constexpr (SP2) {
;             PG8_LDB(B0, 0, 0); PG8_LDB(B1, 0, 1); PG8_SCHED; PG8_LDA(At, 0, 0); PG8_STAGE(PG8_SA(1, 1), a1 + hstep, voffA);
;             PG8_WAIT_V(8); PG8_WAIT_L(0); PG8_BAR; PG8_MMA(0, 0, At, B0); PG8_MMA(0, 1, At, B1); PG8_BAR; PG8_SCHED;
;             PG8_LDA(At, 0, 1); PG8_STAGE(PG8_SB(0, 0), b2, voffB); PG8_STAGE(PG8_SB(0, 1), b2 + hstep, voffB); PG8_STAGE(PG8_SA(0, 0), a2, voffA);
;             PG8_WAIT_V(8); PG8_WAIT_L(0); PG8_BAR; PG8_MMA(1, 0, At, B0); PG8_MMA(1, 1, At, B1); PG8_BAR; PG8_SCHED;
;             PG8_LDB(B0, 1, 0); PG8_LDB(B1, 1, 1); PG8_SCHED; PG8_LDA(At, 1, 0); PG8_STAGE(PG8_SA(0, 1), a2 + hstep, voffA);
;             PG8_WAIT_V(8); PG8_WAIT_L(0); PG8_BAR; PG8_MMA(0, 0, At, B0); PG8_MMA(0, 1, At, B1); PG8_BAR; PG8_SCHED;
;             PG8_LDA(At, 1, 1); PG8_STAGE(PG8_SB(1, 0), b3, voffB); PG8_STAGE(PG8_SB(1, 1), b3 + hstep, voffB); PG8_STAGE(PG8_SA(1, 0), a3, voffA);
;             PG8_WAIT_V(8); PG8_WAIT_L(0); PG8_BAR; PG8_MMA(1, 0, At, B0); PG8_MMA(1, 1, At, B1); PG8_BAR; PG8_SCHED;
	v_mfma_f32_16x16x32_bf16 v[62:65], v[148:151], v[180:183], 0
	v_mfma_f32_16x16x32_bf16 v[58:61], v[156:159], v[180:183], 0
	v_mfma_f32_16x16x32_bf16 v[54:57], v[148:151], v[188:191], 0
	v_mfma_f32_16x16x32_bf16 v[46:49], v[156:159], v[188:191], 0
	v_mfma_f32_16x16x32_bf16 v[38:41], v[148:151], v[196:199], 0
	v_mfma_f32_16x16x32_bf16 v[30:33], v[156:159], v[196:199], 0
	v_mfma_f32_16x16x32_bf16 v[22:25], v[148:151], v[208:211], 0
	v_mfma_f32_16x16x32_bf16 v[12:15], v[156:159], v[208:211], 0
	v_mfma_f32_16x16x32_bf16 v[62:65], v[152:155], v[184:187], v[62:65]
	v_mfma_f32_16x16x32_bf16 v[58:61], v[160:163], v[184:187], v[58:61]
	v_mfma_f32_16x16x32_bf16 v[54:57], v[152:155], v[192:195], v[54:57]
	v_mfma_f32_16x16x32_bf16 v[46:49], v[160:163], v[192:195], v[46:49]
	v_mfma_f32_16x16x32_bf16 v[38:41], v[152:155], v[200:203], v[38:41]
	v_mfma_f32_16x16x32_bf16 v[30:33], v[160:163], v[200:203], v[30:33]
	v_mfma_f32_16x16x32_bf16 v[22:25], v[152:155], v[212:215], v[22:25]
	v_mfma_f32_16x16x32_bf16 v[12:15], v[160:163], v[212:215], v[12:15]
	v_mfma_f32_16x16x32_bf16 v[50:53], v[164:167], v[180:183], 0
	v_mfma_f32_16x16x32_bf16 v[42:45], v[172:175], v[180:183], 0
	v_mfma_f32_16x16x32_bf16 v[34:37], v[164:167], v[188:191], 0
	v_mfma_f32_16x16x32_bf16 v[26:29], v[172:175], v[188:191], 0
	v_mfma_f32_16x16x32_bf16 v[16:19], v[164:167], v[196:199], 0
	v_mfma_f32_16x16x32_bf16 v[8:11], v[172:175], v[196:199], 0
	v_mfma_f32_16x16x32_bf16 v[4:7], v[164:167], v[208:211], 0
	v_mfma_f32_16x16x32_bf16 v[0:3], v[172:175], v[208:211], 0
	v_mfma_f32_16x16x32_bf16 v[50:53], v[168:171], v[184:187], v[50:53]
	v_mfma_f32_16x16x32_bf16 v[42:45], v[176:179], v[184:187], v[42:45]
	v_mfma_f32_16x16x32_bf16 v[34:37], v[168:171], v[192:195], v[34:37]
	v_mfma_f32_16x16x32_bf16 v[26:29], v[176:179], v[192:195], v[26:29]
	v_mfma_f32_16x16x32_bf16 v[16:19], v[168:171], v[200:203], v[16:19]
	v_mfma_f32_16x16x32_bf16 v[8:11], v[176:179], v[200:203], v[8:11]
	v_mfma_f32_16x16x32_bf16 v[4:7], v[168:171], v[212:215], v[4:7]
	v_mfma_f32_16x16x32_bf16 v[0:3], v[176:179], v[212:215], v[0:3]
	s_barrier
	s_add_i32 s54, 0, 0x18000
	s_add_i32 s55, 0, 0x1c000
	v_add_u32_e32 v160, s54, v21
	v_add_u32_e32 v176, s55, v21
	ds_read_b128 v[148:151], v160
	ds_read_b128 v[152:155], v160 offset:1024
	ds_read_b128 v[156:159], v160 offset:2048
	ds_read_b128 v[160:163], v160 offset:3072
	ds_read_b128 v[164:167], v176
	ds_read_b128 v[168:171], v176 offset:1024
	ds_read_b128 v[172:175], v176 offset:2048
	ds_read_b128 v[176:179], v176 offset:3072
	s_mov_b32 m0, s39
	s_nop 0
	global_load_lds_dwordx4 v132, s[34:35]
	s_add_u32 s34, s34, 0x80000
	s_addc_u32 s35, s35, 0
	s_mov_b32 m0, s42
	ds_read_b128 v[180:183], v147 offset:32768
	ds_read_b128 v[184:187], v147 offset:33792
	ds_read_b128 v[188:191], v147 offset:34816
	ds_read_b128 v[192:195], v147 offset:35840
	ds_read_b128 v[196:199], v147 offset:36864
	ds_read_b128 v[200:203], v147 offset:37888
	ds_read_b128 v[208:211], v147 offset:38912
	ds_read_b128 v[212:215], v147 offset:39936
	global_load_lds_dwordx4 v136, s[34:35]
	s_mov_b32 m0, s43
	s_nop 0
	global_load_lds_dwordx4 v132, s[34:35]
	s_waitcnt vmcnt(8)
	s_waitcnt lgkmcnt(0)
	s_barrier
	v_mfma_f32_16x16x32_bf16 v[126:129], v[148:151], v[180:183], v[126:129]
	v_mfma_f32_16x16x32_bf16 v[122:125], v[156:159], v[180:183], v[122:125]
	v_mfma_f32_16x16x32_bf16 v[118:121], v[148:151], v[188:191], v[118:121]
	v_mfma_f32_16x16x32_bf16 v[110:113], v[156:159], v[188:191], v[110:113]
	v_mfma_f32_16x16x32_bf16 v[102:105], v[148:151], v[196:199], v[102:105]
	v_mfma_f32_16x16x32_bf16 v[94:97], v[156:159], v[196:199], v[94:97]
	v_mfma_f32_16x16x32_bf16 v[86:89], v[148:151], v[208:211], v[86:89]
	v_mfma_f32_16x16x32_bf16 v[78:81], v[156:159], v[208:211], v[78:81]
	v_mfma_f32_16x16x32_bf16 v[126:129], v[152:155], v[184:187], v[126:129]
	v_mfma_f32_16x16x32_bf16 v[122:125], v[160:163], v[184:187], v[122:125]
	v_mfma_f32_16x16x32_bf16 v[118:121], v[152:155], v[192:195], v[118:121]
	v_mfma_f32_16x16x32_bf16 v[110:113], v[160:163], v[192:195], v[110:113]
	v_mfma_f32_16x16x32_bf16 v[102:105], v[152:155], v[200:203], v[102:105]
	v_mfma_f32_16x16x32_bf16 v[94:97], v[160:163], v[200:203], v[94:97]
	v_mfma_f32_16x16x32_bf16 v[86:89], v[152:155], v[212:215], v[86:89]
	v_mfma_f32_16x16x32_bf16 v[78:81], v[160:163], v[212:215], v[78:81]
	v_mfma_f32_16x16x32_bf16 v[114:117], v[164:167], v[180:183], v[114:117]
	v_mfma_f32_16x16x32_bf16 v[106:109], v[172:175], v[180:183], v[106:109]
	v_mfma_f32_16x16x32_bf16 v[98:101], v[164:167], v[188:191], v[98:101]
	v_mfma_f32_16x16x32_bf16 v[90:93], v[172:175], v[188:191], v[90:93]
	v_mfma_f32_16x16x32_bf16 v[82:85], v[164:167], v[196:199], v[82:85]
	v_mfma_f32_16x16x32_bf16 v[74:77], v[172:175], v[196:199], v[74:77]
	v_mfma_f32_16x16x32_bf16 v[70:73], v[164:167], v[208:211], v[70:73]
	v_mfma_f32_16x16x32_bf16 v[66:69], v[172:175], v[208:211], v[66:69]
	v_mfma_f32_16x16x32_bf16 v[114:117], v[168:171], v[184:187], v[114:117]
	v_mfma_f32_16x16x32_bf16 v[106:109], v[176:179], v[184:187], v[106:109]
	v_mfma_f32_16x16x32_bf16 v[98:101], v[168:171], v[192:195], v[98:101]
	v_mfma_f32_16x16x32_bf16 v[90:93], v[176:179], v[192:195], v[90:93]
	v_mfma_f32_16x16x32_bf16 v[82:85], v[168:171], v[200:203], v[82:85]
	v_mfma_f32_16x16x32_bf16 v[74:77], v[176:179], v[200:203], v[74:77]
	v_mfma_f32_16x16x32_bf16 v[70:73], v[168:171], v[212:215], v[70:73]
	v_mfma_f32_16x16x32_bf16 v[66:69], v[176:179], v[212:215], v[66:69]
	s_barrier
; #define PG8_STAGE(bufoff, gbase, voff) do { _Pragma("unroll") for (int _i = 0; _i < 2; ++_i) \
;         __builtin_amdgcn_global_load_lds((const unsigned*)((const char*)(gbase) + (voff)[_i]), (PG8_LAS unsigned*)(lds + (bufoff) + ldsw + _i * 8192), 16, 0, 0); } while (0)
; #define PG8_LDA(dst, b, h) do { _Pragma("unroll") for (int m = 0; m < 4; ++m) _Pragma("unroll") for (int k = 0; k < 2; ++k) dst[m][k] = *(const PG8_LAS bf16x8*)(lds + PG8_SA(b, h) + aoff + m * 2048 + k * 1024); } while (0)
; #define PG8_LDB(dst, b, h) do { _Pragma("unroll") for (int n = 0; n < 2; ++n) _Pragma("unroll") for (int k = 0; k < 2; ++k) dst[n][k] = *(const PG8_LAS bf16x8*)(lds + PG8_SB(b, h) + boff + n * 2048 + k * 1024); } while (0)
; #define PG8_MMA(ai, bj, At, Bt) do { __builtin_amdgcn_s_setprio(1); _Pragma("unroll") for (int m = 0; m < 4; ++m) _Pragma("unroll") for (int n = 0; n < 2; ++n) _Pragma("unroll") for (int k = 0; k < 2; ++k) \
;         acc[ai][bj][m][n] = __builtin_amdgcn_mfma_f32_16x16x32_bf16(Bt[n][k], At[m][k], acc[ai][bj][m][n], 0, 0, 0); __builtin_amdgcn_s_setprio(0); } while (0)
; template <class Epi, class Sched, bool ALIGN_EPI = false, bool SP2 = false>
; __device__ __forceinline__ void gemm_phase(PG8_LAS unsigned char* lds, const Gemm g, const Sched& S, const Epi& E, const int tid_in) {
;     ...
;             if constexpr (SP2) {
;             PG8_LDB(B0, 0, 0); PG8_LDB(B1, 0, 1); PG8_SCHED; PG8_LDA(At, 0, 0); PG8_STAGE(PG8_SA(1, 1), a1 + hstep, voffA);
;             PG8_WAIT_V(8); PG8_WAIT_L(0); PG8_BAR; PG8_MMA(0, 0, At, B0); PG8_MMA(0, 1, At, B1); PG8_BAR; PG8_SCHED;
;             PG8_LDA(At, 0, 1); PG8_STAGE(PG8_SB(0, 0), b2, voffB); PG8_STAGE(PG8_SB(0, 1), b2 + hstep, voffB); PG8_STAGE(PG8_SA(0, 0), a2, voffA);
;             PG8_WAIT_V(8); PG8_WAIT_L(0); PG8_BAR; PG8_MMA(1, 0, At, B0); PG8_MMA(1, 1, At, B1); PG8_BAR; PG8_SCHED;
;             PG8_LDB(B0, 1, 0); PG8_LDB(B1, 1, 1); PG8_SCHED; PG8_LDA(At, 1, 0); PG8_STAGE(PG8_SA(0, 1), a2 + hstep, voffA);
;             PG8_WAIT_V(8); PG8_WAIT_L(0); PG8_BAR; PG8_MMA(0, 0, At, B0); PG8_MMA(0, 1, At, B1); PG8_BAR; PG8_SCHED;
;             PG8_LDA(At, 1, 1); PG8_STAGE(PG8_SB(1, 0), b3, voffB); PG8_STAGE(PG8_SB(1, 1), b3 + hstep, voffB); PG8_STAGE(PG8_SA(1, 0), a3, voffA);
;             PG8_WAIT_V(8); PG8_WAIT_L(0); PG8_BAR; PG8_MMA(1, 0, At, B0); PG8_MMA(1, 1, At, B1); PG8_BAR; PG8_SCHED;
	s_add_i32 s34, s54, s19
	s_mov_b32 m0, s34
	ds_read_b128 v[180:183], v147 offset:49152
	ds_read_b128 v[184:187], v147 offset:50176
	ds_read_b128 v[188:191], v147 offset:51200
	ds_read_b128 v[192:195], v147 offset:52224
	ds_read_b128 v[196:199], v147 offset:53248
	ds_read_b128 v[200:203], v147 offset:54272
	ds_read_b128 v[208:211], v147 offset:55296
	ds_read_b128 v[212:215], v147 offset:56320
	global_load_lds_dwordx4 v134, s[98:99]
	s_add_i32 m0, s34, 0x2000
	s_add_u32 s30, s30, 0x80080
	s_addc_u32 s31, s31, 0
	s_add_i32 s34, s55, s19
	global_load_lds_dwordx4 v130, s[98:99]
	s_mov_b32 m0, s34
	s_nop 0
	global_load_lds_dwordx4 v134, s[30:31]
	s_add_i32 m0, s34, 0x2000
	s_nop 0
	global_load_lds_dwordx4 v130, s[30:31]
	s_mov_b32 m0, s44
	s_nop 0
	global_load_lds_dwordx4 v136, s[100:101]
	s_waitcnt vmcnt(7)
	s_waitcnt lgkmcnt(0)
	s_barrier
	v_mfma_f32_16x16x32_bf16 v[62:65], v[148:151], v[180:183], v[62:65]
	v_mfma_f32_16x16x32_bf16 v[58:61], v[156:159], v[180:183], v[58:61]
	v_mfma_f32_16x16x32_bf16 v[54:57], v[148:151], v[188:191], v[54:57]
	v_mfma_f32_16x16x32_bf16 v[46:49], v[156:159], v[188:191], v[46:49]
	v_mfma_f32_16x16x32_bf16 v[38:41], v[148:151], v[196:199], v[38:41]
	v_mfma_f32_16x16x32_bf16 v[30:33], v[156:159], v[196:199], v[30:33]
	v_mfma_f32_16x16x32_bf16 v[22:25], v[148:151], v[208:211], v[22:25]
	v_mfma_f32_16x16x32_bf16 v[12:15], v[156:159], v[208:211], v[12:15]
	v_mfma_f32_16x16x32_bf16 v[62:65], v[152:155], v[184:187], v[62:65]
	v_mfma_f32_16x16x32_bf16 v[58:61], v[160:163], v[184:187], v[58:61]
	v_mfma_f32_16x16x32_bf16 v[54:57], v[152:155], v[192:195], v[54:57]
	v_mfma_f32_16x16x32_bf16 v[46:49], v[160:163], v[192:195], v[46:49]
	v_mfma_f32_16x16x32_bf16 v[38:41], v[152:155], v[200:203], v[38:41]
	v_mfma_f32_16x16x32_bf16 v[30:33], v[160:163], v[200:203], v[30:33]
	v_mfma_f32_16x16x32_bf16 v[22:25], v[152:155], v[212:215], v[22:25]
	v_mfma_f32_16x16x32_bf16 v[12:15], v[160:163], v[212:215], v[12:15]
	v_mfma_f32_16x16x32_bf16 v[50:53], v[164:167], v[180:183], v[50:53]
	v_mfma_f32_16x16x32_bf16 v[42:45], v[172:175], v[180:183], v[42:45]
	v_mfma_f32_16x16x32_bf16 v[34:37], v[164:167], v[188:191], v[34:37]
	v_mfma_f32_16x16x32_bf16 v[26:29], v[172:175], v[188:191], v[26:29]
	v_mfma_f32_16x16x32_bf16 v[16:19], v[164:167], v[196:199], v[16:19]
	v_mfma_f32_16x16x32_bf16 v[8:11], v[172:175], v[196:199], v[8:11]
	v_mfma_f32_16x16x32_bf16 v[4:7], v[164:167], v[208:211], v[4:7]
	v_mfma_f32_16x16x32_bf16 v[0:3], v[172:175], v[208:211], v[0:3]
	v_mfma_f32_16x16x32_bf16 v[50:53], v[168:171], v[184:187], v[50:53]
	v_mfma_f32_16x16x32_bf16 v[42:45], v[176:179], v[184:187], v[42:45]
	v_mfma_f32_16x16x32_bf16 v[34:37], v[168:171], v[192:195], v[34:37]
	v_mfma_f32_16x16x32_bf16 v[26:29], v[176:179], v[192:195], v[26:29]
	v_mfma_f32_16x16x32_bf16 v[16:19], v[168:171], v[200:203], v[16:19]
	v_mfma_f32_16x16x32_bf16 v[8:11], v[176:179], v[200:203], v[8:11]
	v_mfma_f32_16x16x32_bf16 v[4:7], v[168:171], v[212:215], v[4:7]
	v_mfma_f32_16x16x32_bf16 v[0:3], v[176:179], v[212:215], v[0:3]
	s_barrier
	s_add_i32 s53, s53, 2
	s_add_u32 s28, s28, 0x100
	s_addc_u32 s29, s29, 0
	s_add_u32 s51, s51, 0x100
	s_addc_u32 s52, s52, 0
	s_cmp_gt_u32 s53, 29
.LBB0_394:
	s_mov_b32 m0, s45
	s_nop 0
	global_load_lds_dwordx4 v132, s[100:101]
	s_add_u32 s30, s28, 0xfff80080
	s_addc_u32 s31, s29, -1
	s_add_i32 s54, 0, 0x10000
	s_cmp_eq_u32 s53, 28
	s_cselect_b32 s35, s23, s31
	s_cselect_b32 s34, s49, s30
	v_add_u32_e32 v144, s54, v21
	s_cselect_b32 s31, s21, s52
	s_cselect_b32 s30, s50, s51
	s_add_i32 s56, 0, 0x14000
	ds_read_b128 v[148:151], v144
	ds_read_b128 v[152:155], v144 offset:1024
	ds_read_b128 v[156:159], v144 offset:2048
	ds_read_b128 v[160:163], v144 offset:3072
	v_add_u32_e32 v144, s56, v21
	ds_read_b128 v[164:167], v144
	ds_read_b128 v[168:171], v144 offset:1024
	ds_read_b128 v[172:175], v144 offset:2048
	ds_read_b128 v[176:179], v144 offset:3072
	s_add_i32 m0, s38, 0xc000
	ds_read_b128 v[180:183], v147
	ds_read_b128 v[184:187], v147 offset:1024
	ds_read_b128 v[188:191], v147 offset:2048
	ds_read_b128 v[192:195], v147 offset:3072
	ds_read_b128 v[196:199], v147 offset:4096
	ds_read_b128 v[200:203], v147 offset:5120
	ds_read_b128 v[208:211], v147 offset:6144
	ds_read_b128 v[212:215], v147 offset:7168
	global_load_lds_dwordx4 v140, s[28:29]
	s_add_i32 m0, s38, 0xe000
	s_nop 0
	global_load_lds_dwordx4 v142, s[28:29]
	s_waitcnt vmcnt(8)
	s_waitcnt lgkmcnt(0)
	s_barrier
	v_mfma_f32_16x16x32_bf16 v[126:129], v[148:151], v[180:183], v[126:129]
	v_mfma_f32_16x16x32_bf16 v[122:125], v[156:159], v[180:183], v[122:125]
	v_mfma_f32_16x16x32_bf16 v[118:121], v[148:151], v[188:191], v[118:121]
	v_mfma_f32_16x16x32_bf16 v[110:113], v[156:159], v[188:191], v[110:113]
	v_mfma_f32_16x16x32_bf16 v[102:105], v[148:151], v[196:199], v[102:105]
	v_mfma_f32_16x16x32_bf16 v[94:97], v[156:159], v[196:199], v[94:97]
	v_mfma_f32_16x16x32_bf16 v[86:89], v[148:151], v[208:211], v[86:89]
	v_mfma_f32_16x16x32_bf16 v[78:81], v[156:159], v[208:211], v[78:81]
	v_mfma_f32_16x16x32_bf16 v[126:129], v[152:155], v[184:187], v[126:129]
	v_mfma_f32_16x16x32_bf16 v[122:125], v[160:163], v[184:187], v[122:125]
	v_mfma_f32_16x16x32_bf16 v[118:121], v[152:155], v[192:195], v[118:121]
	v_mfma_f32_16x16x32_bf16 v[110:113], v[160:163], v[192:195], v[110:113]
	v_mfma_f32_16x16x32_bf16 v[102:105], v[152:155], v[200:203], v[102:105]
	v_mfma_f32_16x16x32_bf16 v[94:97], v[160:163], v[200:203], v[94:97]
	v_mfma_f32_16x16x32_bf16 v[86:89], v[152:155], v[212:215], v[86:89]
	v_mfma_f32_16x16x32_bf16 v[78:81], v[160:163], v[212:215], v[78:81]
	v_mfma_f32_16x16x32_bf16 v[114:117], v[164:167], v[180:183], v[114:117]
	v_mfma_f32_16x16x32_bf16 v[106:109], v[172:175], v[180:183], v[106:109]
	v_mfma_f32_16x16x32_bf16 v[98:101], v[164:167], v[188:191], v[98:101]
	v_mfma_f32_16x16x32_bf16 v[90:93], v[172:175], v[188:191], v[90:93]
	v_mfma_f32_16x16x32_bf16 v[82:85], v[164:167], v[196:199], v[82:85]
	v_mfma_f32_16x16x32_bf16 v[74:77], v[172:175], v[196:199], v[74:77]
	v_mfma_f32_16x16x32_bf16 v[70:73], v[164:167], v[208:211], v[70:73]
	v_mfma_f32_16x16x32_bf16 v[66:69], v[172:175], v[208:211], v[66:69]
	v_mfma_f32_16x16x32_bf16 v[114:117], v[168:171], v[184:187], v[114:117]
	v_mfma_f32_16x16x32_bf16 v[106:109], v[176:179], v[184:187], v[106:109]
	v_mfma_f32_16x16x32_bf16 v[98:101], v[168:171], v[192:195], v[98:101]
	v_mfma_f32_16x16x32_bf16 v[90:93], v[176:179], v[192:195], v[90:93]
	v_mfma_f32_16x16x32_bf16 v[82:85], v[168:171], v[200:203], v[82:85]
	v_mfma_f32_16x16x32_bf16 v[74:77], v[176:179], v[200:203], v[74:77]
	v_mfma_f32_16x16x32_bf16 v[70:73], v[168:171], v[212:215], v[70:73]
	v_mfma_f32_16x16x32_bf16 v[66:69], v[176:179], v[212:215], v[66:69]
	s_barrier
; #define PG8_STAGE(bufoff, gbase, voff) do { _Pragma("unroll") for (int _i = 0; _i < 2; ++_i) \
;         __builtin_amdgcn_global_load_lds((const unsigned*)((const char*)(gbase) + (voff)[_i]), (PG8_LAS unsigned*)(lds + (bufoff) + ldsw + _i * 8192), 16, 0, 0); } while (0)
; #define PG8_LDA(dst, b, h) do { _Pragma("unroll") for (int m = 0; m < 4; ++m) _Pragma("unroll") for (int k = 0; k < 2; ++k) dst[m][k] = *(const PG8_LAS bf16x8*)(lds + PG8_SA(b, h) + aoff + m * 2048 + k * 1024); } while (0)
; #define PG8_LDB(dst, b, h) do { _Pragma("unroll") for (int n = 0; n < 2; ++n) _Pragma("unroll") for (int k = 0; k < 2; ++k) dst[n][k] = *(const PG8_LAS bf16x8*)(lds + PG8_SB(b, h) + boff + n * 2048 + k * 1024); } while (0)
; #define PG8_MMA(ai, bj, At, Bt) do { __builtin_amdgcn_s_setprio(1); _Pragma("unroll") for (int m = 0; m < 4; ++m) _Pragma("unroll") for (int n = 0; n < 2; ++n) _Pragma("unroll") for (int k = 0; k < 2; ++k) \
;         acc[ai][bj][m][n] = __builtin_amdgcn_mfma_f32_16x16x32_bf16(Bt[n][k], At[m][k], acc[ai][bj][m][n], 0, 0, 0); __builtin_amdgcn_s_setprio(0); } while (0)
; template <class Epi, class Sched, bool ALIGN_EPI = false, bool SP2 = false>
; __device__ __forceinline__ void gemm_phase(PG8_LAS unsigned char* lds, const Gemm g, const Sched& S, const Epi& E, const int tid_in) {
;     ...
;             if constexpr (SP2) {
;             PG8_LDB(B0, 0, 0); PG8_LDB(B1, 0, 1); PG8_SCHED; PG8_LDA(At, 0, 0); PG8_STAGE(PG8_SA(1, 1), a1 + hstep, voffA);
;             PG8_WAIT_V(8); PG8_WAIT_L(0); PG8_BAR; PG8_MMA(0, 0, At, B0); PG8_MMA(0, 1, At, B1); PG8_BAR; PG8_SCHED;
;             PG8_LDA(At, 0, 1); PG8_STAGE(PG8_SB(0, 0), b2, voffB); PG8_STAGE(PG8_SB(0, 1), b2 + hstep, voffB); PG8_STAGE(PG8_SA(0, 0), a2, voffA);
;             PG8_WAIT_V(8); PG8_WAIT_L(0); PG8_BAR; PG8_MMA(1, 0, At, B0); PG8_MMA(1, 1, At, B1); PG8_BAR; PG8_SCHED;
;             PG8_LDB(B0, 1, 0); PG8_LDB(B1, 1, 1); PG8_SCHED; PG8_LDA(At, 1, 0); PG8_STAGE(PG8_SA(0, 1), a2 + hstep, voffA);
;             PG8_WAIT_V(8); PG8_WAIT_L(0); PG8_BAR; PG8_MMA(0, 0, At, B0); PG8_MMA(0, 1, At, B1); PG8_BAR; PG8_SCHED;
;             PG8_LDA(At, 1, 1); PG8_STAGE(PG8_SB(1, 0), b3, voffB); PG8_STAGE(PG8_SB(1, 1), b3 + hstep, voffB); PG8_STAGE(PG8_SA(1, 0), a3, voffA);
;             PG8_WAIT_V(8); PG8_WAIT_L(0); PG8_BAR; PG8_MMA(1, 0, At, B0); PG8_MMA(1, 1, At, B1); PG8_BAR; PG8_SCHED;
	s_add_i32 s54, s54, s19
	s_add_u32 s98, s30, 0x80
	s_addc_u32 s99, s31, 0
	s_mov_b32 m0, s54
	ds_read_b128 v[180:183], v147 offset:16384
	ds_read_b128 v[184:187], v147 offset:17408
	ds_read_b128 v[188:191], v147 offset:18432
	ds_read_b128 v[192:195], v147 offset:19456
	ds_read_b128 v[196:199], v147 offset:20480
	ds_read_b128 v[200:203], v147 offset:21504
	ds_read_b128 v[208:211], v147 offset:22528
	ds_read_b128 v[212:215], v147 offset:23552
	global_load_lds_dwordx4 v134, s[30:31]
	s_add_i32 m0, s54, 0x2000
	s_add_u32 s54, s30, 0x80000
	s_addc_u32 s55, s31, 0
	s_add_i32 s56, s56, s19
	global_load_lds_dwordx4 v130, s[30:31]
	s_mov_b32 m0, s56
	s_add_u32 s100, s34, 0x80
	s_addc_u32 s101, s35, 0
	global_load_lds_dwordx4 v134, s[54:55]
	s_add_i32 m0, s56, 0x2000
	s_nop 0
	global_load_lds_dwordx4 v130, s[54:55]
	s_mov_b32 m0, s38
	s_nop 0
	global_load_lds_dwordx4 v136, s[34:35]
	s_waitcnt vmcnt(7)
	s_waitcnt lgkmcnt(0)
	s_barrier
	v_mfma_f32_16x16x32_bf16 v[62:65], v[148:151], v[180:183], v[62:65]
	v_mfma_f32_16x16x32_bf16 v[58:61], v[156:159], v[180:183], v[58:61]
	v_mfma_f32_16x16x32_bf16 v[54:57], v[148:151], v[188:191], v[54:57]
	v_mfma_f32_16x16x32_bf16 v[46:49], v[156:159], v[188:191], v[46:49]
	v_mfma_f32_16x16x32_bf16 v[38:41], v[148:151], v[196:199], v[38:41]
	v_mfma_f32_16x16x32_bf16 v[30:33], v[156:159], v[196:199], v[30:33]
	v_mfma_f32_16x16x32_bf16 v[22:25], v[148:151], v[208:211], v[22:25]
	v_mfma_f32_16x16x32_bf16 v[12:15], v[156:159], v[208:211], v[12:15]
	v_mfma_f32_16x16x32_bf16 v[62:65], v[152:155], v[184:187], v[62:65]
	v_mfma_f32_16x16x32_bf16 v[58:61], v[160:163], v[184:187], v[58:61]
	v_mfma_f32_16x16x32_bf16 v[54:57], v[152:155], v[192:195], v[54:57]
	v_mfma_f32_16x16x32_bf16 v[46:49], v[160:163], v[192:195], v[46:49]
	v_mfma_f32_16x16x32_bf16 v[38:41], v[152:155], v[200:203], v[38:41]
	v_mfma_f32_16x16x32_bf16 v[30:33], v[160:163], v[200:203], v[30:33]
	v_mfma_f32_16x16x32_bf16 v[22:25], v[152:155], v[212:215], v[22:25]
	v_mfma_f32_16x16x32_bf16 v[12:15], v[160:163], v[212:215], v[12:15]
	v_mfma_f32_16x16x32_bf16 v[50:53], v[164:167], v[180:183], v[50:53]
	v_mfma_f32_16x16x32_bf16 v[42:45], v[172:175], v[180:183], v[42:45]
	v_mfma_f32_16x16x32_bf16 v[34:37], v[164:167], v[188:191], v[34:37]
	v_mfma_f32_16x16x32_bf16 v[26:29], v[172:175], v[188:191], v[26:29]
	v_mfma_f32_16x16x32_bf16 v[16:19], v[164:167], v[196:199], v[16:19]
	v_mfma_f32_16x16x32_bf16 v[8:11], v[172:175], v[196:199], v[8:11]
	v_mfma_f32_16x16x32_bf16 v[4:7], v[164:167], v[208:211], v[4:7]
	v_mfma_f32_16x16x32_bf16 v[0:3], v[172:175], v[208:211], v[0:3]
	v_mfma_f32_16x16x32_bf16 v[50:53], v[168:171], v[184:187], v[50:53]
	v_mfma_f32_16x16x32_bf16 v[42:45], v[176:179], v[184:187], v[42:45]
	v_mfma_f32_16x16x32_bf16 v[34:37], v[168:171], v[192:195], v[34:37]
	v_mfma_f32_16x16x32_bf16 v[26:29], v[176:179], v[192:195], v[26:29]
	v_mfma_f32_16x16x32_bf16 v[16:19], v[168:171], v[200:203], v[16:19]
	v_mfma_f32_16x16x32_bf16 v[8:11], v[176:179], v[200:203], v[8:11]
	v_mfma_f32_16x16x32_bf16 v[4:7], v[168:171], v[212:215], v[4:7]
	v_mfma_f32_16x16x32_bf16 v[0:3], v[176:179], v[212:215], v[0:3]
	s_barrier
	s_add_i32 s54, 0, 0x18000
	s_add_i32 s55, 0, 0x1c000
	v_add_u32_e32 v160, s54, v21
	v_add_u32_e32 v176, s55, v21
	ds_read_b128 v[148:151], v160
	ds_read_b128 v[152:155], v160 offset:1024
	ds_read_b128 v[156:159], v160 offset:2048
	ds_read_b128 v[160:163], v160 offset:3072
	ds_read_b128 v[164:167], v176
	ds_read_b128 v[168:171], v176 offset:1024
	ds_read_b128 v[172:175], v176 offset:2048
	ds_read_b128 v[176:179], v176 offset:3072
	s_mov_b32 m0, s39
	s_nop 0
	global_load_lds_dwordx4 v132, s[34:35]
	s_add_u32 s34, s34, 0x80000
	s_addc_u32 s35, s35, 0
	s_mov_b32 m0, s42
	ds_read_b128 v[180:183], v147 offset:32768
	ds_read_b128 v[184:187], v147 offset:33792
	ds_read_b128 v[188:191], v147 offset:34816
	ds_read_b128 v[192:195], v147 offset:35840
	ds_read_b128 v[196:199], v147 offset:36864
	ds_read_b128 v[200:203], v147 offset:37888
	ds_read_b128 v[208:211], v147 offset:38912
	ds_read_b128 v[212:215], v147 offset:39936
	global_load_lds_dwordx4 v136, s[34:35]
	s_mov_b32 m0, s43
	s_nop 0
	global_load_lds_dwordx4 v132, s[34:35]
	s_waitcnt vmcnt(8)
	s_waitcnt lgkmcnt(0)
	s_barrier
; #define PG8_BAR __builtin_amdgcn_s_barrier()
; template <class Epi, class Sched, bool ALIGN_EPI = false, bool SP2 = false>
; __device__ __forceinline__ void gemm_phase(PG8_LAS unsigned char* lds, const Gemm g, const Sched& S, const Epi& E, const int tid_in) {
;     ...
;             if constexpr (SP2) {
;             PG8_LDB(B0, 0, 0); PG8_LDB(B1, 0, 1); PG8_SCHED; PG8_LDA(At, 0, 0); PG8_STAGE(PG8_SA(1, 1), a1 + hstep, voffA);
;             PG8_WAIT_V(8); PG8_WAIT_L(0); PG8_BAR; PG8_MMA(0, 0, At, B0); PG8_MMA(0, 1, At, B1); PG8_BAR; PG8_SCHED;
;             PG8_LDA(At, 0, 1); PG8_STAGE(PG8_SB(0, 0), b2, voffB); PG8_STAGE(PG8_SB(0, 1), b2 + hstep, voffB); PG8_STAGE(PG8_SA(0, 0), a2, voffA);
;             PG8_WAIT_V(8); PG8_WAIT_L(0); PG8_BAR; PG8_MMA(1, 0, At, B0); PG8_MMA(1, 1, At, B1); PG8_BAR; PG8_SCHED;
;             PG8_LDB(B0, 1, 0); PG8_LDB(B1, 1, 1); PG8_SCHED; PG8_LDA(At, 1, 0); PG8_STAGE(PG8_SA(0, 1), a2 + hstep, voffA);
;             PG8_WAIT_V(8); PG8_WAIT_L(0); PG8_BAR; PG8_MMA(0, 0, At, B0); PG8_MMA(0, 1, At, B1); PG8_BAR; PG8_SCHED;
;             PG8_LDA(At, 1, 1); PG8_STAGE(PG8_SB(1, 0), b3, voffB); PG8_STAGE(PG8_SB(1, 1), b3 + hstep, voffB); PG8_STAGE(PG8_SA(1, 0), a3, voffA);
;             PG8_WAIT_V(8); PG8_WAIT_L(0); PG8_BAR; PG8_MMA(1, 0, At, B0); PG8_MMA(1, 1, At, B1); PG8_BAR; PG8_SCHED;
;             } else {
;             PG8_LDB(B0, 0, 0); PG8_SCHED; PG8_LDA(At, 0, 0); PG8_STAGE(PG8_SA(1, 1), a1 + hstep, voffA);
;             PG8_WAIT_L(8); PG8_BAR; PG8_WAIT_L(0); PG8_MMA(0, 0, At, B0); PG8_BAR; PG8_SCHED;
;             PG8_LDB(B1, 0, 1); PG8_STAGE(PG8_SB(0, 0), b2, voffB);
;             PG8_BAR; PG8_WAIT_L(0); PG8_MMA(0, 1, At, B1); PG8_BAR;
;             PG8_LDA(At, 0, 1); PG8_STAGE(PG8_SA(0, 0), a2, voffA);
;             PG8_BAR; PG8_WAIT_L(0); PG8_MMA(1, 0, At, B0); PG8_BAR; PG8_SCHED;
;             PG8_STAGE(PG8_SB(0, 1), b2 + hstep, voffB);
;             PG8_WAIT_V(6); PG8_BAR; PG8_MMA(1, 1, At, B1); PG8_BAR;
;             PG8_LDB(B0, 1, 0); PG8_SCHED; PG8_LDA(At, 1, 0); PG8_STAGE(PG8_SA(0, 1), a2 + hstep, voffA);
;             PG8_WAIT_L(8); PG8_BAR; PG8_WAIT_L(0); PG8_MMA(0, 0, At, B0); PG8_BAR; PG8_SCHED;
;             PG8_LDB(B1, 1, 1); PG8_STAGE(PG8_SB(1, 0), b3, voffB);
;             PG8_BAR; PG8_WAIT_L(0); PG8_MMA(0, 1, At, B1); PG8_BAR;
;             PG8_LDA(At, 1, 1); PG8_STAGE(PG8_SA(1, 0), a3, voffA);
	v_mfma_f32_16x16x32_bf16 v[126:129], v[148:151], v[180:183], v[126:129]
	v_mfma_f32_16x16x32_bf16 v[122:125], v[156:159], v[180:183], v[122:125]
	v_mfma_f32_16x16x32_bf16 v[118:121], v[148:151], v[188:191], v[118:121]
	v_mfma_f32_16x16x32_bf16 v[110:113], v[156:159], v[188:191], v[110:113]
	v_mfma_f32_16x16x32_bf16 v[102:105], v[148:151], v[196:199], v[102:105]
	v_mfma_f32_16x16x32_bf16 v[94:97], v[156:159], v[196:199], v[94:97]
	v_mfma_f32_16x16x32_bf16 v[86:89], v[148:151], v[208:211], v[86:89]
	v_mfma_f32_16x16x32_bf16 v[78:81], v[156:159], v[208:211], v[78:81]
	v_mfma_f32_16x16x32_bf16 v[126:129], v[152:155], v[184:187], v[126:129]
	v_mfma_f32_16x16x32_bf16 v[122:125], v[160:163], v[184:187], v[122:125]
	v_mfma_f32_16x16x32_bf16 v[118:121], v[152:155], v[192:195], v[118:121]
	v_mfma_f32_16x16x32_bf16 v[110:113], v[160:163], v[192:195], v[110:113]
	v_mfma_f32_16x16x32_bf16 v[102:105], v[152:155], v[200:203], v[102:105]
	v_mfma_f32_16x16x32_bf16 v[94:97], v[160:163], v[200:203], v[94:97]
	v_mfma_f32_16x16x32_bf16 v[86:89], v[152:155], v[212:215], v[86:89]
	v_mfma_f32_16x16x32_bf16 v[78:81], v[160:163], v[212:215], v[78:81]
	v_mfma_f32_16x16x32_bf16 v[114:117], v[164:167], v[180:183], v[114:117]
	v_mfma_f32_16x16x32_bf16 v[106:109], v[172:175], v[180:183], v[106:109]
	v_mfma_f32_16x16x32_bf16 v[98:101], v[164:167], v[188:191], v[98:101]
	v_mfma_f32_16x16x32_bf16 v[90:93], v[172:175], v[188:191], v[90:93]
	v_mfma_f32_16x16x32_bf16 v[82:85], v[164:167], v[196:199], v[82:85]
	v_mfma_f32_16x16x32_bf16 v[74:77], v[172:175], v[196:199], v[74:77]
	v_mfma_f32_16x16x32_bf16 v[70:73], v[164:167], v[208:211], v[70:73]
	v_mfma_f32_16x16x32_bf16 v[66:69], v[172:175], v[208:211], v[66:69]
	v_mfma_f32_16x16x32_bf16 v[114:117], v[168:171], v[184:187], v[114:117]
	v_mfma_f32_16x16x32_bf16 v[106:109], v[176:179], v[184:187], v[106:109]
	v_mfma_f32_16x16x32_bf16 v[98:101], v[168:171], v[192:195], v[98:101]
	v_mfma_f32_16x16x32_bf16 v[90:93], v[176:179], v[192:195], v[90:93]
	v_mfma_f32_16x16x32_bf16 v[82:85], v[168:171], v[200:203], v[82:85]
	v_mfma_f32_16x16x32_bf16 v[74:77], v[176:179], v[200:203], v[74:77]
	v_mfma_f32_16x16x32_bf16 v[70:73], v[168:171], v[212:215], v[70:73]
	v_mfma_f32_16x16x32_bf16 v[66:69], v[176:179], v[212:215], v[66:69]
	s_barrier
	s_add_i32 s34, s54, s19
	s_mov_b32 m0, s34
	ds_read_b128 v[180:183], v147 offset:49152
	ds_read_b128 v[184:187], v147 offset:50176
	ds_read_b128 v[188:191], v147 offset:51200
	ds_read_b128 v[192:195], v147 offset:52224
	ds_read_b128 v[196:199], v147 offset:53248
	ds_read_b128 v[200:203], v147 offset:54272
	ds_read_b128 v[208:211], v147 offset:55296
	ds_read_b128 v[212:215], v147 offset:56320
	global_load_lds_dwordx4 v134, s[98:99]
	s_add_i32 m0, s34, 0x2000
	s_add_u32 s30, s30, 0x80080
	s_addc_u32 s31, s31, 0
	s_add_i32 s34, s55, s19
	global_load_lds_dwordx4 v130, s[98:99]
	s_mov_b32 m0, s34
	s_nop 0
	global_load_lds_dwordx4 v134, s[30:31]
	s_add_i32 m0, s34, 0x2000
	s_nop 0
	global_load_lds_dwordx4 v130, s[30:31]
	s_mov_b32 m0, s44
	s_nop 0
	global_load_lds_dwordx4 v136, s[100:101]
	s_waitcnt vmcnt(7)
	s_waitcnt lgkmcnt(0)
	s_barrier
	v_mfma_f32_16x16x32_bf16 v[62:65], v[148:151], v[180:183], v[62:65]
	v_mfma_f32_16x16x32_bf16 v[58:61], v[156:159], v[180:183], v[58:61]
	v_mfma_f32_16x16x32_bf16 v[54:57], v[148:151], v[188:191], v[54:57]
	v_mfma_f32_16x16x32_bf16 v[46:49], v[156:159], v[188:191], v[46:49]
	v_mfma_f32_16x16x32_bf16 v[38:41], v[148:151], v[196:199], v[38:41]
	v_mfma_f32_16x16x32_bf16 v[30:33], v[156:159], v[196:199], v[30:33]
	v_mfma_f32_16x16x32_bf16 v[22:25], v[148:151], v[208:211], v[22:25]
	v_mfma_f32_16x16x32_bf16 v[12:15], v[156:159], v[208:211], v[12:15]
	v_mfma_f32_16x16x32_bf16 v[62:65], v[152:155], v[184:187], v[62:65]
	v_mfma_f32_16x16x32_bf16 v[58:61], v[160:163], v[184:187], v[58:61]
	v_mfma_f32_16x16x32_bf16 v[54:57], v[152:155], v[192:195], v[54:57]
	v_mfma_f32_16x16x32_bf16 v[46:49], v[160:163], v[192:195], v[46:49]
	v_mfma_f32_16x16x32_bf16 v[38:41], v[152:155], v[200:203], v[38:41]
	v_mfma_f32_16x16x32_bf16 v[30:33], v[160:163], v[200:203], v[30:33]
	v_mfma_f32_16x16x32_bf16 v[22:25], v[152:155], v[212:215], v[22:25]
	v_mfma_f32_16x16x32_bf16 v[12:15], v[160:163], v[212:215], v[12:15]
	v_mfma_f32_16x16x32_bf16 v[50:53], v[164:167], v[180:183], v[50:53]
	v_mfma_f32_16x16x32_bf16 v[42:45], v[172:175], v[180:183], v[42:45]
	v_mfma_f32_16x16x32_bf16 v[34:37], v[164:167], v[188:191], v[34:37]
	v_mfma_f32_16x16x32_bf16 v[26:29], v[172:175], v[188:191], v[26:29]
	v_mfma_f32_16x16x32_bf16 v[16:19], v[164:167], v[196:199], v[16:19]
	v_mfma_f32_16x16x32_bf16 v[8:11], v[172:175], v[196:199], v[8:11]
	v_mfma_f32_16x16x32_bf16 v[4:7], v[164:167], v[208:211], v[4:7]
	v_mfma_f32_16x16x32_bf16 v[0:3], v[172:175], v[208:211], v[0:3]
	v_mfma_f32_16x16x32_bf16 v[50:53], v[168:171], v[184:187], v[50:53]
	v_mfma_f32_16x16x32_bf16 v[42:45], v[176:179], v[184:187], v[42:45]
	v_mfma_f32_16x16x32_bf16 v[34:37], v[168:171], v[192:195], v[34:37]
	v_mfma_f32_16x16x32_bf16 v[26:29], v[176:179], v[192:195], v[26:29]
	v_mfma_f32_16x16x32_bf16 v[16:19], v[168:171], v[200:203], v[16:19]
	v_mfma_f32_16x16x32_bf16 v[8:11], v[176:179], v[200:203], v[8:11]
	v_mfma_f32_16x16x32_bf16 v[4:7], v[168:171], v[212:215], v[4:7]
	v_mfma_f32_16x16x32_bf16 v[0:3], v[176:179], v[212:215], v[0:3]
	s_barrier
	s_add_i32 s53, s53, 2
	s_add_u32 s28, s28, 0x100
	s_addc_u32 s29, s29, 0
	s_add_u32 s51, s51, 0x100
	s_addc_u32 s52, s52, 0
	s_cmp_gt_u32 s53, 29
	s_cbranch_scc0 .LBB0_394
	s_setprio 0
	s_and_b64 vcc, exec, s[6:7]
	v_readlane_b32 s52, v255, 9
	v_readlane_b32 s53, v255, 10
	s_cbranch_vccz .LBB0_397
	s_barrier

; #define PG8_STAGE(bufoff, gbase, voff) do { _Pragma("unroll") for (int _i = 0; _i < 2; ++_i) \
;         __builtin_amdgcn_global_load_lds((const unsigned*)((const char*)(gbase) + (voff)[_i]), (PG8_LAS unsigned*)(lds + (bufoff) + ldsw + _i * 8192), 16, 0, 0); } while (0)
; #define PG8_LDA(dst, b, h) do { _Pragma("unroll") for (int m = 0; m < 4; ++m) _Pragma("unroll") for (int k = 0; k < 2; ++k) dst[m][k] = *(const PG8_LAS bf16x8*)(lds + PG8_SA(b, h) + aoff + m * 2048 + k * 1024); } while (0)
; #define PG8_LDB(dst, b, h) do { _Pragma("unroll") for (int n = 0; n < 2; ++n) _Pragma("unroll") for (int k = 0; k < 2; ++k) dst[n][k] = *(const PG8_LAS bf16x8*)(lds + PG8_SB(b, h) + boff + n * 2048 + k * 1024); } while (0)
; #define PG8_WAIT_V(n) asm volatile("s_waitcnt vmcnt(" #n ")" ::: "memory")
; #define PG8_WAIT_L(n) asm volatile("s_waitcnt lgkmcnt(" #n ")" ::: "memory")
; #define PG8_BAR __builtin_amdgcn_s_barrier()
; #define PG8_SCHED __builtin_amdgcn_sched_barrier(0)
; template <class Epi, class Sched, bool ALIGN_EPI = false, bool SP2 = false>
; __device__ __forceinline__ void gemm_phase(PG8_LAS unsigned char* lds, const Gemm g, const Sched& S, const Epi& E, const int tid_in) {
;     ...
;     for (;;) {
;         const bool has_next = S.next(ui + 1, nxt);
;         const char* nA = has_next ? (const char*)g.A + (size_t)nxt.pm * tstep : cA; const char* nB = has_next ? (const char*)g.Bt + (size_t)nxt.pn * tstep : cB;
;         for (int t = 0; t < nt; t += 2) {
;             if constexpr (Epi::KSPLIT > 0) { if (t == Epi::KSPLIT / BK) E.midk(acc, cur, wr, wc, fr, fq); }
;             const bool last = (t == nt - 2);
;             const char* a1 = cA + (size_t)(t + 1) * kstep;
;             const char* a2 = last ? nA : cA + (size_t)(t + 2) * kstep; const char* b2 = last ? nB : cB + (size_t)(t + 2) * kstep;
;             const char* a3 = a2 + kstep; const char* b3 = b2 + kstep;
;             if (last && has_next) S.a_ready(nxt);
;             if constexpr (SP2) {
;             PG8_LDB(B0, 0, 0); PG8_LDB(B1, 0, 1); PG8_SCHED; PG8_LDA(At, 0, 0); PG8_STAGE(PG8_SA(1, 1), a1 + hstep, voffA);
;             PG8_WAIT_V(8); PG8_WAIT_L(0); PG8_BAR; PG8_MMA(0, 0, At, B0); PG8_MMA(0, 1, At, B1); PG8_BAR; PG8_SCHED;
;             PG8_LDA(At, 0, 1); PG8_STAGE(PG8_SB(0, 0), b2, voffB); PG8_STAGE(PG8_SB(0, 1), b2 + hstep, voffB); PG8_STAGE(PG8_SA(0, 0), a2, voffA);
.LBB0_411:
	s_ashr_i32 s27, s26, 31
	s_lshl_b64 s[28:29], s[26:27], 20
	s_add_u32 s28, s1, s28
	s_addc_u32 s29, s5, s29
	s_and_b64 s[30:31], s[36:37], exec
	s_cselect_b32 s27, s29, s35
	s_cselect_b32 s54, s28, s34
	s_ashr_i32 s7, s6, 31
	s_lshl_b64 s[30:31], s[6:7], 20
	s_add_u32 s30, s8, s30
	s_addc_u32 s31, s10, s31
	s_and_b64 s[42:43], s[36:37], exec
	s_cselect_b32 s7, s31, s39
	s_cselect_b32 s55, s30, s38
	s_add_u32 s34, s34, 0x80080
	s_addc_u32 s35, s35, 0
	s_add_u32 s56, s38, 0x100
	v_mov_b32_e32 v0, 0
	s_addc_u32 s57, s39, 0
	s_mov_b32 s58, -2
	s_cmp_lt_u32 s19, 0x1000
	s_cbranch_scc1 .LPRIO_412
	s_setprio 1
.LPRIO_412:
	s_mov_b32 m0, s49
	s_nop 0
	global_load_lds_dwordx4 v150, s[100:101]
	s_add_u32 s38, s34, 0xfff80080
	s_addc_u32 s39, s35, -1
	s_add_i32 s59, 0, 0x10000
	s_cmp_eq_u32 s58, 28
	s_cselect_b32 s43, s27, s39
	s_cselect_b32 s42, s54, s38
	s_cselect_b32 s39, s7, s57
	s_cselect_b32 s38, s55, s56
	s_add_i32 s62, 0, 0x14000
	v_add_u32_e32 v78, s59, v162
	v_add_u32_e32 v160, s62, v162
	ds_read_b128 v[66:69], v78
	ds_read_b128 v[70:73], v78 offset:1024
	ds_read_b128 v[74:77], v78 offset:2048
	ds_read_b128 v[78:81], v78 offset:3072
	ds_read_b128 v[166:169], v160
	ds_read_b128 v[170:173], v160 offset:1024
	ds_read_b128 v[174:177], v160 offset:2048
	ds_read_b128 v[178:181], v160 offset:3072
	s_add_i32 m0, s44, 0xc000
	ds_read_b128 v[182:185], v165
	ds_read_b128 v[186:189], v165 offset:1024
	ds_read_b128 v[190:193], v165 offset:2048
	ds_read_b128 v[194:197], v165 offset:3072
	ds_read_b128 v[198:201], v165 offset:4096
	ds_read_b128 v[202:205], v165 offset:5120
	ds_read_b128 v[208:211], v165 offset:6144
	ds_read_b128 v[212:215], v165 offset:7168
	global_load_lds_dwordx4 v156, s[34:35]
	s_add_i32 m0, s44, 0xe000
	s_nop 0
	global_load_lds_dwordx4 v158, s[34:35]
	s_waitcnt vmcnt(8)
	s_waitcnt lgkmcnt(0)
	s_barrier
	v_mfma_f32_16x16x32_bf16 v[142:145], v[66:69], v[182:185], 0
	v_mfma_f32_16x16x32_bf16 v[138:141], v[74:77], v[182:185], 0
	v_mfma_f32_16x16x32_bf16 v[126:129], v[66:69], v[190:193], 0
	v_mfma_f32_16x16x32_bf16 v[122:125], v[74:77], v[190:193], 0
	v_mfma_f32_16x16x32_bf16 v[110:113], v[66:69], v[198:201], 0
	v_mfma_f32_16x16x32_bf16 v[106:109], v[74:77], v[198:201], 0
	v_mfma_f32_16x16x32_bf16 v[94:97], v[66:69], v[208:211], 0
	v_mfma_f32_16x16x32_bf16 v[90:93], v[74:77], v[208:211], 0
	v_mfma_f32_16x16x32_bf16 v[142:145], v[70:73], v[186:189], v[142:145]
	v_mfma_f32_16x16x32_bf16 v[138:141], v[78:81], v[186:189], v[138:141]
	v_mfma_f32_16x16x32_bf16 v[126:129], v[70:73], v[194:197], v[126:129]
	v_mfma_f32_16x16x32_bf16 v[122:125], v[78:81], v[194:197], v[122:125]
	v_mfma_f32_16x16x32_bf16 v[110:113], v[70:73], v[202:205], v[110:113]
	v_mfma_f32_16x16x32_bf16 v[106:109], v[78:81], v[202:205], v[106:109]
	v_mfma_f32_16x16x32_bf16 v[94:97], v[70:73], v[212:215], v[94:97]
	v_mfma_f32_16x16x32_bf16 v[90:93], v[78:81], v[212:215], v[90:93]
	v_mfma_f32_16x16x32_bf16 v[134:137], v[166:169], v[182:185], 0
	v_mfma_f32_16x16x32_bf16 v[130:133], v[174:177], v[182:185], 0
	v_mfma_f32_16x16x32_bf16 v[118:121], v[166:169], v[190:193], 0
	v_mfma_f32_16x16x32_bf16 v[114:117], v[174:177], v[190:193], 0
	v_mfma_f32_16x16x32_bf16 v[102:105], v[166:169], v[198:201], 0
	v_mfma_f32_16x16x32_bf16 v[98:101], v[174:177], v[198:201], 0
	v_mfma_f32_16x16x32_bf16 v[86:89], v[166:169], v[208:211], 0
	v_mfma_f32_16x16x32_bf16 v[82:85], v[174:177], v[208:211], 0
	v_mfma_f32_16x16x32_bf16 v[134:137], v[170:173], v[186:189], v[134:137]
	v_mfma_f32_16x16x32_bf16 v[130:133], v[178:181], v[186:189], v[130:133]
	v_mfma_f32_16x16x32_bf16 v[118:121], v[170:173], v[194:197], v[118:121]
	v_mfma_f32_16x16x32_bf16 v[114:117], v[178:181], v[194:197], v[114:117]
	v_mfma_f32_16x16x32_bf16 v[102:105], v[170:173], v[202:205], v[102:105]
	v_mfma_f32_16x16x32_bf16 v[98:101], v[178:181], v[202:205], v[98:101]
	v_mfma_f32_16x16x32_bf16 v[86:89], v[170:173], v[212:215], v[86:89]
	v_mfma_f32_16x16x32_bf16 v[82:85], v[178:181], v[212:215], v[82:85]
	s_barrier
	s_add_i32 s59, s59, s19
	s_add_u32 s98, s38, 0x80
	s_addc_u32 s99, s39, 0
	s_mov_b32 m0, s59
	ds_read_b128 v[182:185], v165 offset:16384
	ds_read_b128 v[186:189], v165 offset:17408
	ds_read_b128 v[190:193], v165 offset:18432
	ds_read_b128 v[194:197], v165 offset:19456
	ds_read_b128 v[198:201], v165 offset:20480
	ds_read_b128 v[202:205], v165 offset:21504
	ds_read_b128 v[208:211], v165 offset:22528
	ds_read_b128 v[212:215], v165 offset:23552
	global_load_lds_dwordx4 v148, s[38:39]
	s_add_i32 m0, s59, 0x2000
	s_add_u32 s60, s38, 0x80000
	s_addc_u32 s61, s39, 0
	s_add_i32 s59, s62, s19
	global_load_lds_dwordx4 v152, s[38:39]
	s_mov_b32 m0, s59
	s_add_u32 s100, s42, 0x80
	s_addc_u32 s101, s43, 0
	global_load_lds_dwordx4 v148, s[60:61]
	s_add_i32 m0, s59, 0x2000
	s_nop 0
	global_load_lds_dwordx4 v152, s[60:61]
	s_mov_b32 m0, s44
	s_nop 0
	global_load_lds_dwordx4 v146, s[42:43]
	s_waitcnt vmcnt(7)
	s_waitcnt lgkmcnt(0)
	s_barrier
; #define PG8_STAGE(bufoff, gbase, voff) do { _Pragma("unroll") for (int _i = 0; _i < 2; ++_i) \
;         __builtin_amdgcn_global_load_lds((const unsigned*)((const char*)(gbase) + (voff)[_i]), (PG8_LAS unsigned*)(lds + (bufoff) + ldsw + _i * 8192), 16, 0, 0); } while (0)
; #define PG8_LDA(dst, b, h) do { _Pragma("unroll") for (int m = 0; m < 4; ++m) _Pragma("unroll") for (int k = 0; k < 2; ++k) dst[m][k] = *(const PG8_LAS bf16x8*)(lds + PG8_SA(b, h) + aoff + m * 2048 + k * 1024); } while (0)
; #define PG8_LDB(dst, b, h) do { _Pragma("unroll") for (int n = 0; n < 2; ++n) _Pragma("unroll") for (int k = 0; k < 2; ++k) dst[n][k] = *(const PG8_LAS bf16x8*)(lds + PG8_SB(b, h) + boff + n * 2048 + k * 1024); } while (0)
; #define PG8_MMA(ai, bj, At, Bt) do { __builtin_amdgcn_s_setprio(1); _Pragma("unroll") for (int m = 0; m < 4; ++m) _Pragma("unroll") for (int n = 0; n < 2; ++n) _Pragma("unroll") for (int k = 0; k < 2; ++k) \
;         acc[ai][bj][m][n] = __builtin_amdgcn_mfma_f32_16x16x32_bf16(Bt[n][k], At[m][k], acc[ai][bj][m][n], 0, 0, 0); __builtin_amdgcn_s_setprio(0); } while (0)
; template <class Epi, class Sched, bool ALIGN_EPI = false, bool SP2 = false>
; __device__ __forceinline__ void gemm_phase(PG8_LAS unsigned char* lds, const Gemm g, const Sched& S, const Epi& E, const int tid_in) {
;     ...
;             if constexpr (SP2) {
;             PG8_LDB(B0, 0, 0); PG8_LDB(B1, 0, 1); PG8_SCHED; PG8_LDA(At, 0, 0); PG8_STAGE(PG8_SA(1, 1), a1 + hstep, voffA);
;             PG8_WAIT_V(8); PG8_WAIT_L(0); PG8_BAR; PG8_MMA(0, 0, At, B0); PG8_MMA(0, 1, At, B1); PG8_BAR; PG8_SCHED;
;             PG8_LDA(At, 0, 1); PG8_STAGE(PG8_SB(0, 0), b2, voffB); PG8_STAGE(PG8_SB(0, 1), b2 + hstep, voffB); PG8_STAGE(PG8_SA(0, 0), a2, voffA);
;             PG8_WAIT_V(8); PG8_WAIT_L(0); PG8_BAR; PG8_MMA(1, 0, At, B0); PG8_MMA(1, 1, At, B1); PG8_BAR; PG8_SCHED;
;             PG8_LDB(B0, 1, 0); PG8_LDB(B1, 1, 1); PG8_SCHED; PG8_LDA(At, 1, 0); PG8_STAGE(PG8_SA(0, 1), a2 + hstep, voffA);
;             PG8_WAIT_V(8); PG8_WAIT_L(0); PG8_BAR; PG8_MMA(0, 0, At, B0); PG8_MMA(0, 1, At, B1); PG8_BAR; PG8_SCHED;
;             PG8_LDA(At, 1, 1); PG8_STAGE(PG8_SB(1, 0), b3, voffB); PG8_STAGE(PG8_SB(1, 1), b3 + hstep, voffB); PG8_STAGE(PG8_SA(1, 0), a3, voffA);
;             PG8_WAIT_V(8); PG8_WAIT_L(0); PG8_BAR; PG8_MMA(1, 0, At, B0); PG8_MMA(1, 1, At, B1); PG8_BAR; PG8_SCHED;
	v_mfma_f32_16x16x32_bf16 v[62:65], v[66:69], v[182:185], 0
	v_mfma_f32_16x16x32_bf16 v[58:61], v[74:77], v[182:185], 0
	v_mfma_f32_16x16x32_bf16 v[46:49], v[66:69], v[190:193], 0
	v_mfma_f32_16x16x32_bf16 v[42:45], v[74:77], v[190:193], 0
	v_mfma_f32_16x16x32_bf16 v[30:33], v[66:69], v[198:201], 0
	v_mfma_f32_16x16x32_bf16 v[26:29], v[74:77], v[198:201], 0
	v_mfma_f32_16x16x32_bf16 v[12:15], v[66:69], v[208:211], 0
	v_mfma_f32_16x16x32_bf16 v[8:11], v[74:77], v[208:211], 0
	v_mfma_f32_16x16x32_bf16 v[62:65], v[70:73], v[186:189], v[62:65]
	v_mfma_f32_16x16x32_bf16 v[58:61], v[78:81], v[186:189], v[58:61]
	v_mfma_f32_16x16x32_bf16 v[46:49], v[70:73], v[194:197], v[46:49]
	v_mfma_f32_16x16x32_bf16 v[42:45], v[78:81], v[194:197], v[42:45]
	v_mfma_f32_16x16x32_bf16 v[30:33], v[70:73], v[202:205], v[30:33]
	v_mfma_f32_16x16x32_bf16 v[26:29], v[78:81], v[202:205], v[26:29]
	v_mfma_f32_16x16x32_bf16 v[12:15], v[70:73], v[212:215], v[12:15]
	v_mfma_f32_16x16x32_bf16 v[8:11], v[78:81], v[212:215], v[8:11]
	v_mfma_f32_16x16x32_bf16 v[54:57], v[166:169], v[182:185], 0
	v_mfma_f32_16x16x32_bf16 v[50:53], v[174:177], v[182:185], 0
	v_mfma_f32_16x16x32_bf16 v[38:41], v[166:169], v[190:193], 0
	v_mfma_f32_16x16x32_bf16 v[34:37], v[174:177], v[190:193], 0
	v_mfma_f32_16x16x32_bf16 v[22:25], v[166:169], v[198:201], 0
	v_mfma_f32_16x16x32_bf16 v[16:19], v[174:177], v[198:201], 0
	v_mfma_f32_16x16x32_bf16 v[4:7], v[166:169], v[208:211], 0
	v_mfma_f32_16x16x32_bf16 v[0:3], v[174:177], v[208:211], 0
	v_mfma_f32_16x16x32_bf16 v[54:57], v[170:173], v[186:189], v[54:57]
	v_mfma_f32_16x16x32_bf16 v[50:53], v[178:181], v[186:189], v[50:53]
	v_mfma_f32_16x16x32_bf16 v[38:41], v[170:173], v[194:197], v[38:41]
	v_mfma_f32_16x16x32_bf16 v[34:37], v[178:181], v[194:197], v[34:37]
	v_mfma_f32_16x16x32_bf16 v[22:25], v[170:173], v[202:205], v[22:25]
	v_mfma_f32_16x16x32_bf16 v[16:19], v[178:181], v[202:205], v[16:19]
	v_mfma_f32_16x16x32_bf16 v[4:7], v[170:173], v[212:215], v[4:7]
	v_mfma_f32_16x16x32_bf16 v[0:3], v[178:181], v[212:215], v[0:3]
	s_barrier
	s_add_i32 s59, 0, 0x18000
	s_add_i32 s60, 0, 0x1c000
	v_add_u32_e32 v78, s59, v162
	v_add_u32_e32 v178, s60, v162
	ds_read_b128 v[66:69], v78
	ds_read_b128 v[70:73], v78 offset:1024
	ds_read_b128 v[74:77], v78 offset:2048
	ds_read_b128 v[78:81], v78 offset:3072
	ds_read_b128 v[166:169], v178
	ds_read_b128 v[170:173], v178 offset:1024
	ds_read_b128 v[174:177], v178 offset:2048
	ds_read_b128 v[178:181], v178 offset:3072
	s_mov_b32 m0, s45
	s_nop 0
	global_load_lds_dwordx4 v150, s[42:43]
	s_add_u32 s42, s42, 0x80000
	s_addc_u32 s43, s43, 0
	s_mov_b32 m0, s46
	ds_read_b128 v[182:185], v165 offset:32768
	ds_read_b128 v[186:189], v165 offset:33792
	ds_read_b128 v[190:193], v165 offset:34816
	ds_read_b128 v[194:197], v165 offset:35840
	ds_read_b128 v[198:201], v165 offset:36864
	ds_read_b128 v[202:205], v165 offset:37888
	ds_read_b128 v[208:211], v165 offset:38912
	ds_read_b128 v[212:215], v165 offset:39936
	global_load_lds_dwordx4 v146, s[42:43]
	s_mov_b32 m0, s47
	s_nop 0
	global_load_lds_dwordx4 v150, s[42:43]
	s_waitcnt vmcnt(8)
	s_waitcnt lgkmcnt(0)
	s_barrier
	v_mfma_f32_16x16x32_bf16 v[142:145], v[66:69], v[182:185], v[142:145]
	v_mfma_f32_16x16x32_bf16 v[138:141], v[74:77], v[182:185], v[138:141]
	v_mfma_f32_16x16x32_bf16 v[126:129], v[66:69], v[190:193], v[126:129]
	v_mfma_f32_16x16x32_bf16 v[122:125], v[74:77], v[190:193], v[122:125]
	v_mfma_f32_16x16x32_bf16 v[110:113], v[66:69], v[198:201], v[110:113]
	v_mfma_f32_16x16x32_bf16 v[106:109], v[74:77], v[198:201], v[106:109]
	v_mfma_f32_16x16x32_bf16 v[94:97], v[66:69], v[208:211], v[94:97]
	v_mfma_f32_16x16x32_bf16 v[90:93], v[74:77], v[208:211], v[90:93]
	v_mfma_f32_16x16x32_bf16 v[142:145], v[70:73], v[186:189], v[142:145]
	v_mfma_f32_16x16x32_bf16 v[138:141], v[78:81], v[186:189], v[138:141]
	v_mfma_f32_16x16x32_bf16 v[126:129], v[70:73], v[194:197], v[126:129]
	v_mfma_f32_16x16x32_bf16 v[122:125], v[78:81], v[194:197], v[122:125]
	v_mfma_f32_16x16x32_bf16 v[110:113], v[70:73], v[202:205], v[110:113]
	v_mfma_f32_16x16x32_bf16 v[106:109], v[78:81], v[202:205], v[106:109]
	v_mfma_f32_16x16x32_bf16 v[94:97], v[70:73], v[212:215], v[94:97]
	v_mfma_f32_16x16x32_bf16 v[90:93], v[78:81], v[212:215], v[90:93]
	v_mfma_f32_16x16x32_bf16 v[134:137], v[166:169], v[182:185], v[134:137]
	v_mfma_f32_16x16x32_bf16 v[130:133], v[174:177], v[182:185], v[130:133]
	v_mfma_f32_16x16x32_bf16 v[118:121], v[166:169], v[190:193], v[118:121]
	v_mfma_f32_16x16x32_bf16 v[114:117], v[174:177], v[190:193], v[114:117]
	v_mfma_f32_16x16x32_bf16 v[102:105], v[166:169], v[198:201], v[102:105]
	v_mfma_f32_16x16x32_bf16 v[98:101], v[174:177], v[198:201], v[98:101]
	v_mfma_f32_16x16x32_bf16 v[86:89], v[166:169], v[208:211], v[86:89]
	v_mfma_f32_16x16x32_bf16 v[82:85], v[174:177], v[208:211], v[82:85]
	v_mfma_f32_16x16x32_bf16 v[134:137], v[170:173], v[186:189], v[134:137]
	v_mfma_f32_16x16x32_bf16 v[130:133], v[178:181], v[186:189], v[130:133]
	v_mfma_f32_16x16x32_bf16 v[118:121], v[170:173], v[194:197], v[118:121]
	v_mfma_f32_16x16x32_bf16 v[114:117], v[178:181], v[194:197], v[114:117]
	v_mfma_f32_16x16x32_bf16 v[102:105], v[170:173], v[202:205], v[102:105]
	v_mfma_f32_16x16x32_bf16 v[98:101], v[178:181], v[202:205], v[98:101]
	v_mfma_f32_16x16x32_bf16 v[86:89], v[170:173], v[212:215], v[86:89]
	v_mfma_f32_16x16x32_bf16 v[82:85], v[178:181], v[212:215], v[82:85]
	s_barrier
; #define PG8_STAGE(bufoff, gbase, voff) do { _Pragma("unroll") for (int _i = 0; _i < 2; ++_i) \
;         __builtin_amdgcn_global_load_lds((const unsigned*)((const char*)(gbase) + (voff)[_i]), (PG8_LAS unsigned*)(lds + (bufoff) + ldsw + _i * 8192), 16, 0, 0); } while (0)
; #define PG8_LDA(dst, b, h) do { _Pragma("unroll") for (int m = 0; m < 4; ++m) _Pragma("unroll") for (int k = 0; k < 2; ++k) dst[m][k] = *(const PG8_LAS bf16x8*)(lds + PG8_SA(b, h) + aoff + m * 2048 + k * 1024); } while (0)
; #define PG8_LDB(dst, b, h) do { _Pragma("unroll") for (int n = 0; n < 2; ++n) _Pragma("unroll") for (int k = 0; k < 2; ++k) dst[n][k] = *(const PG8_LAS bf16x8*)(lds + PG8_SB(b, h) + boff + n * 2048 + k * 1024); } while (0)
; #define PG8_MMA(ai, bj, At, Bt) do { __builtin_amdgcn_s_setprio(1); _Pragma("unroll") for (int m = 0; m < 4; ++m) _Pragma("unroll") for (int n = 0; n < 2; ++n) _Pragma("unroll") for (int k = 0; k < 2; ++k) \
;         acc[ai][bj][m][n] = __builtin_amdgcn_mfma_f32_16x16x32_bf16(Bt[n][k], At[m][k], acc[ai][bj][m][n], 0, 0, 0); __builtin_amdgcn_s_setprio(0); } while (0)
; template <class Epi, class Sched, bool ALIGN_EPI = false, bool SP2 = false>
; __device__ __forceinline__ void gemm_phase(PG8_LAS unsigned char* lds, const Gemm g, const Sched& S, const Epi& E, const int tid_in) {
;     ...
;             if constexpr (SP2) {
;             PG8_LDB(B0, 0, 0); PG8_LDB(B1, 0, 1); PG8_SCHED; PG8_LDA(At, 0, 0); PG8_STAGE(PG8_SA(1, 1), a1 + hstep, voffA);
;             PG8_WAIT_V(8); PG8_WAIT_L(0); PG8_BAR; PG8_MMA(0, 0, At, B0); PG8_MMA(0, 1, At, B1); PG8_BAR; PG8_SCHED;
;             PG8_LDA(At, 0, 1); PG8_STAGE(PG8_SB(0, 0), b2, voffB); PG8_STAGE(PG8_SB(0, 1), b2 + hstep, voffB); PG8_STAGE(PG8_SA(0, 0), a2, voffA);
;             PG8_WAIT_V(8); PG8_WAIT_L(0); PG8_BAR; PG8_MMA(1, 0, At, B0); PG8_MMA(1, 1, At, B1); PG8_BAR; PG8_SCHED;
;             PG8_LDB(B0, 1, 0); PG8_LDB(B1, 1, 1); PG8_SCHED; PG8_LDA(At, 1, 0); PG8_STAGE(PG8_SA(0, 1), a2 + hstep, voffA);
;             PG8_WAIT_V(8); PG8_WAIT_L(0); PG8_BAR; PG8_MMA(0, 0, At, B0); PG8_MMA(0, 1, At, B1); PG8_BAR; PG8_SCHED;
;             PG8_LDA(At, 1, 1); PG8_STAGE(PG8_SB(1, 0), b3, voffB); PG8_STAGE(PG8_SB(1, 1), b3 + hstep, voffB); PG8_STAGE(PG8_SA(1, 0), a3, voffA);
;             PG8_WAIT_V(8); PG8_WAIT_L(0); PG8_BAR; PG8_MMA(1, 0, At, B0); PG8_MMA(1, 1, At, B1); PG8_BAR; PG8_SCHED;
	s_add_i32 s42, s59, s19
	s_mov_b32 m0, s42
	ds_read_b128 v[182:185], v165 offset:49152
	ds_read_b128 v[186:189], v165 offset:50176
	ds_read_b128 v[190:193], v165 offset:51200
	ds_read_b128 v[194:197], v165 offset:52224
	ds_read_b128 v[198:201], v165 offset:53248
	ds_read_b128 v[202:205], v165 offset:54272
	ds_read_b128 v[208:211], v165 offset:55296
	ds_read_b128 v[212:215], v165 offset:56320
	global_load_lds_dwordx4 v148, s[98:99]
	s_add_i32 m0, s42, 0x2000
	s_add_u32 s38, s38, 0x80080
	s_addc_u32 s39, s39, 0
	s_add_i32 s42, s60, s19
	global_load_lds_dwordx4 v152, s[98:99]
	s_mov_b32 m0, s42
	s_nop 0
	global_load_lds_dwordx4 v148, s[38:39]
	s_add_i32 m0, s42, 0x2000
	s_nop 0
	global_load_lds_dwordx4 v152, s[38:39]
	s_mov_b32 m0, s48
	s_nop 0
	global_load_lds_dwordx4 v146, s[100:101]
	s_waitcnt vmcnt(7)
	s_waitcnt lgkmcnt(0)
	s_barrier
	v_mfma_f32_16x16x32_bf16 v[62:65], v[66:69], v[182:185], v[62:65]
	v_mfma_f32_16x16x32_bf16 v[58:61], v[74:77], v[182:185], v[58:61]
	v_mfma_f32_16x16x32_bf16 v[46:49], v[66:69], v[190:193], v[46:49]
	v_mfma_f32_16x16x32_bf16 v[42:45], v[74:77], v[190:193], v[42:45]
	v_mfma_f32_16x16x32_bf16 v[30:33], v[66:69], v[198:201], v[30:33]
	v_mfma_f32_16x16x32_bf16 v[26:29], v[74:77], v[198:201], v[26:29]
	v_mfma_f32_16x16x32_bf16 v[12:15], v[66:69], v[208:211], v[12:15]
	v_mfma_f32_16x16x32_bf16 v[8:11], v[74:77], v[208:211], v[8:11]
	v_mfma_f32_16x16x32_bf16 v[62:65], v[70:73], v[186:189], v[62:65]
	v_mfma_f32_16x16x32_bf16 v[58:61], v[78:81], v[186:189], v[58:61]
	v_mfma_f32_16x16x32_bf16 v[46:49], v[70:73], v[194:197], v[46:49]
	v_mfma_f32_16x16x32_bf16 v[42:45], v[78:81], v[194:197], v[42:45]
	v_mfma_f32_16x16x32_bf16 v[30:33], v[70:73], v[202:205], v[30:33]
	v_mfma_f32_16x16x32_bf16 v[26:29], v[78:81], v[202:205], v[26:29]
	v_mfma_f32_16x16x32_bf16 v[12:15], v[70:73], v[212:215], v[12:15]
	v_mfma_f32_16x16x32_bf16 v[8:11], v[78:81], v[212:215], v[8:11]
	v_mfma_f32_16x16x32_bf16 v[54:57], v[166:169], v[182:185], v[54:57]
	v_mfma_f32_16x16x32_bf16 v[50:53], v[174:177], v[182:185], v[50:53]
	v_mfma_f32_16x16x32_bf16 v[38:41], v[166:169], v[190:193], v[38:41]
	v_mfma_f32_16x16x32_bf16 v[34:37], v[174:177], v[190:193], v[34:37]
	v_mfma_f32_16x16x32_bf16 v[22:25], v[166:169], v[198:201], v[22:25]
	v_mfma_f32_16x16x32_bf16 v[16:19], v[174:177], v[198:201], v[16:19]
	v_mfma_f32_16x16x32_bf16 v[4:7], v[166:169], v[208:211], v[4:7]
	v_mfma_f32_16x16x32_bf16 v[0:3], v[174:177], v[208:211], v[0:3]
	v_mfma_f32_16x16x32_bf16 v[54:57], v[170:173], v[186:189], v[54:57]
	v_mfma_f32_16x16x32_bf16 v[50:53], v[178:181], v[186:189], v[50:53]
	v_mfma_f32_16x16x32_bf16 v[38:41], v[170:173], v[194:197], v[38:41]
	v_mfma_f32_16x16x32_bf16 v[34:37], v[178:181], v[194:197], v[34:37]
	v_mfma_f32_16x16x32_bf16 v[22:25], v[170:173], v[202:205], v[22:25]
	v_mfma_f32_16x16x32_bf16 v[16:19], v[178:181], v[202:205], v[16:19]
	v_mfma_f32_16x16x32_bf16 v[4:7], v[170:173], v[212:215], v[4:7]
	v_mfma_f32_16x16x32_bf16 v[0:3], v[178:181], v[212:215], v[0:3]
	s_barrier
	s_add_i32 s58, s58, 2
	s_add_u32 s34, s34, 0x100
	s_addc_u32 s35, s35, 0
	s_add_u32 s56, s56, 0x100
	s_addc_u32 s57, s57, 0
	s_cmp_gt_u32 s58, 29
.LBB0_412:
	s_mov_b32 m0, s49
	s_nop 0
	global_load_lds_dwordx4 v150, s[100:101]
	s_add_u32 s38, s34, 0xfff80080
	s_addc_u32 s39, s35, -1
	s_add_i32 s59, 0, 0x10000
	s_cmp_eq_u32 s58, 28
	s_cselect_b32 s43, s27, s39
	s_cselect_b32 s42, s54, s38
	s_cselect_b32 s39, s7, s57
	s_cselect_b32 s38, s55, s56
	s_add_i32 s62, 0, 0x14000
	v_add_u32_e32 v78, s59, v162
	v_add_u32_e32 v160, s62, v162
	ds_read_b128 v[66:69], v78
	ds_read_b128 v[70:73], v78 offset:1024
	ds_read_b128 v[74:77], v78 offset:2048
	ds_read_b128 v[78:81], v78 offset:3072
	ds_read_b128 v[166:169], v160
	ds_read_b128 v[170:173], v160 offset:1024
	ds_read_b128 v[174:177], v160 offset:2048
	ds_read_b128 v[178:181], v160 offset:3072
	s_add_i32 m0, s44, 0xc000
	ds_read_b128 v[182:185], v165
	ds_read_b128 v[186:189], v165 offset:1024
	ds_read_b128 v[190:193], v165 offset:2048
	ds_read_b128 v[194:197], v165 offset:3072
	ds_read_b128 v[198:201], v165 offset:4096
	ds_read_b128 v[202:205], v165 offset:5120
	ds_read_b128 v[208:211], v165 offset:6144
	ds_read_b128 v[212:215], v165 offset:7168
	global_load_lds_dwordx4 v156, s[34:35]
	s_add_i32 m0, s44, 0xe000
	s_nop 0
	global_load_lds_dwordx4 v158, s[34:35]
	s_waitcnt vmcnt(8)
	s_waitcnt lgkmcnt(0)
	s_barrier
	v_mfma_f32_16x16x32_bf16 v[142:145], v[66:69], v[182:185], v[142:145]
	v_mfma_f32_16x16x32_bf16 v[138:141], v[74:77], v[182:185], v[138:141]
	v_mfma_f32_16x16x32_bf16 v[126:129], v[66:69], v[190:193], v[126:129]
	v_mfma_f32_16x16x32_bf16 v[122:125], v[74:77], v[190:193], v[122:125]
	v_mfma_f32_16x16x32_bf16 v[110:113], v[66:69], v[198:201], v[110:113]
	v_mfma_f32_16x16x32_bf16 v[106:109], v[74:77], v[198:201], v[106:109]
	v_mfma_f32_16x16x32_bf16 v[94:97], v[66:69], v[208:211], v[94:97]
	v_mfma_f32_16x16x32_bf16 v[90:93], v[74:77], v[208:211], v[90:93]
	v_mfma_f32_16x16x32_bf16 v[142:145], v[70:73], v[186:189], v[142:145]
	v_mfma_f32_16x16x32_bf16 v[138:141], v[78:81], v[186:189], v[138:141]
	v_mfma_f32_16x16x32_bf16 v[126:129], v[70:73], v[194:197], v[126:129]
	v_mfma_f32_16x16x32_bf16 v[122:125], v[78:81], v[194:197], v[122:125]
	v_mfma_f32_16x16x32_bf16 v[110:113], v[70:73], v[202:205], v[110:113]
	v_mfma_f32_16x16x32_bf16 v[106:109], v[78:81], v[202:205], v[106:109]
	v_mfma_f32_16x16x32_bf16 v[94:97], v[70:73], v[212:215], v[94:97]
	v_mfma_f32_16x16x32_bf16 v[90:93], v[78:81], v[212:215], v[90:93]
	v_mfma_f32_16x16x32_bf16 v[134:137], v[166:169], v[182:185], v[134:137]
	v_mfma_f32_16x16x32_bf16 v[130:133], v[174:177], v[182:185], v[130:133]
	v_mfma_f32_16x16x32_bf16 v[118:121], v[166:169], v[190:193], v[118:121]
	v_mfma_f32_16x16x32_bf16 v[114:117], v[174:177], v[190:193], v[114:117]
	v_mfma_f32_16x16x32_bf16 v[102:105], v[166:169], v[198:201], v[102:105]
	v_mfma_f32_16x16x32_bf16 v[98:101], v[174:177], v[198:201], v[98:101]
	v_mfma_f32_16x16x32_bf16 v[86:89], v[166:169], v[208:211], v[86:89]
	v_mfma_f32_16x16x32_bf16 v[82:85], v[174:177], v[208:211], v[82:85]
	v_mfma_f32_16x16x32_bf16 v[134:137], v[170:173], v[186:189], v[134:137]
	v_mfma_f32_16x16x32_bf16 v[130:133], v[178:181], v[186:189], v[130:133]
	v_mfma_f32_16x16x32_bf16 v[118:121], v[170:173], v[194:197], v[118:121]
	v_mfma_f32_16x16x32_bf16 v[114:117], v[178:181], v[194:197], v[114:117]
	v_mfma_f32_16x16x32_bf16 v[102:105], v[170:173], v[202:205], v[102:105]
	v_mfma_f32_16x16x32_bf16 v[98:101], v[178:181], v[202:205], v[98:101]
	v_mfma_f32_16x16x32_bf16 v[86:89], v[170:173], v[212:215], v[86:89]
	v_mfma_f32_16x16x32_bf16 v[82:85], v[178:181], v[212:215], v[82:85]
	s_barrier
; #define PG8_STAGE(bufoff, gbase, voff) do { _Pragma("unroll") for (int _i = 0; _i < 2; ++_i) \
;         __builtin_amdgcn_global_load_lds((const unsigned*)((const char*)(gbase) + (voff)[_i]), (PG8_LAS unsigned*)(lds + (bufoff) + ldsw + _i * 8192), 16, 0, 0); } while (0)
; #define PG8_LDA(dst, b, h) do { _Pragma("unroll") for (int m = 0; m < 4; ++m) _Pragma("unroll") for (int k = 0; k < 2; ++k) dst[m][k] = *(const PG8_LAS bf16x8*)(lds + PG8_SA(b, h) + aoff + m * 2048 + k * 1024); } while (0)
; #define PG8_LDB(dst, b, h) do { _Pragma("unroll") for (int n = 0; n < 2; ++n) _Pragma("unroll") for (int k = 0; k < 2; ++k) dst[n][k] = *(const PG8_LAS bf16x8*)(lds + PG8_SB(b, h) + boff + n * 2048 + k * 1024); } while (0)
; #define PG8_MMA(ai, bj, At, Bt) do { __builtin_amdgcn_s_setprio(1); _Pragma("unroll") for (int m = 0; m < 4; ++m) _Pragma("unroll") for (int n = 0; n < 2; ++n) _Pragma("unroll") for (int k = 0; k < 2; ++k) \
;         acc[ai][bj][m][n] = __builtin_amdgcn_mfma_f32_16x16x32_bf16(Bt[n][k], At[m][k], acc[ai][bj][m][n], 0, 0, 0); __builtin_amdgcn_s_setprio(0); } while (0)
; template <class Epi, class Sched, bool ALIGN_EPI = false, bool SP2 = false>
; __device__ __forceinline__ void gemm_phase(PG8_LAS unsigned char* lds, const Gemm g, const Sched& S, const Epi& E, const int tid_in) {
;     ...
;             if constexpr (SP2) {
;             PG8_LDB(B0, 0, 0); PG8_LDB(B1, 0, 1); PG8_SCHED; PG8_LDA(At, 0, 0); PG8_STAGE(PG8_SA(1, 1), a1 + hstep, voffA);
;             PG8_WAIT_V(8); PG8_WAIT_L(0); PG8_BAR; PG8_MMA(0, 0, At, B0); PG8_MMA(0, 1, At, B1); PG8_BAR; PG8_SCHED;
;             PG8_LDA(At, 0, 1); PG8_STAGE(PG8_SB(0, 0), b2, voffB); PG8_STAGE(PG8_SB(0, 1), b2 + hstep, voffB); PG8_STAGE(PG8_SA(0, 0), a2, voffA);
;             PG8_WAIT_V(8); PG8_WAIT_L(0); PG8_BAR; PG8_MMA(1, 0, At, B0); PG8_MMA(1, 1, At, B1); PG8_BAR; PG8_SCHED;
;             PG8_LDB(B0, 1, 0); PG8_LDB(B1, 1, 1); PG8_SCHED; PG8_LDA(At, 1, 0); PG8_STAGE(PG8_SA(0, 1), a2 + hstep, voffA);
;             PG8_WAIT_V(8); PG8_WAIT_L(0); PG8_BAR; PG8_MMA(0, 0, At, B0); PG8_MMA(0, 1, At, B1); PG8_BAR; PG8_SCHED;
;             PG8_LDA(At, 1, 1); PG8_STAGE(PG8_SB(1, 0), b3, voffB); PG8_STAGE(PG8_SB(1, 1), b3 + hstep, voffB); PG8_STAGE(PG8_SA(1, 0), a3, voffA);
;             PG8_WAIT_V(8); PG8_WAIT_L(0); PG8_BAR; PG8_MMA(1, 0, At, B0); PG8_MMA(1, 1, At, B1); PG8_BAR; PG8_SCHED;
	s_add_i32 s59, s59, s19
	s_add_u32 s98, s38, 0x80
	s_addc_u32 s99, s39, 0
	s_mov_b32 m0, s59
	ds_read_b128 v[182:185], v165 offset:16384
	ds_read_b128 v[186:189], v165 offset:17408
	ds_read_b128 v[190:193], v165 offset:18432
	ds_read_b128 v[194:197], v165 offset:19456
	ds_read_b128 v[198:201], v165 offset:20480
	ds_read_b128 v[202:205], v165 offset:21504
	ds_read_b128 v[208:211], v165 offset:22528
	ds_read_b128 v[212:215], v165 offset:23552
	global_load_lds_dwordx4 v148, s[38:39]
	s_add_i32 m0, s59, 0x2000
	s_add_u32 s60, s38, 0x80000
	s_addc_u32 s61, s39, 0
	s_add_i32 s59, s62, s19
	global_load_lds_dwordx4 v152, s[38:39]
	s_mov_b32 m0, s59
	s_add_u32 s100, s42, 0x80
	s_addc_u32 s101, s43, 0
	global_load_lds_dwordx4 v148, s[60:61]
	s_add_i32 m0, s59, 0x2000
	s_nop 0
	global_load_lds_dwordx4 v152, s[60:61]
	s_mov_b32 m0, s44
	s_nop 0
	global_load_lds_dwordx4 v146, s[42:43]
	s_waitcnt vmcnt(7)
	s_waitcnt lgkmcnt(0)
	s_barrier
	v_mfma_f32_16x16x32_bf16 v[62:65], v[66:69], v[182:185], v[62:65]
	v_mfma_f32_16x16x32_bf16 v[58:61], v[74:77], v[182:185], v[58:61]
	v_mfma_f32_16x16x32_bf16 v[46:49], v[66:69], v[190:193], v[46:49]
	v_mfma_f32_16x16x32_bf16 v[42:45], v[74:77], v[190:193], v[42:45]
	v_mfma_f32_16x16x32_bf16 v[30:33], v[66:69], v[198:201], v[30:33]
	v_mfma_f32_16x16x32_bf16 v[26:29], v[74:77], v[198:201], v[26:29]
	v_mfma_f32_16x16x32_bf16 v[12:15], v[66:69], v[208:211], v[12:15]
	v_mfma_f32_16x16x32_bf16 v[8:11], v[74:77], v[208:211], v[8:11]
	v_mfma_f32_16x16x32_bf16 v[62:65], v[70:73], v[186:189], v[62:65]
	v_mfma_f32_16x16x32_bf16 v[58:61], v[78:81], v[186:189], v[58:61]
	v_mfma_f32_16x16x32_bf16 v[46:49], v[70:73], v[194:197], v[46:49]
	v_mfma_f32_16x16x32_bf16 v[42:45], v[78:81], v[194:197], v[42:45]
	v_mfma_f32_16x16x32_bf16 v[30:33], v[70:73], v[202:205], v[30:33]
	v_mfma_f32_16x16x32_bf16 v[26:29], v[78:81], v[202:205], v[26:29]
	v_mfma_f32_16x16x32_bf16 v[12:15], v[70:73], v[212:215], v[12:15]
	v_mfma_f32_16x16x32_bf16 v[8:11], v[78:81], v[212:215], v[8:11]
	v_mfma_f32_16x16x32_bf16 v[54:57], v[166:169], v[182:185], v[54:57]
	v_mfma_f32_16x16x32_bf16 v[50:53], v[174:177], v[182:185], v[50:53]
	v_mfma_f32_16x16x32_bf16 v[38:41], v[166:169], v[190:193], v[38:41]
	v_mfma_f32_16x16x32_bf16 v[34:37], v[174:177], v[190:193], v[34:37]
	v_mfma_f32_16x16x32_bf16 v[22:25], v[166:169], v[198:201], v[22:25]
	v_mfma_f32_16x16x32_bf16 v[16:19], v[174:177], v[198:201], v[16:19]
	v_mfma_f32_16x16x32_bf16 v[4:7], v[166:169], v[208:211], v[4:7]
	v_mfma_f32_16x16x32_bf16 v[0:3], v[174:177], v[208:211], v[0:3]
	v_mfma_f32_16x16x32_bf16 v[54:57], v[170:173], v[186:189], v[54:57]
	v_mfma_f32_16x16x32_bf16 v[50:53], v[178:181], v[186:189], v[50:53]
	v_mfma_f32_16x16x32_bf16 v[38:41], v[170:173], v[194:197], v[38:41]
	v_mfma_f32_16x16x32_bf16 v[34:37], v[178:181], v[194:197], v[34:37]
	v_mfma_f32_16x16x32_bf16 v[22:25], v[170:173], v[202:205], v[22:25]
	v_mfma_f32_16x16x32_bf16 v[16:19], v[178:181], v[202:205], v[16:19]
	v_mfma_f32_16x16x32_bf16 v[4:7], v[170:173], v[212:215], v[4:7]
	v_mfma_f32_16x16x32_bf16 v[0:3], v[178:181], v[212:215], v[0:3]
	s_barrier
	s_add_i32 s59, 0, 0x18000
	s_add_i32 s60, 0, 0x1c000
	v_add_u32_e32 v78, s59, v162
	v_add_u32_e32 v178, s60, v162
	ds_read_b128 v[66:69], v78
	ds_read_b128 v[70:73], v78 offset:1024
	ds_read_b128 v[74:77], v78 offset:2048
	ds_read_b128 v[78:81], v78 offset:3072
	ds_read_b128 v[166:169], v178
	ds_read_b128 v[170:173], v178 offset:1024
	ds_read_b128 v[174:177], v178 offset:2048
	ds_read_b128 v[178:181], v178 offset:3072
	s_mov_b32 m0, s45
	s_nop 0
	global_load_lds_dwordx4 v150, s[42:43]
	s_add_u32 s42, s42, 0x80000
	s_addc_u32 s43, s43, 0
	s_mov_b32 m0, s46
	ds_read_b128 v[182:185], v165 offset:32768
	ds_read_b128 v[186:189], v165 offset:33792
	ds_read_b128 v[190:193], v165 offset:34816
	ds_read_b128 v[194:197], v165 offset:35840
	ds_read_b128 v[198:201], v165 offset:36864
	ds_read_b128 v[202:205], v165 offset:37888
	ds_read_b128 v[208:211], v165 offset:38912
	ds_read_b128 v[212:215], v165 offset:39936
	global_load_lds_dwordx4 v146, s[42:43]
	s_mov_b32 m0, s47
	s_nop 0
	global_load_lds_dwordx4 v150, s[42:43]
	s_waitcnt vmcnt(8)
	s_waitcnt lgkmcnt(0)
	s_barrier
; #define PG8_BAR __builtin_amdgcn_s_barrier()
; template <class Epi, class Sched, bool ALIGN_EPI = false, bool SP2 = false>
; __device__ __forceinline__ void gemm_phase(PG8_LAS unsigned char* lds, const Gemm g, const Sched& S, const Epi& E, const int tid_in) {
;     ...
;             if constexpr (SP2) {
;             PG8_LDB(B0, 0, 0); PG8_LDB(B1, 0, 1); PG8_SCHED; PG8_LDA(At, 0, 0); PG8_STAGE(PG8_SA(1, 1), a1 + hstep, voffA);
;             PG8_WAIT_V(8); PG8_WAIT_L(0); PG8_BAR; PG8_MMA(0, 0, At, B0); PG8_MMA(0, 1, At, B1); PG8_BAR; PG8_SCHED;
;             PG8_LDA(At, 0, 1); PG8_STAGE(PG8_SB(0, 0), b2, voffB); PG8_STAGE(PG8_SB(0, 1), b2 + hstep, voffB); PG8_STAGE(PG8_SA(0, 0), a2, voffA);
;             PG8_WAIT_V(8); PG8_WAIT_L(0); PG8_BAR; PG8_MMA(1, 0, At, B0); PG8_MMA(1, 1, At, B1); PG8_BAR; PG8_SCHED;
;             PG8_LDB(B0, 1, 0); PG8_LDB(B1, 1, 1); PG8_SCHED; PG8_LDA(At, 1, 0); PG8_STAGE(PG8_SA(0, 1), a2 + hstep, voffA);
;             PG8_WAIT_V(8); PG8_WAIT_L(0); PG8_BAR; PG8_MMA(0, 0, At, B0); PG8_MMA(0, 1, At, B1); PG8_BAR; PG8_SCHED;
;             PG8_LDA(At, 1, 1); PG8_STAGE(PG8_SB(1, 0), b3, voffB); PG8_STAGE(PG8_SB(1, 1), b3 + hstep, voffB); PG8_STAGE(PG8_SA(1, 0), a3, voffA);
;             PG8_WAIT_V(8); PG8_WAIT_L(0); PG8_BAR; PG8_MMA(1, 0, At, B0); PG8_MMA(1, 1, At, B1); PG8_BAR; PG8_SCHED;
;             } else {
;             PG8_LDB(B0, 0, 0); PG8_SCHED; PG8_LDA(At, 0, 0); PG8_STAGE(PG8_SA(1, 1), a1 + hstep, voffA);
;             PG8_WAIT_L(8); PG8_BAR; PG8_WAIT_L(0); PG8_MMA(0, 0, At, B0); PG8_BAR; PG8_SCHED;
;             PG8_LDB(B1, 0, 1); PG8_STAGE(PG8_SB(0, 0), b2, voffB);
;             PG8_BAR; PG8_WAIT_L(0); PG8_MMA(0, 1, At, B1); PG8_BAR;
;             PG8_LDA(At, 0, 1); PG8_STAGE(PG8_SA(0, 0), a2, voffA);
;             PG8_BAR; PG8_WAIT_L(0); PG8_MMA(1, 0, At, B0); PG8_BAR; PG8_SCHED;
;             PG8_STAGE(PG8_SB(0, 1), b2 + hstep, voffB);
;             PG8_WAIT_V(6); PG8_BAR; PG8_MMA(1, 1, At, B1); PG8_BAR;
;             PG8_LDB(B0, 1, 0); PG8_SCHED; PG8_LDA(At, 1, 0); PG8_STAGE(PG8_SA(0, 1), a2 + hstep, voffA);
;             PG8_WAIT_L(8); PG8_BAR; PG8_WAIT_L(0); PG8_MMA(0, 0, At, B0); PG8_BAR; PG8_SCHED;
;             PG8_LDB(B1, 1, 1); PG8_STAGE(PG8_SB(1, 0), b3, voffB);
;             PG8_BAR; PG8_WAIT_L(0); PG8_MMA(0, 1, At, B1); PG8_BAR;
;             PG8_LDA(At, 1, 1); PG8_STAGE(PG8_SA(1, 0), a3, voffA);
	v_mfma_f32_16x16x32_bf16 v[142:145], v[66:69], v[182:185], v[142:145]
	v_mfma_f32_16x16x32_bf16 v[138:141], v[74:77], v[182:185], v[138:141]
	v_mfma_f32_16x16x32_bf16 v[126:129], v[66:69], v[190:193], v[126:129]
	v_mfma_f32_16x16x32_bf16 v[122:125], v[74:77], v[190:193], v[122:125]
	v_mfma_f32_16x16x32_bf16 v[110:113], v[66:69], v[198:201], v[110:113]
	v_mfma_f32_16x16x32_bf16 v[106:109], v[74:77], v[198:201], v[106:109]
	v_mfma_f32_16x16x32_bf16 v[94:97], v[66:69], v[208:211], v[94:97]
	v_mfma_f32_16x16x32_bf16 v[90:93], v[74:77], v[208:211], v[90:93]
	v_mfma_f32_16x16x32_bf16 v[142:145], v[70:73], v[186:189], v[142:145]
	v_mfma_f32_16x16x32_bf16 v[138:141], v[78:81], v[186:189], v[138:141]
	v_mfma_f32_16x16x32_bf16 v[126:129], v[70:73], v[194:197], v[126:129]
	v_mfma_f32_16x16x32_bf16 v[122:125], v[78:81], v[194:197], v[122:125]
	v_mfma_f32_16x16x32_bf16 v[110:113], v[70:73], v[202:205], v[110:113]
	v_mfma_f32_16x16x32_bf16 v[106:109], v[78:81], v[202:205], v[106:109]
	v_mfma_f32_16x16x32_bf16 v[94:97], v[70:73], v[212:215], v[94:97]
	v_mfma_f32_16x16x32_bf16 v[90:93], v[78:81], v[212:215], v[90:93]
	v_mfma_f32_16x16x32_bf16 v[134:137], v[166:169], v[182:185], v[134:137]
	v_mfma_f32_16x16x32_bf16 v[130:133], v[174:177], v[182:185], v[130:133]
	v_mfma_f32_16x16x32_bf16 v[118:121], v[166:169], v[190:193], v[118:121]
	v_mfma_f32_16x16x32_bf16 v[114:117], v[174:177], v[190:193], v[114:117]
	v_mfma_f32_16x16x32_bf16 v[102:105], v[166:169], v[198:201], v[102:105]
	v_mfma_f32_16x16x32_bf16 v[98:101], v[174:177], v[198:201], v[98:101]
	v_mfma_f32_16x16x32_bf16 v[86:89], v[166:169], v[208:211], v[86:89]
	v_mfma_f32_16x16x32_bf16 v[82:85], v[174:177], v[208:211], v[82:85]
	v_mfma_f32_16x16x32_bf16 v[134:137], v[170:173], v[186:189], v[134:137]
	v_mfma_f32_16x16x32_bf16 v[130:133], v[178:181], v[186:189], v[130:133]
	v_mfma_f32_16x16x32_bf16 v[118:121], v[170:173], v[194:197], v[118:121]
	v_mfma_f32_16x16x32_bf16 v[114:117], v[178:181], v[194:197], v[114:117]
	v_mfma_f32_16x16x32_bf16 v[102:105], v[170:173], v[202:205], v[102:105]
	v_mfma_f32_16x16x32_bf16 v[98:101], v[178:181], v[202:205], v[98:101]
	v_mfma_f32_16x16x32_bf16 v[86:89], v[170:173], v[212:215], v[86:89]
	v_mfma_f32_16x16x32_bf16 v[82:85], v[178:181], v[212:215], v[82:85]
	s_barrier
	s_add_i32 s42, s59, s19
	s_mov_b32 m0, s42
	ds_read_b128 v[182:185], v165 offset:49152
	ds_read_b128 v[186:189], v165 offset:50176
	ds_read_b128 v[190:193], v165 offset:51200
	ds_read_b128 v[194:197], v165 offset:52224
	ds_read_b128 v[198:201], v165 offset:53248
	ds_read_b128 v[202:205], v165 offset:54272
	ds_read_b128 v[208:211], v165 offset:55296
	ds_read_b128 v[212:215], v165 offset:56320
	global_load_lds_dwordx4 v148, s[98:99]
	s_add_i32 m0, s42, 0x2000
	s_add_u32 s38, s38, 0x80080
	s_addc_u32 s39, s39, 0
	s_add_i32 s42, s60, s19
	global_load_lds_dwordx4 v152, s[98:99]
	s_mov_b32 m0, s42
	s_nop 0
	global_load_lds_dwordx4 v148, s[38:39]
	s_add_i32 m0, s42, 0x2000
	s_nop 0
	global_load_lds_dwordx4 v152, s[38:39]
	s_mov_b32 m0, s48
	s_nop 0
	global_load_lds_dwordx4 v146, s[100:101]
	s_waitcnt vmcnt(7)
	s_waitcnt lgkmcnt(0)
	s_barrier
	v_mfma_f32_16x16x32_bf16 v[62:65], v[66:69], v[182:185], v[62:65]
	v_mfma_f32_16x16x32_bf16 v[58:61], v[74:77], v[182:185], v[58:61]
	v_mfma_f32_16x16x32_bf16 v[46:49], v[66:69], v[190:193], v[46:49]
	v_mfma_f32_16x16x32_bf16 v[42:45], v[74:77], v[190:193], v[42:45]
	v_mfma_f32_16x16x32_bf16 v[30:33], v[66:69], v[198:201], v[30:33]
	v_mfma_f32_16x16x32_bf16 v[26:29], v[74:77], v[198:201], v[26:29]
	v_mfma_f32_16x16x32_bf16 v[12:15], v[66:69], v[208:211], v[12:15]
	v_mfma_f32_16x16x32_bf16 v[8:11], v[74:77], v[208:211], v[8:11]
	v_mfma_f32_16x16x32_bf16 v[62:65], v[70:73], v[186:189], v[62:65]
	v_mfma_f32_16x16x32_bf16 v[58:61], v[78:81], v[186:189], v[58:61]
	v_mfma_f32_16x16x32_bf16 v[46:49], v[70:73], v[194:197], v[46:49]
	v_mfma_f32_16x16x32_bf16 v[42:45], v[78:81], v[194:197], v[42:45]
	v_mfma_f32_16x16x32_bf16 v[30:33], v[70:73], v[202:205], v[30:33]
	v_mfma_f32_16x16x32_bf16 v[26:29], v[78:81], v[202:205], v[26:29]
	v_mfma_f32_16x16x32_bf16 v[12:15], v[70:73], v[212:215], v[12:15]
	v_mfma_f32_16x16x32_bf16 v[8:11], v[78:81], v[212:215], v[8:11]
	v_mfma_f32_16x16x32_bf16 v[54:57], v[166:169], v[182:185], v[54:57]
	v_mfma_f32_16x16x32_bf16 v[50:53], v[174:177], v[182:185], v[50:53]
	v_mfma_f32_16x16x32_bf16 v[38:41], v[166:169], v[190:193], v[38:41]
	v_mfma_f32_16x16x32_bf16 v[34:37], v[174:177], v[190:193], v[34:37]
	v_mfma_f32_16x16x32_bf16 v[22:25], v[166:169], v[198:201], v[22:25]
	v_mfma_f32_16x16x32_bf16 v[16:19], v[174:177], v[198:201], v[16:19]
	v_mfma_f32_16x16x32_bf16 v[4:7], v[166:169], v[208:211], v[4:7]
	v_mfma_f32_16x16x32_bf16 v[0:3], v[174:177], v[208:211], v[0:3]
	v_mfma_f32_16x16x32_bf16 v[54:57], v[170:173], v[186:189], v[54:57]
	v_mfma_f32_16x16x32_bf16 v[50:53], v[178:181], v[186:189], v[50:53]
	v_mfma_f32_16x16x32_bf16 v[38:41], v[170:173], v[194:197], v[38:41]
	v_mfma_f32_16x16x32_bf16 v[34:37], v[178:181], v[194:197], v[34:37]
	v_mfma_f32_16x16x32_bf16 v[22:25], v[170:173], v[202:205], v[22:25]
	v_mfma_f32_16x16x32_bf16 v[16:19], v[178:181], v[202:205], v[16:19]
	v_mfma_f32_16x16x32_bf16 v[4:7], v[170:173], v[212:215], v[4:7]
	v_mfma_f32_16x16x32_bf16 v[0:3], v[178:181], v[212:215], v[0:3]
	s_barrier
	s_add_i32 s58, s58, 2
	s_add_u32 s34, s34, 0x100
	s_addc_u32 s35, s35, 0
	s_add_u32 s56, s56, 0x100
	s_addc_u32 s57, s57, 0
	s_cmp_gt_u32 s58, 29
	s_cbranch_scc0 .LBB0_412
	s_setprio 0
	s_and_b64 vcc, exec, s[2:3]
	s_cbranch_vccz .LBB0_415
	s_barrier

; #define PG8_STAGE(bufoff, gbase, voff) do { _Pragma("unroll") for (int _i = 0; _i < 2; ++_i) \
;         __builtin_amdgcn_global_load_lds((const unsigned*)((const char*)(gbase) + (voff)[_i]), (PG8_LAS unsigned*)(lds + (bufoff) + ldsw + _i * 8192), 16, 0, 0); } while (0)
; #define PG8_LDA(dst, b, h) do { _Pragma("unroll") for (int m = 0; m < 4; ++m) _Pragma("unroll") for (int k = 0; k < 2; ++k) dst[m][k] = *(const PG8_LAS bf16x8*)(lds + PG8_SA(b, h) + aoff + m * 2048 + k * 1024); } while (0)
; #define PG8_WAIT_V(n) asm volatile("s_waitcnt vmcnt(" #n ")" ::: "memory")
; #define PG8_WAIT_L(n) asm volatile("s_waitcnt lgkmcnt(" #n ")" ::: "memory")
; template <class Epi, class Sched, bool ALIGN_EPI = false, bool SP2 = false>
; __device__ __forceinline__ void gemm_phase(PG8_LAS unsigned char* lds, const Gemm g, const Sched& S, const Epi& E, const int tid_in) {
;     ...
;     for (;;) {
;         const bool has_next = S.next(ui + 1, nxt);
;         const char* nA = has_next ? (const char*)g.A + (size_t)nxt.pm * tstep : cA; const char* nB = has_next ? (const char*)g.Bt + (size_t)nxt.pn * tstep : cB;
;         for (int t = 0; t < nt; t += 2) {
;             if constexpr (Epi::KSPLIT > 0) { if (t == Epi::KSPLIT / BK) E.midk(acc, cur, wr, wc, fr, fq); }
;             const bool last = (t == nt - 2);
;             const char* a1 = cA + (size_t)(t + 1) * kstep;
;             const char* a2 = last ? nA : cA + (size_t)(t + 2) * kstep; const char* b2 = last ? nB : cB + (size_t)(t + 2) * kstep;
;             const char* a3 = a2 + kstep; const char* b3 = b2 + kstep;
;             if (last && has_next) S.a_ready(nxt);
;             if constexpr (SP2) {
;             PG8_LDB(B0, 0, 0); PG8_LDB(B1, 0, 1); PG8_SCHED; PG8_LDA(At, 0, 0); PG8_STAGE(PG8_SA(1, 1), a1 + hstep, voffA);
;             PG8_WAIT_V(8); PG8_WAIT_L(0); PG8_BAR; PG8_MMA(0, 0, At, B0); PG8_MMA(0, 1, At, B1); PG8_BAR; PG8_SCHED;
;             PG8_LDA(At, 0, 1); PG8_STAGE(PG8_SB(0, 0), b2, voffB); PG8_STAGE(PG8_SB(0, 1), b2 + hstep, voffB); PG8_STAGE(PG8_SA(0, 0), a2, voffA);
;     ...
;         for (int a = 0; a < 2; ++a)
; #pragma unroll
;             for (int b = 0; b < 2; ++b)
; #pragma unroll
;                 for (int m = 0; m < 4; ++m)
; #pragma unroll
;                     for (int n = 0; n < 2; ++n) acc[a][b][m][n] = (f32x4){0.f, 0.f, 0.f, 0.f};
;         cur = nxt; cA = nA; cB = nB; ++ui;
.LBB0_959:
	s_lshl_b32 s54, s36, 8
	s_lshl_b32 s55, s53, 9
	s_add_i32 s56, s54, s46
	s_add_i32 s57, s49, s55
	s_add_u32 s36, s30, 0x60080
	s_addc_u32 s37, s31, 0
	s_add_u32 s58, s34, 0x100
	v_mov_b32_e32 v0, 0
	v_lshl_add_u64 v[182:183], s[36:37], 0, v[202:203]
	v_lshl_add_u64 v[184:185], s[36:37], 0, v[204:205]
	s_addc_u32 s59, s35, 0
	s_mov_b32 s60, -2
	s_mov_b64 s[34:35], 0
	v_mov_b32_e32 v1, v0
	v_mov_b32_e32 v2, v0
	v_mov_b32_e32 v3, v0
	v_mov_b32_e32 v4, v0
	v_mov_b32_e32 v5, v0
	v_mov_b32_e32 v6, v0
	v_mov_b32_e32 v7, v0
	v_mov_b32_e32 v8, v0
	v_mov_b32_e32 v9, v0
	v_mov_b32_e32 v10, v0
	v_mov_b32_e32 v11, v0
	v_mov_b32_e32 v16, v0
	v_mov_b32_e32 v17, v0
	v_mov_b32_e32 v18, v0
	v_mov_b32_e32 v19, v0
	v_mov_b32_e32 v26, v0
	v_mov_b32_e32 v27, v0
	v_mov_b32_e32 v28, v0
	v_mov_b32_e32 v29, v0
	v_mov_b32_e32 v34, v0
	v_mov_b32_e32 v35, v0
	v_mov_b32_e32 v36, v0
	v_mov_b32_e32 v37, v0
	v_mov_b32_e32 v42, v0
	v_mov_b32_e32 v43, v0
	v_mov_b32_e32 v44, v0
	v_mov_b32_e32 v45, v0
	v_mov_b32_e32 v50, v0
	v_mov_b32_e32 v51, v0
	v_mov_b32_e32 v52, v0
	v_mov_b32_e32 v53, v0
	v_mov_b32_e32 v12, v0
	v_mov_b32_e32 v13, v0
	v_mov_b32_e32 v14, v0
	v_mov_b32_e32 v15, v0
	v_mov_b32_e32 v22, v0
	v_mov_b32_e32 v23, v0
	v_mov_b32_e32 v24, v0
	v_mov_b32_e32 v25, v0
	v_mov_b32_e32 v30, v0
	v_mov_b32_e32 v31, v0
	v_mov_b32_e32 v32, v0
	v_mov_b32_e32 v33, v0
	v_mov_b32_e32 v38, v0
	v_mov_b32_e32 v39, v0
	v_mov_b32_e32 v40, v0
	v_mov_b32_e32 v41, v0
	v_mov_b32_e32 v46, v0
	v_mov_b32_e32 v47, v0
	v_mov_b32_e32 v48, v0
	v_mov_b32_e32 v49, v0
	v_mov_b32_e32 v54, v0
	v_mov_b32_e32 v55, v0
	v_mov_b32_e32 v56, v0
	v_mov_b32_e32 v57, v0
	v_mov_b32_e32 v58, v0
	v_mov_b32_e32 v59, v0
	v_mov_b32_e32 v60, v0
	v_mov_b32_e32 v61, v0
	v_mov_b32_e32 v62, v0
	v_mov_b32_e32 v63, v0
	v_mov_b32_e32 v64, v0
	v_mov_b32_e32 v65, v0
	v_mov_b32_e32 v66, v0
	v_mov_b32_e32 v67, v0
	v_mov_b32_e32 v68, v0
	v_mov_b32_e32 v69, v0
	v_mov_b32_e32 v70, v0
	v_mov_b32_e32 v71, v0
	v_mov_b32_e32 v72, v0
	v_mov_b32_e32 v73, v0
	v_mov_b32_e32 v74, v0
	v_mov_b32_e32 v75, v0
	v_mov_b32_e32 v76, v0
	v_mov_b32_e32 v77, v0
	v_mov_b32_e32 v82, v0
	v_mov_b32_e32 v83, v0
	v_mov_b32_e32 v84, v0
	v_mov_b32_e32 v85, v0
	v_mov_b32_e32 v90, v0
	v_mov_b32_e32 v91, v0
	v_mov_b32_e32 v92, v0
	v_mov_b32_e32 v93, v0
	v_mov_b32_e32 v98, v0
	v_mov_b32_e32 v99, v0
	v_mov_b32_e32 v100, v0
	v_mov_b32_e32 v101, v0
	v_mov_b32_e32 v114, v0
	v_mov_b32_e32 v115, v0
	v_mov_b32_e32 v116, v0
	v_mov_b32_e32 v117, v0
	v_mov_b32_e32 v118, v0
	v_mov_b32_e32 v119, v0
	v_mov_b32_e32 v120, v0
	v_mov_b32_e32 v121, v0
	v_mov_b32_e32 v78, v0
	v_mov_b32_e32 v79, v0
	v_mov_b32_e32 v80, v0
	v_mov_b32_e32 v81, v0
	v_mov_b32_e32 v86, v0
	v_mov_b32_e32 v87, v0
	v_mov_b32_e32 v88, v0
	v_mov_b32_e32 v89, v0
	v_mov_b32_e32 v94, v0
	v_mov_b32_e32 v95, v0
	v_mov_b32_e32 v96, v0
	v_mov_b32_e32 v97, v0
	v_mov_b32_e32 v102, v0
	v_mov_b32_e32 v103, v0
	v_mov_b32_e32 v104, v0
	v_mov_b32_e32 v105, v0
	v_mov_b32_e32 v106, v0
	v_mov_b32_e32 v107, v0
	v_mov_b32_e32 v108, v0
	v_mov_b32_e32 v109, v0
	v_mov_b32_e32 v110, v0
	v_mov_b32_e32 v111, v0
	v_mov_b32_e32 v112, v0
	v_mov_b32_e32 v113, v0
	v_mov_b32_e32 v122, v0
	v_mov_b32_e32 v123, v0
	v_mov_b32_e32 v124, v0
	v_mov_b32_e32 v125, v0
	v_mov_b32_e32 v126, v0
	v_mov_b32_e32 v127, v0
	v_mov_b32_e32 v128, v0
	v_mov_b32_e32 v129, v0
	s_cmp_lt_u32 s19, 0x1000
	s_cbranch_scc1 .LPRIO_960
	s_setprio 1
.LPRIO_960:
	s_branch .LBB0_961
.LBB0_960:
	s_mov_b32 m0, s48
	s_nop 0
	global_load_lds_dwordx4 v196, s[100:101]
	s_add_u32 s36, s30, s34
	s_addc_u32 s37, s31, s35
	s_add_u32 s36, s36, 0x100
	s_addc_u32 s37, s37, 0
	s_add_u32 s61, s58, s34
	s_addc_u32 s62, s59, s35
	s_add_i32 s63, 0, 0x10000
	s_cmpk_eq_i32 s34, 0xb00
	s_cselect_b32 s41, s27, s37
	s_cselect_b32 s40, s26, s36
	s_cselect_b32 s37, s29, s62
	s_cselect_b32 s36, s28, s61
	s_add_i32 s61, 0, 0x14000
	v_add_u32_e32 v142, s63, v230
	v_add_u32_e32 v158, s61, v230
	ds_read_b128 v[130:133], v142
	ds_read_b128 v[134:137], v142 offset:1024
	ds_read_b128 v[138:141], v142 offset:2048
	ds_read_b128 v[142:145], v142 offset:3072
	ds_read_b128 v[146:149], v158
	ds_read_b128 v[150:153], v158 offset:1024
	ds_read_b128 v[154:157], v158 offset:2048
	ds_read_b128 v[158:161], v158 offset:3072
	v_lshl_add_u64 v[214:215], v[182:183], 0, s[34:35]
	s_add_i32 m0, s42, 0xc000
	ds_read_b128 v[162:165], v233
	ds_read_b128 v[166:169], v233 offset:1024
	ds_read_b128 v[170:173], v233 offset:2048
	ds_read_b128 v[174:177], v233 offset:3072
	ds_read_b128 v[178:181], v233 offset:4096
	ds_read_b128 v[186:189], v233 offset:5120
	ds_read_b128 v[190:193], v233 offset:6144
	ds_read_b128 v[210:213], v233 offset:7168
	global_load_lds_dwordx4 v[214:215], off
	v_lshl_add_u64 v[214:215], v[184:185], 0, s[34:35]
	s_add_i32 m0, s42, 0xe000
	s_nop 0
	global_load_lds_dwordx4 v[214:215], off
	s_waitcnt vmcnt(8)
	s_waitcnt lgkmcnt(0)
	s_barrier
; #define PG8_STAGE(bufoff, gbase, voff) do { _Pragma("unroll") for (int _i = 0; _i < 2; ++_i) \
;         __builtin_amdgcn_global_load_lds((const unsigned*)((const char*)(gbase) + (voff)[_i]), (PG8_LAS unsigned*)(lds + (bufoff) + ldsw + _i * 8192), 16, 0, 0); } while (0)
; #define PG8_LDA(dst, b, h) do { _Pragma("unroll") for (int m = 0; m < 4; ++m) _Pragma("unroll") for (int k = 0; k < 2; ++k) dst[m][k] = *(const PG8_LAS bf16x8*)(lds + PG8_SA(b, h) + aoff + m * 2048 + k * 1024); } while (0)
; #define PG8_LDB(dst, b, h) do { _Pragma("unroll") for (int n = 0; n < 2; ++n) _Pragma("unroll") for (int k = 0; k < 2; ++k) dst[n][k] = *(const PG8_LAS bf16x8*)(lds + PG8_SB(b, h) + boff + n * 2048 + k * 1024); } while (0)
; #define PG8_MMA(ai, bj, At, Bt) do { __builtin_amdgcn_s_setprio(1); _Pragma("unroll") for (int m = 0; m < 4; ++m) _Pragma("unroll") for (int n = 0; n < 2; ++n) _Pragma("unroll") for (int k = 0; k < 2; ++k) \
;         acc[ai][bj][m][n] = __builtin_amdgcn_mfma_f32_16x16x32_bf16(Bt[n][k], At[m][k], acc[ai][bj][m][n], 0, 0, 0); __builtin_amdgcn_s_setprio(0); } while (0)
; template <class Epi, class Sched, bool ALIGN_EPI = false, bool SP2 = false>
; __device__ __forceinline__ void gemm_phase(PG8_LAS unsigned char* lds, const Gemm g, const Sched& S, const Epi& E, const int tid_in) {
;     ...
;             if constexpr (SP2) {
;             PG8_LDB(B0, 0, 0); PG8_LDB(B1, 0, 1); PG8_SCHED; PG8_LDA(At, 0, 0); PG8_STAGE(PG8_SA(1, 1), a1 + hstep, voffA);
;             PG8_WAIT_V(8); PG8_WAIT_L(0); PG8_BAR; PG8_MMA(0, 0, At, B0); PG8_MMA(0, 1, At, B1); PG8_BAR; PG8_SCHED;
;             PG8_LDA(At, 0, 1); PG8_STAGE(PG8_SB(0, 0), b2, voffB); PG8_STAGE(PG8_SB(0, 1), b2 + hstep, voffB); PG8_STAGE(PG8_SA(0, 0), a2, voffA);
;             PG8_WAIT_V(8); PG8_WAIT_L(0); PG8_BAR; PG8_MMA(1, 0, At, B0); PG8_MMA(1, 1, At, B1); PG8_BAR; PG8_SCHED;
;             PG8_LDB(B0, 1, 0); PG8_LDB(B1, 1, 1); PG8_SCHED; PG8_LDA(At, 1, 0); PG8_STAGE(PG8_SA(0, 1), a2 + hstep, voffA);
;             PG8_WAIT_V(8); PG8_WAIT_L(0); PG8_BAR; PG8_MMA(0, 0, At, B0); PG8_MMA(0, 1, At, B1); PG8_BAR; PG8_SCHED;
;             PG8_LDA(At, 1, 1); PG8_STAGE(PG8_SB(1, 0), b3, voffB); PG8_STAGE(PG8_SB(1, 1), b3 + hstep, voffB); PG8_STAGE(PG8_SA(1, 0), a3, voffA);
;             PG8_WAIT_V(8); PG8_WAIT_L(0); PG8_BAR; PG8_MMA(1, 0, At, B0); PG8_MMA(1, 1, At, B1); PG8_BAR; PG8_SCHED;
	v_mfma_f32_16x16x32_bf16 v[126:129], v[130:133], v[162:165], v[126:129]
	v_mfma_f32_16x16x32_bf16 v[122:125], v[138:141], v[162:165], v[122:125]
	v_mfma_f32_16x16x32_bf16 v[110:113], v[130:133], v[170:173], v[110:113]
	v_mfma_f32_16x16x32_bf16 v[106:109], v[138:141], v[170:173], v[106:109]
	v_mfma_f32_16x16x32_bf16 v[102:105], v[130:133], v[178:181], v[102:105]
	v_mfma_f32_16x16x32_bf16 v[94:97], v[138:141], v[178:181], v[94:97]
	v_mfma_f32_16x16x32_bf16 v[86:89], v[130:133], v[190:193], v[86:89]
	v_mfma_f32_16x16x32_bf16 v[78:81], v[138:141], v[190:193], v[78:81]
	v_mfma_f32_16x16x32_bf16 v[126:129], v[134:137], v[166:169], v[126:129]
	v_mfma_f32_16x16x32_bf16 v[122:125], v[142:145], v[166:169], v[122:125]
	v_mfma_f32_16x16x32_bf16 v[110:113], v[134:137], v[174:177], v[110:113]
	v_mfma_f32_16x16x32_bf16 v[106:109], v[142:145], v[174:177], v[106:109]
	v_mfma_f32_16x16x32_bf16 v[102:105], v[134:137], v[186:189], v[102:105]
	v_mfma_f32_16x16x32_bf16 v[94:97], v[142:145], v[186:189], v[94:97]
	v_mfma_f32_16x16x32_bf16 v[86:89], v[134:137], v[210:213], v[86:89]
	v_mfma_f32_16x16x32_bf16 v[78:81], v[142:145], v[210:213], v[78:81]
	v_mfma_f32_16x16x32_bf16 v[118:121], v[146:149], v[162:165], v[118:121]
	v_mfma_f32_16x16x32_bf16 v[114:117], v[154:157], v[162:165], v[114:117]
	v_mfma_f32_16x16x32_bf16 v[98:101], v[146:149], v[170:173], v[98:101]
	v_mfma_f32_16x16x32_bf16 v[90:93], v[154:157], v[170:173], v[90:93]
	v_mfma_f32_16x16x32_bf16 v[82:85], v[146:149], v[178:181], v[82:85]
	v_mfma_f32_16x16x32_bf16 v[74:77], v[154:157], v[178:181], v[74:77]
	v_mfma_f32_16x16x32_bf16 v[70:73], v[146:149], v[190:193], v[70:73]
	v_mfma_f32_16x16x32_bf16 v[66:69], v[154:157], v[190:193], v[66:69]
	v_mfma_f32_16x16x32_bf16 v[118:121], v[150:153], v[166:169], v[118:121]
	v_mfma_f32_16x16x32_bf16 v[114:117], v[158:161], v[166:169], v[114:117]
	v_mfma_f32_16x16x32_bf16 v[98:101], v[150:153], v[174:177], v[98:101]
	v_mfma_f32_16x16x32_bf16 v[90:93], v[158:161], v[174:177], v[90:93]
	v_mfma_f32_16x16x32_bf16 v[82:85], v[150:153], v[186:189], v[82:85]
	v_mfma_f32_16x16x32_bf16 v[74:77], v[158:161], v[186:189], v[74:77]
	v_mfma_f32_16x16x32_bf16 v[70:73], v[150:153], v[210:213], v[70:73]
	v_mfma_f32_16x16x32_bf16 v[66:69], v[158:161], v[210:213], v[66:69]
	s_barrier
	s_add_i32 s62, s63, s19
	s_add_u32 s98, s36, 0x80
	s_addc_u32 s99, s37, 0
	s_mov_b32 m0, s62
	ds_read_b128 v[162:165], v233 offset:16384
	ds_read_b128 v[166:169], v233 offset:17408
	ds_read_b128 v[170:173], v233 offset:18432
	ds_read_b128 v[174:177], v233 offset:19456
	ds_read_b128 v[178:181], v233 offset:20480
	ds_read_b128 v[186:189], v233 offset:21504
	ds_read_b128 v[190:193], v233 offset:22528
	ds_read_b128 v[210:213], v233 offset:23552
	global_load_lds_dwordx4 v198, s[36:37]
	s_add_i32 m0, s62, 0x2000
	s_add_u32 s62, s36, 0x60000
	s_addc_u32 s63, s37, 0
	s_add_i32 s61, s61, s19
	global_load_lds_dwordx4 v194, s[36:37]
	s_mov_b32 m0, s61
	s_add_u32 s100, s40, 0x80
	s_addc_u32 s101, s41, 0
	global_load_lds_dwordx4 v198, s[62:63]
	s_add_i32 m0, s61, 0x2000
	s_nop 0
	global_load_lds_dwordx4 v194, s[62:63]
	s_mov_b32 m0, s42
	s_nop 0
	global_load_lds_dwordx4 v200, s[40:41]
	s_waitcnt vmcnt(7)
	s_waitcnt lgkmcnt(0)
	s_barrier
	v_mfma_f32_16x16x32_bf16 v[62:65], v[130:133], v[162:165], v[62:65]
	v_mfma_f32_16x16x32_bf16 v[58:61], v[138:141], v[162:165], v[58:61]
	v_mfma_f32_16x16x32_bf16 v[54:57], v[130:133], v[170:173], v[54:57]
	v_mfma_f32_16x16x32_bf16 v[46:49], v[138:141], v[170:173], v[46:49]
	v_mfma_f32_16x16x32_bf16 v[38:41], v[130:133], v[178:181], v[38:41]
	v_mfma_f32_16x16x32_bf16 v[30:33], v[138:141], v[178:181], v[30:33]
	v_mfma_f32_16x16x32_bf16 v[22:25], v[130:133], v[190:193], v[22:25]
	v_mfma_f32_16x16x32_bf16 v[12:15], v[138:141], v[190:193], v[12:15]
	v_mfma_f32_16x16x32_bf16 v[62:65], v[134:137], v[166:169], v[62:65]
	v_mfma_f32_16x16x32_bf16 v[58:61], v[142:145], v[166:169], v[58:61]
	v_mfma_f32_16x16x32_bf16 v[54:57], v[134:137], v[174:177], v[54:57]
	v_mfma_f32_16x16x32_bf16 v[46:49], v[142:145], v[174:177], v[46:49]
	v_mfma_f32_16x16x32_bf16 v[38:41], v[134:137], v[186:189], v[38:41]
	v_mfma_f32_16x16x32_bf16 v[30:33], v[142:145], v[186:189], v[30:33]
	v_mfma_f32_16x16x32_bf16 v[22:25], v[134:137], v[210:213], v[22:25]
	v_mfma_f32_16x16x32_bf16 v[12:15], v[142:145], v[210:213], v[12:15]
	v_mfma_f32_16x16x32_bf16 v[50:53], v[146:149], v[162:165], v[50:53]
	v_mfma_f32_16x16x32_bf16 v[42:45], v[154:157], v[162:165], v[42:45]
	v_mfma_f32_16x16x32_bf16 v[34:37], v[146:149], v[170:173], v[34:37]
	v_mfma_f32_16x16x32_bf16 v[26:29], v[154:157], v[170:173], v[26:29]
	v_mfma_f32_16x16x32_bf16 v[16:19], v[146:149], v[178:181], v[16:19]
	v_mfma_f32_16x16x32_bf16 v[8:11], v[154:157], v[178:181], v[8:11]
	v_mfma_f32_16x16x32_bf16 v[4:7], v[146:149], v[190:193], v[4:7]
	v_mfma_f32_16x16x32_bf16 v[0:3], v[154:157], v[190:193], v[0:3]
	v_mfma_f32_16x16x32_bf16 v[50:53], v[150:153], v[166:169], v[50:53]
	v_mfma_f32_16x16x32_bf16 v[42:45], v[158:161], v[166:169], v[42:45]
	v_mfma_f32_16x16x32_bf16 v[34:37], v[150:153], v[174:177], v[34:37]
	v_mfma_f32_16x16x32_bf16 v[26:29], v[158:161], v[174:177], v[26:29]
	v_mfma_f32_16x16x32_bf16 v[16:19], v[150:153], v[186:189], v[16:19]
	v_mfma_f32_16x16x32_bf16 v[8:11], v[158:161], v[186:189], v[8:11]
	v_mfma_f32_16x16x32_bf16 v[4:7], v[150:153], v[210:213], v[4:7]
	v_mfma_f32_16x16x32_bf16 v[0:3], v[158:161], v[210:213], v[0:3]
	s_barrier
; #define PG8_STAGE(bufoff, gbase, voff) do { _Pragma("unroll") for (int _i = 0; _i < 2; ++_i) \
;         __builtin_amdgcn_global_load_lds((const unsigned*)((const char*)(gbase) + (voff)[_i]), (PG8_LAS unsigned*)(lds + (bufoff) + ldsw + _i * 8192), 16, 0, 0); } while (0)
; #define PG8_LDA(dst, b, h) do { _Pragma("unroll") for (int m = 0; m < 4; ++m) _Pragma("unroll") for (int k = 0; k < 2; ++k) dst[m][k] = *(const PG8_LAS bf16x8*)(lds + PG8_SA(b, h) + aoff + m * 2048 + k * 1024); } while (0)
; #define PG8_LDB(dst, b, h) do { _Pragma("unroll") for (int n = 0; n < 2; ++n) _Pragma("unroll") for (int k = 0; k < 2; ++k) dst[n][k] = *(const PG8_LAS bf16x8*)(lds + PG8_SB(b, h) + boff + n * 2048 + k * 1024); } while (0)
; #define PG8_MMA(ai, bj, At, Bt) do { __builtin_amdgcn_s_setprio(1); _Pragma("unroll") for (int m = 0; m < 4; ++m) _Pragma("unroll") for (int n = 0; n < 2; ++n) _Pragma("unroll") for (int k = 0; k < 2; ++k) \
;         acc[ai][bj][m][n] = __builtin_amdgcn_mfma_f32_16x16x32_bf16(Bt[n][k], At[m][k], acc[ai][bj][m][n], 0, 0, 0); __builtin_amdgcn_s_setprio(0); } while (0)
; template <class Epi, class Sched, bool ALIGN_EPI = false, bool SP2 = false>
; __device__ __forceinline__ void gemm_phase(PG8_LAS unsigned char* lds, const Gemm g, const Sched& S, const Epi& E, const int tid_in) {
;     ...
;             if constexpr (SP2) {
;             PG8_LDB(B0, 0, 0); PG8_LDB(B1, 0, 1); PG8_SCHED; PG8_LDA(At, 0, 0); PG8_STAGE(PG8_SA(1, 1), a1 + hstep, voffA);
;             PG8_WAIT_V(8); PG8_WAIT_L(0); PG8_BAR; PG8_MMA(0, 0, At, B0); PG8_MMA(0, 1, At, B1); PG8_BAR; PG8_SCHED;
;             PG8_LDA(At, 0, 1); PG8_STAGE(PG8_SB(0, 0), b2, voffB); PG8_STAGE(PG8_SB(0, 1), b2 + hstep, voffB); PG8_STAGE(PG8_SA(0, 0), a2, voffA);
;             PG8_WAIT_V(8); PG8_WAIT_L(0); PG8_BAR; PG8_MMA(1, 0, At, B0); PG8_MMA(1, 1, At, B1); PG8_BAR; PG8_SCHED;
;             PG8_LDB(B0, 1, 0); PG8_LDB(B1, 1, 1); PG8_SCHED; PG8_LDA(At, 1, 0); PG8_STAGE(PG8_SA(0, 1), a2 + hstep, voffA);
;             PG8_WAIT_V(8); PG8_WAIT_L(0); PG8_BAR; PG8_MMA(0, 0, At, B0); PG8_MMA(0, 1, At, B1); PG8_BAR; PG8_SCHED;
;             PG8_LDA(At, 1, 1); PG8_STAGE(PG8_SB(1, 0), b3, voffB); PG8_STAGE(PG8_SB(1, 1), b3 + hstep, voffB); PG8_STAGE(PG8_SA(1, 0), a3, voffA);
;             PG8_WAIT_V(8); PG8_WAIT_L(0); PG8_BAR; PG8_MMA(1, 0, At, B0); PG8_MMA(1, 1, At, B1); PG8_BAR; PG8_SCHED;
	s_add_i32 s61, 0, 0x18000
	s_add_i32 s62, 0, 0x1c000
	v_add_u32_e32 v142, s61, v230
	v_add_u32_e32 v158, s62, v230
	ds_read_b128 v[130:133], v142
	ds_read_b128 v[134:137], v142 offset:1024
	ds_read_b128 v[138:141], v142 offset:2048
	ds_read_b128 v[142:145], v142 offset:3072
	ds_read_b128 v[146:149], v158
	ds_read_b128 v[150:153], v158 offset:1024
	ds_read_b128 v[154:157], v158 offset:2048
	ds_read_b128 v[158:161], v158 offset:3072
	s_mov_b32 m0, s43
	s_nop 0
	global_load_lds_dwordx4 v196, s[40:41]
	s_add_u32 s40, s40, 0x60000
	s_addc_u32 s41, s41, 0
	s_mov_b32 m0, s44
	ds_read_b128 v[162:165], v233 offset:32768
	ds_read_b128 v[166:169], v233 offset:33792
	ds_read_b128 v[170:173], v233 offset:34816
	ds_read_b128 v[174:177], v233 offset:35840
	ds_read_b128 v[178:181], v233 offset:36864
	ds_read_b128 v[186:189], v233 offset:37888
	ds_read_b128 v[190:193], v233 offset:38912
	ds_read_b128 v[210:213], v233 offset:39936
	global_load_lds_dwordx4 v200, s[40:41]
	s_mov_b32 m0, s45
	s_nop 0
	global_load_lds_dwordx4 v196, s[40:41]
	s_waitcnt vmcnt(8)
	s_waitcnt lgkmcnt(0)
	s_barrier
	v_mfma_f32_16x16x32_bf16 v[126:129], v[130:133], v[162:165], v[126:129]
	v_mfma_f32_16x16x32_bf16 v[122:125], v[138:141], v[162:165], v[122:125]
	v_mfma_f32_16x16x32_bf16 v[110:113], v[130:133], v[170:173], v[110:113]
	v_mfma_f32_16x16x32_bf16 v[106:109], v[138:141], v[170:173], v[106:109]
	v_mfma_f32_16x16x32_bf16 v[102:105], v[130:133], v[178:181], v[102:105]
	v_mfma_f32_16x16x32_bf16 v[94:97], v[138:141], v[178:181], v[94:97]
	v_mfma_f32_16x16x32_bf16 v[86:89], v[130:133], v[190:193], v[86:89]
	v_mfma_f32_16x16x32_bf16 v[78:81], v[138:141], v[190:193], v[78:81]
	v_mfma_f32_16x16x32_bf16 v[126:129], v[134:137], v[166:169], v[126:129]
	v_mfma_f32_16x16x32_bf16 v[122:125], v[142:145], v[166:169], v[122:125]
	v_mfma_f32_16x16x32_bf16 v[110:113], v[134:137], v[174:177], v[110:113]
	v_mfma_f32_16x16x32_bf16 v[106:109], v[142:145], v[174:177], v[106:109]
	v_mfma_f32_16x16x32_bf16 v[102:105], v[134:137], v[186:189], v[102:105]
	v_mfma_f32_16x16x32_bf16 v[94:97], v[142:145], v[186:189], v[94:97]
	v_mfma_f32_16x16x32_bf16 v[86:89], v[134:137], v[210:213], v[86:89]
	v_mfma_f32_16x16x32_bf16 v[78:81], v[142:145], v[210:213], v[78:81]
	v_mfma_f32_16x16x32_bf16 v[118:121], v[146:149], v[162:165], v[118:121]
	v_mfma_f32_16x16x32_bf16 v[114:117], v[154:157], v[162:165], v[114:117]
	v_mfma_f32_16x16x32_bf16 v[98:101], v[146:149], v[170:173], v[98:101]
	v_mfma_f32_16x16x32_bf16 v[90:93], v[154:157], v[170:173], v[90:93]
	v_mfma_f32_16x16x32_bf16 v[82:85], v[146:149], v[178:181], v[82:85]
	v_mfma_f32_16x16x32_bf16 v[74:77], v[154:157], v[178:181], v[74:77]
	v_mfma_f32_16x16x32_bf16 v[70:73], v[146:149], v[190:193], v[70:73]
	v_mfma_f32_16x16x32_bf16 v[66:69], v[154:157], v[190:193], v[66:69]
	v_mfma_f32_16x16x32_bf16 v[118:121], v[150:153], v[166:169], v[118:121]
	v_mfma_f32_16x16x32_bf16 v[114:117], v[158:161], v[166:169], v[114:117]
	v_mfma_f32_16x16x32_bf16 v[98:101], v[150:153], v[174:177], v[98:101]
	v_mfma_f32_16x16x32_bf16 v[90:93], v[158:161], v[174:177], v[90:93]
	v_mfma_f32_16x16x32_bf16 v[82:85], v[150:153], v[186:189], v[82:85]
	v_mfma_f32_16x16x32_bf16 v[74:77], v[158:161], v[186:189], v[74:77]
	v_mfma_f32_16x16x32_bf16 v[70:73], v[150:153], v[210:213], v[70:73]
	v_mfma_f32_16x16x32_bf16 v[66:69], v[158:161], v[210:213], v[66:69]
	s_barrier
	s_add_i32 s40, s61, s19
	s_mov_b32 m0, s40
	ds_read_b128 v[162:165], v233 offset:49152
	ds_read_b128 v[166:169], v233 offset:50176
	ds_read_b128 v[170:173], v233 offset:51200
	ds_read_b128 v[174:177], v233 offset:52224
	ds_read_b128 v[178:181], v233 offset:53248
	ds_read_b128 v[186:189], v233 offset:54272
	ds_read_b128 v[190:193], v233 offset:55296
	ds_read_b128 v[210:213], v233 offset:56320
	global_load_lds_dwordx4 v198, s[98:99]
	s_add_i32 m0, s40, 0x2000
	s_add_u32 s36, s36, 0x60080
	s_addc_u32 s37, s37, 0
	s_add_i32 s40, s62, s19
	global_load_lds_dwordx4 v194, s[98:99]
	s_mov_b32 m0, s40
	s_nop 0
	global_load_lds_dwordx4 v198, s[36:37]
	s_add_i32 m0, s40, 0x2000
	s_nop 0
	global_load_lds_dwordx4 v194, s[36:37]
	s_mov_b32 m0, s47
	s_nop 0
	global_load_lds_dwordx4 v200, s[100:101]
	s_waitcnt vmcnt(7)
	s_waitcnt lgkmcnt(0)
	s_barrier
	v_mfma_f32_16x16x32_bf16 v[62:65], v[130:133], v[162:165], v[62:65]
	v_mfma_f32_16x16x32_bf16 v[58:61], v[138:141], v[162:165], v[58:61]
	v_mfma_f32_16x16x32_bf16 v[54:57], v[130:133], v[170:173], v[54:57]
	v_mfma_f32_16x16x32_bf16 v[46:49], v[138:141], v[170:173], v[46:49]
	v_mfma_f32_16x16x32_bf16 v[38:41], v[130:133], v[178:181], v[38:41]
	v_mfma_f32_16x16x32_bf16 v[30:33], v[138:141], v[178:181], v[30:33]
	v_mfma_f32_16x16x32_bf16 v[22:25], v[130:133], v[190:193], v[22:25]
	v_mfma_f32_16x16x32_bf16 v[12:15], v[138:141], v[190:193], v[12:15]
	v_mfma_f32_16x16x32_bf16 v[62:65], v[134:137], v[166:169], v[62:65]
	v_mfma_f32_16x16x32_bf16 v[58:61], v[142:145], v[166:169], v[58:61]
	v_mfma_f32_16x16x32_bf16 v[54:57], v[134:137], v[174:177], v[54:57]
	v_mfma_f32_16x16x32_bf16 v[46:49], v[142:145], v[174:177], v[46:49]
	v_mfma_f32_16x16x32_bf16 v[38:41], v[134:137], v[186:189], v[38:41]
	v_mfma_f32_16x16x32_bf16 v[30:33], v[142:145], v[186:189], v[30:33]
	v_mfma_f32_16x16x32_bf16 v[22:25], v[134:137], v[210:213], v[22:25]
	v_mfma_f32_16x16x32_bf16 v[12:15], v[142:145], v[210:213], v[12:15]
	v_mfma_f32_16x16x32_bf16 v[50:53], v[146:149], v[162:165], v[50:53]
	v_mfma_f32_16x16x32_bf16 v[42:45], v[154:157], v[162:165], v[42:45]
	v_mfma_f32_16x16x32_bf16 v[34:37], v[146:149], v[170:173], v[34:37]
	v_mfma_f32_16x16x32_bf16 v[26:29], v[154:157], v[170:173], v[26:29]
	v_mfma_f32_16x16x32_bf16 v[16:19], v[146:149], v[178:181], v[16:19]
	v_mfma_f32_16x16x32_bf16 v[8:11], v[154:157], v[178:181], v[8:11]
	v_mfma_f32_16x16x32_bf16 v[4:7], v[146:149], v[190:193], v[4:7]
	v_mfma_f32_16x16x32_bf16 v[0:3], v[154:157], v[190:193], v[0:3]
	v_mfma_f32_16x16x32_bf16 v[50:53], v[150:153], v[166:169], v[50:53]
	v_mfma_f32_16x16x32_bf16 v[42:45], v[158:161], v[166:169], v[42:45]
	v_mfma_f32_16x16x32_bf16 v[34:37], v[150:153], v[174:177], v[34:37]
	v_mfma_f32_16x16x32_bf16 v[26:29], v[158:161], v[174:177], v[26:29]
	v_mfma_f32_16x16x32_bf16 v[16:19], v[150:153], v[186:189], v[16:19]
	v_mfma_f32_16x16x32_bf16 v[8:11], v[158:161], v[186:189], v[8:11]
	v_mfma_f32_16x16x32_bf16 v[4:7], v[150:153], v[210:213], v[4:7]
	v_mfma_f32_16x16x32_bf16 v[0:3], v[158:161], v[210:213], v[0:3]
	s_barrier
	s_add_i32 s60, s60, 2
	s_add_u32 s34, s34, 0x100
	s_addc_u32 s35, s35, 0
	s_cmp_gt_u32 s60, 21
	s_cbranch_scc1 .LBB0_963

; #define PG8_BAR __builtin_amdgcn_s_barrier()
; template <class Epi, class Sched, bool ALIGN_EPI = false, bool SP2 = false>
; __device__ __forceinline__ void gemm_phase(PG8_LAS unsigned char* lds, const Gemm g, const Sched& S, const Epi& E, const int tid_in) {
;     ...
;         if constexpr (ALIGN_EPI) { if (wr == 0) PG8_BAR; }
;         if constexpr (Epi::PREF) { if (has_next) E.prefetch(nxt, (ui + 1) & 1, lds, wid, lane); E.run(acc, cur, wr, wc, fr, fq, lds, ui & 1); S.done(cur); }
;         else if constexpr (!Epi::AFTER_DRAIN) { E(acc, cur, wr, wc, fr, fq); S.done(cur); }
;         if (!has_next) break;
.LBB0_963:
	s_setprio 0
	s_and_b64 vcc, exec, s[24:25]
	s_cbranch_vccz .LBB0_965
	s_barrier

; #define PG8_STAGE(bufoff, gbase, voff) do { _Pragma("unroll") for (int _i = 0; _i < 2; ++_i) \
;         __builtin_amdgcn_global_load_lds((const unsigned*)((const char*)(gbase) + (voff)[_i]), (PG8_LAS unsigned*)(lds + (bufoff) + ldsw + _i * 8192), 16, 0, 0); } while (0)
; #define PG8_LDA(dst, b, h) do { _Pragma("unroll") for (int m = 0; m < 4; ++m) _Pragma("unroll") for (int k = 0; k < 2; ++k) dst[m][k] = *(const PG8_LAS bf16x8*)(lds + PG8_SA(b, h) + aoff + m * 2048 + k * 1024); } while (0)
; #define PG8_LDB(dst, b, h) do { _Pragma("unroll") for (int n = 0; n < 2; ++n) _Pragma("unroll") for (int k = 0; k < 2; ++k) dst[n][k] = *(const PG8_LAS bf16x8*)(lds + PG8_SB(b, h) + boff + n * 2048 + k * 1024); } while (0)
; #define PG8_WAIT_V(n) asm volatile("s_waitcnt vmcnt(" #n ")" ::: "memory")
; #define PG8_WAIT_L(n) asm volatile("s_waitcnt lgkmcnt(" #n ")" ::: "memory")
; #define PG8_BAR __builtin_amdgcn_s_barrier()
; #define PG8_SCHED __builtin_amdgcn_sched_barrier(0)
; template <class Epi, class Sched, bool ALIGN_EPI = false, bool SP2 = false>
; __device__ __forceinline__ void gemm_phase(PG8_LAS unsigned char* lds, const Gemm g, const Sched& S, const Epi& E, const int tid_in) {
;     ...
;     for (;;) {
;         const bool has_next = S.next(ui + 1, nxt);
;         const char* nA = has_next ? (const char*)g.A + (size_t)nxt.pm * tstep : cA; const char* nB = has_next ? (const char*)g.Bt + (size_t)nxt.pn * tstep : cB;
;         for (int t = 0; t < nt; t += 2) {
;             if constexpr (Epi::KSPLIT > 0) { if (t == Epi::KSPLIT / BK) E.midk(acc, cur, wr, wc, fr, fq); }
;             const bool last = (t == nt - 2);
;             const char* a1 = cA + (size_t)(t + 1) * kstep;
;             const char* a2 = last ? nA : cA + (size_t)(t + 2) * kstep; const char* b2 = last ? nB : cB + (size_t)(t + 2) * kstep;
;             const char* a3 = a2 + kstep; const char* b3 = b2 + kstep;
;             if (last && has_next) S.a_ready(nxt);
;             if constexpr (SP2) {
;             PG8_LDB(B0, 0, 0); PG8_LDB(B1, 0, 1); PG8_SCHED; PG8_LDA(At, 0, 0); PG8_STAGE(PG8_SA(1, 1), a1 + hstep, voffA);
;             PG8_WAIT_V(8); PG8_WAIT_L(0); PG8_BAR; PG8_MMA(0, 0, At, B0); PG8_MMA(0, 1, At, B1); PG8_BAR; PG8_SCHED;
;             PG8_LDA(At, 0, 1); PG8_STAGE(PG8_SB(0, 0), b2, voffB); PG8_STAGE(PG8_SB(0, 1), b2 + hstep, voffB); PG8_STAGE(PG8_SA(0, 0), a2, voffA);
.LBB0_1036:
	s_ashr_i32 s57, s56, 31
	s_lshl_b64 s[34:35], s[56:57], 20
	s_add_u32 s36, s10, s34
	s_addc_u32 s37, s19, s35
	s_and_b64 s[34:35], exec, s[6:7]
	v_readlane_b32 s34, v254, 36
	v_readlane_b32 s35, v254, 37
	s_cselect_b32 s38, s29, s37
	s_cselect_b32 s39, s28, s36
	s_mov_b32 s40, s34
	s_ashr_i32 s41, s34, 31
	v_writelane_b32 v254, s34, 36
	v_mov_b32_e32 v0, 0
	s_mov_b32 vcc_lo, -2
	v_writelane_b32 v254, s35, 37
	s_lshl_b64 s[34:35], s[40:41], 20
	s_add_u32 s60, s62, s34
	s_addc_u32 s61, s63, s35
	s_and_b64 s[34:35], exec, s[6:7]
	s_cselect_b32 s40, s31, s61
	s_cselect_b32 s41, s30, s60
	s_add_u32 s28, s28, 0x80080
	s_addc_u32 s29, s29, 0
	s_add_u32 s57, s30, 0x100
	s_addc_u32 s92, s31, 0
	s_cmp_lt_u32 s8, 0x1000
	s_cbranch_scc1 .LPRIO_1037
	s_setprio 1
.LPRIO_1037:
	s_mov_b32 m0, s76
	s_nop 0
	global_load_lds_dwordx4 v214, s[100:101]
	s_add_u32 s30, s28, 0xfff80080
	s_addc_u32 s31, s29, -1
	s_add_i32 s46, 0, 0x10000
	s_cmp_eq_u32 vcc_lo, 28
	s_cselect_b32 s35, s38, s31
	s_cselect_b32 s34, s39, s30
	s_cselect_b32 s31, s40, s92
	s_cselect_b32 s30, s41, s57
	s_add_i32 vcc_hi, 0, 0x14000
	v_add_u32_e32 v142, s46, v21
	v_add_u32_e32 v158, vcc_hi, v21
	ds_read_b128 v[130:133], v142
	ds_read_b128 v[134:137], v142 offset:1024
	ds_read_b128 v[138:141], v142 offset:2048
	ds_read_b128 v[142:145], v142 offset:3072
	ds_read_b128 v[146:149], v158
	ds_read_b128 v[150:153], v158 offset:1024
	ds_read_b128 v[154:157], v158 offset:2048
	ds_read_b128 v[158:161], v158 offset:3072
	s_add_i32 m0, s64, 0xc000
	ds_read_b128 v[162:165], v208
	ds_read_b128 v[166:169], v208 offset:1024
	ds_read_b128 v[170:173], v208 offset:2048
	ds_read_b128 v[174:177], v208 offset:3072
	ds_read_b128 v[178:181], v208 offset:4096
	ds_read_b128 v[182:185], v208 offset:5120
	ds_read_b128 v[186:189], v208 offset:6144
	ds_read_b128 v[190:193], v208 offset:7168
	global_load_lds_dwordx4 v218, s[28:29]
	s_add_i32 m0, s64, 0xe000
	s_nop 0
	global_load_lds_dwordx4 v220, s[28:29]
	s_waitcnt vmcnt(8)
	s_waitcnt lgkmcnt(0)
	s_barrier
	v_mfma_f32_16x16x32_bf16 v[126:129], v[130:133], v[162:165], 0
	v_mfma_f32_16x16x32_bf16 v[122:125], v[138:141], v[162:165], 0
	v_mfma_f32_16x16x32_bf16 v[110:113], v[130:133], v[170:173], 0
	v_mfma_f32_16x16x32_bf16 v[106:109], v[138:141], v[170:173], 0
	v_mfma_f32_16x16x32_bf16 v[94:97], v[130:133], v[178:181], 0
	v_mfma_f32_16x16x32_bf16 v[90:93], v[138:141], v[178:181], 0
	v_mfma_f32_16x16x32_bf16 v[78:81], v[130:133], v[186:189], 0
	v_mfma_f32_16x16x32_bf16 v[74:77], v[138:141], v[186:189], 0
	v_mfma_f32_16x16x32_bf16 v[126:129], v[134:137], v[166:169], v[126:129]
	v_mfma_f32_16x16x32_bf16 v[122:125], v[142:145], v[166:169], v[122:125]
	v_mfma_f32_16x16x32_bf16 v[110:113], v[134:137], v[174:177], v[110:113]
	v_mfma_f32_16x16x32_bf16 v[106:109], v[142:145], v[174:177], v[106:109]
	v_mfma_f32_16x16x32_bf16 v[94:97], v[134:137], v[182:185], v[94:97]
	v_mfma_f32_16x16x32_bf16 v[90:93], v[142:145], v[182:185], v[90:93]
	v_mfma_f32_16x16x32_bf16 v[78:81], v[134:137], v[190:193], v[78:81]
	v_mfma_f32_16x16x32_bf16 v[74:77], v[142:145], v[190:193], v[74:77]
	v_mfma_f32_16x16x32_bf16 v[118:121], v[146:149], v[162:165], 0
	v_mfma_f32_16x16x32_bf16 v[114:117], v[154:157], v[162:165], 0
	v_mfma_f32_16x16x32_bf16 v[102:105], v[146:149], v[170:173], 0
	v_mfma_f32_16x16x32_bf16 v[98:101], v[154:157], v[170:173], 0
	v_mfma_f32_16x16x32_bf16 v[86:89], v[146:149], v[178:181], 0
	v_mfma_f32_16x16x32_bf16 v[82:85], v[154:157], v[178:181], 0
	v_mfma_f32_16x16x32_bf16 v[70:73], v[146:149], v[186:189], 0
	v_mfma_f32_16x16x32_bf16 v[66:69], v[154:157], v[186:189], 0
	v_mfma_f32_16x16x32_bf16 v[118:121], v[150:153], v[166:169], v[118:121]
	v_mfma_f32_16x16x32_bf16 v[114:117], v[158:161], v[166:169], v[114:117]
	v_mfma_f32_16x16x32_bf16 v[102:105], v[150:153], v[174:177], v[102:105]
	v_mfma_f32_16x16x32_bf16 v[98:101], v[158:161], v[174:177], v[98:101]
	v_mfma_f32_16x16x32_bf16 v[86:89], v[150:153], v[182:185], v[86:89]
	v_mfma_f32_16x16x32_bf16 v[82:85], v[158:161], v[182:185], v[82:85]
	v_mfma_f32_16x16x32_bf16 v[70:73], v[150:153], v[190:193], v[70:73]
	v_mfma_f32_16x16x32_bf16 v[66:69], v[158:161], v[190:193], v[66:69]
	s_barrier
	s_add_i32 s46, s46, s8
	s_add_u32 s98, s30, 0x80
	s_addc_u32 s99, s31, 0
	s_mov_b32 m0, s46
	ds_read_b128 v[162:165], v208 offset:16384
	ds_read_b128 v[166:169], v208 offset:17408
	ds_read_b128 v[170:173], v208 offset:18432
	ds_read_b128 v[174:177], v208 offset:19456
	ds_read_b128 v[178:181], v208 offset:20480
	ds_read_b128 v[182:185], v208 offset:21504
	ds_read_b128 v[186:189], v208 offset:22528
	ds_read_b128 v[190:193], v208 offset:23552
	global_load_lds_dwordx4 v204, s[30:31]
	s_add_i32 m0, s46, 0x2000
	s_add_u32 s46, s30, 0x80000
	s_addc_u32 s47, s31, 0
	s_add_i32 vcc_hi, vcc_hi, s8
	global_load_lds_dwordx4 v216, s[30:31]
	s_mov_b32 m0, vcc_hi
	s_add_u32 s100, s34, 0x80
	s_addc_u32 s101, s35, 0
	global_load_lds_dwordx4 v204, s[46:47]
	s_add_i32 m0, vcc_hi, 0x2000
	s_nop 0
	global_load_lds_dwordx4 v216, s[46:47]
	s_mov_b32 m0, s64
	s_nop 0
	global_load_lds_dwordx4 v202, s[34:35]
	s_waitcnt vmcnt(7)
	s_waitcnt lgkmcnt(0)
	s_barrier
; #define PG8_STAGE(bufoff, gbase, voff) do { _Pragma("unroll") for (int _i = 0; _i < 2; ++_i) \
;         __builtin_amdgcn_global_load_lds((const unsigned*)((const char*)(gbase) + (voff)[_i]), (PG8_LAS unsigned*)(lds + (bufoff) + ldsw + _i * 8192), 16, 0, 0); } while (0)
; #define PG8_LDA(dst, b, h) do { _Pragma("unroll") for (int m = 0; m < 4; ++m) _Pragma("unroll") for (int k = 0; k < 2; ++k) dst[m][k] = *(const PG8_LAS bf16x8*)(lds + PG8_SA(b, h) + aoff + m * 2048 + k * 1024); } while (0)
; #define PG8_LDB(dst, b, h) do { _Pragma("unroll") for (int n = 0; n < 2; ++n) _Pragma("unroll") for (int k = 0; k < 2; ++k) dst[n][k] = *(const PG8_LAS bf16x8*)(lds + PG8_SB(b, h) + boff + n * 2048 + k * 1024); } while (0)
; #define PG8_MMA(ai, bj, At, Bt) do { __builtin_amdgcn_s_setprio(1); _Pragma("unroll") for (int m = 0; m < 4; ++m) _Pragma("unroll") for (int n = 0; n < 2; ++n) _Pragma("unroll") for (int k = 0; k < 2; ++k) \
;         acc[ai][bj][m][n] = __builtin_amdgcn_mfma_f32_16x16x32_bf16(Bt[n][k], At[m][k], acc[ai][bj][m][n], 0, 0, 0); __builtin_amdgcn_s_setprio(0); } while (0)
; template <class Epi, class Sched, bool ALIGN_EPI = false, bool SP2 = false>
; __device__ __forceinline__ void gemm_phase(PG8_LAS unsigned char* lds, const Gemm g, const Sched& S, const Epi& E, const int tid_in) {
;     ...
;             if constexpr (SP2) {
;             PG8_LDB(B0, 0, 0); PG8_LDB(B1, 0, 1); PG8_SCHED; PG8_LDA(At, 0, 0); PG8_STAGE(PG8_SA(1, 1), a1 + hstep, voffA);
;             PG8_WAIT_V(8); PG8_WAIT_L(0); PG8_BAR; PG8_MMA(0, 0, At, B0); PG8_MMA(0, 1, At, B1); PG8_BAR; PG8_SCHED;
;             PG8_LDA(At, 0, 1); PG8_STAGE(PG8_SB(0, 0), b2, voffB); PG8_STAGE(PG8_SB(0, 1), b2 + hstep, voffB); PG8_STAGE(PG8_SA(0, 0), a2, voffA);
;             PG8_WAIT_V(8); PG8_WAIT_L(0); PG8_BAR; PG8_MMA(1, 0, At, B0); PG8_MMA(1, 1, At, B1); PG8_BAR; PG8_SCHED;
;             PG8_LDB(B0, 1, 0); PG8_LDB(B1, 1, 1); PG8_SCHED; PG8_LDA(At, 1, 0); PG8_STAGE(PG8_SA(0, 1), a2 + hstep, voffA);
;             PG8_WAIT_V(8); PG8_WAIT_L(0); PG8_BAR; PG8_MMA(0, 0, At, B0); PG8_MMA(0, 1, At, B1); PG8_BAR; PG8_SCHED;
;             PG8_LDA(At, 1, 1); PG8_STAGE(PG8_SB(1, 0), b3, voffB); PG8_STAGE(PG8_SB(1, 1), b3 + hstep, voffB); PG8_STAGE(PG8_SA(1, 0), a3, voffA);
;             PG8_WAIT_V(8); PG8_WAIT_L(0); PG8_BAR; PG8_MMA(1, 0, At, B0); PG8_MMA(1, 1, At, B1); PG8_BAR; PG8_SCHED;
	v_mfma_f32_16x16x32_bf16 v[62:65], v[130:133], v[162:165], 0
	v_mfma_f32_16x16x32_bf16 v[58:61], v[138:141], v[162:165], 0
	v_mfma_f32_16x16x32_bf16 v[46:49], v[130:133], v[170:173], 0
	v_mfma_f32_16x16x32_bf16 v[42:45], v[138:141], v[170:173], 0
	v_mfma_f32_16x16x32_bf16 v[30:33], v[130:133], v[178:181], 0
	v_mfma_f32_16x16x32_bf16 v[26:29], v[138:141], v[178:181], 0
	v_mfma_f32_16x16x32_bf16 v[12:15], v[130:133], v[186:189], 0
	v_mfma_f32_16x16x32_bf16 v[8:11], v[138:141], v[186:189], 0
	v_mfma_f32_16x16x32_bf16 v[62:65], v[134:137], v[166:169], v[62:65]
	v_mfma_f32_16x16x32_bf16 v[58:61], v[142:145], v[166:169], v[58:61]
	v_mfma_f32_16x16x32_bf16 v[46:49], v[134:137], v[174:177], v[46:49]
	v_mfma_f32_16x16x32_bf16 v[42:45], v[142:145], v[174:177], v[42:45]
	v_mfma_f32_16x16x32_bf16 v[30:33], v[134:137], v[182:185], v[30:33]
	v_mfma_f32_16x16x32_bf16 v[26:29], v[142:145], v[182:185], v[26:29]
	v_mfma_f32_16x16x32_bf16 v[12:15], v[134:137], v[190:193], v[12:15]
	v_mfma_f32_16x16x32_bf16 v[8:11], v[142:145], v[190:193], v[8:11]
	v_mfma_f32_16x16x32_bf16 v[54:57], v[146:149], v[162:165], 0
	v_mfma_f32_16x16x32_bf16 v[50:53], v[154:157], v[162:165], 0
	v_mfma_f32_16x16x32_bf16 v[38:41], v[146:149], v[170:173], 0
	v_mfma_f32_16x16x32_bf16 v[34:37], v[154:157], v[170:173], 0
	v_mfma_f32_16x16x32_bf16 v[22:25], v[146:149], v[178:181], 0
	v_mfma_f32_16x16x32_bf16 v[16:19], v[154:157], v[178:181], 0
	v_mfma_f32_16x16x32_bf16 v[4:7], v[146:149], v[186:189], 0
	v_mfma_f32_16x16x32_bf16 v[0:3], v[154:157], v[186:189], 0
	v_mfma_f32_16x16x32_bf16 v[54:57], v[150:153], v[166:169], v[54:57]
	v_mfma_f32_16x16x32_bf16 v[50:53], v[158:161], v[166:169], v[50:53]
	v_mfma_f32_16x16x32_bf16 v[38:41], v[150:153], v[174:177], v[38:41]
	v_mfma_f32_16x16x32_bf16 v[34:37], v[158:161], v[174:177], v[34:37]
	v_mfma_f32_16x16x32_bf16 v[22:25], v[150:153], v[182:185], v[22:25]
	v_mfma_f32_16x16x32_bf16 v[16:19], v[158:161], v[182:185], v[16:19]
	v_mfma_f32_16x16x32_bf16 v[4:7], v[150:153], v[190:193], v[4:7]
	v_mfma_f32_16x16x32_bf16 v[0:3], v[158:161], v[190:193], v[0:3]
	s_barrier
	s_add_i32 s46, 0, 0x18000
	s_add_i32 s47, 0, 0x1c000
	v_add_u32_e32 v142, s46, v21
	v_add_u32_e32 v158, s47, v21
	ds_read_b128 v[130:133], v142
	ds_read_b128 v[134:137], v142 offset:1024
	ds_read_b128 v[138:141], v142 offset:2048
	ds_read_b128 v[142:145], v142 offset:3072
	ds_read_b128 v[146:149], v158
	ds_read_b128 v[150:153], v158 offset:1024
	ds_read_b128 v[154:157], v158 offset:2048
	ds_read_b128 v[158:161], v158 offset:3072
	s_mov_b32 m0, s65
	s_nop 0
	global_load_lds_dwordx4 v214, s[34:35]
	s_add_u32 s34, s34, 0x80000
	s_addc_u32 s35, s35, 0
	s_mov_b32 m0, s66
	ds_read_b128 v[162:165], v208 offset:32768
	ds_read_b128 v[166:169], v208 offset:33792
	ds_read_b128 v[170:173], v208 offset:34816
	ds_read_b128 v[174:177], v208 offset:35840
	ds_read_b128 v[178:181], v208 offset:36864
	ds_read_b128 v[182:185], v208 offset:37888
	ds_read_b128 v[186:189], v208 offset:38912
	ds_read_b128 v[190:193], v208 offset:39936
	global_load_lds_dwordx4 v202, s[34:35]
	s_mov_b32 m0, s67
	s_nop 0
	global_load_lds_dwordx4 v214, s[34:35]
	s_waitcnt vmcnt(8)
	s_waitcnt lgkmcnt(0)
	s_barrier
	v_mfma_f32_16x16x32_bf16 v[126:129], v[130:133], v[162:165], v[126:129]
	v_mfma_f32_16x16x32_bf16 v[122:125], v[138:141], v[162:165], v[122:125]
	v_mfma_f32_16x16x32_bf16 v[110:113], v[130:133], v[170:173], v[110:113]
	v_mfma_f32_16x16x32_bf16 v[106:109], v[138:141], v[170:173], v[106:109]
	v_mfma_f32_16x16x32_bf16 v[94:97], v[130:133], v[178:181], v[94:97]
	v_mfma_f32_16x16x32_bf16 v[90:93], v[138:141], v[178:181], v[90:93]
	v_mfma_f32_16x16x32_bf16 v[78:81], v[130:133], v[186:189], v[78:81]
	v_mfma_f32_16x16x32_bf16 v[74:77], v[138:141], v[186:189], v[74:77]
	v_mfma_f32_16x16x32_bf16 v[126:129], v[134:137], v[166:169], v[126:129]
	v_mfma_f32_16x16x32_bf16 v[122:125], v[142:145], v[166:169], v[122:125]
	v_mfma_f32_16x16x32_bf16 v[110:113], v[134:137], v[174:177], v[110:113]
	v_mfma_f32_16x16x32_bf16 v[106:109], v[142:145], v[174:177], v[106:109]
	v_mfma_f32_16x16x32_bf16 v[94:97], v[134:137], v[182:185], v[94:97]
	v_mfma_f32_16x16x32_bf16 v[90:93], v[142:145], v[182:185], v[90:93]
	v_mfma_f32_16x16x32_bf16 v[78:81], v[134:137], v[190:193], v[78:81]
	v_mfma_f32_16x16x32_bf16 v[74:77], v[142:145], v[190:193], v[74:77]
	v_mfma_f32_16x16x32_bf16 v[118:121], v[146:149], v[162:165], v[118:121]
	v_mfma_f32_16x16x32_bf16 v[114:117], v[154:157], v[162:165], v[114:117]
	v_mfma_f32_16x16x32_bf16 v[102:105], v[146:149], v[170:173], v[102:105]
	v_mfma_f32_16x16x32_bf16 v[98:101], v[154:157], v[170:173], v[98:101]
	v_mfma_f32_16x16x32_bf16 v[86:89], v[146:149], v[178:181], v[86:89]
	v_mfma_f32_16x16x32_bf16 v[82:85], v[154:157], v[178:181], v[82:85]
	v_mfma_f32_16x16x32_bf16 v[70:73], v[146:149], v[186:189], v[70:73]
	v_mfma_f32_16x16x32_bf16 v[66:69], v[154:157], v[186:189], v[66:69]
	v_mfma_f32_16x16x32_bf16 v[118:121], v[150:153], v[166:169], v[118:121]
	v_mfma_f32_16x16x32_bf16 v[114:117], v[158:161], v[166:169], v[114:117]
	v_mfma_f32_16x16x32_bf16 v[102:105], v[150:153], v[174:177], v[102:105]
	v_mfma_f32_16x16x32_bf16 v[98:101], v[158:161], v[174:177], v[98:101]
	v_mfma_f32_16x16x32_bf16 v[86:89], v[150:153], v[182:185], v[86:89]
	v_mfma_f32_16x16x32_bf16 v[82:85], v[158:161], v[182:185], v[82:85]
	v_mfma_f32_16x16x32_bf16 v[70:73], v[150:153], v[190:193], v[70:73]
	v_mfma_f32_16x16x32_bf16 v[66:69], v[158:161], v[190:193], v[66:69]
	s_barrier
; #define PG8_STAGE(bufoff, gbase, voff) do { _Pragma("unroll") for (int _i = 0; _i < 2; ++_i) \
;         __builtin_amdgcn_global_load_lds((const unsigned*)((const char*)(gbase) + (voff)[_i]), (PG8_LAS unsigned*)(lds + (bufoff) + ldsw + _i * 8192), 16, 0, 0); } while (0)
; #define PG8_LDA(dst, b, h) do { _Pragma("unroll") for (int m = 0; m < 4; ++m) _Pragma("unroll") for (int k = 0; k < 2; ++k) dst[m][k] = *(const PG8_LAS bf16x8*)(lds + PG8_SA(b, h) + aoff + m * 2048 + k * 1024); } while (0)
; #define PG8_LDB(dst, b, h) do { _Pragma("unroll") for (int n = 0; n < 2; ++n) _Pragma("unroll") for (int k = 0; k < 2; ++k) dst[n][k] = *(const PG8_LAS bf16x8*)(lds + PG8_SB(b, h) + boff + n * 2048 + k * 1024); } while (0)
; #define PG8_MMA(ai, bj, At, Bt) do { __builtin_amdgcn_s_setprio(1); _Pragma("unroll") for (int m = 0; m < 4; ++m) _Pragma("unroll") for (int n = 0; n < 2; ++n) _Pragma("unroll") for (int k = 0; k < 2; ++k) \
;         acc[ai][bj][m][n] = __builtin_amdgcn_mfma_f32_16x16x32_bf16(Bt[n][k], At[m][k], acc[ai][bj][m][n], 0, 0, 0); __builtin_amdgcn_s_setprio(0); } while (0)
; template <class Epi, class Sched, bool ALIGN_EPI = false, bool SP2 = false>
; __device__ __forceinline__ void gemm_phase(PG8_LAS unsigned char* lds, const Gemm g, const Sched& S, const Epi& E, const int tid_in) {
;     ...
;             if constexpr (SP2) {
;             PG8_LDB(B0, 0, 0); PG8_LDB(B1, 0, 1); PG8_SCHED; PG8_LDA(At, 0, 0); PG8_STAGE(PG8_SA(1, 1), a1 + hstep, voffA);
;             PG8_WAIT_V(8); PG8_WAIT_L(0); PG8_BAR; PG8_MMA(0, 0, At, B0); PG8_MMA(0, 1, At, B1); PG8_BAR; PG8_SCHED;
;             PG8_LDA(At, 0, 1); PG8_STAGE(PG8_SB(0, 0), b2, voffB); PG8_STAGE(PG8_SB(0, 1), b2 + hstep, voffB); PG8_STAGE(PG8_SA(0, 0), a2, voffA);
;             PG8_WAIT_V(8); PG8_WAIT_L(0); PG8_BAR; PG8_MMA(1, 0, At, B0); PG8_MMA(1, 1, At, B1); PG8_BAR; PG8_SCHED;
;             PG8_LDB(B0, 1, 0); PG8_LDB(B1, 1, 1); PG8_SCHED; PG8_LDA(At, 1, 0); PG8_STAGE(PG8_SA(0, 1), a2 + hstep, voffA);
;             PG8_WAIT_V(8); PG8_WAIT_L(0); PG8_BAR; PG8_MMA(0, 0, At, B0); PG8_MMA(0, 1, At, B1); PG8_BAR; PG8_SCHED;
;             PG8_LDA(At, 1, 1); PG8_STAGE(PG8_SB(1, 0), b3, voffB); PG8_STAGE(PG8_SB(1, 1), b3 + hstep, voffB); PG8_STAGE(PG8_SA(1, 0), a3, voffA);
;             PG8_WAIT_V(8); PG8_WAIT_L(0); PG8_BAR; PG8_MMA(1, 0, At, B0); PG8_MMA(1, 1, At, B1); PG8_BAR; PG8_SCHED;
	s_add_i32 s34, s46, s8
	s_mov_b32 m0, s34
	ds_read_b128 v[162:165], v208 offset:49152
	ds_read_b128 v[166:169], v208 offset:50176
	ds_read_b128 v[170:173], v208 offset:51200
	ds_read_b128 v[174:177], v208 offset:52224
	ds_read_b128 v[178:181], v208 offset:53248
	ds_read_b128 v[182:185], v208 offset:54272
	ds_read_b128 v[186:189], v208 offset:55296
	ds_read_b128 v[190:193], v208 offset:56320
	global_load_lds_dwordx4 v204, s[98:99]
	s_add_i32 m0, s34, 0x2000
	s_add_u32 s30, s30, 0x80080
	s_addc_u32 s31, s31, 0
	s_add_i32 s34, s47, s8
	global_load_lds_dwordx4 v216, s[98:99]
	s_mov_b32 m0, s34
	s_nop 0
	global_load_lds_dwordx4 v204, s[30:31]
	s_add_i32 m0, s34, 0x2000
	s_nop 0
	global_load_lds_dwordx4 v216, s[30:31]
	s_mov_b32 m0, s75
	s_nop 0
	global_load_lds_dwordx4 v202, s[100:101]
	s_waitcnt vmcnt(7)
	s_waitcnt lgkmcnt(0)
	s_barrier
	v_mfma_f32_16x16x32_bf16 v[62:65], v[130:133], v[162:165], v[62:65]
	v_mfma_f32_16x16x32_bf16 v[58:61], v[138:141], v[162:165], v[58:61]
	v_mfma_f32_16x16x32_bf16 v[46:49], v[130:133], v[170:173], v[46:49]
	v_mfma_f32_16x16x32_bf16 v[42:45], v[138:141], v[170:173], v[42:45]
	v_mfma_f32_16x16x32_bf16 v[30:33], v[130:133], v[178:181], v[30:33]
	v_mfma_f32_16x16x32_bf16 v[26:29], v[138:141], v[178:181], v[26:29]
	v_mfma_f32_16x16x32_bf16 v[12:15], v[130:133], v[186:189], v[12:15]
	v_mfma_f32_16x16x32_bf16 v[8:11], v[138:141], v[186:189], v[8:11]
	v_mfma_f32_16x16x32_bf16 v[62:65], v[134:137], v[166:169], v[62:65]
	v_mfma_f32_16x16x32_bf16 v[58:61], v[142:145], v[166:169], v[58:61]
	v_mfma_f32_16x16x32_bf16 v[46:49], v[134:137], v[174:177], v[46:49]
	v_mfma_f32_16x16x32_bf16 v[42:45], v[142:145], v[174:177], v[42:45]
	v_mfma_f32_16x16x32_bf16 v[30:33], v[134:137], v[182:185], v[30:33]
	v_mfma_f32_16x16x32_bf16 v[26:29], v[142:145], v[182:185], v[26:29]
	v_mfma_f32_16x16x32_bf16 v[12:15], v[134:137], v[190:193], v[12:15]
	v_mfma_f32_16x16x32_bf16 v[8:11], v[142:145], v[190:193], v[8:11]
	v_mfma_f32_16x16x32_bf16 v[54:57], v[146:149], v[162:165], v[54:57]
	v_mfma_f32_16x16x32_bf16 v[50:53], v[154:157], v[162:165], v[50:53]
	v_mfma_f32_16x16x32_bf16 v[38:41], v[146:149], v[170:173], v[38:41]
	v_mfma_f32_16x16x32_bf16 v[34:37], v[154:157], v[170:173], v[34:37]
	v_mfma_f32_16x16x32_bf16 v[22:25], v[146:149], v[178:181], v[22:25]
	v_mfma_f32_16x16x32_bf16 v[16:19], v[154:157], v[178:181], v[16:19]
	v_mfma_f32_16x16x32_bf16 v[4:7], v[146:149], v[186:189], v[4:7]
	v_mfma_f32_16x16x32_bf16 v[0:3], v[154:157], v[186:189], v[0:3]
	v_mfma_f32_16x16x32_bf16 v[54:57], v[150:153], v[166:169], v[54:57]
	v_mfma_f32_16x16x32_bf16 v[50:53], v[158:161], v[166:169], v[50:53]
	v_mfma_f32_16x16x32_bf16 v[38:41], v[150:153], v[174:177], v[38:41]
	v_mfma_f32_16x16x32_bf16 v[34:37], v[158:161], v[174:177], v[34:37]
	v_mfma_f32_16x16x32_bf16 v[22:25], v[150:153], v[182:185], v[22:25]
	v_mfma_f32_16x16x32_bf16 v[16:19], v[158:161], v[182:185], v[16:19]
	v_mfma_f32_16x16x32_bf16 v[4:7], v[150:153], v[190:193], v[4:7]
	v_mfma_f32_16x16x32_bf16 v[0:3], v[158:161], v[190:193], v[0:3]
	s_barrier
	s_add_i32 vcc_lo, vcc_lo, 2
	s_add_u32 s28, s28, 0x100
	s_addc_u32 s29, s29, 0
	s_add_u32 s57, s57, 0x100
	s_addc_u32 s92, s92, 0
	s_cmp_gt_u32 vcc_lo, 29
.LBB0_1037:
	s_mov_b32 m0, s76
	s_nop 0
	global_load_lds_dwordx4 v214, s[100:101]
	s_add_u32 s30, s28, 0xfff80080
	s_addc_u32 s31, s29, -1
	s_add_i32 s46, 0, 0x10000
	s_cmp_eq_u32 vcc_lo, 28
	s_cselect_b32 s35, s38, s31
	s_cselect_b32 s34, s39, s30
	s_cselect_b32 s31, s40, s92
	s_cselect_b32 s30, s41, s57
	s_add_i32 vcc_hi, 0, 0x14000
	v_add_u32_e32 v142, s46, v21
	v_add_u32_e32 v158, vcc_hi, v21
	ds_read_b128 v[130:133], v142
	ds_read_b128 v[134:137], v142 offset:1024
	ds_read_b128 v[138:141], v142 offset:2048
	ds_read_b128 v[142:145], v142 offset:3072
	ds_read_b128 v[146:149], v158
	ds_read_b128 v[150:153], v158 offset:1024
	ds_read_b128 v[154:157], v158 offset:2048
	ds_read_b128 v[158:161], v158 offset:3072
	s_add_i32 m0, s64, 0xc000
	ds_read_b128 v[162:165], v208
	ds_read_b128 v[166:169], v208 offset:1024
	ds_read_b128 v[170:173], v208 offset:2048
	ds_read_b128 v[174:177], v208 offset:3072
	ds_read_b128 v[178:181], v208 offset:4096
	ds_read_b128 v[182:185], v208 offset:5120
	ds_read_b128 v[186:189], v208 offset:6144
	ds_read_b128 v[190:193], v208 offset:7168
	global_load_lds_dwordx4 v218, s[28:29]
	s_add_i32 m0, s64, 0xe000
	s_nop 0
	global_load_lds_dwordx4 v220, s[28:29]
	s_waitcnt vmcnt(8)
	s_waitcnt lgkmcnt(0)
	s_barrier
	v_mfma_f32_16x16x32_bf16 v[126:129], v[130:133], v[162:165], v[126:129]
	v_mfma_f32_16x16x32_bf16 v[122:125], v[138:141], v[162:165], v[122:125]
	v_mfma_f32_16x16x32_bf16 v[110:113], v[130:133], v[170:173], v[110:113]
	v_mfma_f32_16x16x32_bf16 v[106:109], v[138:141], v[170:173], v[106:109]
	v_mfma_f32_16x16x32_bf16 v[94:97], v[130:133], v[178:181], v[94:97]
	v_mfma_f32_16x16x32_bf16 v[90:93], v[138:141], v[178:181], v[90:93]
	v_mfma_f32_16x16x32_bf16 v[78:81], v[130:133], v[186:189], v[78:81]
	v_mfma_f32_16x16x32_bf16 v[74:77], v[138:141], v[186:189], v[74:77]
	v_mfma_f32_16x16x32_bf16 v[126:129], v[134:137], v[166:169], v[126:129]
	v_mfma_f32_16x16x32_bf16 v[122:125], v[142:145], v[166:169], v[122:125]
	v_mfma_f32_16x16x32_bf16 v[110:113], v[134:137], v[174:177], v[110:113]
	v_mfma_f32_16x16x32_bf16 v[106:109], v[142:145], v[174:177], v[106:109]
	v_mfma_f32_16x16x32_bf16 v[94:97], v[134:137], v[182:185], v[94:97]
	v_mfma_f32_16x16x32_bf16 v[90:93], v[142:145], v[182:185], v[90:93]
	v_mfma_f32_16x16x32_bf16 v[78:81], v[134:137], v[190:193], v[78:81]
	v_mfma_f32_16x16x32_bf16 v[74:77], v[142:145], v[190:193], v[74:77]
	v_mfma_f32_16x16x32_bf16 v[118:121], v[146:149], v[162:165], v[118:121]
	v_mfma_f32_16x16x32_bf16 v[114:117], v[154:157], v[162:165], v[114:117]
	v_mfma_f32_16x16x32_bf16 v[102:105], v[146:149], v[170:173], v[102:105]
	v_mfma_f32_16x16x32_bf16 v[98:101], v[154:157], v[170:173], v[98:101]
	v_mfma_f32_16x16x32_bf16 v[86:89], v[146:149], v[178:181], v[86:89]
	v_mfma_f32_16x16x32_bf16 v[82:85], v[154:157], v[178:181], v[82:85]
	v_mfma_f32_16x16x32_bf16 v[70:73], v[146:149], v[186:189], v[70:73]
	v_mfma_f32_16x16x32_bf16 v[66:69], v[154:157], v[186:189], v[66:69]
	v_mfma_f32_16x16x32_bf16 v[118:121], v[150:153], v[166:169], v[118:121]
	v_mfma_f32_16x16x32_bf16 v[114:117], v[158:161], v[166:169], v[114:117]
	v_mfma_f32_16x16x32_bf16 v[102:105], v[150:153], v[174:177], v[102:105]
	v_mfma_f32_16x16x32_bf16 v[98:101], v[158:161], v[174:177], v[98:101]
	v_mfma_f32_16x16x32_bf16 v[86:89], v[150:153], v[182:185], v[86:89]
	v_mfma_f32_16x16x32_bf16 v[82:85], v[158:161], v[182:185], v[82:85]
	v_mfma_f32_16x16x32_bf16 v[70:73], v[150:153], v[190:193], v[70:73]
	v_mfma_f32_16x16x32_bf16 v[66:69], v[158:161], v[190:193], v[66:69]
	s_barrier
; #define PG8_STAGE(bufoff, gbase, voff) do { _Pragma("unroll") for (int _i = 0; _i < 2; ++_i) \
;         __builtin_amdgcn_global_load_lds((const unsigned*)((const char*)(gbase) + (voff)[_i]), (PG8_LAS unsigned*)(lds + (bufoff) + ldsw + _i * 8192), 16, 0, 0); } while (0)
; #define PG8_LDA(dst, b, h) do { _Pragma("unroll") for (int m = 0; m < 4; ++m) _Pragma("unroll") for (int k = 0; k < 2; ++k) dst[m][k] = *(const PG8_LAS bf16x8*)(lds + PG8_SA(b, h) + aoff + m * 2048 + k * 1024); } while (0)
; #define PG8_LDB(dst, b, h) do { _Pragma("unroll") for (int n = 0; n < 2; ++n) _Pragma("unroll") for (int k = 0; k < 2; ++k) dst[n][k] = *(const PG8_LAS bf16x8*)(lds + PG8_SB(b, h) + boff + n * 2048 + k * 1024); } while (0)
; #define PG8_MMA(ai, bj, At, Bt) do { __builtin_amdgcn_s_setprio(1); _Pragma("unroll") for (int m = 0; m < 4; ++m) _Pragma("unroll") for (int n = 0; n < 2; ++n) _Pragma("unroll") for (int k = 0; k < 2; ++k) \
;         acc[ai][bj][m][n] = __builtin_amdgcn_mfma_f32_16x16x32_bf16(Bt[n][k], At[m][k], acc[ai][bj][m][n], 0, 0, 0); __builtin_amdgcn_s_setprio(0); } while (0)
; template <class Epi, class Sched, bool ALIGN_EPI = false, bool SP2 = false>
; __device__ __forceinline__ void gemm_phase(PG8_LAS unsigned char* lds, const Gemm g, const Sched& S, const Epi& E, const int tid_in) {
;     ...
;             if constexpr (SP2) {
;             PG8_LDB(B0, 0, 0); PG8_LDB(B1, 0, 1); PG8_SCHED; PG8_LDA(At, 0, 0); PG8_STAGE(PG8_SA(1, 1), a1 + hstep, voffA);
;             PG8_WAIT_V(8); PG8_WAIT_L(0); PG8_BAR; PG8_MMA(0, 0, At, B0); PG8_MMA(0, 1, At, B1); PG8_BAR; PG8_SCHED;
;             PG8_LDA(At, 0, 1); PG8_STAGE(PG8_SB(0, 0), b2, voffB); PG8_STAGE(PG8_SB(0, 1), b2 + hstep, voffB); PG8_STAGE(PG8_SA(0, 0), a2, voffA);
;             PG8_WAIT_V(8); PG8_WAIT_L(0); PG8_BAR; PG8_MMA(1, 0, At, B0); PG8_MMA(1, 1, At, B1); PG8_BAR; PG8_SCHED;
;             PG8_LDB(B0, 1, 0); PG8_LDB(B1, 1, 1); PG8_SCHED; PG8_LDA(At, 1, 0); PG8_STAGE(PG8_SA(0, 1), a2 + hstep, voffA);
;             PG8_WAIT_V(8); PG8_WAIT_L(0); PG8_BAR; PG8_MMA(0, 0, At, B0); PG8_MMA(0, 1, At, B1); PG8_BAR; PG8_SCHED;
;             PG8_LDA(At, 1, 1); PG8_STAGE(PG8_SB(1, 0), b3, voffB); PG8_STAGE(PG8_SB(1, 1), b3 + hstep, voffB); PG8_STAGE(PG8_SA(1, 0), a3, voffA);
;             PG8_WAIT_V(8); PG8_WAIT_L(0); PG8_BAR; PG8_MMA(1, 0, At, B0); PG8_MMA(1, 1, At, B1); PG8_BAR; PG8_SCHED;
	s_add_i32 s46, s46, s8
	s_add_u32 s98, s30, 0x80
	s_addc_u32 s99, s31, 0
	s_mov_b32 m0, s46
	ds_read_b128 v[162:165], v208 offset:16384
	ds_read_b128 v[166:169], v208 offset:17408
	ds_read_b128 v[170:173], v208 offset:18432
	ds_read_b128 v[174:177], v208 offset:19456
	ds_read_b128 v[178:181], v208 offset:20480
	ds_read_b128 v[182:185], v208 offset:21504
	ds_read_b128 v[186:189], v208 offset:22528
	ds_read_b128 v[190:193], v208 offset:23552
	global_load_lds_dwordx4 v204, s[30:31]
	s_add_i32 m0, s46, 0x2000
	s_add_u32 s46, s30, 0x80000
	s_addc_u32 s47, s31, 0
	s_add_i32 vcc_hi, vcc_hi, s8
	global_load_lds_dwordx4 v216, s[30:31]
	s_mov_b32 m0, vcc_hi
	s_add_u32 s100, s34, 0x80
	s_addc_u32 s101, s35, 0
	global_load_lds_dwordx4 v204, s[46:47]
	s_add_i32 m0, vcc_hi, 0x2000
	s_nop 0
	global_load_lds_dwordx4 v216, s[46:47]
	s_mov_b32 m0, s64
	s_nop 0
	global_load_lds_dwordx4 v202, s[34:35]
	s_waitcnt vmcnt(7)
	s_waitcnt lgkmcnt(0)
	s_barrier
	v_mfma_f32_16x16x32_bf16 v[62:65], v[130:133], v[162:165], v[62:65]
	v_mfma_f32_16x16x32_bf16 v[58:61], v[138:141], v[162:165], v[58:61]
	v_mfma_f32_16x16x32_bf16 v[46:49], v[130:133], v[170:173], v[46:49]
	v_mfma_f32_16x16x32_bf16 v[42:45], v[138:141], v[170:173], v[42:45]
	v_mfma_f32_16x16x32_bf16 v[30:33], v[130:133], v[178:181], v[30:33]
	v_mfma_f32_16x16x32_bf16 v[26:29], v[138:141], v[178:181], v[26:29]
	v_mfma_f32_16x16x32_bf16 v[12:15], v[130:133], v[186:189], v[12:15]
	v_mfma_f32_16x16x32_bf16 v[8:11], v[138:141], v[186:189], v[8:11]
	v_mfma_f32_16x16x32_bf16 v[62:65], v[134:137], v[166:169], v[62:65]
	v_mfma_f32_16x16x32_bf16 v[58:61], v[142:145], v[166:169], v[58:61]
	v_mfma_f32_16x16x32_bf16 v[46:49], v[134:137], v[174:177], v[46:49]
	v_mfma_f32_16x16x32_bf16 v[42:45], v[142:145], v[174:177], v[42:45]
	v_mfma_f32_16x16x32_bf16 v[30:33], v[134:137], v[182:185], v[30:33]
	v_mfma_f32_16x16x32_bf16 v[26:29], v[142:145], v[182:185], v[26:29]
	v_mfma_f32_16x16x32_bf16 v[12:15], v[134:137], v[190:193], v[12:15]
	v_mfma_f32_16x16x32_bf16 v[8:11], v[142:145], v[190:193], v[8:11]
	v_mfma_f32_16x16x32_bf16 v[54:57], v[146:149], v[162:165], v[54:57]
	v_mfma_f32_16x16x32_bf16 v[50:53], v[154:157], v[162:165], v[50:53]
	v_mfma_f32_16x16x32_bf16 v[38:41], v[146:149], v[170:173], v[38:41]
	v_mfma_f32_16x16x32_bf16 v[34:37], v[154:157], v[170:173], v[34:37]
	v_mfma_f32_16x16x32_bf16 v[22:25], v[146:149], v[178:181], v[22:25]
	v_mfma_f32_16x16x32_bf16 v[16:19], v[154:157], v[178:181], v[16:19]
	v_mfma_f32_16x16x32_bf16 v[4:7], v[146:149], v[186:189], v[4:7]
	v_mfma_f32_16x16x32_bf16 v[0:3], v[154:157], v[186:189], v[0:3]
	v_mfma_f32_16x16x32_bf16 v[54:57], v[150:153], v[166:169], v[54:57]
	v_mfma_f32_16x16x32_bf16 v[50:53], v[158:161], v[166:169], v[50:53]
	v_mfma_f32_16x16x32_bf16 v[38:41], v[150:153], v[174:177], v[38:41]
	v_mfma_f32_16x16x32_bf16 v[34:37], v[158:161], v[174:177], v[34:37]
	v_mfma_f32_16x16x32_bf16 v[22:25], v[150:153], v[182:185], v[22:25]
	v_mfma_f32_16x16x32_bf16 v[16:19], v[158:161], v[182:185], v[16:19]
	v_mfma_f32_16x16x32_bf16 v[4:7], v[150:153], v[190:193], v[4:7]
	v_mfma_f32_16x16x32_bf16 v[0:3], v[158:161], v[190:193], v[0:3]
	s_barrier
	s_add_i32 s46, 0, 0x18000
	s_add_i32 s47, 0, 0x1c000
	v_add_u32_e32 v142, s46, v21
	v_add_u32_e32 v158, s47, v21
	ds_read_b128 v[130:133], v142
	ds_read_b128 v[134:137], v142 offset:1024
	ds_read_b128 v[138:141], v142 offset:2048
	ds_read_b128 v[142:145], v142 offset:3072
	ds_read_b128 v[146:149], v158
	ds_read_b128 v[150:153], v158 offset:1024
	ds_read_b128 v[154:157], v158 offset:2048
	ds_read_b128 v[158:161], v158 offset:3072
	s_mov_b32 m0, s65
	s_nop 0
	global_load_lds_dwordx4 v214, s[34:35]
	s_add_u32 s34, s34, 0x80000
	s_addc_u32 s35, s35, 0
	s_mov_b32 m0, s66
	ds_read_b128 v[162:165], v208 offset:32768
	ds_read_b128 v[166:169], v208 offset:33792
	ds_read_b128 v[170:173], v208 offset:34816
	ds_read_b128 v[174:177], v208 offset:35840
	ds_read_b128 v[178:181], v208 offset:36864
	ds_read_b128 v[182:185], v208 offset:37888
	ds_read_b128 v[186:189], v208 offset:38912
	ds_read_b128 v[190:193], v208 offset:39936
	global_load_lds_dwordx4 v202, s[34:35]
	s_mov_b32 m0, s67
	s_nop 0
	global_load_lds_dwordx4 v214, s[34:35]
	s_waitcnt vmcnt(8)
	s_waitcnt lgkmcnt(0)
	s_barrier
; #define PG8_BAR __builtin_amdgcn_s_barrier()
; template <class Epi, class Sched, bool ALIGN_EPI = false, bool SP2 = false>
; __device__ __forceinline__ void gemm_phase(PG8_LAS unsigned char* lds, const Gemm g, const Sched& S, const Epi& E, const int tid_in) {
;     ...
;             if constexpr (SP2) {
;             PG8_LDB(B0, 0, 0); PG8_LDB(B1, 0, 1); PG8_SCHED; PG8_LDA(At, 0, 0); PG8_STAGE(PG8_SA(1, 1), a1 + hstep, voffA);
;             PG8_WAIT_V(8); PG8_WAIT_L(0); PG8_BAR; PG8_MMA(0, 0, At, B0); PG8_MMA(0, 1, At, B1); PG8_BAR; PG8_SCHED;
;             PG8_LDA(At, 0, 1); PG8_STAGE(PG8_SB(0, 0), b2, voffB); PG8_STAGE(PG8_SB(0, 1), b2 + hstep, voffB); PG8_STAGE(PG8_SA(0, 0), a2, voffA);
;             PG8_WAIT_V(8); PG8_WAIT_L(0); PG8_BAR; PG8_MMA(1, 0, At, B0); PG8_MMA(1, 1, At, B1); PG8_BAR; PG8_SCHED;
;             PG8_LDB(B0, 1, 0); PG8_LDB(B1, 1, 1); PG8_SCHED; PG8_LDA(At, 1, 0); PG8_STAGE(PG8_SA(0, 1), a2 + hstep, voffA);
;             PG8_WAIT_V(8); PG8_WAIT_L(0); PG8_BAR; PG8_MMA(0, 0, At, B0); PG8_MMA(0, 1, At, B1); PG8_BAR; PG8_SCHED;
;             PG8_LDA(At, 1, 1); PG8_STAGE(PG8_SB(1, 0), b3, voffB); PG8_STAGE(PG8_SB(1, 1), b3 + hstep, voffB); PG8_STAGE(PG8_SA(1, 0), a3, voffA);
;             PG8_WAIT_V(8); PG8_WAIT_L(0); PG8_BAR; PG8_MMA(1, 0, At, B0); PG8_MMA(1, 1, At, B1); PG8_BAR; PG8_SCHED;
;             } else {
;             PG8_LDB(B0, 0, 0); PG8_SCHED; PG8_LDA(At, 0, 0); PG8_STAGE(PG8_SA(1, 1), a1 + hstep, voffA);
;             PG8_WAIT_L(8); PG8_BAR; PG8_WAIT_L(0); PG8_MMA(0, 0, At, B0); PG8_BAR; PG8_SCHED;
;             PG8_LDB(B1, 0, 1); PG8_STAGE(PG8_SB(0, 0), b2, voffB);
;             PG8_BAR; PG8_WAIT_L(0); PG8_MMA(0, 1, At, B1); PG8_BAR;
;             PG8_LDA(At, 0, 1); PG8_STAGE(PG8_SA(0, 0), a2, voffA);
;             PG8_BAR; PG8_WAIT_L(0); PG8_MMA(1, 0, At, B0); PG8_BAR; PG8_SCHED;
;             PG8_STAGE(PG8_SB(0, 1), b2 + hstep, voffB);
;             PG8_WAIT_V(6); PG8_BAR; PG8_MMA(1, 1, At, B1); PG8_BAR;
;             PG8_LDB(B0, 1, 0); PG8_SCHED; PG8_LDA(At, 1, 0); PG8_STAGE(PG8_SA(0, 1), a2 + hstep, voffA);
;             PG8_WAIT_L(8); PG8_BAR; PG8_WAIT_L(0); PG8_MMA(0, 0, At, B0); PG8_BAR; PG8_SCHED;
;             PG8_LDB(B1, 1, 1); PG8_STAGE(PG8_SB(1, 0), b3, voffB);
;             PG8_BAR; PG8_WAIT_L(0); PG8_MMA(0, 1, At, B1); PG8_BAR;
;             PG8_LDA(At, 1, 1); PG8_STAGE(PG8_SA(1, 0), a3, voffA);
	v_mfma_f32_16x16x32_bf16 v[126:129], v[130:133], v[162:165], v[126:129]
	v_mfma_f32_16x16x32_bf16 v[122:125], v[138:141], v[162:165], v[122:125]
	v_mfma_f32_16x16x32_bf16 v[110:113], v[130:133], v[170:173], v[110:113]
	v_mfma_f32_16x16x32_bf16 v[106:109], v[138:141], v[170:173], v[106:109]
	v_mfma_f32_16x16x32_bf16 v[94:97], v[130:133], v[178:181], v[94:97]
	v_mfma_f32_16x16x32_bf16 v[90:93], v[138:141], v[178:181], v[90:93]
	v_mfma_f32_16x16x32_bf16 v[78:81], v[130:133], v[186:189], v[78:81]
	v_mfma_f32_16x16x32_bf16 v[74:77], v[138:141], v[186:189], v[74:77]
	v_mfma_f32_16x16x32_bf16 v[126:129], v[134:137], v[166:169], v[126:129]
	v_mfma_f32_16x16x32_bf16 v[122:125], v[142:145], v[166:169], v[122:125]
	v_mfma_f32_16x16x32_bf16 v[110:113], v[134:137], v[174:177], v[110:113]
	v_mfma_f32_16x16x32_bf16 v[106:109], v[142:145], v[174:177], v[106:109]
	v_mfma_f32_16x16x32_bf16 v[94:97], v[134:137], v[182:185], v[94:97]
	v_mfma_f32_16x16x32_bf16 v[90:93], v[142:145], v[182:185], v[90:93]
	v_mfma_f32_16x16x32_bf16 v[78:81], v[134:137], v[190:193], v[78:81]
	v_mfma_f32_16x16x32_bf16 v[74:77], v[142:145], v[190:193], v[74:77]
	v_mfma_f32_16x16x32_bf16 v[118:121], v[146:149], v[162:165], v[118:121]
	v_mfma_f32_16x16x32_bf16 v[114:117], v[154:157], v[162:165], v[114:117]
	v_mfma_f32_16x16x32_bf16 v[102:105], v[146:149], v[170:173], v[102:105]
	v_mfma_f32_16x16x32_bf16 v[98:101], v[154:157], v[170:173], v[98:101]
	v_mfma_f32_16x16x32_bf16 v[86:89], v[146:149], v[178:181], v[86:89]
	v_mfma_f32_16x16x32_bf16 v[82:85], v[154:157], v[178:181], v[82:85]
	v_mfma_f32_16x16x32_bf16 v[70:73], v[146:149], v[186:189], v[70:73]
	v_mfma_f32_16x16x32_bf16 v[66:69], v[154:157], v[186:189], v[66:69]
	v_mfma_f32_16x16x32_bf16 v[118:121], v[150:153], v[166:169], v[118:121]
	v_mfma_f32_16x16x32_bf16 v[114:117], v[158:161], v[166:169], v[114:117]
	v_mfma_f32_16x16x32_bf16 v[102:105], v[150:153], v[174:177], v[102:105]
	v_mfma_f32_16x16x32_bf16 v[98:101], v[158:161], v[174:177], v[98:101]
	v_mfma_f32_16x16x32_bf16 v[86:89], v[150:153], v[182:185], v[86:89]
	v_mfma_f32_16x16x32_bf16 v[82:85], v[158:161], v[182:185], v[82:85]
	v_mfma_f32_16x16x32_bf16 v[70:73], v[150:153], v[190:193], v[70:73]
	v_mfma_f32_16x16x32_bf16 v[66:69], v[158:161], v[190:193], v[66:69]
	s_barrier
	s_add_i32 s34, s46, s8
	s_mov_b32 m0, s34
	ds_read_b128 v[162:165], v208 offset:49152
	ds_read_b128 v[166:169], v208 offset:50176
	ds_read_b128 v[170:173], v208 offset:51200
	ds_read_b128 v[174:177], v208 offset:52224
	ds_read_b128 v[178:181], v208 offset:53248
	ds_read_b128 v[182:185], v208 offset:54272
	ds_read_b128 v[186:189], v208 offset:55296
	ds_read_b128 v[190:193], v208 offset:56320
	global_load_lds_dwordx4 v204, s[98:99]
	s_add_i32 m0, s34, 0x2000
	s_add_u32 s30, s30, 0x80080
	s_addc_u32 s31, s31, 0
	s_add_i32 s34, s47, s8
	global_load_lds_dwordx4 v216, s[98:99]
	s_mov_b32 m0, s34
	s_nop 0
	global_load_lds_dwordx4 v204, s[30:31]
	s_add_i32 m0, s34, 0x2000
	s_nop 0
	global_load_lds_dwordx4 v216, s[30:31]
	s_mov_b32 m0, s75
	s_nop 0
	global_load_lds_dwordx4 v202, s[100:101]
	s_waitcnt vmcnt(7)
	s_waitcnt lgkmcnt(0)
	s_barrier
	v_mfma_f32_16x16x32_bf16 v[62:65], v[130:133], v[162:165], v[62:65]
	v_mfma_f32_16x16x32_bf16 v[58:61], v[138:141], v[162:165], v[58:61]
	v_mfma_f32_16x16x32_bf16 v[46:49], v[130:133], v[170:173], v[46:49]
	v_mfma_f32_16x16x32_bf16 v[42:45], v[138:141], v[170:173], v[42:45]
	v_mfma_f32_16x16x32_bf16 v[30:33], v[130:133], v[178:181], v[30:33]
	v_mfma_f32_16x16x32_bf16 v[26:29], v[138:141], v[178:181], v[26:29]
	v_mfma_f32_16x16x32_bf16 v[12:15], v[130:133], v[186:189], v[12:15]
	v_mfma_f32_16x16x32_bf16 v[8:11], v[138:141], v[186:189], v[8:11]
	v_mfma_f32_16x16x32_bf16 v[62:65], v[134:137], v[166:169], v[62:65]
	v_mfma_f32_16x16x32_bf16 v[58:61], v[142:145], v[166:169], v[58:61]
	v_mfma_f32_16x16x32_bf16 v[46:49], v[134:137], v[174:177], v[46:49]
	v_mfma_f32_16x16x32_bf16 v[42:45], v[142:145], v[174:177], v[42:45]
	v_mfma_f32_16x16x32_bf16 v[30:33], v[134:137], v[182:185], v[30:33]
	v_mfma_f32_16x16x32_bf16 v[26:29], v[142:145], v[182:185], v[26:29]
	v_mfma_f32_16x16x32_bf16 v[12:15], v[134:137], v[190:193], v[12:15]
	v_mfma_f32_16x16x32_bf16 v[8:11], v[142:145], v[190:193], v[8:11]
	v_mfma_f32_16x16x32_bf16 v[54:57], v[146:149], v[162:165], v[54:57]
	v_mfma_f32_16x16x32_bf16 v[50:53], v[154:157], v[162:165], v[50:53]
	v_mfma_f32_16x16x32_bf16 v[38:41], v[146:149], v[170:173], v[38:41]
	v_mfma_f32_16x16x32_bf16 v[34:37], v[154:157], v[170:173], v[34:37]
	v_mfma_f32_16x16x32_bf16 v[22:25], v[146:149], v[178:181], v[22:25]
	v_mfma_f32_16x16x32_bf16 v[16:19], v[154:157], v[178:181], v[16:19]
	v_mfma_f32_16x16x32_bf16 v[4:7], v[146:149], v[186:189], v[4:7]
	v_mfma_f32_16x16x32_bf16 v[0:3], v[154:157], v[186:189], v[0:3]
	v_mfma_f32_16x16x32_bf16 v[54:57], v[150:153], v[166:169], v[54:57]
	v_mfma_f32_16x16x32_bf16 v[50:53], v[158:161], v[166:169], v[50:53]
	v_mfma_f32_16x16x32_bf16 v[38:41], v[150:153], v[174:177], v[38:41]
	v_mfma_f32_16x16x32_bf16 v[34:37], v[158:161], v[174:177], v[34:37]
	v_mfma_f32_16x16x32_bf16 v[22:25], v[150:153], v[182:185], v[22:25]
	v_mfma_f32_16x16x32_bf16 v[16:19], v[158:161], v[182:185], v[16:19]
	v_mfma_f32_16x16x32_bf16 v[4:7], v[150:153], v[190:193], v[4:7]
	v_mfma_f32_16x16x32_bf16 v[0:3], v[158:161], v[190:193], v[0:3]
	s_barrier
	s_add_i32 vcc_lo, vcc_lo, 2
	s_add_u32 s28, s28, 0x100
	s_addc_u32 s29, s29, 0
	s_add_u32 s57, s57, 0x100
	s_addc_u32 s92, s92, 0
	s_cmp_gt_u32 vcc_lo, 29
	s_cbranch_scc0 .LBB0_1037
	s_setprio 0
	s_and_b64 vcc, exec, s[48:49]
	s_cbranch_vccz .LBB0_1040
	s_barrier

; #define PG8_STAGE(bufoff, gbase, voff) do { _Pragma("unroll") for (int _i = 0; _i < 2; ++_i) \
;         __builtin_amdgcn_global_load_lds((const unsigned*)((const char*)(gbase) + (voff)[_i]), (PG8_LAS unsigned*)(lds + (bufoff) + ldsw + _i * 8192), 16, 0, 0); } while (0)
; #define PG8_LDA(dst, b, h) do { _Pragma("unroll") for (int m = 0; m < 4; ++m) _Pragma("unroll") for (int k = 0; k < 2; ++k) dst[m][k] = *(const PG8_LAS bf16x8*)(lds + PG8_SA(b, h) + aoff + m * 2048 + k * 1024); } while (0)
; #define PG8_LDB(dst, b, h) do { _Pragma("unroll") for (int n = 0; n < 2; ++n) _Pragma("unroll") for (int k = 0; k < 2; ++k) dst[n][k] = *(const PG8_LAS bf16x8*)(lds + PG8_SB(b, h) + boff + n * 2048 + k * 1024); } while (0)
; #define PG8_WAIT_V(n) asm volatile("s_waitcnt vmcnt(" #n ")" ::: "memory")
; #define PG8_WAIT_L(n) asm volatile("s_waitcnt lgkmcnt(" #n ")" ::: "memory")
; #define PG8_BAR __builtin_amdgcn_s_barrier()
; #define PG8_SCHED __builtin_amdgcn_sched_barrier(0)
; template <class Epi, class Sched, bool ALIGN_EPI = false, bool SP2 = false>
; __device__ __forceinline__ void gemm_phase(PG8_LAS unsigned char* lds, const Gemm g, const Sched& S, const Epi& E, const int tid_in) {
;     ...
;     for (;;) {
;         const bool has_next = S.next(ui + 1, nxt);
;         const char* nA = has_next ? (const char*)g.A + (size_t)nxt.pm * tstep : cA; const char* nB = has_next ? (const char*)g.Bt + (size_t)nxt.pn * tstep : cB;
;         for (int t = 0; t < nt; t += 2) {
;             if constexpr (Epi::KSPLIT > 0) { if (t == Epi::KSPLIT / BK) E.midk(acc, cur, wr, wc, fr, fq); }
;             const bool last = (t == nt - 2);
;             const char* a1 = cA + (size_t)(t + 1) * kstep;
;             const char* a2 = last ? nA : cA + (size_t)(t + 2) * kstep; const char* b2 = last ? nB : cB + (size_t)(t + 2) * kstep;
;             const char* a3 = a2 + kstep; const char* b3 = b2 + kstep;
;             if (last && has_next) S.a_ready(nxt);
;             if constexpr (SP2) {
;             PG8_LDB(B0, 0, 0); PG8_LDB(B1, 0, 1); PG8_SCHED; PG8_LDA(At, 0, 0); PG8_STAGE(PG8_SA(1, 1), a1 + hstep, voffA);
;             PG8_WAIT_V(8); PG8_WAIT_L(0); PG8_BAR; PG8_MMA(0, 0, At, B0); PG8_MMA(0, 1, At, B1); PG8_BAR; PG8_SCHED;
;             PG8_LDA(At, 0, 1); PG8_STAGE(PG8_SB(0, 0), b2, voffB); PG8_STAGE(PG8_SB(0, 1), b2 + hstep, voffB); PG8_STAGE(PG8_SA(0, 0), a2, voffA);
.LBB0_1156:
	s_ashr_i32 s35, s34, 31
	s_lshl_b64 s[6:7], s[34:35], 20
	s_add_u32 s6, s5, s6
	s_addc_u32 s7, s8, s7
	s_and_b64 s[20:21], exec, s[48:49]
	s_cselect_b32 s35, s51, s7
	s_cselect_b32 s58, s50, s6
	s_ashr_i32 s31, s30, 31
	s_lshl_b64 s[20:21], s[30:31], 20
	s_add_u32 s20, s10, s20
	s_addc_u32 s21, s19, s21
	s_and_b64 s[54:55], exec, s[48:49]
	s_cselect_b32 s31, s53, s21
	s_cselect_b32 s59, s52, s20
	s_add_u32 s50, s50, 0x80080
	s_addc_u32 s51, s51, 0
	s_add_u32 s60, s52, 0x100
	v_mov_b32_e32 v0, 0
	s_addc_u32 s61, s53, 0
	s_mov_b32 s62, -2
	s_cmp_lt_u32 s1, 0x1000
	s_cbranch_scc1 .LPRIO_1157
	s_setprio 1
.LPRIO_1157:
	s_mov_b32 m0, s25
	s_nop 0
	global_load_lds_dwordx4 v166, s[100:101]
	s_add_u32 s52, s50, 0xfff80080
	s_addc_u32 s53, s51, -1
	s_add_i32 s63, 0, 0x10000
	s_cmp_eq_u32 s62, 28
	s_cselect_b32 s55, s35, s53
	s_cselect_b32 s54, s58, s52
	s_cselect_b32 s53, s31, s61
	s_cselect_b32 s52, s59, s60
	s_add_i32 s66, 0, 0x14000
	v_add_u32_e32 v78, s63, v177
	v_add_u32_e32 v134, s66, v177
	ds_read_b128 v[66:69], v78
	ds_read_b128 v[70:73], v78 offset:1024
	ds_read_b128 v[74:77], v78 offset:2048
	ds_read_b128 v[78:81], v78 offset:3072
	ds_read_b128 v[122:125], v134
	ds_read_b128 v[126:129], v134 offset:1024
	ds_read_b128 v[130:133], v134 offset:2048
	ds_read_b128 v[134:137], v134 offset:3072
	s_add_i32 m0, s89, 0xc000
	ds_read_b128 v[188:191], v193
	ds_read_b128 v[194:197], v193 offset:1024
	ds_read_b128 v[198:201], v193 offset:2048
	ds_read_b128 v[202:205], v193 offset:3072
	ds_read_b128 v[208:211], v193 offset:4096
	ds_read_b128 v[212:215], v193 offset:5120
	ds_read_b128 v[216:219], v193 offset:6144
	ds_read_b128 v[220:223], v193 offset:7168
	global_load_lds_dwordx4 v184, s[50:51]
	s_add_i32 m0, s89, 0xe000
	s_nop 0
	global_load_lds_dwordx4 v186, s[50:51]
	s_waitcnt vmcnt(8)
	s_waitcnt lgkmcnt(0)
	s_barrier
	v_mfma_f32_16x16x32_bf16 v[150:153], v[66:69], v[188:191], 0
	v_mfma_f32_16x16x32_bf16 v[110:113], v[74:77], v[188:191], 0
	v_mfma_f32_16x16x32_bf16 v[146:149], v[66:69], v[198:201], 0
	v_mfma_f32_16x16x32_bf16 v[106:109], v[74:77], v[198:201], 0
	v_mfma_f32_16x16x32_bf16 v[142:145], v[66:69], v[208:211], 0
	v_mfma_f32_16x16x32_bf16 v[102:105], v[74:77], v[208:211], 0
	v_mfma_f32_16x16x32_bf16 v[138:141], v[66:69], v[216:219], 0
	v_mfma_f32_16x16x32_bf16 v[98:101], v[74:77], v[216:219], 0
	v_mfma_f32_16x16x32_bf16 v[150:153], v[70:73], v[194:197], v[150:153]
	v_mfma_f32_16x16x32_bf16 v[110:113], v[78:81], v[194:197], v[110:113]
	v_mfma_f32_16x16x32_bf16 v[146:149], v[70:73], v[202:205], v[146:149]
	v_mfma_f32_16x16x32_bf16 v[106:109], v[78:81], v[202:205], v[106:109]
	v_mfma_f32_16x16x32_bf16 v[142:145], v[70:73], v[212:215], v[142:145]
	v_mfma_f32_16x16x32_bf16 v[102:105], v[78:81], v[212:215], v[102:105]
	v_mfma_f32_16x16x32_bf16 v[138:141], v[70:73], v[220:223], v[138:141]
	v_mfma_f32_16x16x32_bf16 v[98:101], v[78:81], v[220:223], v[98:101]
	v_mfma_f32_16x16x32_bf16 v[94:97], v[122:125], v[188:191], 0
	v_mfma_f32_16x16x32_bf16 v[90:93], v[130:133], v[188:191], 0
	v_mfma_f32_16x16x32_bf16 v[158:161], v[122:125], v[198:201], 0
	v_mfma_f32_16x16x32_bf16 v[118:121], v[130:133], v[198:201], 0
	v_mfma_f32_16x16x32_bf16 v[154:157], v[122:125], v[208:211], 0
	v_mfma_f32_16x16x32_bf16 v[114:117], v[130:133], v[208:211], 0
	v_mfma_f32_16x16x32_bf16 v[86:89], v[122:125], v[216:219], 0
	v_mfma_f32_16x16x32_bf16 v[82:85], v[130:133], v[216:219], 0
	v_mfma_f32_16x16x32_bf16 v[94:97], v[126:129], v[194:197], v[94:97]
	v_mfma_f32_16x16x32_bf16 v[90:93], v[134:137], v[194:197], v[90:93]
	v_mfma_f32_16x16x32_bf16 v[158:161], v[126:129], v[202:205], v[158:161]
	v_mfma_f32_16x16x32_bf16 v[118:121], v[134:137], v[202:205], v[118:121]
	v_mfma_f32_16x16x32_bf16 v[154:157], v[126:129], v[212:215], v[154:157]
	v_mfma_f32_16x16x32_bf16 v[114:117], v[134:137], v[212:215], v[114:117]
	v_mfma_f32_16x16x32_bf16 v[86:89], v[126:129], v[220:223], v[86:89]
	v_mfma_f32_16x16x32_bf16 v[82:85], v[134:137], v[220:223], v[82:85]
	s_barrier
	s_add_i32 s63, s63, s1
	s_add_u32 s98, s52, 0x80
	s_addc_u32 s99, s53, 0
	s_mov_b32 m0, s63
	ds_read_b128 v[188:191], v193 offset:16384
	ds_read_b128 v[194:197], v193 offset:17408
	ds_read_b128 v[198:201], v193 offset:18432
	ds_read_b128 v[202:205], v193 offset:19456
	ds_read_b128 v[208:211], v193 offset:20480
	ds_read_b128 v[212:215], v193 offset:21504
	ds_read_b128 v[216:219], v193 offset:22528
	ds_read_b128 v[220:223], v193 offset:23552
	global_load_lds_dwordx4 v164, s[52:53]
	s_add_i32 m0, s63, 0x2000
	s_add_u32 s64, s52, 0x80000
	s_addc_u32 s65, s53, 0
	s_add_i32 s63, s66, s1
	global_load_lds_dwordx4 v168, s[52:53]
	s_mov_b32 m0, s63
	s_add_u32 s100, s54, 0x80
	s_addc_u32 s101, s55, 0
	global_load_lds_dwordx4 v164, s[64:65]
	s_add_i32 m0, s63, 0x2000
	s_nop 0
	global_load_lds_dwordx4 v168, s[64:65]
	s_mov_b32 m0, s89
	s_nop 0
	global_load_lds_dwordx4 v162, s[54:55]
	s_waitcnt vmcnt(7)
	s_waitcnt lgkmcnt(0)
	s_barrier
; #define PG8_STAGE(bufoff, gbase, voff) do { _Pragma("unroll") for (int _i = 0; _i < 2; ++_i) \
;         __builtin_amdgcn_global_load_lds((const unsigned*)((const char*)(gbase) + (voff)[_i]), (PG8_LAS unsigned*)(lds + (bufoff) + ldsw + _i * 8192), 16, 0, 0); } while (0)
; #define PG8_LDA(dst, b, h) do { _Pragma("unroll") for (int m = 0; m < 4; ++m) _Pragma("unroll") for (int k = 0; k < 2; ++k) dst[m][k] = *(const PG8_LAS bf16x8*)(lds + PG8_SA(b, h) + aoff + m * 2048 + k * 1024); } while (0)
; #define PG8_LDB(dst, b, h) do { _Pragma("unroll") for (int n = 0; n < 2; ++n) _Pragma("unroll") for (int k = 0; k < 2; ++k) dst[n][k] = *(const PG8_LAS bf16x8*)(lds + PG8_SB(b, h) + boff + n * 2048 + k * 1024); } while (0)
; #define PG8_MMA(ai, bj, At, Bt) do { __builtin_amdgcn_s_setprio(1); _Pragma("unroll") for (int m = 0; m < 4; ++m) _Pragma("unroll") for (int n = 0; n < 2; ++n) _Pragma("unroll") for (int k = 0; k < 2; ++k) \
;         acc[ai][bj][m][n] = __builtin_amdgcn_mfma_f32_16x16x32_bf16(Bt[n][k], At[m][k], acc[ai][bj][m][n], 0, 0, 0); __builtin_amdgcn_s_setprio(0); } while (0)
; template <class Epi, class Sched, bool ALIGN_EPI = false, bool SP2 = false>
; __device__ __forceinline__ void gemm_phase(PG8_LAS unsigned char* lds, const Gemm g, const Sched& S, const Epi& E, const int tid_in) {
;     ...
;             if constexpr (SP2) {
;             PG8_LDB(B0, 0, 0); PG8_LDB(B1, 0, 1); PG8_SCHED; PG8_LDA(At, 0, 0); PG8_STAGE(PG8_SA(1, 1), a1 + hstep, voffA);
;             PG8_WAIT_V(8); PG8_WAIT_L(0); PG8_BAR; PG8_MMA(0, 0, At, B0); PG8_MMA(0, 1, At, B1); PG8_BAR; PG8_SCHED;
;             PG8_LDA(At, 0, 1); PG8_STAGE(PG8_SB(0, 0), b2, voffB); PG8_STAGE(PG8_SB(0, 1), b2 + hstep, voffB); PG8_STAGE(PG8_SA(0, 0), a2, voffA);
;             PG8_WAIT_V(8); PG8_WAIT_L(0); PG8_BAR; PG8_MMA(1, 0, At, B0); PG8_MMA(1, 1, At, B1); PG8_BAR; PG8_SCHED;
;             PG8_LDB(B0, 1, 0); PG8_LDB(B1, 1, 1); PG8_SCHED; PG8_LDA(At, 1, 0); PG8_STAGE(PG8_SA(0, 1), a2 + hstep, voffA);
;             PG8_WAIT_V(8); PG8_WAIT_L(0); PG8_BAR; PG8_MMA(0, 0, At, B0); PG8_MMA(0, 1, At, B1); PG8_BAR; PG8_SCHED;
;             PG8_LDA(At, 1, 1); PG8_STAGE(PG8_SB(1, 0), b3, voffB); PG8_STAGE(PG8_SB(1, 1), b3 + hstep, voffB); PG8_STAGE(PG8_SA(1, 0), a3, voffA);
;             PG8_WAIT_V(8); PG8_WAIT_L(0); PG8_BAR; PG8_MMA(1, 0, At, B0); PG8_MMA(1, 1, At, B1); PG8_BAR; PG8_SCHED;
	v_mfma_f32_16x16x32_bf16 v[54:57], v[66:69], v[188:191], 0
	v_mfma_f32_16x16x32_bf16 v[30:33], v[74:77], v[188:191], 0
	v_mfma_f32_16x16x32_bf16 v[50:53], v[66:69], v[198:201], 0
	v_mfma_f32_16x16x32_bf16 v[26:29], v[74:77], v[198:201], 0
	v_mfma_f32_16x16x32_bf16 v[46:49], v[66:69], v[208:211], 0
	v_mfma_f32_16x16x32_bf16 v[22:25], v[74:77], v[208:211], 0
	v_mfma_f32_16x16x32_bf16 v[42:45], v[66:69], v[216:219], 0
	v_mfma_f32_16x16x32_bf16 v[16:19], v[74:77], v[216:219], 0
	v_mfma_f32_16x16x32_bf16 v[54:57], v[70:73], v[194:197], v[54:57]
	v_mfma_f32_16x16x32_bf16 v[30:33], v[78:81], v[194:197], v[30:33]
	v_mfma_f32_16x16x32_bf16 v[50:53], v[70:73], v[202:205], v[50:53]
	v_mfma_f32_16x16x32_bf16 v[26:29], v[78:81], v[202:205], v[26:29]
	v_mfma_f32_16x16x32_bf16 v[46:49], v[70:73], v[212:215], v[46:49]
	v_mfma_f32_16x16x32_bf16 v[22:25], v[78:81], v[212:215], v[22:25]
	v_mfma_f32_16x16x32_bf16 v[42:45], v[70:73], v[220:223], v[42:45]
	v_mfma_f32_16x16x32_bf16 v[16:19], v[78:81], v[220:223], v[16:19]
	v_mfma_f32_16x16x32_bf16 v[12:15], v[122:125], v[188:191], 0
	v_mfma_f32_16x16x32_bf16 v[8:11], v[130:133], v[188:191], 0
	v_mfma_f32_16x16x32_bf16 v[62:65], v[122:125], v[198:201], 0
	v_mfma_f32_16x16x32_bf16 v[38:41], v[130:133], v[198:201], 0
	v_mfma_f32_16x16x32_bf16 v[58:61], v[122:125], v[208:211], 0
	v_mfma_f32_16x16x32_bf16 v[34:37], v[130:133], v[208:211], 0
	v_mfma_f32_16x16x32_bf16 v[4:7], v[122:125], v[216:219], 0
	v_mfma_f32_16x16x32_bf16 v[0:3], v[130:133], v[216:219], 0
	v_mfma_f32_16x16x32_bf16 v[12:15], v[126:129], v[194:197], v[12:15]
	v_mfma_f32_16x16x32_bf16 v[8:11], v[134:137], v[194:197], v[8:11]
	v_mfma_f32_16x16x32_bf16 v[62:65], v[126:129], v[202:205], v[62:65]
	v_mfma_f32_16x16x32_bf16 v[38:41], v[134:137], v[202:205], v[38:41]
	v_mfma_f32_16x16x32_bf16 v[58:61], v[126:129], v[212:215], v[58:61]
	v_mfma_f32_16x16x32_bf16 v[34:37], v[134:137], v[212:215], v[34:37]
	v_mfma_f32_16x16x32_bf16 v[4:7], v[126:129], v[220:223], v[4:7]
	v_mfma_f32_16x16x32_bf16 v[0:3], v[134:137], v[220:223], v[0:3]
	s_barrier
	s_add_i32 s63, 0, 0x18000
	s_add_i32 s64, 0, 0x1c000
	v_add_u32_e32 v78, s63, v177
	v_add_u32_e32 v134, s64, v177
	ds_read_b128 v[66:69], v78
	ds_read_b128 v[70:73], v78 offset:1024
	ds_read_b128 v[74:77], v78 offset:2048
	ds_read_b128 v[78:81], v78 offset:3072
	ds_read_b128 v[122:125], v134
	ds_read_b128 v[126:129], v134 offset:1024
	ds_read_b128 v[130:133], v134 offset:2048
	ds_read_b128 v[134:137], v134 offset:3072
	s_mov_b32 m0, s92
	s_nop 0
	global_load_lds_dwordx4 v166, s[54:55]
	s_add_u32 s54, s54, 0x80000
	s_addc_u32 s55, s55, 0
	s_mov_b32 m0, s2
	ds_read_b128 v[188:191], v193 offset:32768
	ds_read_b128 v[194:197], v193 offset:33792
	ds_read_b128 v[198:201], v193 offset:34816
	ds_read_b128 v[202:205], v193 offset:35840
	ds_read_b128 v[208:211], v193 offset:36864
	ds_read_b128 v[212:215], v193 offset:37888
	ds_read_b128 v[216:219], v193 offset:38912
	ds_read_b128 v[220:223], v193 offset:39936
	global_load_lds_dwordx4 v162, s[54:55]
	s_mov_b32 m0, s3
	s_nop 0
	global_load_lds_dwordx4 v166, s[54:55]
	s_waitcnt vmcnt(8)
	s_waitcnt lgkmcnt(0)
	s_barrier
	v_mfma_f32_16x16x32_bf16 v[150:153], v[66:69], v[188:191], v[150:153]
	v_mfma_f32_16x16x32_bf16 v[110:113], v[74:77], v[188:191], v[110:113]
	v_mfma_f32_16x16x32_bf16 v[146:149], v[66:69], v[198:201], v[146:149]
	v_mfma_f32_16x16x32_bf16 v[106:109], v[74:77], v[198:201], v[106:109]
	v_mfma_f32_16x16x32_bf16 v[142:145], v[66:69], v[208:211], v[142:145]
	v_mfma_f32_16x16x32_bf16 v[102:105], v[74:77], v[208:211], v[102:105]
	v_mfma_f32_16x16x32_bf16 v[138:141], v[66:69], v[216:219], v[138:141]
	v_mfma_f32_16x16x32_bf16 v[98:101], v[74:77], v[216:219], v[98:101]
	v_mfma_f32_16x16x32_bf16 v[150:153], v[70:73], v[194:197], v[150:153]
	v_mfma_f32_16x16x32_bf16 v[110:113], v[78:81], v[194:197], v[110:113]
	v_mfma_f32_16x16x32_bf16 v[146:149], v[70:73], v[202:205], v[146:149]
	v_mfma_f32_16x16x32_bf16 v[106:109], v[78:81], v[202:205], v[106:109]
	v_mfma_f32_16x16x32_bf16 v[142:145], v[70:73], v[212:215], v[142:145]
	v_mfma_f32_16x16x32_bf16 v[102:105], v[78:81], v[212:215], v[102:105]
	v_mfma_f32_16x16x32_bf16 v[138:141], v[70:73], v[220:223], v[138:141]
	v_mfma_f32_16x16x32_bf16 v[98:101], v[78:81], v[220:223], v[98:101]
	v_mfma_f32_16x16x32_bf16 v[94:97], v[122:125], v[188:191], v[94:97]
	v_mfma_f32_16x16x32_bf16 v[90:93], v[130:133], v[188:191], v[90:93]
	v_mfma_f32_16x16x32_bf16 v[158:161], v[122:125], v[198:201], v[158:161]
	v_mfma_f32_16x16x32_bf16 v[118:121], v[130:133], v[198:201], v[118:121]
	v_mfma_f32_16x16x32_bf16 v[154:157], v[122:125], v[208:211], v[154:157]
	v_mfma_f32_16x16x32_bf16 v[114:117], v[130:133], v[208:211], v[114:117]
	v_mfma_f32_16x16x32_bf16 v[86:89], v[122:125], v[216:219], v[86:89]
	v_mfma_f32_16x16x32_bf16 v[82:85], v[130:133], v[216:219], v[82:85]
	v_mfma_f32_16x16x32_bf16 v[94:97], v[126:129], v[194:197], v[94:97]
	v_mfma_f32_16x16x32_bf16 v[90:93], v[134:137], v[194:197], v[90:93]
	v_mfma_f32_16x16x32_bf16 v[158:161], v[126:129], v[202:205], v[158:161]
	v_mfma_f32_16x16x32_bf16 v[118:121], v[134:137], v[202:205], v[118:121]
	v_mfma_f32_16x16x32_bf16 v[154:157], v[126:129], v[212:215], v[154:157]
	v_mfma_f32_16x16x32_bf16 v[114:117], v[134:137], v[212:215], v[114:117]
	v_mfma_f32_16x16x32_bf16 v[86:89], v[126:129], v[220:223], v[86:89]
	v_mfma_f32_16x16x32_bf16 v[82:85], v[134:137], v[220:223], v[82:85]
	s_barrier
; #define PG8_STAGE(bufoff, gbase, voff) do { _Pragma("unroll") for (int _i = 0; _i < 2; ++_i) \
;         __builtin_amdgcn_global_load_lds((const unsigned*)((const char*)(gbase) + (voff)[_i]), (PG8_LAS unsigned*)(lds + (bufoff) + ldsw + _i * 8192), 16, 0, 0); } while (0)
; #define PG8_LDA(dst, b, h) do { _Pragma("unroll") for (int m = 0; m < 4; ++m) _Pragma("unroll") for (int k = 0; k < 2; ++k) dst[m][k] = *(const PG8_LAS bf16x8*)(lds + PG8_SA(b, h) + aoff + m * 2048 + k * 1024); } while (0)
; #define PG8_LDB(dst, b, h) do { _Pragma("unroll") for (int n = 0; n < 2; ++n) _Pragma("unroll") for (int k = 0; k < 2; ++k) dst[n][k] = *(const PG8_LAS bf16x8*)(lds + PG8_SB(b, h) + boff + n * 2048 + k * 1024); } while (0)
; #define PG8_MMA(ai, bj, At, Bt) do { __builtin_amdgcn_s_setprio(1); _Pragma("unroll") for (int m = 0; m < 4; ++m) _Pragma("unroll") for (int n = 0; n < 2; ++n) _Pragma("unroll") for (int k = 0; k < 2; ++k) \
;         acc[ai][bj][m][n] = __builtin_amdgcn_mfma_f32_16x16x32_bf16(Bt[n][k], At[m][k], acc[ai][bj][m][n], 0, 0, 0); __builtin_amdgcn_s_setprio(0); } while (0)
; template <class Epi, class Sched, bool ALIGN_EPI = false, bool SP2 = false>
; __device__ __forceinline__ void gemm_phase(PG8_LAS unsigned char* lds, const Gemm g, const Sched& S, const Epi& E, const int tid_in) {
;     ...
;             if constexpr (SP2) {
;             PG8_LDB(B0, 0, 0); PG8_LDB(B1, 0, 1); PG8_SCHED; PG8_LDA(At, 0, 0); PG8_STAGE(PG8_SA(1, 1), a1 + hstep, voffA);
;             PG8_WAIT_V(8); PG8_WAIT_L(0); PG8_BAR; PG8_MMA(0, 0, At, B0); PG8_MMA(0, 1, At, B1); PG8_BAR; PG8_SCHED;
;             PG8_LDA(At, 0, 1); PG8_STAGE(PG8_SB(0, 0), b2, voffB); PG8_STAGE(PG8_SB(0, 1), b2 + hstep, voffB); PG8_STAGE(PG8_SA(0, 0), a2, voffA);
;             PG8_WAIT_V(8); PG8_WAIT_L(0); PG8_BAR; PG8_MMA(1, 0, At, B0); PG8_MMA(1, 1, At, B1); PG8_BAR; PG8_SCHED;
;             PG8_LDB(B0, 1, 0); PG8_LDB(B1, 1, 1); PG8_SCHED; PG8_LDA(At, 1, 0); PG8_STAGE(PG8_SA(0, 1), a2 + hstep, voffA);
;             PG8_WAIT_V(8); PG8_WAIT_L(0); PG8_BAR; PG8_MMA(0, 0, At, B0); PG8_MMA(0, 1, At, B1); PG8_BAR; PG8_SCHED;
;             PG8_LDA(At, 1, 1); PG8_STAGE(PG8_SB(1, 0), b3, voffB); PG8_STAGE(PG8_SB(1, 1), b3 + hstep, voffB); PG8_STAGE(PG8_SA(1, 0), a3, voffA);
;             PG8_WAIT_V(8); PG8_WAIT_L(0); PG8_BAR; PG8_MMA(1, 0, At, B0); PG8_MMA(1, 1, At, B1); PG8_BAR; PG8_SCHED;
	s_add_i32 s54, s63, s1
	s_mov_b32 m0, s54
	ds_read_b128 v[188:191], v193 offset:49152
	ds_read_b128 v[194:197], v193 offset:50176
	ds_read_b128 v[198:201], v193 offset:51200
	ds_read_b128 v[202:205], v193 offset:52224
	ds_read_b128 v[208:211], v193 offset:53248
	ds_read_b128 v[212:215], v193 offset:54272
	ds_read_b128 v[216:219], v193 offset:55296
	ds_read_b128 v[220:223], v193 offset:56320
	global_load_lds_dwordx4 v164, s[98:99]
	s_add_i32 m0, s54, 0x2000
	s_add_u32 s52, s52, 0x80080
	s_addc_u32 s53, s53, 0
	s_add_i32 s54, s64, s1
	global_load_lds_dwordx4 v168, s[98:99]
	s_mov_b32 m0, s54
	s_nop 0
	global_load_lds_dwordx4 v164, s[52:53]
	s_add_i32 m0, s54, 0x2000
	s_nop 0
	global_load_lds_dwordx4 v168, s[52:53]
	s_mov_b32 m0, s24
	s_nop 0
	global_load_lds_dwordx4 v162, s[100:101]
	s_waitcnt vmcnt(7)
	s_waitcnt lgkmcnt(0)
	s_barrier
	v_mfma_f32_16x16x32_bf16 v[54:57], v[66:69], v[188:191], v[54:57]
	v_mfma_f32_16x16x32_bf16 v[30:33], v[74:77], v[188:191], v[30:33]
	v_mfma_f32_16x16x32_bf16 v[50:53], v[66:69], v[198:201], v[50:53]
	v_mfma_f32_16x16x32_bf16 v[26:29], v[74:77], v[198:201], v[26:29]
	v_mfma_f32_16x16x32_bf16 v[46:49], v[66:69], v[208:211], v[46:49]
	v_mfma_f32_16x16x32_bf16 v[22:25], v[74:77], v[208:211], v[22:25]
	v_mfma_f32_16x16x32_bf16 v[42:45], v[66:69], v[216:219], v[42:45]
	v_mfma_f32_16x16x32_bf16 v[16:19], v[74:77], v[216:219], v[16:19]
	v_mfma_f32_16x16x32_bf16 v[54:57], v[70:73], v[194:197], v[54:57]
	v_mfma_f32_16x16x32_bf16 v[30:33], v[78:81], v[194:197], v[30:33]
	v_mfma_f32_16x16x32_bf16 v[50:53], v[70:73], v[202:205], v[50:53]
	v_mfma_f32_16x16x32_bf16 v[26:29], v[78:81], v[202:205], v[26:29]
	v_mfma_f32_16x16x32_bf16 v[46:49], v[70:73], v[212:215], v[46:49]
	v_mfma_f32_16x16x32_bf16 v[22:25], v[78:81], v[212:215], v[22:25]
	v_mfma_f32_16x16x32_bf16 v[42:45], v[70:73], v[220:223], v[42:45]
	v_mfma_f32_16x16x32_bf16 v[16:19], v[78:81], v[220:223], v[16:19]
	v_mfma_f32_16x16x32_bf16 v[12:15], v[122:125], v[188:191], v[12:15]
	v_mfma_f32_16x16x32_bf16 v[8:11], v[130:133], v[188:191], v[8:11]
	v_mfma_f32_16x16x32_bf16 v[62:65], v[122:125], v[198:201], v[62:65]
	v_mfma_f32_16x16x32_bf16 v[38:41], v[130:133], v[198:201], v[38:41]
	v_mfma_f32_16x16x32_bf16 v[58:61], v[122:125], v[208:211], v[58:61]
	v_mfma_f32_16x16x32_bf16 v[34:37], v[130:133], v[208:211], v[34:37]
	v_mfma_f32_16x16x32_bf16 v[4:7], v[122:125], v[216:219], v[4:7]
	v_mfma_f32_16x16x32_bf16 v[0:3], v[130:133], v[216:219], v[0:3]
	v_mfma_f32_16x16x32_bf16 v[12:15], v[126:129], v[194:197], v[12:15]
	v_mfma_f32_16x16x32_bf16 v[8:11], v[134:137], v[194:197], v[8:11]
	v_mfma_f32_16x16x32_bf16 v[62:65], v[126:129], v[202:205], v[62:65]
	v_mfma_f32_16x16x32_bf16 v[38:41], v[134:137], v[202:205], v[38:41]
	v_mfma_f32_16x16x32_bf16 v[58:61], v[126:129], v[212:215], v[58:61]
	v_mfma_f32_16x16x32_bf16 v[34:37], v[134:137], v[212:215], v[34:37]
	v_mfma_f32_16x16x32_bf16 v[4:7], v[126:129], v[220:223], v[4:7]
	v_mfma_f32_16x16x32_bf16 v[0:3], v[134:137], v[220:223], v[0:3]
	s_barrier
	s_add_i32 s62, s62, 2
	s_add_u32 s50, s50, 0x100
	s_addc_u32 s51, s51, 0
	s_add_u32 s60, s60, 0x100
	s_addc_u32 s61, s61, 0
	s_cmp_gt_u32 s62, 29
.LBB0_1157:
	s_mov_b32 m0, s25
	s_nop 0
	global_load_lds_dwordx4 v166, s[100:101]
	s_add_u32 s52, s50, 0xfff80080
	s_addc_u32 s53, s51, -1
	s_add_i32 s63, 0, 0x10000
	s_cmp_eq_u32 s62, 28
	s_cselect_b32 s55, s35, s53
	s_cselect_b32 s54, s58, s52
	s_cselect_b32 s53, s31, s61
	s_cselect_b32 s52, s59, s60
	s_add_i32 s66, 0, 0x14000
	v_add_u32_e32 v78, s63, v177
	v_add_u32_e32 v134, s66, v177
	ds_read_b128 v[66:69], v78
	ds_read_b128 v[70:73], v78 offset:1024
	ds_read_b128 v[74:77], v78 offset:2048
	ds_read_b128 v[78:81], v78 offset:3072
	ds_read_b128 v[122:125], v134
	ds_read_b128 v[126:129], v134 offset:1024
	ds_read_b128 v[130:133], v134 offset:2048
	ds_read_b128 v[134:137], v134 offset:3072
	s_add_i32 m0, s89, 0xc000
	ds_read_b128 v[188:191], v193
	ds_read_b128 v[194:197], v193 offset:1024
	ds_read_b128 v[198:201], v193 offset:2048
	ds_read_b128 v[202:205], v193 offset:3072
	ds_read_b128 v[208:211], v193 offset:4096
	ds_read_b128 v[212:215], v193 offset:5120
	ds_read_b128 v[216:219], v193 offset:6144
	ds_read_b128 v[220:223], v193 offset:7168
	global_load_lds_dwordx4 v184, s[50:51]
	s_add_i32 m0, s89, 0xe000
	s_nop 0
	global_load_lds_dwordx4 v186, s[50:51]
	s_waitcnt vmcnt(8)
	s_waitcnt lgkmcnt(0)
	s_barrier
	v_mfma_f32_16x16x32_bf16 v[150:153], v[66:69], v[188:191], v[150:153]
	v_mfma_f32_16x16x32_bf16 v[110:113], v[74:77], v[188:191], v[110:113]
	v_mfma_f32_16x16x32_bf16 v[146:149], v[66:69], v[198:201], v[146:149]
	v_mfma_f32_16x16x32_bf16 v[106:109], v[74:77], v[198:201], v[106:109]
	v_mfma_f32_16x16x32_bf16 v[142:145], v[66:69], v[208:211], v[142:145]
	v_mfma_f32_16x16x32_bf16 v[102:105], v[74:77], v[208:211], v[102:105]
	v_mfma_f32_16x16x32_bf16 v[138:141], v[66:69], v[216:219], v[138:141]
	v_mfma_f32_16x16x32_bf16 v[98:101], v[74:77], v[216:219], v[98:101]
	v_mfma_f32_16x16x32_bf16 v[150:153], v[70:73], v[194:197], v[150:153]
	v_mfma_f32_16x16x32_bf16 v[110:113], v[78:81], v[194:197], v[110:113]
	v_mfma_f32_16x16x32_bf16 v[146:149], v[70:73], v[202:205], v[146:149]
	v_mfma_f32_16x16x32_bf16 v[106:109], v[78:81], v[202:205], v[106:109]
	v_mfma_f32_16x16x32_bf16 v[142:145], v[70:73], v[212:215], v[142:145]
	v_mfma_f32_16x16x32_bf16 v[102:105], v[78:81], v[212:215], v[102:105]
	v_mfma_f32_16x16x32_bf16 v[138:141], v[70:73], v[220:223], v[138:141]
	v_mfma_f32_16x16x32_bf16 v[98:101], v[78:81], v[220:223], v[98:101]
	v_mfma_f32_16x16x32_bf16 v[94:97], v[122:125], v[188:191], v[94:97]
	v_mfma_f32_16x16x32_bf16 v[90:93], v[130:133], v[188:191], v[90:93]
	v_mfma_f32_16x16x32_bf16 v[158:161], v[122:125], v[198:201], v[158:161]
	v_mfma_f32_16x16x32_bf16 v[118:121], v[130:133], v[198:201], v[118:121]
	v_mfma_f32_16x16x32_bf16 v[154:157], v[122:125], v[208:211], v[154:157]
	v_mfma_f32_16x16x32_bf16 v[114:117], v[130:133], v[208:211], v[114:117]
	v_mfma_f32_16x16x32_bf16 v[86:89], v[122:125], v[216:219], v[86:89]
	v_mfma_f32_16x16x32_bf16 v[82:85], v[130:133], v[216:219], v[82:85]
	v_mfma_f32_16x16x32_bf16 v[94:97], v[126:129], v[194:197], v[94:97]
	v_mfma_f32_16x16x32_bf16 v[90:93], v[134:137], v[194:197], v[90:93]
	v_mfma_f32_16x16x32_bf16 v[158:161], v[126:129], v[202:205], v[158:161]
	v_mfma_f32_16x16x32_bf16 v[118:121], v[134:137], v[202:205], v[118:121]
	v_mfma_f32_16x16x32_bf16 v[154:157], v[126:129], v[212:215], v[154:157]
	v_mfma_f32_16x16x32_bf16 v[114:117], v[134:137], v[212:215], v[114:117]
	v_mfma_f32_16x16x32_bf16 v[86:89], v[126:129], v[220:223], v[86:89]
	v_mfma_f32_16x16x32_bf16 v[82:85], v[134:137], v[220:223], v[82:85]
	s_barrier
; #define PG8_STAGE(bufoff, gbase, voff) do { _Pragma("unroll") for (int _i = 0; _i < 2; ++_i) \
;         __builtin_amdgcn_global_load_lds((const unsigned*)((const char*)(gbase) + (voff)[_i]), (PG8_LAS unsigned*)(lds + (bufoff) + ldsw + _i * 8192), 16, 0, 0); } while (0)
; #define PG8_LDA(dst, b, h) do { _Pragma("unroll") for (int m = 0; m < 4; ++m) _Pragma("unroll") for (int k = 0; k < 2; ++k) dst[m][k] = *(const PG8_LAS bf16x8*)(lds + PG8_SA(b, h) + aoff + m * 2048 + k * 1024); } while (0)
; #define PG8_LDB(dst, b, h) do { _Pragma("unroll") for (int n = 0; n < 2; ++n) _Pragma("unroll") for (int k = 0; k < 2; ++k) dst[n][k] = *(const PG8_LAS bf16x8*)(lds + PG8_SB(b, h) + boff + n * 2048 + k * 1024); } while (0)
; #define PG8_MMA(ai, bj, At, Bt) do { __builtin_amdgcn_s_setprio(1); _Pragma("unroll") for (int m = 0; m < 4; ++m) _Pragma("unroll") for (int n = 0; n < 2; ++n) _Pragma("unroll") for (int k = 0; k < 2; ++k) \
;         acc[ai][bj][m][n] = __builtin_amdgcn_mfma_f32_16x16x32_bf16(Bt[n][k], At[m][k], acc[ai][bj][m][n], 0, 0, 0); __builtin_amdgcn_s_setprio(0); } while (0)
; template <class Epi, class Sched, bool ALIGN_EPI = false, bool SP2 = false>
; __device__ __forceinline__ void gemm_phase(PG8_LAS unsigned char* lds, const Gemm g, const Sched& S, const Epi& E, const int tid_in) {
;     ...
;             if constexpr (SP2) {
;             PG8_LDB(B0, 0, 0); PG8_LDB(B1, 0, 1); PG8_SCHED; PG8_LDA(At, 0, 0); PG8_STAGE(PG8_SA(1, 1), a1 + hstep, voffA);
;             PG8_WAIT_V(8); PG8_WAIT_L(0); PG8_BAR; PG8_MMA(0, 0, At, B0); PG8_MMA(0, 1, At, B1); PG8_BAR; PG8_SCHED;
;             PG8_LDA(At, 0, 1); PG8_STAGE(PG8_SB(0, 0), b2, voffB); PG8_STAGE(PG8_SB(0, 1), b2 + hstep, voffB); PG8_STAGE(PG8_SA(0, 0), a2, voffA);
;             PG8_WAIT_V(8); PG8_WAIT_L(0); PG8_BAR; PG8_MMA(1, 0, At, B0); PG8_MMA(1, 1, At, B1); PG8_BAR; PG8_SCHED;
;             PG8_LDB(B0, 1, 0); PG8_LDB(B1, 1, 1); PG8_SCHED; PG8_LDA(At, 1, 0); PG8_STAGE(PG8_SA(0, 1), a2 + hstep, voffA);
;             PG8_WAIT_V(8); PG8_WAIT_L(0); PG8_BAR; PG8_MMA(0, 0, At, B0); PG8_MMA(0, 1, At, B1); PG8_BAR; PG8_SCHED;
;             PG8_LDA(At, 1, 1); PG8_STAGE(PG8_SB(1, 0), b3, voffB); PG8_STAGE(PG8_SB(1, 1), b3 + hstep, voffB); PG8_STAGE(PG8_SA(1, 0), a3, voffA);
;             PG8_WAIT_V(8); PG8_WAIT_L(0); PG8_BAR; PG8_MMA(1, 0, At, B0); PG8_MMA(1, 1, At, B1); PG8_BAR; PG8_SCHED;
	s_add_i32 s63, s63, s1
	s_add_u32 s98, s52, 0x80
	s_addc_u32 s99, s53, 0
	s_mov_b32 m0, s63
	ds_read_b128 v[188:191], v193 offset:16384
	ds_read_b128 v[194:197], v193 offset:17408
	ds_read_b128 v[198:201], v193 offset:18432
	ds_read_b128 v[202:205], v193 offset:19456
	ds_read_b128 v[208:211], v193 offset:20480
	ds_read_b128 v[212:215], v193 offset:21504
	ds_read_b128 v[216:219], v193 offset:22528
	ds_read_b128 v[220:223], v193 offset:23552
	global_load_lds_dwordx4 v164, s[52:53]
	s_add_i32 m0, s63, 0x2000
	s_add_u32 s64, s52, 0x80000
	s_addc_u32 s65, s53, 0
	s_add_i32 s63, s66, s1
	global_load_lds_dwordx4 v168, s[52:53]
	s_mov_b32 m0, s63
	s_add_u32 s100, s54, 0x80
	s_addc_u32 s101, s55, 0
	global_load_lds_dwordx4 v164, s[64:65]
	s_add_i32 m0, s63, 0x2000
	s_nop 0
	global_load_lds_dwordx4 v168, s[64:65]
	s_mov_b32 m0, s89
	s_nop 0
	global_load_lds_dwordx4 v162, s[54:55]
	s_waitcnt vmcnt(7)
	s_waitcnt lgkmcnt(0)
	s_barrier
	v_mfma_f32_16x16x32_bf16 v[54:57], v[66:69], v[188:191], v[54:57]
	v_mfma_f32_16x16x32_bf16 v[30:33], v[74:77], v[188:191], v[30:33]
	v_mfma_f32_16x16x32_bf16 v[50:53], v[66:69], v[198:201], v[50:53]
	v_mfma_f32_16x16x32_bf16 v[26:29], v[74:77], v[198:201], v[26:29]
	v_mfma_f32_16x16x32_bf16 v[46:49], v[66:69], v[208:211], v[46:49]
	v_mfma_f32_16x16x32_bf16 v[22:25], v[74:77], v[208:211], v[22:25]
	v_mfma_f32_16x16x32_bf16 v[42:45], v[66:69], v[216:219], v[42:45]
	v_mfma_f32_16x16x32_bf16 v[16:19], v[74:77], v[216:219], v[16:19]
	v_mfma_f32_16x16x32_bf16 v[54:57], v[70:73], v[194:197], v[54:57]
	v_mfma_f32_16x16x32_bf16 v[30:33], v[78:81], v[194:197], v[30:33]
	v_mfma_f32_16x16x32_bf16 v[50:53], v[70:73], v[202:205], v[50:53]
	v_mfma_f32_16x16x32_bf16 v[26:29], v[78:81], v[202:205], v[26:29]
	v_mfma_f32_16x16x32_bf16 v[46:49], v[70:73], v[212:215], v[46:49]
	v_mfma_f32_16x16x32_bf16 v[22:25], v[78:81], v[212:215], v[22:25]
	v_mfma_f32_16x16x32_bf16 v[42:45], v[70:73], v[220:223], v[42:45]
	v_mfma_f32_16x16x32_bf16 v[16:19], v[78:81], v[220:223], v[16:19]
	v_mfma_f32_16x16x32_bf16 v[12:15], v[122:125], v[188:191], v[12:15]
	v_mfma_f32_16x16x32_bf16 v[8:11], v[130:133], v[188:191], v[8:11]
	v_mfma_f32_16x16x32_bf16 v[62:65], v[122:125], v[198:201], v[62:65]
	v_mfma_f32_16x16x32_bf16 v[38:41], v[130:133], v[198:201], v[38:41]
	v_mfma_f32_16x16x32_bf16 v[58:61], v[122:125], v[208:211], v[58:61]
	v_mfma_f32_16x16x32_bf16 v[34:37], v[130:133], v[208:211], v[34:37]
	v_mfma_f32_16x16x32_bf16 v[4:7], v[122:125], v[216:219], v[4:7]
	v_mfma_f32_16x16x32_bf16 v[0:3], v[130:133], v[216:219], v[0:3]
	v_mfma_f32_16x16x32_bf16 v[12:15], v[126:129], v[194:197], v[12:15]
	v_mfma_f32_16x16x32_bf16 v[8:11], v[134:137], v[194:197], v[8:11]
	v_mfma_f32_16x16x32_bf16 v[62:65], v[126:129], v[202:205], v[62:65]
	v_mfma_f32_16x16x32_bf16 v[38:41], v[134:137], v[202:205], v[38:41]
	v_mfma_f32_16x16x32_bf16 v[58:61], v[126:129], v[212:215], v[58:61]
	v_mfma_f32_16x16x32_bf16 v[34:37], v[134:137], v[212:215], v[34:37]
	v_mfma_f32_16x16x32_bf16 v[4:7], v[126:129], v[220:223], v[4:7]
	v_mfma_f32_16x16x32_bf16 v[0:3], v[134:137], v[220:223], v[0:3]
	s_barrier
	s_add_i32 s63, 0, 0x18000
	s_add_i32 s64, 0, 0x1c000
	v_add_u32_e32 v78, s63, v177
	v_add_u32_e32 v134, s64, v177
	ds_read_b128 v[66:69], v78
	ds_read_b128 v[70:73], v78 offset:1024
	ds_read_b128 v[74:77], v78 offset:2048
	ds_read_b128 v[78:81], v78 offset:3072
	ds_read_b128 v[122:125], v134
	ds_read_b128 v[126:129], v134 offset:1024
	ds_read_b128 v[130:133], v134 offset:2048
	ds_read_b128 v[134:137], v134 offset:3072
	s_mov_b32 m0, s92
	s_nop 0
	global_load_lds_dwordx4 v166, s[54:55]
	s_add_u32 s54, s54, 0x80000
	s_addc_u32 s55, s55, 0
	s_mov_b32 m0, s2
	ds_read_b128 v[188:191], v193 offset:32768
	ds_read_b128 v[194:197], v193 offset:33792
	ds_read_b128 v[198:201], v193 offset:34816
	ds_read_b128 v[202:205], v193 offset:35840
	ds_read_b128 v[208:211], v193 offset:36864
	ds_read_b128 v[212:215], v193 offset:37888
	ds_read_b128 v[216:219], v193 offset:38912
	ds_read_b128 v[220:223], v193 offset:39936
	global_load_lds_dwordx4 v162, s[54:55]
	s_mov_b32 m0, s3
	s_nop 0
	global_load_lds_dwordx4 v166, s[54:55]
	s_waitcnt vmcnt(8)
	s_waitcnt lgkmcnt(0)
	s_barrier
; #define PG8_BAR __builtin_amdgcn_s_barrier()
; template <class Epi, class Sched, bool ALIGN_EPI = false, bool SP2 = false>
; __device__ __forceinline__ void gemm_phase(PG8_LAS unsigned char* lds, const Gemm g, const Sched& S, const Epi& E, const int tid_in) {
;     ...
;             if constexpr (SP2) {
;             PG8_LDB(B0, 0, 0); PG8_LDB(B1, 0, 1); PG8_SCHED; PG8_LDA(At, 0, 0); PG8_STAGE(PG8_SA(1, 1), a1 + hstep, voffA);
;             PG8_WAIT_V(8); PG8_WAIT_L(0); PG8_BAR; PG8_MMA(0, 0, At, B0); PG8_MMA(0, 1, At, B1); PG8_BAR; PG8_SCHED;
;             PG8_LDA(At, 0, 1); PG8_STAGE(PG8_SB(0, 0), b2, voffB); PG8_STAGE(PG8_SB(0, 1), b2 + hstep, voffB); PG8_STAGE(PG8_SA(0, 0), a2, voffA);
;             PG8_WAIT_V(8); PG8_WAIT_L(0); PG8_BAR; PG8_MMA(1, 0, At, B0); PG8_MMA(1, 1, At, B1); PG8_BAR; PG8_SCHED;
;             PG8_LDB(B0, 1, 0); PG8_LDB(B1, 1, 1); PG8_SCHED; PG8_LDA(At, 1, 0); PG8_STAGE(PG8_SA(0, 1), a2 + hstep, voffA);
;             PG8_WAIT_V(8); PG8_WAIT_L(0); PG8_BAR; PG8_MMA(0, 0, At, B0); PG8_MMA(0, 1, At, B1); PG8_BAR; PG8_SCHED;
;             PG8_LDA(At, 1, 1); PG8_STAGE(PG8_SB(1, 0), b3, voffB); PG8_STAGE(PG8_SB(1, 1), b3 + hstep, voffB); PG8_STAGE(PG8_SA(1, 0), a3, voffA);
;             PG8_WAIT_V(8); PG8_WAIT_L(0); PG8_BAR; PG8_MMA(1, 0, At, B0); PG8_MMA(1, 1, At, B1); PG8_BAR; PG8_SCHED;
;             } else {
;             PG8_LDB(B0, 0, 0); PG8_SCHED; PG8_LDA(At, 0, 0); PG8_STAGE(PG8_SA(1, 1), a1 + hstep, voffA);
;             PG8_WAIT_L(8); PG8_BAR; PG8_WAIT_L(0); PG8_MMA(0, 0, At, B0); PG8_BAR; PG8_SCHED;
;             PG8_LDB(B1, 0, 1); PG8_STAGE(PG8_SB(0, 0), b2, voffB);
;             PG8_BAR; PG8_WAIT_L(0); PG8_MMA(0, 1, At, B1); PG8_BAR;
;             PG8_LDA(At, 0, 1); PG8_STAGE(PG8_SA(0, 0), a2, voffA);
;             PG8_BAR; PG8_WAIT_L(0); PG8_MMA(1, 0, At, B0); PG8_BAR; PG8_SCHED;
;             PG8_STAGE(PG8_SB(0, 1), b2 + hstep, voffB);
;             PG8_WAIT_V(6); PG8_BAR; PG8_MMA(1, 1, At, B1); PG8_BAR;
;             PG8_LDB(B0, 1, 0); PG8_SCHED; PG8_LDA(At, 1, 0); PG8_STAGE(PG8_SA(0, 1), a2 + hstep, voffA);
;             PG8_WAIT_L(8); PG8_BAR; PG8_WAIT_L(0); PG8_MMA(0, 0, At, B0); PG8_BAR; PG8_SCHED;
;             PG8_LDB(B1, 1, 1); PG8_STAGE(PG8_SB(1, 0), b3, voffB);
;             PG8_BAR; PG8_WAIT_L(0); PG8_MMA(0, 1, At, B1); PG8_BAR;
;             PG8_LDA(At, 1, 1); PG8_STAGE(PG8_SA(1, 0), a3, voffA);
	v_mfma_f32_16x16x32_bf16 v[150:153], v[66:69], v[188:191], v[150:153]
	v_mfma_f32_16x16x32_bf16 v[110:113], v[74:77], v[188:191], v[110:113]
	v_mfma_f32_16x16x32_bf16 v[146:149], v[66:69], v[198:201], v[146:149]
	v_mfma_f32_16x16x32_bf16 v[106:109], v[74:77], v[198:201], v[106:109]
	v_mfma_f32_16x16x32_bf16 v[142:145], v[66:69], v[208:211], v[142:145]
	v_mfma_f32_16x16x32_bf16 v[102:105], v[74:77], v[208:211], v[102:105]
	v_mfma_f32_16x16x32_bf16 v[138:141], v[66:69], v[216:219], v[138:141]
	v_mfma_f32_16x16x32_bf16 v[98:101], v[74:77], v[216:219], v[98:101]
	v_mfma_f32_16x16x32_bf16 v[150:153], v[70:73], v[194:197], v[150:153]
	v_mfma_f32_16x16x32_bf16 v[110:113], v[78:81], v[194:197], v[110:113]
	v_mfma_f32_16x16x32_bf16 v[146:149], v[70:73], v[202:205], v[146:149]
	v_mfma_f32_16x16x32_bf16 v[106:109], v[78:81], v[202:205], v[106:109]
	v_mfma_f32_16x16x32_bf16 v[142:145], v[70:73], v[212:215], v[142:145]
	v_mfma_f32_16x16x32_bf16 v[102:105], v[78:81], v[212:215], v[102:105]
	v_mfma_f32_16x16x32_bf16 v[138:141], v[70:73], v[220:223], v[138:141]
	v_mfma_f32_16x16x32_bf16 v[98:101], v[78:81], v[220:223], v[98:101]
	v_mfma_f32_16x16x32_bf16 v[94:97], v[122:125], v[188:191], v[94:97]
	v_mfma_f32_16x16x32_bf16 v[90:93], v[130:133], v[188:191], v[90:93]
	v_mfma_f32_16x16x32_bf16 v[158:161], v[122:125], v[198:201], v[158:161]
	v_mfma_f32_16x16x32_bf16 v[118:121], v[130:133], v[198:201], v[118:121]
	v_mfma_f32_16x16x32_bf16 v[154:157], v[122:125], v[208:211], v[154:157]
	v_mfma_f32_16x16x32_bf16 v[114:117], v[130:133], v[208:211], v[114:117]
	v_mfma_f32_16x16x32_bf16 v[86:89], v[122:125], v[216:219], v[86:89]
	v_mfma_f32_16x16x32_bf16 v[82:85], v[130:133], v[216:219], v[82:85]
	v_mfma_f32_16x16x32_bf16 v[94:97], v[126:129], v[194:197], v[94:97]
	v_mfma_f32_16x16x32_bf16 v[90:93], v[134:137], v[194:197], v[90:93]
	v_mfma_f32_16x16x32_bf16 v[158:161], v[126:129], v[202:205], v[158:161]
	v_mfma_f32_16x16x32_bf16 v[118:121], v[134:137], v[202:205], v[118:121]
	v_mfma_f32_16x16x32_bf16 v[154:157], v[126:129], v[212:215], v[154:157]
	v_mfma_f32_16x16x32_bf16 v[114:117], v[134:137], v[212:215], v[114:117]
	v_mfma_f32_16x16x32_bf16 v[86:89], v[126:129], v[220:223], v[86:89]
	v_mfma_f32_16x16x32_bf16 v[82:85], v[134:137], v[220:223], v[82:85]
	s_barrier
	s_add_i32 s54, s63, s1
	s_mov_b32 m0, s54
	ds_read_b128 v[188:191], v193 offset:49152
	ds_read_b128 v[194:197], v193 offset:50176
	ds_read_b128 v[198:201], v193 offset:51200
	ds_read_b128 v[202:205], v193 offset:52224
	ds_read_b128 v[208:211], v193 offset:53248
	ds_read_b128 v[212:215], v193 offset:54272
	ds_read_b128 v[216:219], v193 offset:55296
	ds_read_b128 v[220:223], v193 offset:56320
	global_load_lds_dwordx4 v164, s[98:99]
	s_add_i32 m0, s54, 0x2000
	s_add_u32 s52, s52, 0x80080
	s_addc_u32 s53, s53, 0
	s_add_i32 s54, s64, s1
	global_load_lds_dwordx4 v168, s[98:99]
	s_mov_b32 m0, s54
	s_nop 0
	global_load_lds_dwordx4 v164, s[52:53]
	s_add_i32 m0, s54, 0x2000
	s_nop 0
	global_load_lds_dwordx4 v168, s[52:53]
	s_mov_b32 m0, s24
	s_nop 0
	global_load_lds_dwordx4 v162, s[100:101]
	s_waitcnt vmcnt(7)
	s_waitcnt lgkmcnt(0)
	s_barrier
	v_mfma_f32_16x16x32_bf16 v[54:57], v[66:69], v[188:191], v[54:57]
	v_mfma_f32_16x16x32_bf16 v[30:33], v[74:77], v[188:191], v[30:33]
	v_mfma_f32_16x16x32_bf16 v[50:53], v[66:69], v[198:201], v[50:53]
	v_mfma_f32_16x16x32_bf16 v[26:29], v[74:77], v[198:201], v[26:29]
	v_mfma_f32_16x16x32_bf16 v[46:49], v[66:69], v[208:211], v[46:49]
	v_mfma_f32_16x16x32_bf16 v[22:25], v[74:77], v[208:211], v[22:25]
	v_mfma_f32_16x16x32_bf16 v[42:45], v[66:69], v[216:219], v[42:45]
	v_mfma_f32_16x16x32_bf16 v[16:19], v[74:77], v[216:219], v[16:19]
	v_mfma_f32_16x16x32_bf16 v[54:57], v[70:73], v[194:197], v[54:57]
	v_mfma_f32_16x16x32_bf16 v[30:33], v[78:81], v[194:197], v[30:33]
	v_mfma_f32_16x16x32_bf16 v[50:53], v[70:73], v[202:205], v[50:53]
	v_mfma_f32_16x16x32_bf16 v[26:29], v[78:81], v[202:205], v[26:29]
	v_mfma_f32_16x16x32_bf16 v[46:49], v[70:73], v[212:215], v[46:49]
	v_mfma_f32_16x16x32_bf16 v[22:25], v[78:81], v[212:215], v[22:25]
	v_mfma_f32_16x16x32_bf16 v[42:45], v[70:73], v[220:223], v[42:45]
	v_mfma_f32_16x16x32_bf16 v[16:19], v[78:81], v[220:223], v[16:19]
	v_mfma_f32_16x16x32_bf16 v[12:15], v[122:125], v[188:191], v[12:15]
	v_mfma_f32_16x16x32_bf16 v[8:11], v[130:133], v[188:191], v[8:11]
	v_mfma_f32_16x16x32_bf16 v[62:65], v[122:125], v[198:201], v[62:65]
	v_mfma_f32_16x16x32_bf16 v[38:41], v[130:133], v[198:201], v[38:41]
	v_mfma_f32_16x16x32_bf16 v[58:61], v[122:125], v[208:211], v[58:61]
	v_mfma_f32_16x16x32_bf16 v[34:37], v[130:133], v[208:211], v[34:37]
	v_mfma_f32_16x16x32_bf16 v[4:7], v[122:125], v[216:219], v[4:7]
	v_mfma_f32_16x16x32_bf16 v[0:3], v[130:133], v[216:219], v[0:3]
	v_mfma_f32_16x16x32_bf16 v[12:15], v[126:129], v[194:197], v[12:15]
	v_mfma_f32_16x16x32_bf16 v[8:11], v[134:137], v[194:197], v[8:11]
	v_mfma_f32_16x16x32_bf16 v[62:65], v[126:129], v[202:205], v[62:65]
	v_mfma_f32_16x16x32_bf16 v[38:41], v[134:137], v[202:205], v[38:41]
	v_mfma_f32_16x16x32_bf16 v[58:61], v[126:129], v[212:215], v[58:61]
	v_mfma_f32_16x16x32_bf16 v[34:37], v[134:137], v[212:215], v[34:37]
	v_mfma_f32_16x16x32_bf16 v[4:7], v[126:129], v[220:223], v[4:7]
	v_mfma_f32_16x16x32_bf16 v[0:3], v[134:137], v[220:223], v[0:3]
	s_barrier
	s_add_i32 s62, s62, 2
	s_add_u32 s50, s50, 0x100
	s_addc_u32 s51, s51, 0
	s_add_u32 s60, s60, 0x100
	s_addc_u32 s61, s61, 0
	s_cmp_gt_u32 s62, 29
	s_cbranch_scc0 .LBB0_1157
	s_setprio 0
	s_and_b64 vcc, exec, s[28:29]
	s_cbranch_vccz .LBB0_1160
	s_barrier

; #define PG8_STAGE(bufoff, gbase, voff) do { _Pragma("unroll") for (int _i = 0; _i < 2; ++_i) \
;         __builtin_amdgcn_global_load_lds((const unsigned*)((const char*)(gbase) + (voff)[_i]), (PG8_LAS unsigned*)(lds + (bufoff) + ldsw + _i * 8192), 16, 0, 0); } while (0)
; #define PG8_LDA(dst, b, h) do { _Pragma("unroll") for (int m = 0; m < 4; ++m) _Pragma("unroll") for (int k = 0; k < 2; ++k) dst[m][k] = *(const PG8_LAS bf16x8*)(lds + PG8_SA(b, h) + aoff + m * 2048 + k * 1024); } while (0)
; #define PG8_LDB(dst, b, h) do { _Pragma("unroll") for (int n = 0; n < 2; ++n) _Pragma("unroll") for (int k = 0; k < 2; ++k) dst[n][k] = *(const PG8_LAS bf16x8*)(lds + PG8_SB(b, h) + boff + n * 2048 + k * 1024); } while (0)
; #define PG8_WAIT_V(n) asm volatile("s_waitcnt vmcnt(" #n ")" ::: "memory")
; #define PG8_WAIT_L(n) asm volatile("s_waitcnt lgkmcnt(" #n ")" ::: "memory")
; #define PG8_BAR __builtin_amdgcn_s_barrier()
; #define PG8_SCHED __builtin_amdgcn_sched_barrier(0)
; template <class Epi, class Sched, bool ALIGN_EPI = false, bool SP2 = false>
; __device__ __forceinline__ void gemm_phase(PG8_LAS unsigned char* lds, const Gemm g, const Sched& S, const Epi& E, const int tid_in) {
;     ...
;     for (;;) {
;         const bool has_next = S.next(ui + 1, nxt);
;         const char* nA = has_next ? (const char*)g.A + (size_t)nxt.pm * tstep : cA; const char* nB = has_next ? (const char*)g.Bt + (size_t)nxt.pn * tstep : cB;
;         for (int t = 0; t < nt; t += 2) {
;             if constexpr (Epi::KSPLIT > 0) { if (t == Epi::KSPLIT / BK) E.midk(acc, cur, wr, wc, fr, fq); }
;             const bool last = (t == nt - 2);
;             const char* a1 = cA + (size_t)(t + 1) * kstep;
;             const char* a2 = last ? nA : cA + (size_t)(t + 2) * kstep; const char* b2 = last ? nB : cB + (size_t)(t + 2) * kstep;
;             const char* a3 = a2 + kstep; const char* b3 = b2 + kstep;
;             if (last && has_next) S.a_ready(nxt);
;             if constexpr (SP2) {
;             PG8_LDB(B0, 0, 0); PG8_LDB(B1, 0, 1); PG8_SCHED; PG8_LDA(At, 0, 0); PG8_STAGE(PG8_SA(1, 1), a1 + hstep, voffA);
;             PG8_WAIT_V(8); PG8_WAIT_L(0); PG8_BAR; PG8_MMA(0, 0, At, B0); PG8_MMA(0, 1, At, B1); PG8_BAR; PG8_SCHED;
;             PG8_LDA(At, 0, 1); PG8_STAGE(PG8_SB(0, 0), b2, voffB); PG8_STAGE(PG8_SB(0, 1), b2 + hstep, voffB); PG8_STAGE(PG8_SA(0, 0), a2, voffA);
.LBB0_1304:
	s_add_u32 s54, s30, 0x100
	v_mov_b32_e32 v0, 0
	s_addc_u32 s55, s31, 0
	s_mov_b32 s56, -2
	s_cmp_lt_u32 s19, 0x1000
	s_cbranch_scc1 .LPRIO_1305
	s_setprio 1
.LPRIO_1305:
	s_mov_b32 m0, s47
	s_nop 0
	global_load_lds_dwordx4 v216, s[100:101]
	s_add_u32 s30, s28, 0x100
	s_addc_u32 s31, s29, 0
	s_add_i32 s57, 0, 0x10000
	s_cmpk_eq_i32 s56, 0x54
	s_cselect_b32 s39, s25, s31
	s_cselect_b32 s38, s24, s30
	s_cselect_b32 s35, s27, s55
	s_cselect_b32 s34, s26, s54
	s_add_i32 s58, 0, 0x14000
	v_add_u32_e32 v102, s57, v208
	v_add_u32_e32 v142, s58, v208
	ds_read_b128 v[78:81], v102
	ds_read_b128 v[86:89], v102 offset:1024
	ds_read_b128 v[94:97], v102 offset:2048
	ds_read_b128 v[102:105], v102 offset:3072
	ds_read_b128 v[118:121], v142
	ds_read_b128 v[126:129], v142 offset:1024
	ds_read_b128 v[134:137], v142 offset:2048
	ds_read_b128 v[142:145], v142 offset:3072
	v_lshl_add_u64 v[194:195], s[28:29], 0, v[222:223]
	s_add_i32 m0, s40, 0xc000
	ds_read_b128 v[154:157], v244
	ds_read_b128 v[158:161], v244 offset:1024
	ds_read_b128 v[162:165], v244 offset:2048
	ds_read_b128 v[166:169], v244 offset:3072
	ds_read_b128 v[170:173], v244 offset:4096
	ds_read_b128 v[182:185], v244 offset:5120
	ds_read_b128 v[186:189], v244 offset:6144
	ds_read_b128 v[190:193], v244 offset:7168
	global_load_lds_dwordx4 v[194:195], off
	v_lshl_add_u64 v[194:195], s[28:29], 0, v[224:225]
	s_add_i32 m0, s40, 0xe000
	s_nop 0
	global_load_lds_dwordx4 v[194:195], off
	s_waitcnt vmcnt(8)
	s_waitcnt lgkmcnt(0)
	s_barrier
	v_mfma_f32_16x16x32_bf16 v[178:181], v[78:81], v[154:157], 0
	v_mfma_f32_16x16x32_bf16 v[174:177], v[94:97], v[154:157], 0
	v_mfma_f32_16x16x32_bf16 v[138:141], v[78:81], v[162:165], 0
	v_mfma_f32_16x16x32_bf16 v[130:133], v[94:97], v[162:165], 0
	v_mfma_f32_16x16x32_bf16 v[110:113], v[78:81], v[170:173], 0
	v_mfma_f32_16x16x32_bf16 v[106:109], v[94:97], v[170:173], 0
	v_mfma_f32_16x16x32_bf16 v[82:85], v[78:81], v[186:189], 0
	v_mfma_f32_16x16x32_bf16 v[74:77], v[94:97], v[186:189], 0
	v_mfma_f32_16x16x32_bf16 v[178:181], v[86:89], v[158:161], v[178:181]
	v_mfma_f32_16x16x32_bf16 v[174:177], v[102:105], v[158:161], v[174:177]
	v_mfma_f32_16x16x32_bf16 v[138:141], v[86:89], v[166:169], v[138:141]
	v_mfma_f32_16x16x32_bf16 v[130:133], v[102:105], v[166:169], v[130:133]
	v_mfma_f32_16x16x32_bf16 v[110:113], v[86:89], v[182:185], v[110:113]
	v_mfma_f32_16x16x32_bf16 v[106:109], v[102:105], v[182:185], v[106:109]
	v_mfma_f32_16x16x32_bf16 v[82:85], v[86:89], v[190:193], v[82:85]
	v_mfma_f32_16x16x32_bf16 v[74:77], v[102:105], v[190:193], v[74:77]
	v_mfma_f32_16x16x32_bf16 v[150:153], v[118:121], v[154:157], 0
	v_mfma_f32_16x16x32_bf16 v[146:149], v[134:137], v[154:157], 0
	v_mfma_f32_16x16x32_bf16 v[122:125], v[118:121], v[162:165], 0
	v_mfma_f32_16x16x32_bf16 v[114:117], v[134:137], v[162:165], 0
	v_mfma_f32_16x16x32_bf16 v[98:101], v[118:121], v[170:173], 0
	v_mfma_f32_16x16x32_bf16 v[90:93], v[134:137], v[170:173], 0
	v_mfma_f32_16x16x32_bf16 v[70:73], v[118:121], v[186:189], 0
	v_mfma_f32_16x16x32_bf16 v[66:69], v[134:137], v[186:189], 0
	v_mfma_f32_16x16x32_bf16 v[150:153], v[126:129], v[158:161], v[150:153]
	v_mfma_f32_16x16x32_bf16 v[146:149], v[142:145], v[158:161], v[146:149]
	v_mfma_f32_16x16x32_bf16 v[122:125], v[126:129], v[166:169], v[122:125]
	v_mfma_f32_16x16x32_bf16 v[114:117], v[142:145], v[166:169], v[114:117]
	v_mfma_f32_16x16x32_bf16 v[98:101], v[126:129], v[182:185], v[98:101]
	v_mfma_f32_16x16x32_bf16 v[90:93], v[142:145], v[182:185], v[90:93]
	v_mfma_f32_16x16x32_bf16 v[70:73], v[126:129], v[190:193], v[70:73]
	v_mfma_f32_16x16x32_bf16 v[66:69], v[142:145], v[190:193], v[66:69]
	s_barrier
	s_add_i32 s28, s57, s19
	s_add_u32 s98, s34, 0x80
	s_addc_u32 s99, s35, 0
	s_mov_b32 m0, s28
	ds_read_b128 v[154:157], v244 offset:16384
	ds_read_b128 v[158:161], v244 offset:17408
	ds_read_b128 v[162:165], v244 offset:18432
	ds_read_b128 v[166:169], v244 offset:19456
	ds_read_b128 v[170:173], v244 offset:20480
	ds_read_b128 v[182:185], v244 offset:21504
	ds_read_b128 v[186:189], v244 offset:22528
	ds_read_b128 v[190:193], v244 offset:23552
	global_load_lds_dwordx4 v218, s[34:35]
	s_add_i32 m0, s28, 0x2000
	s_add_u32 s28, s34, 0x160000
	s_addc_u32 s29, s35, 0
	s_add_i32 s57, s58, s19
	global_load_lds_dwordx4 v214, s[34:35]
	s_mov_b32 m0, s57
	s_add_u32 s100, s38, 0x80
	s_addc_u32 s101, s39, 0
	global_load_lds_dwordx4 v218, s[28:29]
	s_add_i32 m0, s57, 0x2000
	s_nop 0
	global_load_lds_dwordx4 v214, s[28:29]
	s_mov_b32 m0, s40
	s_nop 0
	global_load_lds_dwordx4 v220, s[38:39]
	s_waitcnt vmcnt(7)
	s_waitcnt lgkmcnt(0)
	s_barrier
	v_mfma_f32_16x16x32_bf16 v[62:65], v[78:81], v[154:157], 0
	v_mfma_f32_16x16x32_bf16 v[58:61], v[94:97], v[154:157], 0
	v_mfma_f32_16x16x32_bf16 v[46:49], v[78:81], v[162:165], 0
	v_mfma_f32_16x16x32_bf16 v[42:45], v[94:97], v[162:165], 0
	v_mfma_f32_16x16x32_bf16 v[30:33], v[78:81], v[170:173], 0
	v_mfma_f32_16x16x32_bf16 v[26:29], v[94:97], v[170:173], 0
	v_mfma_f32_16x16x32_bf16 v[12:15], v[78:81], v[186:189], 0
	v_mfma_f32_16x16x32_bf16 v[8:11], v[94:97], v[186:189], 0
	v_mfma_f32_16x16x32_bf16 v[62:65], v[86:89], v[158:161], v[62:65]
	v_mfma_f32_16x16x32_bf16 v[58:61], v[102:105], v[158:161], v[58:61]
	v_mfma_f32_16x16x32_bf16 v[46:49], v[86:89], v[166:169], v[46:49]
	v_mfma_f32_16x16x32_bf16 v[42:45], v[102:105], v[166:169], v[42:45]
	v_mfma_f32_16x16x32_bf16 v[30:33], v[86:89], v[182:185], v[30:33]
	v_mfma_f32_16x16x32_bf16 v[26:29], v[102:105], v[182:185], v[26:29]
	v_mfma_f32_16x16x32_bf16 v[12:15], v[86:89], v[190:193], v[12:15]
	v_mfma_f32_16x16x32_bf16 v[8:11], v[102:105], v[190:193], v[8:11]
	v_mfma_f32_16x16x32_bf16 v[54:57], v[118:121], v[154:157], 0
	v_mfma_f32_16x16x32_bf16 v[50:53], v[134:137], v[154:157], 0
	v_mfma_f32_16x16x32_bf16 v[38:41], v[118:121], v[162:165], 0
	v_mfma_f32_16x16x32_bf16 v[34:37], v[134:137], v[162:165], 0
	v_mfma_f32_16x16x32_bf16 v[22:25], v[118:121], v[170:173], 0
	v_mfma_f32_16x16x32_bf16 v[16:19], v[134:137], v[170:173], 0
	v_mfma_f32_16x16x32_bf16 v[4:7], v[118:121], v[186:189], 0
	v_mfma_f32_16x16x32_bf16 v[0:3], v[134:137], v[186:189], 0
	v_mfma_f32_16x16x32_bf16 v[54:57], v[126:129], v[158:161], v[54:57]
	v_mfma_f32_16x16x32_bf16 v[50:53], v[142:145], v[158:161], v[50:53]
	v_mfma_f32_16x16x32_bf16 v[38:41], v[126:129], v[166:169], v[38:41]
	v_mfma_f32_16x16x32_bf16 v[34:37], v[142:145], v[166:169], v[34:37]
	v_mfma_f32_16x16x32_bf16 v[22:25], v[126:129], v[182:185], v[22:25]
	v_mfma_f32_16x16x32_bf16 v[16:19], v[142:145], v[182:185], v[16:19]
	v_mfma_f32_16x16x32_bf16 v[4:7], v[126:129], v[190:193], v[4:7]
	v_mfma_f32_16x16x32_bf16 v[0:3], v[142:145], v[190:193], v[0:3]
	s_barrier
; #define PG8_STAGE(bufoff, gbase, voff) do { _Pragma("unroll") for (int _i = 0; _i < 2; ++_i) \
;         __builtin_amdgcn_global_load_lds((const unsigned*)((const char*)(gbase) + (voff)[_i]), (PG8_LAS unsigned*)(lds + (bufoff) + ldsw + _i * 8192), 16, 0, 0); } while (0)
; #define PG8_LDA(dst, b, h) do { _Pragma("unroll") for (int m = 0; m < 4; ++m) _Pragma("unroll") for (int k = 0; k < 2; ++k) dst[m][k] = *(const PG8_LAS bf16x8*)(lds + PG8_SA(b, h) + aoff + m * 2048 + k * 1024); } while (0)
; #define PG8_LDB(dst, b, h) do { _Pragma("unroll") for (int n = 0; n < 2; ++n) _Pragma("unroll") for (int k = 0; k < 2; ++k) dst[n][k] = *(const PG8_LAS bf16x8*)(lds + PG8_SB(b, h) + boff + n * 2048 + k * 1024); } while (0)
; #define PG8_MMA(ai, bj, At, Bt) do { __builtin_amdgcn_s_setprio(1); _Pragma("unroll") for (int m = 0; m < 4; ++m) _Pragma("unroll") for (int n = 0; n < 2; ++n) _Pragma("unroll") for (int k = 0; k < 2; ++k) \
;         acc[ai][bj][m][n] = __builtin_amdgcn_mfma_f32_16x16x32_bf16(Bt[n][k], At[m][k], acc[ai][bj][m][n], 0, 0, 0); __builtin_amdgcn_s_setprio(0); } while (0)
; #define PG8_WAIT_V(n) asm volatile("s_waitcnt vmcnt(" #n ")" ::: "memory")
; #define PG8_WAIT_L(n) asm volatile("s_waitcnt lgkmcnt(" #n ")" ::: "memory")
; #define PG8_BAR __builtin_amdgcn_s_barrier()
; #define PG8_SCHED __builtin_amdgcn_sched_barrier(0)
; template <class Epi, class Sched, bool ALIGN_EPI = false, bool SP2 = false>
; __device__ __forceinline__ void gemm_phase(PG8_LAS unsigned char* lds, const Gemm g, const Sched& S, const Epi& E, const int tid_in) {
;     ...
;             PG8_LDB(B0, 1, 0); PG8_LDB(B1, 1, 1); PG8_SCHED; PG8_LDA(At, 1, 0); PG8_STAGE(PG8_SA(0, 1), a2 + hstep, voffA);
;             PG8_WAIT_V(8); PG8_WAIT_L(0); PG8_BAR; PG8_MMA(0, 0, At, B0); PG8_MMA(0, 1, At, B1); PG8_BAR; PG8_SCHED;
;             PG8_LDA(At, 1, 1); PG8_STAGE(PG8_SB(1, 0), b3, voffB); PG8_STAGE(PG8_SB(1, 1), b3 + hstep, voffB); PG8_STAGE(PG8_SA(1, 0), a3, voffA);
;             PG8_WAIT_V(8); PG8_WAIT_L(0); PG8_BAR; PG8_MMA(1, 0, At, B0); PG8_MMA(1, 1, At, B1); PG8_BAR; PG8_SCHED;
	s_add_i32 s57, 0, 0x18000
	s_add_i32 s58, 0, 0x1c000
	v_add_u32_e32 v102, s57, v208
	v_add_u32_e32 v142, s58, v208
	ds_read_b128 v[78:81], v102
	ds_read_b128 v[86:89], v102 offset:1024
	ds_read_b128 v[94:97], v102 offset:2048
	ds_read_b128 v[102:105], v102 offset:3072
	ds_read_b128 v[118:121], v142
	ds_read_b128 v[126:129], v142 offset:1024
	ds_read_b128 v[134:137], v142 offset:2048
	ds_read_b128 v[142:145], v142 offset:3072
	s_add_u32 s28, s38, 0x160000
	s_addc_u32 s29, s39, 0
	s_mov_b32 m0, s41
	s_nop 0
	global_load_lds_dwordx4 v216, s[38:39]
	s_mov_b32 m0, s42
	ds_read_b128 v[154:157], v244 offset:32768
	ds_read_b128 v[158:161], v244 offset:33792
	ds_read_b128 v[162:165], v244 offset:34816
	ds_read_b128 v[166:169], v244 offset:35840
	ds_read_b128 v[170:173], v244 offset:36864
	ds_read_b128 v[182:185], v244 offset:37888
	ds_read_b128 v[186:189], v244 offset:38912
	ds_read_b128 v[190:193], v244 offset:39936
	global_load_lds_dwordx4 v220, s[28:29]
	s_mov_b32 m0, s43
	s_nop 0
	global_load_lds_dwordx4 v216, s[28:29]
	s_waitcnt vmcnt(8)
	s_waitcnt lgkmcnt(0)
	s_barrier
	v_mfma_f32_16x16x32_bf16 v[178:181], v[78:81], v[154:157], v[178:181]
	v_mfma_f32_16x16x32_bf16 v[174:177], v[94:97], v[154:157], v[174:177]
	v_mfma_f32_16x16x32_bf16 v[138:141], v[78:81], v[162:165], v[138:141]
	v_mfma_f32_16x16x32_bf16 v[130:133], v[94:97], v[162:165], v[130:133]
	v_mfma_f32_16x16x32_bf16 v[110:113], v[78:81], v[170:173], v[110:113]
	v_mfma_f32_16x16x32_bf16 v[106:109], v[94:97], v[170:173], v[106:109]
	v_mfma_f32_16x16x32_bf16 v[82:85], v[78:81], v[186:189], v[82:85]
	v_mfma_f32_16x16x32_bf16 v[74:77], v[94:97], v[186:189], v[74:77]
	v_mfma_f32_16x16x32_bf16 v[178:181], v[86:89], v[158:161], v[178:181]
	v_mfma_f32_16x16x32_bf16 v[174:177], v[102:105], v[158:161], v[174:177]
	v_mfma_f32_16x16x32_bf16 v[138:141], v[86:89], v[166:169], v[138:141]
	v_mfma_f32_16x16x32_bf16 v[130:133], v[102:105], v[166:169], v[130:133]
	v_mfma_f32_16x16x32_bf16 v[110:113], v[86:89], v[182:185], v[110:113]
	v_mfma_f32_16x16x32_bf16 v[106:109], v[102:105], v[182:185], v[106:109]
	v_mfma_f32_16x16x32_bf16 v[82:85], v[86:89], v[190:193], v[82:85]
	v_mfma_f32_16x16x32_bf16 v[74:77], v[102:105], v[190:193], v[74:77]
	v_mfma_f32_16x16x32_bf16 v[150:153], v[118:121], v[154:157], v[150:153]
	v_mfma_f32_16x16x32_bf16 v[146:149], v[134:137], v[154:157], v[146:149]
	v_mfma_f32_16x16x32_bf16 v[122:125], v[118:121], v[162:165], v[122:125]
	v_mfma_f32_16x16x32_bf16 v[114:117], v[134:137], v[162:165], v[114:117]
	v_mfma_f32_16x16x32_bf16 v[98:101], v[118:121], v[170:173], v[98:101]
	v_mfma_f32_16x16x32_bf16 v[90:93], v[134:137], v[170:173], v[90:93]
	v_mfma_f32_16x16x32_bf16 v[70:73], v[118:121], v[186:189], v[70:73]
	v_mfma_f32_16x16x32_bf16 v[66:69], v[134:137], v[186:189], v[66:69]
	v_mfma_f32_16x16x32_bf16 v[150:153], v[126:129], v[158:161], v[150:153]
	v_mfma_f32_16x16x32_bf16 v[146:149], v[142:145], v[158:161], v[146:149]
	v_mfma_f32_16x16x32_bf16 v[122:125], v[126:129], v[166:169], v[122:125]
	v_mfma_f32_16x16x32_bf16 v[114:117], v[142:145], v[166:169], v[114:117]
	v_mfma_f32_16x16x32_bf16 v[98:101], v[126:129], v[182:185], v[98:101]
	v_mfma_f32_16x16x32_bf16 v[90:93], v[142:145], v[182:185], v[90:93]
	v_mfma_f32_16x16x32_bf16 v[70:73], v[126:129], v[190:193], v[70:73]
	v_mfma_f32_16x16x32_bf16 v[66:69], v[142:145], v[190:193], v[66:69]
	s_barrier
	s_add_i32 s28, s57, s19
	s_mov_b32 m0, s28
	ds_read_b128 v[154:157], v244 offset:49152
	ds_read_b128 v[158:161], v244 offset:50176
	ds_read_b128 v[162:165], v244 offset:51200
	ds_read_b128 v[166:169], v244 offset:52224
	ds_read_b128 v[170:173], v244 offset:53248
	ds_read_b128 v[182:185], v244 offset:54272
	ds_read_b128 v[186:189], v244 offset:55296
	ds_read_b128 v[190:193], v244 offset:56320
	global_load_lds_dwordx4 v218, s[98:99]
	s_add_i32 m0, s28, 0x2000
	s_add_u32 s28, s34, 0x160080
	s_addc_u32 s29, s35, 0
	s_add_i32 s34, s58, s19
	global_load_lds_dwordx4 v214, s[98:99]
	s_mov_b32 m0, s34
	s_nop 0
	global_load_lds_dwordx4 v218, s[28:29]
	s_add_i32 m0, s34, 0x2000
	s_nop 0
	global_load_lds_dwordx4 v214, s[28:29]
	s_mov_b32 m0, s46
	s_nop 0
	global_load_lds_dwordx4 v220, s[100:101]
	s_waitcnt vmcnt(7)
	s_waitcnt lgkmcnt(0)
	s_barrier
	v_mfma_f32_16x16x32_bf16 v[62:65], v[78:81], v[154:157], v[62:65]
	v_mfma_f32_16x16x32_bf16 v[58:61], v[94:97], v[154:157], v[58:61]
	v_mfma_f32_16x16x32_bf16 v[46:49], v[78:81], v[162:165], v[46:49]
	v_mfma_f32_16x16x32_bf16 v[42:45], v[94:97], v[162:165], v[42:45]
	v_mfma_f32_16x16x32_bf16 v[30:33], v[78:81], v[170:173], v[30:33]
	v_mfma_f32_16x16x32_bf16 v[26:29], v[94:97], v[170:173], v[26:29]
	v_mfma_f32_16x16x32_bf16 v[12:15], v[78:81], v[186:189], v[12:15]
	v_mfma_f32_16x16x32_bf16 v[8:11], v[94:97], v[186:189], v[8:11]
	v_mfma_f32_16x16x32_bf16 v[62:65], v[86:89], v[158:161], v[62:65]
	v_mfma_f32_16x16x32_bf16 v[58:61], v[102:105], v[158:161], v[58:61]
	v_mfma_f32_16x16x32_bf16 v[46:49], v[86:89], v[166:169], v[46:49]
	v_mfma_f32_16x16x32_bf16 v[42:45], v[102:105], v[166:169], v[42:45]
	v_mfma_f32_16x16x32_bf16 v[30:33], v[86:89], v[182:185], v[30:33]
	v_mfma_f32_16x16x32_bf16 v[26:29], v[102:105], v[182:185], v[26:29]
	v_mfma_f32_16x16x32_bf16 v[12:15], v[86:89], v[190:193], v[12:15]
	v_mfma_f32_16x16x32_bf16 v[8:11], v[102:105], v[190:193], v[8:11]
	v_mfma_f32_16x16x32_bf16 v[54:57], v[118:121], v[154:157], v[54:57]
	v_mfma_f32_16x16x32_bf16 v[50:53], v[134:137], v[154:157], v[50:53]
	v_mfma_f32_16x16x32_bf16 v[38:41], v[118:121], v[162:165], v[38:41]
	v_mfma_f32_16x16x32_bf16 v[34:37], v[134:137], v[162:165], v[34:37]
	v_mfma_f32_16x16x32_bf16 v[22:25], v[118:121], v[170:173], v[22:25]
	v_mfma_f32_16x16x32_bf16 v[16:19], v[134:137], v[170:173], v[16:19]
	v_mfma_f32_16x16x32_bf16 v[4:7], v[118:121], v[186:189], v[4:7]
	v_mfma_f32_16x16x32_bf16 v[0:3], v[134:137], v[186:189], v[0:3]
	v_mfma_f32_16x16x32_bf16 v[54:57], v[126:129], v[158:161], v[54:57]
	v_mfma_f32_16x16x32_bf16 v[50:53], v[142:145], v[158:161], v[50:53]
	v_mfma_f32_16x16x32_bf16 v[38:41], v[126:129], v[166:169], v[38:41]
	v_mfma_f32_16x16x32_bf16 v[34:37], v[142:145], v[166:169], v[34:37]
	v_mfma_f32_16x16x32_bf16 v[22:25], v[126:129], v[182:185], v[22:25]
	v_mfma_f32_16x16x32_bf16 v[16:19], v[142:145], v[182:185], v[16:19]
	v_mfma_f32_16x16x32_bf16 v[4:7], v[126:129], v[190:193], v[4:7]
	v_mfma_f32_16x16x32_bf16 v[0:3], v[142:145], v[190:193], v[0:3]
	s_barrier
	s_add_i32 s56, s56, 2
	s_add_u32 s54, s54, 0x100
	s_addc_u32 s55, s55, 0
	s_cmpk_gt_u32 s56, 0x55
	s_mov_b64 s[28:29], s[30:31]
; #define PG8_STAGE(bufoff, gbase, voff) do { _Pragma("unroll") for (int _i = 0; _i < 2; ++_i) \
;         __builtin_amdgcn_global_load_lds((const unsigned*)((const char*)(gbase) + (voff)[_i]), (PG8_LAS unsigned*)(lds + (bufoff) + ldsw + _i * 8192), 16, 0, 0); } while (0)
; #define PG8_LDA(dst, b, h) do { _Pragma("unroll") for (int m = 0; m < 4; ++m) _Pragma("unroll") for (int k = 0; k < 2; ++k) dst[m][k] = *(const PG8_LAS bf16x8*)(lds + PG8_SA(b, h) + aoff + m * 2048 + k * 1024); } while (0)
; #define PG8_LDB(dst, b, h) do { _Pragma("unroll") for (int n = 0; n < 2; ++n) _Pragma("unroll") for (int k = 0; k < 2; ++k) dst[n][k] = *(const PG8_LAS bf16x8*)(lds + PG8_SB(b, h) + boff + n * 2048 + k * 1024); } while (0)
; #define PG8_MMA(ai, bj, At, Bt) do { __builtin_amdgcn_s_setprio(1); _Pragma("unroll") for (int m = 0; m < 4; ++m) _Pragma("unroll") for (int n = 0; n < 2; ++n) _Pragma("unroll") for (int k = 0; k < 2; ++k) \
;         acc[ai][bj][m][n] = __builtin_amdgcn_mfma_f32_16x16x32_bf16(Bt[n][k], At[m][k], acc[ai][bj][m][n], 0, 0, 0); __builtin_amdgcn_s_setprio(0); } while (0)
; #define PG8_WAIT_V(n) asm volatile("s_waitcnt vmcnt(" #n ")" ::: "memory")
; #define PG8_WAIT_L(n) asm volatile("s_waitcnt lgkmcnt(" #n ")" ::: "memory")
; template <class Epi, class Sched, bool ALIGN_EPI = false, bool SP2 = false>
; __device__ __forceinline__ void gemm_phase(PG8_LAS unsigned char* lds, const Gemm g, const Sched& S, const Epi& E, const int tid_in) {
;     ...
;             const bool last = (t == nt - 2);
;             const char* a1 = cA + (size_t)(t + 1) * kstep;
;             const char* a2 = last ? nA : cA + (size_t)(t + 2) * kstep; const char* b2 = last ? nB : cB + (size_t)(t + 2) * kstep;
;             const char* a3 = a2 + kstep; const char* b3 = b2 + kstep;
;             if (last && has_next) S.a_ready(nxt);
;             if constexpr (SP2) {
;             PG8_LDB(B0, 0, 0); PG8_LDB(B1, 0, 1); PG8_SCHED; PG8_LDA(At, 0, 0); PG8_STAGE(PG8_SA(1, 1), a1 + hstep, voffA);
;             PG8_WAIT_V(8); PG8_WAIT_L(0); PG8_BAR; PG8_MMA(0, 0, At, B0); PG8_MMA(0, 1, At, B1); PG8_BAR; PG8_SCHED;
;             PG8_LDA(At, 0, 1); PG8_STAGE(PG8_SB(0, 0), b2, voffB); PG8_STAGE(PG8_SB(0, 1), b2 + hstep, voffB); PG8_STAGE(PG8_SA(0, 0), a2, voffA);
;             PG8_WAIT_V(8); PG8_WAIT_L(0); PG8_BAR; PG8_MMA(1, 0, At, B0); PG8_MMA(1, 1, At, B1); PG8_BAR; PG8_SCHED;
.LBB0_1305:
	s_mov_b32 m0, s47
	s_nop 0
	global_load_lds_dwordx4 v216, s[100:101]
	s_add_u32 s30, s28, 0x100
	s_addc_u32 s31, s29, 0
	s_add_i32 s57, 0, 0x10000
	s_cmpk_eq_i32 s56, 0x54
	s_cselect_b32 s39, s25, s31
	s_cselect_b32 s38, s24, s30
	s_cselect_b32 s35, s27, s55
	s_cselect_b32 s34, s26, s54
	s_add_i32 s58, 0, 0x14000
	v_add_u32_e32 v102, s57, v208
	v_add_u32_e32 v142, s58, v208
	ds_read_b128 v[78:81], v102
	ds_read_b128 v[86:89], v102 offset:1024
	ds_read_b128 v[94:97], v102 offset:2048
	ds_read_b128 v[102:105], v102 offset:3072
	ds_read_b128 v[118:121], v142
	ds_read_b128 v[126:129], v142 offset:1024
	ds_read_b128 v[134:137], v142 offset:2048
	ds_read_b128 v[142:145], v142 offset:3072
	v_lshl_add_u64 v[194:195], s[28:29], 0, v[222:223]
	s_add_i32 m0, s40, 0xc000
	ds_read_b128 v[154:157], v244
	ds_read_b128 v[158:161], v244 offset:1024
	ds_read_b128 v[162:165], v244 offset:2048
	ds_read_b128 v[166:169], v244 offset:3072
	ds_read_b128 v[170:173], v244 offset:4096
	ds_read_b128 v[182:185], v244 offset:5120
	ds_read_b128 v[186:189], v244 offset:6144
	ds_read_b128 v[190:193], v244 offset:7168
	global_load_lds_dwordx4 v[194:195], off
	v_lshl_add_u64 v[194:195], s[28:29], 0, v[224:225]
	s_add_i32 m0, s40, 0xe000
	s_nop 0
	global_load_lds_dwordx4 v[194:195], off
	s_waitcnt vmcnt(8)
	s_waitcnt lgkmcnt(0)
	s_barrier
	v_mfma_f32_16x16x32_bf16 v[178:181], v[78:81], v[154:157], v[178:181]
	v_mfma_f32_16x16x32_bf16 v[174:177], v[94:97], v[154:157], v[174:177]
	v_mfma_f32_16x16x32_bf16 v[138:141], v[78:81], v[162:165], v[138:141]
	v_mfma_f32_16x16x32_bf16 v[130:133], v[94:97], v[162:165], v[130:133]
	v_mfma_f32_16x16x32_bf16 v[110:113], v[78:81], v[170:173], v[110:113]
	v_mfma_f32_16x16x32_bf16 v[106:109], v[94:97], v[170:173], v[106:109]
	v_mfma_f32_16x16x32_bf16 v[82:85], v[78:81], v[186:189], v[82:85]
	v_mfma_f32_16x16x32_bf16 v[74:77], v[94:97], v[186:189], v[74:77]
	v_mfma_f32_16x16x32_bf16 v[178:181], v[86:89], v[158:161], v[178:181]
	v_mfma_f32_16x16x32_bf16 v[174:177], v[102:105], v[158:161], v[174:177]
	v_mfma_f32_16x16x32_bf16 v[138:141], v[86:89], v[166:169], v[138:141]
	v_mfma_f32_16x16x32_bf16 v[130:133], v[102:105], v[166:169], v[130:133]
	v_mfma_f32_16x16x32_bf16 v[110:113], v[86:89], v[182:185], v[110:113]
	v_mfma_f32_16x16x32_bf16 v[106:109], v[102:105], v[182:185], v[106:109]
	v_mfma_f32_16x16x32_bf16 v[82:85], v[86:89], v[190:193], v[82:85]
	v_mfma_f32_16x16x32_bf16 v[74:77], v[102:105], v[190:193], v[74:77]
	v_mfma_f32_16x16x32_bf16 v[150:153], v[118:121], v[154:157], v[150:153]
	v_mfma_f32_16x16x32_bf16 v[146:149], v[134:137], v[154:157], v[146:149]
	v_mfma_f32_16x16x32_bf16 v[122:125], v[118:121], v[162:165], v[122:125]
	v_mfma_f32_16x16x32_bf16 v[114:117], v[134:137], v[162:165], v[114:117]
	v_mfma_f32_16x16x32_bf16 v[98:101], v[118:121], v[170:173], v[98:101]
	v_mfma_f32_16x16x32_bf16 v[90:93], v[134:137], v[170:173], v[90:93]
	v_mfma_f32_16x16x32_bf16 v[70:73], v[118:121], v[186:189], v[70:73]
	v_mfma_f32_16x16x32_bf16 v[66:69], v[134:137], v[186:189], v[66:69]
	v_mfma_f32_16x16x32_bf16 v[150:153], v[126:129], v[158:161], v[150:153]
	v_mfma_f32_16x16x32_bf16 v[146:149], v[142:145], v[158:161], v[146:149]
	v_mfma_f32_16x16x32_bf16 v[122:125], v[126:129], v[166:169], v[122:125]
	v_mfma_f32_16x16x32_bf16 v[114:117], v[142:145], v[166:169], v[114:117]
	v_mfma_f32_16x16x32_bf16 v[98:101], v[126:129], v[182:185], v[98:101]
	v_mfma_f32_16x16x32_bf16 v[90:93], v[142:145], v[182:185], v[90:93]
	v_mfma_f32_16x16x32_bf16 v[70:73], v[126:129], v[190:193], v[70:73]
	v_mfma_f32_16x16x32_bf16 v[66:69], v[142:145], v[190:193], v[66:69]
	s_barrier
	s_add_i32 s28, s57, s19
	s_add_u32 s98, s34, 0x80
	s_addc_u32 s99, s35, 0
	s_mov_b32 m0, s28
	ds_read_b128 v[154:157], v244 offset:16384
	ds_read_b128 v[158:161], v244 offset:17408
	ds_read_b128 v[162:165], v244 offset:18432
	ds_read_b128 v[166:169], v244 offset:19456
	ds_read_b128 v[170:173], v244 offset:20480
	ds_read_b128 v[182:185], v244 offset:21504
	ds_read_b128 v[186:189], v244 offset:22528
	ds_read_b128 v[190:193], v244 offset:23552
	global_load_lds_dwordx4 v218, s[34:35]
	s_add_i32 m0, s28, 0x2000
	s_add_u32 s28, s34, 0x160000
	s_addc_u32 s29, s35, 0
	s_add_i32 s57, s58, s19
	global_load_lds_dwordx4 v214, s[34:35]
	s_mov_b32 m0, s57
	s_add_u32 s100, s38, 0x80
	s_addc_u32 s101, s39, 0
	global_load_lds_dwordx4 v218, s[28:29]
	s_add_i32 m0, s57, 0x2000
	s_nop 0
	global_load_lds_dwordx4 v214, s[28:29]
	s_mov_b32 m0, s40
	s_nop 0
	global_load_lds_dwordx4 v220, s[38:39]
	s_waitcnt vmcnt(7)
	s_waitcnt lgkmcnt(0)
	s_barrier
; #define PG8_STAGE(bufoff, gbase, voff) do { _Pragma("unroll") for (int _i = 0; _i < 2; ++_i) \
;         __builtin_amdgcn_global_load_lds((const unsigned*)((const char*)(gbase) + (voff)[_i]), (PG8_LAS unsigned*)(lds + (bufoff) + ldsw + _i * 8192), 16, 0, 0); } while (0)
; #define PG8_LDA(dst, b, h) do { _Pragma("unroll") for (int m = 0; m < 4; ++m) _Pragma("unroll") for (int k = 0; k < 2; ++k) dst[m][k] = *(const PG8_LAS bf16x8*)(lds + PG8_SA(b, h) + aoff + m * 2048 + k * 1024); } while (0)
; #define PG8_LDB(dst, b, h) do { _Pragma("unroll") for (int n = 0; n < 2; ++n) _Pragma("unroll") for (int k = 0; k < 2; ++k) dst[n][k] = *(const PG8_LAS bf16x8*)(lds + PG8_SB(b, h) + boff + n * 2048 + k * 1024); } while (0)
; #define PG8_MMA(ai, bj, At, Bt) do { __builtin_amdgcn_s_setprio(1); _Pragma("unroll") for (int m = 0; m < 4; ++m) _Pragma("unroll") for (int n = 0; n < 2; ++n) _Pragma("unroll") for (int k = 0; k < 2; ++k) \
;         acc[ai][bj][m][n] = __builtin_amdgcn_mfma_f32_16x16x32_bf16(Bt[n][k], At[m][k], acc[ai][bj][m][n], 0, 0, 0); __builtin_amdgcn_s_setprio(0); } while (0)
; #define PG8_WAIT_V(n) asm volatile("s_waitcnt vmcnt(" #n ")" ::: "memory")
; #define PG8_WAIT_L(n) asm volatile("s_waitcnt lgkmcnt(" #n ")" ::: "memory")
; #define PG8_BAR __builtin_amdgcn_s_barrier()
; #define PG8_SCHED __builtin_amdgcn_sched_barrier(0)
; template <class Epi, class Sched, bool ALIGN_EPI = false, bool SP2 = false>
; __device__ __forceinline__ void gemm_phase(PG8_LAS unsigned char* lds, const Gemm g, const Sched& S, const Epi& E, const int tid_in) {
;     ...
;             PG8_WAIT_V(8); PG8_WAIT_L(0); PG8_BAR; PG8_MMA(1, 0, At, B0); PG8_MMA(1, 1, At, B1); PG8_BAR; PG8_SCHED;
;             PG8_LDB(B0, 1, 0); PG8_LDB(B1, 1, 1); PG8_SCHED; PG8_LDA(At, 1, 0); PG8_STAGE(PG8_SA(0, 1), a2 + hstep, voffA);
;             PG8_WAIT_V(8); PG8_WAIT_L(0); PG8_BAR; PG8_MMA(0, 0, At, B0); PG8_MMA(0, 1, At, B1); PG8_BAR; PG8_SCHED;
;             PG8_LDA(At, 1, 1); PG8_STAGE(PG8_SB(1, 0), b3, voffB); PG8_STAGE(PG8_SB(1, 1), b3 + hstep, voffB); PG8_STAGE(PG8_SA(1, 0), a3, voffA);
	v_mfma_f32_16x16x32_bf16 v[62:65], v[78:81], v[154:157], v[62:65]
	v_mfma_f32_16x16x32_bf16 v[58:61], v[94:97], v[154:157], v[58:61]
	v_mfma_f32_16x16x32_bf16 v[46:49], v[78:81], v[162:165], v[46:49]
	v_mfma_f32_16x16x32_bf16 v[42:45], v[94:97], v[162:165], v[42:45]
	v_mfma_f32_16x16x32_bf16 v[30:33], v[78:81], v[170:173], v[30:33]
	v_mfma_f32_16x16x32_bf16 v[26:29], v[94:97], v[170:173], v[26:29]
	v_mfma_f32_16x16x32_bf16 v[12:15], v[78:81], v[186:189], v[12:15]
	v_mfma_f32_16x16x32_bf16 v[8:11], v[94:97], v[186:189], v[8:11]
	v_mfma_f32_16x16x32_bf16 v[62:65], v[86:89], v[158:161], v[62:65]
	v_mfma_f32_16x16x32_bf16 v[58:61], v[102:105], v[158:161], v[58:61]
	v_mfma_f32_16x16x32_bf16 v[46:49], v[86:89], v[166:169], v[46:49]
	v_mfma_f32_16x16x32_bf16 v[42:45], v[102:105], v[166:169], v[42:45]
	v_mfma_f32_16x16x32_bf16 v[30:33], v[86:89], v[182:185], v[30:33]
	v_mfma_f32_16x16x32_bf16 v[26:29], v[102:105], v[182:185], v[26:29]
	v_mfma_f32_16x16x32_bf16 v[12:15], v[86:89], v[190:193], v[12:15]
	v_mfma_f32_16x16x32_bf16 v[8:11], v[102:105], v[190:193], v[8:11]
	v_mfma_f32_16x16x32_bf16 v[54:57], v[118:121], v[154:157], v[54:57]
	v_mfma_f32_16x16x32_bf16 v[50:53], v[134:137], v[154:157], v[50:53]
	v_mfma_f32_16x16x32_bf16 v[38:41], v[118:121], v[162:165], v[38:41]
	v_mfma_f32_16x16x32_bf16 v[34:37], v[134:137], v[162:165], v[34:37]
	v_mfma_f32_16x16x32_bf16 v[22:25], v[118:121], v[170:173], v[22:25]
	v_mfma_f32_16x16x32_bf16 v[16:19], v[134:137], v[170:173], v[16:19]
	v_mfma_f32_16x16x32_bf16 v[4:7], v[118:121], v[186:189], v[4:7]
	v_mfma_f32_16x16x32_bf16 v[0:3], v[134:137], v[186:189], v[0:3]
	v_mfma_f32_16x16x32_bf16 v[54:57], v[126:129], v[158:161], v[54:57]
	v_mfma_f32_16x16x32_bf16 v[50:53], v[142:145], v[158:161], v[50:53]
	v_mfma_f32_16x16x32_bf16 v[38:41], v[126:129], v[166:169], v[38:41]
	v_mfma_f32_16x16x32_bf16 v[34:37], v[142:145], v[166:169], v[34:37]
	v_mfma_f32_16x16x32_bf16 v[22:25], v[126:129], v[182:185], v[22:25]
	v_mfma_f32_16x16x32_bf16 v[16:19], v[142:145], v[182:185], v[16:19]
	v_mfma_f32_16x16x32_bf16 v[4:7], v[126:129], v[190:193], v[4:7]
	v_mfma_f32_16x16x32_bf16 v[0:3], v[142:145], v[190:193], v[0:3]
	s_barrier
	s_add_i32 s57, 0, 0x18000
	s_add_i32 s58, 0, 0x1c000
	v_add_u32_e32 v102, s57, v208
	v_add_u32_e32 v142, s58, v208
	ds_read_b128 v[78:81], v102
	ds_read_b128 v[86:89], v102 offset:1024
	ds_read_b128 v[94:97], v102 offset:2048
	ds_read_b128 v[102:105], v102 offset:3072
	ds_read_b128 v[118:121], v142
	ds_read_b128 v[126:129], v142 offset:1024
	ds_read_b128 v[134:137], v142 offset:2048
	ds_read_b128 v[142:145], v142 offset:3072
	s_add_u32 s28, s38, 0x160000
	s_addc_u32 s29, s39, 0
	s_mov_b32 m0, s41
	s_nop 0
	global_load_lds_dwordx4 v216, s[38:39]
	s_mov_b32 m0, s42
	ds_read_b128 v[154:157], v244 offset:32768
	ds_read_b128 v[158:161], v244 offset:33792
	ds_read_b128 v[162:165], v244 offset:34816
	ds_read_b128 v[166:169], v244 offset:35840
	ds_read_b128 v[170:173], v244 offset:36864
	ds_read_b128 v[182:185], v244 offset:37888
	ds_read_b128 v[186:189], v244 offset:38912
	ds_read_b128 v[190:193], v244 offset:39936
	global_load_lds_dwordx4 v220, s[28:29]
	s_mov_b32 m0, s43
	s_nop 0
	global_load_lds_dwordx4 v216, s[28:29]
	s_waitcnt vmcnt(8)
	s_waitcnt lgkmcnt(0)
	s_barrier
	v_mfma_f32_16x16x32_bf16 v[178:181], v[78:81], v[154:157], v[178:181]
	v_mfma_f32_16x16x32_bf16 v[174:177], v[94:97], v[154:157], v[174:177]
	v_mfma_f32_16x16x32_bf16 v[138:141], v[78:81], v[162:165], v[138:141]
	v_mfma_f32_16x16x32_bf16 v[130:133], v[94:97], v[162:165], v[130:133]
	v_mfma_f32_16x16x32_bf16 v[110:113], v[78:81], v[170:173], v[110:113]
	v_mfma_f32_16x16x32_bf16 v[106:109], v[94:97], v[170:173], v[106:109]
	v_mfma_f32_16x16x32_bf16 v[82:85], v[78:81], v[186:189], v[82:85]
	v_mfma_f32_16x16x32_bf16 v[74:77], v[94:97], v[186:189], v[74:77]
	v_mfma_f32_16x16x32_bf16 v[178:181], v[86:89], v[158:161], v[178:181]
	v_mfma_f32_16x16x32_bf16 v[174:177], v[102:105], v[158:161], v[174:177]
	v_mfma_f32_16x16x32_bf16 v[138:141], v[86:89], v[166:169], v[138:141]
	v_mfma_f32_16x16x32_bf16 v[130:133], v[102:105], v[166:169], v[130:133]
	v_mfma_f32_16x16x32_bf16 v[110:113], v[86:89], v[182:185], v[110:113]
	v_mfma_f32_16x16x32_bf16 v[106:109], v[102:105], v[182:185], v[106:109]
	v_mfma_f32_16x16x32_bf16 v[82:85], v[86:89], v[190:193], v[82:85]
	v_mfma_f32_16x16x32_bf16 v[74:77], v[102:105], v[190:193], v[74:77]
	v_mfma_f32_16x16x32_bf16 v[150:153], v[118:121], v[154:157], v[150:153]
	v_mfma_f32_16x16x32_bf16 v[146:149], v[134:137], v[154:157], v[146:149]
	v_mfma_f32_16x16x32_bf16 v[122:125], v[118:121], v[162:165], v[122:125]
	v_mfma_f32_16x16x32_bf16 v[114:117], v[134:137], v[162:165], v[114:117]
	v_mfma_f32_16x16x32_bf16 v[98:101], v[118:121], v[170:173], v[98:101]
	v_mfma_f32_16x16x32_bf16 v[90:93], v[134:137], v[170:173], v[90:93]
	v_mfma_f32_16x16x32_bf16 v[70:73], v[118:121], v[186:189], v[70:73]
	v_mfma_f32_16x16x32_bf16 v[66:69], v[134:137], v[186:189], v[66:69]
	v_mfma_f32_16x16x32_bf16 v[150:153], v[126:129], v[158:161], v[150:153]
	v_mfma_f32_16x16x32_bf16 v[146:149], v[142:145], v[158:161], v[146:149]
	v_mfma_f32_16x16x32_bf16 v[122:125], v[126:129], v[166:169], v[122:125]
	v_mfma_f32_16x16x32_bf16 v[114:117], v[142:145], v[166:169], v[114:117]
	v_mfma_f32_16x16x32_bf16 v[98:101], v[126:129], v[182:185], v[98:101]
	v_mfma_f32_16x16x32_bf16 v[90:93], v[142:145], v[182:185], v[90:93]
	v_mfma_f32_16x16x32_bf16 v[70:73], v[126:129], v[190:193], v[70:73]
	v_mfma_f32_16x16x32_bf16 v[66:69], v[142:145], v[190:193], v[66:69]
	s_barrier
; #define PG8_STAGE(bufoff, gbase, voff) do { _Pragma("unroll") for (int _i = 0; _i < 2; ++_i) \
;         __builtin_amdgcn_global_load_lds((const unsigned*)((const char*)(gbase) + (voff)[_i]), (PG8_LAS unsigned*)(lds + (bufoff) + ldsw + _i * 8192), 16, 0, 0); } while (0)
; #define PG8_LDA(dst, b, h) do { _Pragma("unroll") for (int m = 0; m < 4; ++m) _Pragma("unroll") for (int k = 0; k < 2; ++k) dst[m][k] = *(const PG8_LAS bf16x8*)(lds + PG8_SA(b, h) + aoff + m * 2048 + k * 1024); } while (0)
; #define PG8_MMA(ai, bj, At, Bt) do { __builtin_amdgcn_s_setprio(1); _Pragma("unroll") for (int m = 0; m < 4; ++m) _Pragma("unroll") for (int n = 0; n < 2; ++n) _Pragma("unroll") for (int k = 0; k < 2; ++k) \
;         acc[ai][bj][m][n] = __builtin_amdgcn_mfma_f32_16x16x32_bf16(Bt[n][k], At[m][k], acc[ai][bj][m][n], 0, 0, 0); __builtin_amdgcn_s_setprio(0); } while (0)
; #define PG8_WAIT_V(n) asm volatile("s_waitcnt vmcnt(" #n ")" ::: "memory")
; #define PG8_WAIT_L(n) asm volatile("s_waitcnt lgkmcnt(" #n ")" ::: "memory")
; #define PG8_BAR __builtin_amdgcn_s_barrier()
; #define PG8_SCHED __builtin_amdgcn_sched_barrier(0)
; template <class Epi, class Sched, bool ALIGN_EPI = false, bool SP2 = false>
; __device__ __forceinline__ void gemm_phase(PG8_LAS unsigned char* lds, const Gemm g, const Sched& S, const Epi& E, const int tid_in) {
;     ...
;             PG8_LDA(At, 1, 1); PG8_STAGE(PG8_SB(1, 0), b3, voffB); PG8_STAGE(PG8_SB(1, 1), b3 + hstep, voffB); PG8_STAGE(PG8_SA(1, 0), a3, voffA);
;             PG8_WAIT_V(8); PG8_WAIT_L(0); PG8_BAR; PG8_MMA(1, 0, At, B0); PG8_MMA(1, 1, At, B1); PG8_BAR; PG8_SCHED;
;     ...
;         if constexpr (ALIGN_EPI) { if (wr == 0) PG8_BAR; }
;         if constexpr (Epi::PREF) { if (has_next) E.prefetch(nxt, (ui + 1) & 1, lds, wid, lane); E.run(acc, cur, wr, wc, fr, fq, lds, ui & 1); S.done(cur); }
	s_add_i32 s28, s57, s19
	s_mov_b32 m0, s28
	ds_read_b128 v[154:157], v244 offset:49152
	ds_read_b128 v[158:161], v244 offset:50176
	ds_read_b128 v[162:165], v244 offset:51200
	ds_read_b128 v[166:169], v244 offset:52224
	ds_read_b128 v[170:173], v244 offset:53248
	ds_read_b128 v[182:185], v244 offset:54272
	ds_read_b128 v[186:189], v244 offset:55296
	ds_read_b128 v[190:193], v244 offset:56320
	global_load_lds_dwordx4 v218, s[98:99]
	s_add_i32 m0, s28, 0x2000
	s_add_u32 s28, s34, 0x160080
	s_addc_u32 s29, s35, 0
	s_add_i32 s34, s58, s19
	global_load_lds_dwordx4 v214, s[98:99]
	s_mov_b32 m0, s34
	s_nop 0
	global_load_lds_dwordx4 v218, s[28:29]
	s_add_i32 m0, s34, 0x2000
	s_nop 0
	global_load_lds_dwordx4 v214, s[28:29]
	s_mov_b32 m0, s46
	s_nop 0
	global_load_lds_dwordx4 v220, s[100:101]
	s_waitcnt vmcnt(7)
	s_waitcnt lgkmcnt(0)
	s_barrier
	v_mfma_f32_16x16x32_bf16 v[62:65], v[78:81], v[154:157], v[62:65]
	v_mfma_f32_16x16x32_bf16 v[58:61], v[94:97], v[154:157], v[58:61]
	v_mfma_f32_16x16x32_bf16 v[46:49], v[78:81], v[162:165], v[46:49]
	v_mfma_f32_16x16x32_bf16 v[42:45], v[94:97], v[162:165], v[42:45]
	v_mfma_f32_16x16x32_bf16 v[30:33], v[78:81], v[170:173], v[30:33]
	v_mfma_f32_16x16x32_bf16 v[26:29], v[94:97], v[170:173], v[26:29]
	v_mfma_f32_16x16x32_bf16 v[12:15], v[78:81], v[186:189], v[12:15]
	v_mfma_f32_16x16x32_bf16 v[8:11], v[94:97], v[186:189], v[8:11]
	v_mfma_f32_16x16x32_bf16 v[62:65], v[86:89], v[158:161], v[62:65]
	v_mfma_f32_16x16x32_bf16 v[58:61], v[102:105], v[158:161], v[58:61]
	v_mfma_f32_16x16x32_bf16 v[46:49], v[86:89], v[166:169], v[46:49]
	v_mfma_f32_16x16x32_bf16 v[42:45], v[102:105], v[166:169], v[42:45]
	v_mfma_f32_16x16x32_bf16 v[30:33], v[86:89], v[182:185], v[30:33]
	v_mfma_f32_16x16x32_bf16 v[26:29], v[102:105], v[182:185], v[26:29]
	v_mfma_f32_16x16x32_bf16 v[12:15], v[86:89], v[190:193], v[12:15]
	v_mfma_f32_16x16x32_bf16 v[8:11], v[102:105], v[190:193], v[8:11]
	v_mfma_f32_16x16x32_bf16 v[54:57], v[118:121], v[154:157], v[54:57]
	v_mfma_f32_16x16x32_bf16 v[50:53], v[134:137], v[154:157], v[50:53]
	v_mfma_f32_16x16x32_bf16 v[38:41], v[118:121], v[162:165], v[38:41]
	v_mfma_f32_16x16x32_bf16 v[34:37], v[134:137], v[162:165], v[34:37]
	v_mfma_f32_16x16x32_bf16 v[22:25], v[118:121], v[170:173], v[22:25]
	v_mfma_f32_16x16x32_bf16 v[16:19], v[134:137], v[170:173], v[16:19]
	v_mfma_f32_16x16x32_bf16 v[4:7], v[118:121], v[186:189], v[4:7]
	v_mfma_f32_16x16x32_bf16 v[0:3], v[134:137], v[186:189], v[0:3]
	v_mfma_f32_16x16x32_bf16 v[54:57], v[126:129], v[158:161], v[54:57]
	v_mfma_f32_16x16x32_bf16 v[50:53], v[142:145], v[158:161], v[50:53]
	v_mfma_f32_16x16x32_bf16 v[38:41], v[126:129], v[166:169], v[38:41]
	v_mfma_f32_16x16x32_bf16 v[34:37], v[142:145], v[166:169], v[34:37]
	v_mfma_f32_16x16x32_bf16 v[22:25], v[126:129], v[182:185], v[22:25]
	v_mfma_f32_16x16x32_bf16 v[16:19], v[142:145], v[182:185], v[16:19]
	v_mfma_f32_16x16x32_bf16 v[4:7], v[126:129], v[190:193], v[4:7]
	v_mfma_f32_16x16x32_bf16 v[0:3], v[142:145], v[190:193], v[0:3]
	s_barrier
	s_add_i32 s56, s56, 2
	s_add_u32 s54, s54, 0x100
	s_addc_u32 s55, s55, 0
	s_cmpk_gt_u32 s56, 0x55
	s_mov_b64 s[28:29], s[30:31]
	s_cbranch_scc0 .LBB0_1305
	s_setprio 0
	v_mov_b32_e32 v207, 0x7f800000
	s_and_b64 vcc, exec, s[22:23]
	s_cbranch_vccz .LBB0_1308
	s_barrier
